# redundant-wait elision: 58 s_waitcnt already satisfied by counter upper bounds removed (13 narrowed), on top of the dead-code sweep
# baseline (speedup 1.0000x reference)
.LBB0_268:
	s_add_u32 s4, s82, s40
	s_addc_u32 s7, s83, s41
	s_and_b64 s[10:11], s[12:13], exec
	s_cselect_b32 s10, s4, 0
	v_readlane_b32 s4, v251, 58
	s_cselect_b32 s11, s7, 0
	s_add_u32 s4, s4, s42
	v_readlane_b32 s7, v251, 59
	s_addc_u32 s7, s7, s43
	s_and_b64 s[40:41], s[12:13], exec
	s_cselect_b32 s41, s7, 0
	s_cselect_b32 s40, s4, 0
	v_lshl_add_u64 v[4:5], s[10:11], 0, v[0:1]
	v_lshl_add_u64 v[0:1], s[40:41], 0, v[0:1]
	v_lshl_add_u64 v[146:147], v[0:1], 0, v[96:97]
	v_lshrrev_b32_e32 v0, 1, v2
	v_and_b32_e32 v1, 31, v2
	v_and_or_b32 v1, v0, s81, v1
	v_lshrrev_b32_e32 v0, 2, v2
	v_and_b32_e32 v0, 8, v0
	v_lshl_add_u64 v[148:149], v[4:5], 0, v[96:97]
	v_mad_u64_u32 v[4:5], s[10:11], v1, s84, v[0:1]
	v_and_b32_e32 v1, 0x5f, v2
	v_mad_u32_u24 v0, v1, s84, v0
	v_lshl_add_u32 v176, v4, 1, 0
	v_lshl_add_u32 v96, v0, 1, 0
	v_add_u32_e32 v177, 0xd800, v175
	s_setprio 1
	ds_read_b128 v[212:215], v96 offset:36864
	ds_read_b128 v[216:219], v176
	ds_read_b128 v[220:223], v176 offset:4608
	ds_read_b128 v[224:227], v96 offset:36896
	ds_read_b128 v[228:231], v176 offset:32
	ds_read_b128 v[244:247], v176 offset:4640
	ds_read_b128 v[252:255], v96 offset:41472
	s_waitcnt lgkmcnt(5)
	v_mfma_f32_32x32x16_bf16 v[32:47], v[212:215], v[216:219], 0
	s_waitcnt lgkmcnt(4)
	v_mfma_f32_32x32x16_bf16 v[0:15], v[212:215], v[220:223], 0
	ds_read_b128 v[212:215], v96 offset:41504
	s_waitcnt lgkmcnt(3)
	v_mfma_f32_32x32x16_bf16 v[32:47], v[224:227], v[228:231], v[32:47]
	s_waitcnt lgkmcnt(2)
	v_mfma_f32_32x32x16_bf16 v[0:15], v[224:227], v[244:247], v[0:15]
	ds_read_b128 v[224:227], v96 offset:36928
	s_waitcnt lgkmcnt(2)
	v_mfma_f32_32x32x16_bf16 v[48:63], v[252:255], v[216:219], 0
	ds_read_b128 v[216:219], v176 offset:64
	v_mfma_f32_32x32x16_bf16 v[16:31], v[252:255], v[220:223], 0
	ds_read_b128 v[252:255], v176 offset:4672
	ds_read_b128 v[220:223], v96 offset:41536
	s_waitcnt lgkmcnt(4)
	v_mfma_f32_32x32x16_bf16 v[48:63], v[212:215], v[228:231], v[48:63]
	ds_read_b128 v[228:231], v96 offset:36960
	v_mfma_f32_32x32x16_bf16 v[16:31], v[212:215], v[244:247], v[16:31]
	ds_read_b128 v[212:215], v176 offset:96
	ds_read_b128 v[244:247], v176 offset:4704
	s_waitcnt lgkmcnt(5)
	v_mfma_f32_32x32x16_bf16 v[32:47], v[224:227], v[216:219], v[32:47]
	s_mov_b32 s4, 0x10000
	v_add_co_u32_e32 v154, vcc, s4, v152
	s_mov_b32 s7, 0x20000
	s_nop 0
	v_addc_co_u32_e32 v155, vcc, 0, v153, vcc
	v_add_co_u32_e32 v156, vcc, s7, v152
	s_mov_b32 s9, 0x30000
	s_nop 0
	s_waitcnt lgkmcnt(4)
	v_mfma_f32_32x32x16_bf16 v[0:15], v[224:227], v[252:255], v[0:15]
	ds_read_b128 v[224:227], v96 offset:41568
	v_addc_co_u32_e32 v157, vcc, 0, v153, vcc
	v_add_co_u32_e32 v158, vcc, s9, v152
	s_waitcnt vmcnt(11)
	ds_write_b128 v175, v[100:103] offset:18432
	s_waitcnt vmcnt(10)
	ds_write_b128 v175, v[104:107] offset:23040
	s_waitcnt lgkmcnt(6)
	v_mfma_f32_32x32x16_bf16 v[48:63], v[220:223], v[216:219], v[48:63]
	s_waitcnt vmcnt(9)
	ds_write_b128 v175, v[108:111] offset:27648
	s_waitcnt vmcnt(8)
	ds_write_b128 v175, v[112:115] offset:32256
	v_mfma_f32_32x32x16_bf16 v[16:31], v[220:223], v[252:255], v[16:31]
	s_waitcnt vmcnt(7)
	ds_write_b128 v175, v[116:119] offset:55296
	s_waitcnt vmcnt(6)
	ds_write_b128 v175, v[124:127] offset:59904
	s_waitcnt vmcnt(5)
	ds_write_b128 v175, v[120:123] offset:64512
	s_waitcnt lgkmcnt(9)
	v_mfma_f32_32x32x16_bf16 v[32:47], v[228:231], v[212:215], v[32:47]
	s_waitcnt vmcnt(4)
	ds_write_b128 v177, v[128:131] offset:13824
	v_addc_co_u32_e32 v159, vcc, 0, v153, vcc
	v_add_co_u32_e32 v160, vcc, s4, v150
	s_waitcnt lgkmcnt(9)
	v_mfma_f32_32x32x16_bf16 v[0:15], v[228:231], v[244:247], v[0:15]
	global_load_dwordx4 v[98:101], v[152:153], off offset:384
	global_load_dwordx4 v[102:105], v[154:155], off offset:384
	v_addc_co_u32_e32 v161, vcc, 0, v151, vcc
	v_add_co_u32_e32 v170, vcc, s7, v150
	global_load_dwordx4 v[106:109], v[156:157], off offset:384
	s_waitcnt lgkmcnt(8)
	v_mfma_f32_32x32x16_bf16 v[48:63], v[224:227], v[212:215], v[48:63]
	s_nop 0
	v_addc_co_u32_e32 v171, vcc, 0, v151, vcc
	v_add_co_u32_e32 v172, vcc, s9, v150
	global_load_dwordx4 v[110:113], v[158:159], off offset:384
	global_load_dwordx4 v[114:117], v[150:151], off offset:384
	v_mfma_f32_32x32x16_bf16 v[16:31], v[224:227], v[244:247], v[16:31]
	v_addc_co_u32_e32 v173, vcc, 0, v151, vcc
	global_load_dwordx4 v[118:121], v[160:161], off offset:384
	global_load_dwordx4 v[122:125], v[170:171], off offset:384
	global_load_dwordx4 v[130:133], v[172:173], off offset:384
	s_setprio 0
	s_waitcnt lgkmcnt(0)
	s_barrier
	s_setprio 1
	ds_read_b128 v[212:215], v96 offset:55296
	ds_read_b128 v[216:219], v176 offset:18432
	ds_read_b128 v[220:223], v176 offset:23040
	ds_read_b128 v[224:227], v96 offset:59904
	ds_read_b128 v[228:231], v96 offset:55328
	ds_read_b128 v[244:247], v176 offset:18464
	ds_read_b128 v[252:255], v176 offset:23072
	s_waitcnt lgkmcnt(5)
	v_mfma_f32_32x32x16_bf16 v[32:47], v[212:215], v[216:219], v[32:47]
	s_waitcnt lgkmcnt(4)
	v_mfma_f32_32x32x16_bf16 v[0:15], v[212:215], v[220:223], v[0:15]
	ds_read_b128 v[212:215], v96 offset:59936
	s_waitcnt lgkmcnt(4)
	v_mfma_f32_32x32x16_bf16 v[48:63], v[224:227], v[216:219], v[48:63]
	ds_read_b128 v[216:219], v96 offset:55360
	v_mfma_f32_32x32x16_bf16 v[16:31], v[224:227], v[220:223], v[16:31]
	ds_read_b128 v[224:227], v176 offset:18496
	ds_read_b128 v[220:223], v176 offset:23104
	s_waitcnt lgkmcnt(5)
	v_mfma_f32_32x32x16_bf16 v[32:47], v[228:231], v[244:247], v[32:47]
	s_waitcnt lgkmcnt(4)
	v_mfma_f32_32x32x16_bf16 v[0:15], v[228:231], v[252:255], v[0:15]
	ds_read_b128 v[228:231], v96 offset:59968
	s_waitcnt lgkmcnt(4)
	v_mfma_f32_32x32x16_bf16 v[48:63], v[212:215], v[244:247], v[48:63]
	ds_read_b128 v[244:247], v96 offset:55392
	v_mfma_f32_32x32x16_bf16 v[16:31], v[212:215], v[252:255], v[16:31]
	ds_read_b128 v[212:215], v176 offset:18528
	ds_read_b128 v[252:255], v176 offset:23136
	s_waitcnt lgkmcnt(5)
	v_mfma_f32_32x32x16_bf16 v[32:47], v[216:219], v[224:227], v[32:47]
	s_nop 0
	ds_write_b128 v175, v[64:67]
	global_load_dwordx4 v[64:67], v[152:153], off offset:512
	s_waitcnt lgkmcnt(5)
	v_mfma_f32_32x32x16_bf16 v[0:15], v[216:219], v[220:223], v[0:15]
	ds_read_b128 v[216:219], v96 offset:60000
	s_nop 0
	ds_write_b128 v175, v[68:71] offset:4608
	s_nop 0
	ds_write_b128 v175, v[72:75] offset:9216
	s_waitcnt lgkmcnt(7)
	v_mfma_f32_32x32x16_bf16 v[48:63], v[228:231], v[224:227], v[48:63]
	global_load_dwordx4 v[72:75], v[154:155], off offset:512
	s_nop 0
	ds_write_b128 v175, v[76:79] offset:13824
	v_mfma_f32_32x32x16_bf16 v[16:31], v[228:231], v[220:223], v[16:31]
	global_load_dwordx4 v[76:79], v[156:157], off offset:512
	s_waitcnt vmcnt(14)
	ds_write_b128 v175, v[80:83] offset:36864
	s_waitcnt lgkmcnt(7)
	v_mfma_f32_32x32x16_bf16 v[32:47], v[244:247], v[212:215], v[32:47]
	global_load_dwordx4 v[80:83], v[158:159], off offset:512
	global_load_dwordx4 v[126:129], v[150:151], off offset:512
	s_waitcnt lgkmcnt(6)
	v_mfma_f32_32x32x16_bf16 v[0:15], v[244:247], v[252:255], v[0:15]
	s_waitcnt vmcnt(15)
	ds_write_b128 v175, v[84:87] offset:41472
	global_load_dwordx4 v[134:137], v[160:161], off offset:512
	s_waitcnt lgkmcnt(5)
	v_mfma_f32_32x32x16_bf16 v[48:63], v[216:219], v[212:215], v[48:63]
	s_waitcnt vmcnt(15)
	ds_write_b128 v175, v[88:91] offset:46080
	global_load_dwordx4 v[138:141], v[170:171], off offset:512
	v_mfma_f32_32x32x16_bf16 v[16:31], v[216:219], v[252:255], v[16:31]
	s_waitcnt vmcnt(15)
	ds_write_b128 v175, v[92:95] offset:50688
	global_load_dwordx4 v[142:145], v[172:173], off offset:512
	s_setprio 0
	s_waitcnt lgkmcnt(0)
	s_barrier
	s_setprio 1
	ds_read_b128 v[212:215], v96 offset:36864
	ds_read_b128 v[216:219], v176
	ds_read_b128 v[220:223], v176 offset:4608
	ds_read_b128 v[224:227], v96 offset:41472
	ds_read_b128 v[228:231], v96 offset:36896
	ds_read_b128 v[244:247], v176 offset:32
	ds_read_b128 v[252:255], v176 offset:4640
	s_waitcnt lgkmcnt(5)
	v_mfma_f32_32x32x16_bf16 v[32:47], v[212:215], v[216:219], v[32:47]
	s_waitcnt lgkmcnt(4)
	v_mfma_f32_32x32x16_bf16 v[0:15], v[212:215], v[220:223], v[0:15]
	ds_read_b128 v[212:215], v96 offset:41504
	s_waitcnt lgkmcnt(4)
	v_mfma_f32_32x32x16_bf16 v[48:63], v[224:227], v[216:219], v[48:63]
	ds_read_b128 v[216:219], v96 offset:36928
	v_mfma_f32_32x32x16_bf16 v[16:31], v[224:227], v[220:223], v[16:31]
	ds_read_b128 v[224:227], v176 offset:64
	ds_read_b128 v[220:223], v176 offset:4672
	s_waitcnt lgkmcnt(5)
	v_mfma_f32_32x32x16_bf16 v[32:47], v[228:231], v[244:247], v[32:47]
	s_waitcnt lgkmcnt(4)
	v_mfma_f32_32x32x16_bf16 v[0:15], v[228:231], v[252:255], v[0:15]
	ds_read_b128 v[228:231], v96 offset:41536
	s_waitcnt lgkmcnt(4)
	v_mfma_f32_32x32x16_bf16 v[48:63], v[212:215], v[244:247], v[48:63]
	ds_read_b128 v[244:247], v96 offset:36960
	v_mfma_f32_32x32x16_bf16 v[16:31], v[212:215], v[252:255], v[16:31]
	ds_read_b128 v[212:215], v176 offset:96
	ds_read_b128 v[252:255], v176 offset:4704
	s_waitcnt lgkmcnt(5)
	v_mfma_f32_32x32x16_bf16 v[32:47], v[216:219], v[224:227], v[32:47]
	s_waitcnt vmcnt(15)
	ds_write_b128 v175, v[98:101] offset:18432
	global_load_dwordx4 v[68:71], v[152:153], off offset:640
	s_waitcnt lgkmcnt(5)
	v_mfma_f32_32x32x16_bf16 v[0:15], v[216:219], v[220:223], v[0:15]
	ds_read_b128 v[216:219], v96 offset:41568
	s_waitcnt vmcnt(15)
	ds_write_b128 v175, v[102:105] offset:23040
	global_load_dwordx4 v[84:87], v[154:155], off offset:640
	s_waitcnt lgkmcnt(6)
	v_mfma_f32_32x32x16_bf16 v[48:63], v[228:231], v[224:227], v[48:63]
	s_waitcnt vmcnt(15)
	ds_write_b128 v175, v[106:109] offset:27648
	global_load_dwordx4 v[88:91], v[156:157], off offset:640
	v_mfma_f32_32x32x16_bf16 v[16:31], v[228:231], v[220:223], v[16:31]
	s_waitcnt vmcnt(15)
	ds_write_b128 v175, v[110:113] offset:32256
	global_load_dwordx4 v[92:95], v[158:159], off offset:640
	s_waitcnt lgkmcnt(6)
	v_mfma_f32_32x32x16_bf16 v[32:47], v[244:247], v[212:215], v[32:47]
	s_waitcnt vmcnt(15)
	ds_write_b128 v175, v[114:117] offset:55296
	global_load_dwordx4 v[98:101], v[150:151], off offset:640
	s_waitcnt lgkmcnt(6)
	v_mfma_f32_32x32x16_bf16 v[0:15], v[244:247], v[252:255], v[0:15]
	s_waitcnt vmcnt(15)
	ds_write_b128 v175, v[118:121] offset:59904
	global_load_dwordx4 v[106:109], v[160:161], off offset:640
	s_waitcnt lgkmcnt(5)
	v_mfma_f32_32x32x16_bf16 v[48:63], v[216:219], v[212:215], v[48:63]
	s_waitcnt vmcnt(15)
	ds_write_b128 v175, v[122:125] offset:64512
	global_load_dwordx4 v[110:113], v[170:171], off offset:640
	v_mfma_f32_32x32x16_bf16 v[16:31], v[216:219], v[252:255], v[16:31]
	s_waitcnt vmcnt(15)
	ds_write_b128 v177, v[130:133] offset:13824
	global_load_dwordx4 v[114:117], v[172:173], off offset:640
	s_setprio 0
	s_waitcnt lgkmcnt(0)
	s_barrier
	s_setprio 1
	ds_read_b128 v[212:215], v96 offset:55296
	ds_read_b128 v[216:219], v176 offset:18432
	ds_read_b128 v[220:223], v176 offset:23040
	ds_read_b128 v[224:227], v96 offset:59904
	ds_read_b128 v[228:231], v96 offset:55328
	ds_read_b128 v[244:247], v176 offset:18464
	ds_read_b128 v[252:255], v176 offset:23072
	s_waitcnt lgkmcnt(5)
	v_mfma_f32_32x32x16_bf16 v[32:47], v[212:215], v[216:219], v[32:47]
	s_waitcnt lgkmcnt(4)
	v_mfma_f32_32x32x16_bf16 v[0:15], v[212:215], v[220:223], v[0:15]
	ds_read_b128 v[212:215], v96 offset:59936
	s_waitcnt lgkmcnt(4)
	v_mfma_f32_32x32x16_bf16 v[48:63], v[224:227], v[216:219], v[48:63]
	ds_read_b128 v[216:219], v96 offset:55360
	v_mfma_f32_32x32x16_bf16 v[16:31], v[224:227], v[220:223], v[16:31]
	ds_read_b128 v[224:227], v176 offset:18496
	ds_read_b128 v[220:223], v176 offset:23104
	s_waitcnt lgkmcnt(5)
	v_mfma_f32_32x32x16_bf16 v[32:47], v[228:231], v[244:247], v[32:47]
	s_waitcnt lgkmcnt(4)
	v_mfma_f32_32x32x16_bf16 v[0:15], v[228:231], v[252:255], v[0:15]
	ds_read_b128 v[228:231], v96 offset:59968
	s_waitcnt lgkmcnt(4)
	v_mfma_f32_32x32x16_bf16 v[48:63], v[212:215], v[244:247], v[48:63]
	ds_read_b128 v[244:247], v96 offset:55392
	v_mfma_f32_32x32x16_bf16 v[16:31], v[212:215], v[252:255], v[16:31]
	ds_read_b128 v[212:215], v176 offset:18528
	ds_read_b128 v[252:255], v176 offset:23136
	s_waitcnt lgkmcnt(5)
	v_mfma_f32_32x32x16_bf16 v[32:47], v[216:219], v[224:227], v[32:47]
	s_waitcnt vmcnt(15)
	ds_write_b128 v175, v[64:67]
	global_load_dwordx4 v[64:67], v[152:153], off offset:768
	s_waitcnt lgkmcnt(5)
	v_mfma_f32_32x32x16_bf16 v[0:15], v[216:219], v[220:223], v[0:15]
	ds_read_b128 v[216:219], v96 offset:60000
	s_waitcnt vmcnt(15)
	ds_write_b128 v175, v[72:75] offset:4608
	global_load_dwordx4 v[72:75], v[154:155], off offset:768
	s_waitcnt lgkmcnt(6)
	v_mfma_f32_32x32x16_bf16 v[48:63], v[228:231], v[224:227], v[48:63]
	s_waitcnt vmcnt(15)
	ds_write_b128 v175, v[76:79] offset:9216
	global_load_dwordx4 v[76:79], v[156:157], off offset:768
	v_mfma_f32_32x32x16_bf16 v[16:31], v[228:231], v[220:223], v[16:31]
	s_waitcnt vmcnt(15)
	ds_write_b128 v175, v[80:83] offset:13824
	global_load_dwordx4 v[80:83], v[158:159], off offset:768
	s_waitcnt lgkmcnt(6)
	v_mfma_f32_32x32x16_bf16 v[32:47], v[244:247], v[212:215], v[32:47]
	s_waitcnt vmcnt(15)
	ds_write_b128 v175, v[126:129] offset:36864
	global_load_dwordx4 v[102:105], v[150:151], off offset:768
	s_waitcnt lgkmcnt(6)
	v_mfma_f32_32x32x16_bf16 v[0:15], v[244:247], v[252:255], v[0:15]
	s_waitcnt vmcnt(15)
	ds_write_b128 v175, v[134:137] offset:41472
	global_load_dwordx4 v[118:121], v[160:161], off offset:768
	s_waitcnt lgkmcnt(5)
	v_mfma_f32_32x32x16_bf16 v[48:63], v[216:219], v[212:215], v[48:63]
	s_waitcnt vmcnt(15)
	ds_write_b128 v175, v[138:141] offset:46080
	global_load_dwordx4 v[122:125], v[170:171], off offset:768
	v_mfma_f32_32x32x16_bf16 v[16:31], v[216:219], v[252:255], v[16:31]
	s_waitcnt vmcnt(15)
	ds_write_b128 v175, v[142:145] offset:50688
	global_load_dwordx4 v[126:129], v[172:173], off offset:768
	s_setprio 0
	s_waitcnt lgkmcnt(0)
	s_barrier
	s_setprio 1
	ds_read_b128 v[212:215], v96 offset:36864
	ds_read_b128 v[216:219], v176
	ds_read_b128 v[220:223], v176 offset:4608
	ds_read_b128 v[224:227], v96 offset:41472
	ds_read_b128 v[228:231], v96 offset:36896
	ds_read_b128 v[244:247], v176 offset:32
	ds_read_b128 v[252:255], v176 offset:4640
	s_waitcnt lgkmcnt(5)
	v_mfma_f32_32x32x16_bf16 v[32:47], v[212:215], v[216:219], v[32:47]
	s_waitcnt lgkmcnt(4)
	v_mfma_f32_32x32x16_bf16 v[0:15], v[212:215], v[220:223], v[0:15]
	ds_read_b128 v[212:215], v96 offset:41504
	s_waitcnt lgkmcnt(4)
	v_mfma_f32_32x32x16_bf16 v[48:63], v[224:227], v[216:219], v[48:63]
	ds_read_b128 v[216:219], v96 offset:36928
	v_mfma_f32_32x32x16_bf16 v[16:31], v[224:227], v[220:223], v[16:31]
	ds_read_b128 v[224:227], v176 offset:64
	ds_read_b128 v[220:223], v176 offset:4672
	s_waitcnt lgkmcnt(5)
	v_mfma_f32_32x32x16_bf16 v[32:47], v[228:231], v[244:247], v[32:47]
	s_waitcnt lgkmcnt(4)
	v_mfma_f32_32x32x16_bf16 v[0:15], v[228:231], v[252:255], v[0:15]
	ds_read_b128 v[228:231], v96 offset:41536
	s_waitcnt lgkmcnt(4)
	v_mfma_f32_32x32x16_bf16 v[48:63], v[212:215], v[244:247], v[48:63]
	ds_read_b128 v[244:247], v96 offset:36960
	v_mfma_f32_32x32x16_bf16 v[16:31], v[212:215], v[252:255], v[16:31]
	ds_read_b128 v[212:215], v176 offset:96
	ds_read_b128 v[252:255], v176 offset:4704
	s_waitcnt lgkmcnt(5)
	v_mfma_f32_32x32x16_bf16 v[32:47], v[216:219], v[224:227], v[32:47]
	s_waitcnt vmcnt(15)
	ds_write_b128 v175, v[68:71] offset:18432
	global_load_dwordx4 v[68:71], v[152:153], off offset:896
	s_waitcnt lgkmcnt(5)
	v_mfma_f32_32x32x16_bf16 v[0:15], v[216:219], v[220:223], v[0:15]
	ds_read_b128 v[216:219], v96 offset:41568
	s_waitcnt vmcnt(15)
	ds_write_b128 v175, v[84:87] offset:23040
	global_load_dwordx4 v[84:87], v[154:155], off offset:896
	s_waitcnt lgkmcnt(6)
	v_mfma_f32_32x32x16_bf16 v[48:63], v[228:231], v[224:227], v[48:63]
	s_waitcnt vmcnt(15)
	ds_write_b128 v175, v[88:91] offset:27648
	global_load_dwordx4 v[88:91], v[156:157], off offset:896
	v_mfma_f32_32x32x16_bf16 v[16:31], v[228:231], v[220:223], v[16:31]
	s_waitcnt vmcnt(15)
	ds_write_b128 v175, v[92:95] offset:32256
	global_load_dwordx4 v[92:95], v[158:159], off offset:896
	s_waitcnt lgkmcnt(6)
	v_mfma_f32_32x32x16_bf16 v[32:47], v[244:247], v[212:215], v[32:47]
	s_waitcnt vmcnt(15)
	ds_write_b128 v175, v[98:101] offset:55296
	global_load_dwordx4 v[98:101], v[150:151], off offset:896
	s_waitcnt lgkmcnt(6)
	v_mfma_f32_32x32x16_bf16 v[0:15], v[244:247], v[252:255], v[0:15]
	s_waitcnt vmcnt(15)
	ds_write_b128 v175, v[106:109] offset:59904
	global_load_dwordx4 v[106:109], v[160:161], off offset:896
	s_waitcnt lgkmcnt(5)
	v_mfma_f32_32x32x16_bf16 v[48:63], v[216:219], v[212:215], v[48:63]
	s_waitcnt vmcnt(15)
	ds_write_b128 v175, v[110:113] offset:64512
	global_load_dwordx4 v[110:113], v[170:171], off offset:896
	v_mfma_f32_32x32x16_bf16 v[16:31], v[216:219], v[252:255], v[16:31]
	s_waitcnt vmcnt(15)
	ds_write_b128 v177, v[114:117] offset:13824
	global_load_dwordx4 v[114:117], v[172:173], off offset:896
	s_setprio 0
	s_waitcnt lgkmcnt(0)
	s_barrier
	s_setprio 1
	ds_read_b128 v[212:215], v96 offset:55296
	ds_read_b128 v[216:219], v176 offset:18432
	ds_read_b128 v[220:223], v176 offset:23040
	ds_read_b128 v[224:227], v96 offset:59904
	ds_read_b128 v[228:231], v96 offset:55328
	ds_read_b128 v[244:247], v176 offset:18464
	ds_read_b128 v[252:255], v176 offset:23072
	s_waitcnt lgkmcnt(5)
	v_mfma_f32_32x32x16_bf16 v[32:47], v[212:215], v[216:219], v[32:47]
	s_waitcnt lgkmcnt(4)
	v_mfma_f32_32x32x16_bf16 v[0:15], v[212:215], v[220:223], v[0:15]
	ds_read_b128 v[212:215], v96 offset:59936
	s_waitcnt lgkmcnt(4)
	v_mfma_f32_32x32x16_bf16 v[48:63], v[224:227], v[216:219], v[48:63]
	ds_read_b128 v[216:219], v96 offset:55360
	v_mfma_f32_32x32x16_bf16 v[16:31], v[224:227], v[220:223], v[16:31]
	ds_read_b128 v[224:227], v176 offset:18496
	ds_read_b128 v[220:223], v176 offset:23104
	s_waitcnt lgkmcnt(5)
	v_mfma_f32_32x32x16_bf16 v[32:47], v[228:231], v[244:247], v[32:47]
	s_waitcnt lgkmcnt(4)
	v_mfma_f32_32x32x16_bf16 v[0:15], v[228:231], v[252:255], v[0:15]
	ds_read_b128 v[228:231], v96 offset:59968
	s_waitcnt lgkmcnt(4)
	v_mfma_f32_32x32x16_bf16 v[48:63], v[212:215], v[244:247], v[48:63]
	ds_read_b128 v[244:247], v96 offset:55392
	v_mfma_f32_32x32x16_bf16 v[16:31], v[212:215], v[252:255], v[16:31]
	ds_read_b128 v[212:215], v176 offset:18528
	ds_read_b128 v[252:255], v176 offset:23136
	s_waitcnt lgkmcnt(5)
	v_mfma_f32_32x32x16_bf16 v[32:47], v[216:219], v[224:227], v[32:47]
	s_waitcnt vmcnt(15)
	ds_write_b128 v175, v[64:67]
	global_load_dwordx4 v[64:67], v[152:153], off offset:1024
	s_waitcnt lgkmcnt(5)
	v_mfma_f32_32x32x16_bf16 v[0:15], v[216:219], v[220:223], v[0:15]
	ds_read_b128 v[216:219], v96 offset:60000
	s_waitcnt vmcnt(15)
	ds_write_b128 v175, v[72:75] offset:4608
	global_load_dwordx4 v[72:75], v[154:155], off offset:1024
	s_waitcnt lgkmcnt(6)
	v_mfma_f32_32x32x16_bf16 v[48:63], v[228:231], v[224:227], v[48:63]
	s_waitcnt vmcnt(15)
	ds_write_b128 v175, v[76:79] offset:9216
	global_load_dwordx4 v[76:79], v[156:157], off offset:1024
	v_mfma_f32_32x32x16_bf16 v[16:31], v[228:231], v[220:223], v[16:31]
	s_waitcnt vmcnt(15)
	ds_write_b128 v175, v[80:83] offset:13824
	global_load_dwordx4 v[80:83], v[158:159], off offset:1024
	s_waitcnt lgkmcnt(6)
	v_mfma_f32_32x32x16_bf16 v[32:47], v[244:247], v[212:215], v[32:47]
	s_waitcnt vmcnt(15)
	ds_write_b128 v175, v[102:105] offset:36864
	global_load_dwordx4 v[102:105], v[150:151], off offset:1024
	s_waitcnt lgkmcnt(6)
	v_mfma_f32_32x32x16_bf16 v[0:15], v[244:247], v[252:255], v[0:15]
	s_waitcnt vmcnt(15)
	ds_write_b128 v175, v[118:121] offset:41472
	global_load_dwordx4 v[118:121], v[160:161], off offset:1024
	s_waitcnt lgkmcnt(5)
	v_mfma_f32_32x32x16_bf16 v[48:63], v[216:219], v[212:215], v[48:63]
	s_waitcnt vmcnt(15)
	ds_write_b128 v175, v[122:125] offset:46080
	global_load_dwordx4 v[122:125], v[170:171], off offset:1024
	v_mfma_f32_32x32x16_bf16 v[16:31], v[216:219], v[252:255], v[16:31]
	s_waitcnt vmcnt(15)
	ds_write_b128 v175, v[126:129] offset:50688
	global_load_dwordx4 v[126:129], v[172:173], off offset:1024
	s_setprio 0
	s_waitcnt lgkmcnt(0)
	s_barrier
	s_setprio 1
	ds_read_b128 v[212:215], v96 offset:36864
	ds_read_b128 v[216:219], v176
	ds_read_b128 v[220:223], v176 offset:4608
	ds_read_b128 v[224:227], v96 offset:41472
	ds_read_b128 v[228:231], v96 offset:36896
	ds_read_b128 v[244:247], v176 offset:32
	ds_read_b128 v[252:255], v176 offset:4640
	s_waitcnt lgkmcnt(5)
	v_mfma_f32_32x32x16_bf16 v[32:47], v[212:215], v[216:219], v[32:47]
	s_waitcnt lgkmcnt(4)
	v_mfma_f32_32x32x16_bf16 v[0:15], v[212:215], v[220:223], v[0:15]
	ds_read_b128 v[212:215], v96 offset:41504
	s_waitcnt lgkmcnt(4)
	v_mfma_f32_32x32x16_bf16 v[48:63], v[224:227], v[216:219], v[48:63]
	ds_read_b128 v[216:219], v96 offset:36928
	v_mfma_f32_32x32x16_bf16 v[16:31], v[224:227], v[220:223], v[16:31]
	ds_read_b128 v[224:227], v176 offset:64
	ds_read_b128 v[220:223], v176 offset:4672
	s_waitcnt lgkmcnt(5)
	v_mfma_f32_32x32x16_bf16 v[32:47], v[228:231], v[244:247], v[32:47]
	s_waitcnt lgkmcnt(4)
	v_mfma_f32_32x32x16_bf16 v[0:15], v[228:231], v[252:255], v[0:15]
	ds_read_b128 v[228:231], v96 offset:41536
	s_waitcnt lgkmcnt(4)
	v_mfma_f32_32x32x16_bf16 v[48:63], v[212:215], v[244:247], v[48:63]
	ds_read_b128 v[244:247], v96 offset:36960
	v_mfma_f32_32x32x16_bf16 v[16:31], v[212:215], v[252:255], v[16:31]
	ds_read_b128 v[212:215], v176 offset:96
	ds_read_b128 v[252:255], v176 offset:4704
	s_waitcnt lgkmcnt(5)
	v_mfma_f32_32x32x16_bf16 v[32:47], v[216:219], v[224:227], v[32:47]
	s_waitcnt vmcnt(15)
	ds_write_b128 v175, v[68:71] offset:18432
	global_load_dwordx4 v[68:71], v[152:153], off offset:1152
	s_waitcnt lgkmcnt(5)
	v_mfma_f32_32x32x16_bf16 v[0:15], v[216:219], v[220:223], v[0:15]
	ds_read_b128 v[216:219], v96 offset:41568
	s_waitcnt vmcnt(15)
	ds_write_b128 v175, v[84:87] offset:23040
	global_load_dwordx4 v[84:87], v[154:155], off offset:1152
	s_waitcnt lgkmcnt(6)
	v_mfma_f32_32x32x16_bf16 v[48:63], v[228:231], v[224:227], v[48:63]
	s_waitcnt vmcnt(15)
	ds_write_b128 v175, v[88:91] offset:27648
	global_load_dwordx4 v[88:91], v[156:157], off offset:1152
	v_mfma_f32_32x32x16_bf16 v[16:31], v[228:231], v[220:223], v[16:31]
	s_waitcnt vmcnt(15)
	ds_write_b128 v175, v[92:95] offset:32256
	global_load_dwordx4 v[92:95], v[158:159], off offset:1152
	s_waitcnt lgkmcnt(6)
	v_mfma_f32_32x32x16_bf16 v[32:47], v[244:247], v[212:215], v[32:47]
	s_waitcnt vmcnt(15)
	ds_write_b128 v175, v[98:101] offset:55296
	global_load_dwordx4 v[98:101], v[150:151], off offset:1152
	s_waitcnt lgkmcnt(6)
	v_mfma_f32_32x32x16_bf16 v[0:15], v[244:247], v[252:255], v[0:15]
	s_waitcnt vmcnt(15)
	ds_write_b128 v175, v[106:109] offset:59904
	global_load_dwordx4 v[106:109], v[160:161], off offset:1152
	s_waitcnt lgkmcnt(5)
	v_mfma_f32_32x32x16_bf16 v[48:63], v[216:219], v[212:215], v[48:63]
	s_waitcnt vmcnt(15)
	ds_write_b128 v175, v[110:113] offset:64512
	global_load_dwordx4 v[110:113], v[170:171], off offset:1152
	v_mfma_f32_32x32x16_bf16 v[16:31], v[216:219], v[252:255], v[16:31]
	s_waitcnt vmcnt(15)
	ds_write_b128 v177, v[114:117] offset:13824
	global_load_dwordx4 v[114:117], v[172:173], off offset:1152
	s_setprio 0
	s_waitcnt lgkmcnt(0)
	s_barrier
	s_setprio 1
	ds_read_b128 v[212:215], v96 offset:55296
	ds_read_b128 v[216:219], v176 offset:18432
	ds_read_b128 v[220:223], v176 offset:23040
	ds_read_b128 v[224:227], v96 offset:59904
	ds_read_b128 v[228:231], v96 offset:55328
	ds_read_b128 v[244:247], v176 offset:18464
	ds_read_b128 v[252:255], v176 offset:23072
	s_waitcnt lgkmcnt(5)
	v_mfma_f32_32x32x16_bf16 v[32:47], v[212:215], v[216:219], v[32:47]
	s_waitcnt lgkmcnt(4)
	v_mfma_f32_32x32x16_bf16 v[0:15], v[212:215], v[220:223], v[0:15]
	ds_read_b128 v[212:215], v96 offset:59936
	s_waitcnt lgkmcnt(4)
	v_mfma_f32_32x32x16_bf16 v[48:63], v[224:227], v[216:219], v[48:63]
	ds_read_b128 v[216:219], v96 offset:55360
	v_mfma_f32_32x32x16_bf16 v[16:31], v[224:227], v[220:223], v[16:31]
	ds_read_b128 v[224:227], v176 offset:18496
	ds_read_b128 v[220:223], v176 offset:23104
	s_waitcnt lgkmcnt(5)
	v_mfma_f32_32x32x16_bf16 v[32:47], v[228:231], v[244:247], v[32:47]
	s_waitcnt lgkmcnt(4)
	v_mfma_f32_32x32x16_bf16 v[0:15], v[228:231], v[252:255], v[0:15]
	ds_read_b128 v[228:231], v96 offset:59968
	s_waitcnt lgkmcnt(4)
	v_mfma_f32_32x32x16_bf16 v[48:63], v[212:215], v[244:247], v[48:63]
	ds_read_b128 v[244:247], v96 offset:55392
	v_mfma_f32_32x32x16_bf16 v[16:31], v[212:215], v[252:255], v[16:31]
	ds_read_b128 v[212:215], v176 offset:18528
	ds_read_b128 v[252:255], v176 offset:23136
	s_waitcnt lgkmcnt(5)
	v_mfma_f32_32x32x16_bf16 v[32:47], v[216:219], v[224:227], v[32:47]
	s_waitcnt vmcnt(15)
	ds_write_b128 v175, v[64:67]
	global_load_dwordx4 v[64:67], v[152:153], off offset:1280
	s_waitcnt lgkmcnt(5)
	v_mfma_f32_32x32x16_bf16 v[0:15], v[216:219], v[220:223], v[0:15]
	ds_read_b128 v[216:219], v96 offset:60000
	s_waitcnt vmcnt(15)
	ds_write_b128 v175, v[72:75] offset:4608
	global_load_dwordx4 v[72:75], v[154:155], off offset:1280
	s_waitcnt lgkmcnt(6)
	v_mfma_f32_32x32x16_bf16 v[48:63], v[228:231], v[224:227], v[48:63]
	s_waitcnt vmcnt(15)
	ds_write_b128 v175, v[76:79] offset:9216
	global_load_dwordx4 v[76:79], v[156:157], off offset:1280
	v_mfma_f32_32x32x16_bf16 v[16:31], v[228:231], v[220:223], v[16:31]
	s_waitcnt vmcnt(15)
	ds_write_b128 v175, v[80:83] offset:13824
	global_load_dwordx4 v[80:83], v[158:159], off offset:1280
	s_waitcnt lgkmcnt(6)
	v_mfma_f32_32x32x16_bf16 v[32:47], v[244:247], v[212:215], v[32:47]
	s_waitcnt vmcnt(15)
	ds_write_b128 v175, v[102:105] offset:36864
	global_load_dwordx4 v[102:105], v[150:151], off offset:1280
	s_waitcnt lgkmcnt(6)
	v_mfma_f32_32x32x16_bf16 v[0:15], v[244:247], v[252:255], v[0:15]
	s_waitcnt vmcnt(15)
	ds_write_b128 v175, v[118:121] offset:41472
	global_load_dwordx4 v[118:121], v[160:161], off offset:1280
	s_waitcnt lgkmcnt(5)
	v_mfma_f32_32x32x16_bf16 v[48:63], v[216:219], v[212:215], v[48:63]
	s_waitcnt vmcnt(15)
	ds_write_b128 v175, v[122:125] offset:46080
	global_load_dwordx4 v[122:125], v[170:171], off offset:1280
	v_mfma_f32_32x32x16_bf16 v[16:31], v[216:219], v[252:255], v[16:31]
	s_waitcnt vmcnt(15)
	ds_write_b128 v175, v[126:129] offset:50688
	global_load_dwordx4 v[126:129], v[172:173], off offset:1280
	s_setprio 0
	s_waitcnt lgkmcnt(0)
	s_barrier
	s_setprio 1
	ds_read_b128 v[212:215], v96 offset:36864
	ds_read_b128 v[216:219], v176
	ds_read_b128 v[220:223], v176 offset:4608
	ds_read_b128 v[224:227], v96 offset:41472
	ds_read_b128 v[228:231], v96 offset:36896
	ds_read_b128 v[244:247], v176 offset:32
	ds_read_b128 v[252:255], v176 offset:4640
	s_waitcnt lgkmcnt(5)
	v_mfma_f32_32x32x16_bf16 v[32:47], v[212:215], v[216:219], v[32:47]
	s_waitcnt lgkmcnt(4)
	v_mfma_f32_32x32x16_bf16 v[0:15], v[212:215], v[220:223], v[0:15]
	ds_read_b128 v[212:215], v96 offset:41504
	s_waitcnt lgkmcnt(4)
	v_mfma_f32_32x32x16_bf16 v[48:63], v[224:227], v[216:219], v[48:63]
	ds_read_b128 v[216:219], v96 offset:36928
	v_mfma_f32_32x32x16_bf16 v[16:31], v[224:227], v[220:223], v[16:31]
	ds_read_b128 v[224:227], v176 offset:64
	ds_read_b128 v[220:223], v176 offset:4672
	s_waitcnt lgkmcnt(5)
	v_mfma_f32_32x32x16_bf16 v[32:47], v[228:231], v[244:247], v[32:47]
	s_waitcnt lgkmcnt(4)
	v_mfma_f32_32x32x16_bf16 v[0:15], v[228:231], v[252:255], v[0:15]
	ds_read_b128 v[228:231], v96 offset:41536
	s_waitcnt lgkmcnt(4)
	v_mfma_f32_32x32x16_bf16 v[48:63], v[212:215], v[244:247], v[48:63]
	ds_read_b128 v[244:247], v96 offset:36960
	v_mfma_f32_32x32x16_bf16 v[16:31], v[212:215], v[252:255], v[16:31]
	ds_read_b128 v[212:215], v176 offset:96
	ds_read_b128 v[252:255], v176 offset:4704
	s_waitcnt lgkmcnt(5)
	v_mfma_f32_32x32x16_bf16 v[32:47], v[216:219], v[224:227], v[32:47]
	s_waitcnt vmcnt(15)
	ds_write_b128 v175, v[68:71] offset:18432
	global_load_dwordx4 v[68:71], v[152:153], off offset:1408
	s_waitcnt lgkmcnt(5)
	v_mfma_f32_32x32x16_bf16 v[0:15], v[216:219], v[220:223], v[0:15]
	ds_read_b128 v[216:219], v96 offset:41568
	s_waitcnt vmcnt(15)
	ds_write_b128 v175, v[84:87] offset:23040
	global_load_dwordx4 v[84:87], v[154:155], off offset:1408
	s_waitcnt lgkmcnt(6)
	v_mfma_f32_32x32x16_bf16 v[48:63], v[228:231], v[224:227], v[48:63]
	s_waitcnt vmcnt(15)
	ds_write_b128 v175, v[88:91] offset:27648
	global_load_dwordx4 v[88:91], v[156:157], off offset:1408
	v_mfma_f32_32x32x16_bf16 v[16:31], v[228:231], v[220:223], v[16:31]
	s_waitcnt vmcnt(15)
	ds_write_b128 v175, v[92:95] offset:32256
	global_load_dwordx4 v[92:95], v[158:159], off offset:1408
	s_waitcnt lgkmcnt(6)
	v_mfma_f32_32x32x16_bf16 v[32:47], v[244:247], v[212:215], v[32:47]
	s_waitcnt vmcnt(15)
	ds_write_b128 v175, v[98:101] offset:55296
	global_load_dwordx4 v[98:101], v[150:151], off offset:1408
	s_waitcnt lgkmcnt(6)
	v_mfma_f32_32x32x16_bf16 v[0:15], v[244:247], v[252:255], v[0:15]
	s_waitcnt vmcnt(15)
	ds_write_b128 v175, v[106:109] offset:59904
	global_load_dwordx4 v[106:109], v[160:161], off offset:1408
	s_waitcnt lgkmcnt(5)
	v_mfma_f32_32x32x16_bf16 v[48:63], v[216:219], v[212:215], v[48:63]
	s_waitcnt vmcnt(15)
	ds_write_b128 v175, v[110:113] offset:64512
	global_load_dwordx4 v[110:113], v[170:171], off offset:1408
	v_mfma_f32_32x32x16_bf16 v[16:31], v[216:219], v[252:255], v[16:31]
	s_waitcnt vmcnt(15)
	ds_write_b128 v177, v[114:117] offset:13824
	global_load_dwordx4 v[130:133], v[172:173], off offset:1408
	s_setprio 0
	s_waitcnt lgkmcnt(0)
	s_barrier
	s_setprio 1
	ds_read_b128 v[212:215], v96 offset:55296
	ds_read_b128 v[216:219], v176 offset:18432
	ds_read_b128 v[220:223], v176 offset:23040
	ds_read_b128 v[224:227], v96 offset:59904
	ds_read_b128 v[228:231], v96 offset:55328
	ds_read_b128 v[244:247], v176 offset:18464
	ds_read_b128 v[252:255], v176 offset:23072
	s_waitcnt lgkmcnt(5)
	v_mfma_f32_32x32x16_bf16 v[32:47], v[212:215], v[216:219], v[32:47]
	s_waitcnt lgkmcnt(4)
	v_mfma_f32_32x32x16_bf16 v[0:15], v[212:215], v[220:223], v[0:15]
	ds_read_b128 v[212:215], v96 offset:59936
	s_waitcnt lgkmcnt(4)
	v_mfma_f32_32x32x16_bf16 v[48:63], v[224:227], v[216:219], v[48:63]
	ds_read_b128 v[216:219], v96 offset:55360
	v_mfma_f32_32x32x16_bf16 v[16:31], v[224:227], v[220:223], v[16:31]
	ds_read_b128 v[224:227], v176 offset:18496
	ds_read_b128 v[220:223], v176 offset:23104
	s_waitcnt lgkmcnt(5)
	v_mfma_f32_32x32x16_bf16 v[32:47], v[228:231], v[244:247], v[32:47]
	s_waitcnt lgkmcnt(4)
	v_mfma_f32_32x32x16_bf16 v[0:15], v[228:231], v[252:255], v[0:15]
	ds_read_b128 v[228:231], v96 offset:59968
	s_waitcnt lgkmcnt(4)
	v_mfma_f32_32x32x16_bf16 v[48:63], v[212:215], v[244:247], v[48:63]
	ds_read_b128 v[244:247], v96 offset:55392
	v_mfma_f32_32x32x16_bf16 v[16:31], v[212:215], v[252:255], v[16:31]
	ds_read_b128 v[212:215], v176 offset:18528
	ds_read_b128 v[252:255], v176 offset:23136
	s_waitcnt lgkmcnt(5)
	v_mfma_f32_32x32x16_bf16 v[32:47], v[216:219], v[224:227], v[32:47]
	s_waitcnt vmcnt(15)
	ds_write_b128 v175, v[64:67]
	global_load_dwordx4 v[64:67], v[152:153], off offset:1536
	s_waitcnt lgkmcnt(5)
	v_mfma_f32_32x32x16_bf16 v[0:15], v[216:219], v[220:223], v[0:15]
	ds_read_b128 v[216:219], v96 offset:60000
	s_waitcnt vmcnt(15)
	ds_write_b128 v175, v[72:75] offset:4608
	global_load_dwordx4 v[72:75], v[154:155], off offset:1536
	s_waitcnt lgkmcnt(6)
	v_mfma_f32_32x32x16_bf16 v[48:63], v[228:231], v[224:227], v[48:63]
	s_waitcnt vmcnt(15)
	ds_write_b128 v175, v[76:79] offset:9216
	global_load_dwordx4 v[76:79], v[156:157], off offset:1536
	v_mfma_f32_32x32x16_bf16 v[16:31], v[228:231], v[220:223], v[16:31]
	s_waitcnt vmcnt(15)
	ds_write_b128 v175, v[80:83] offset:13824
	global_load_dwordx4 v[80:83], v[158:159], off offset:1536
	s_waitcnt lgkmcnt(6)
	v_mfma_f32_32x32x16_bf16 v[32:47], v[244:247], v[212:215], v[32:47]
	s_waitcnt vmcnt(15)
	ds_write_b128 v175, v[102:105] offset:36864
	global_load_dwordx4 v[114:117], v[150:151], off offset:1536
	s_waitcnt lgkmcnt(6)
	v_mfma_f32_32x32x16_bf16 v[0:15], v[244:247], v[252:255], v[0:15]
	s_waitcnt vmcnt(15)
	ds_write_b128 v175, v[118:121] offset:41472
	s_waitcnt vmcnt(14)
	ds_write_b128 v175, v[122:125] offset:46080
	s_waitcnt lgkmcnt(6)
	v_mfma_f32_32x32x16_bf16 v[48:63], v[216:219], v[212:215], v[48:63]
	global_load_dwordx4 v[122:125], v[160:161], off offset:1536
	s_waitcnt vmcnt(14)
	ds_write_b128 v175, v[126:129] offset:50688
	v_mfma_f32_32x32x16_bf16 v[16:31], v[216:219], v[252:255], v[16:31]
	global_load_dwordx4 v[126:129], v[170:171], off offset:1536
	global_load_dwordx4 v[134:137], v[172:173], off offset:1536
	s_setprio 0
	s_waitcnt lgkmcnt(0)
	s_barrier
	s_setprio 1
	ds_read_b128 v[212:215], v96 offset:36864
	ds_read_b128 v[216:219], v176
	ds_read_b128 v[220:223], v176 offset:4608
	ds_read_b128 v[224:227], v96 offset:41472
	ds_read_b128 v[228:231], v96 offset:36896
	ds_read_b128 v[244:247], v176 offset:32
	ds_read_b128 v[252:255], v176 offset:4640
	s_waitcnt lgkmcnt(5)
	v_mfma_f32_32x32x16_bf16 v[32:47], v[212:215], v[216:219], v[32:47]
	s_waitcnt lgkmcnt(4)
	v_mfma_f32_32x32x16_bf16 v[0:15], v[212:215], v[220:223], v[0:15]
	ds_read_b128 v[212:215], v96 offset:41504
	s_waitcnt lgkmcnt(4)
	v_mfma_f32_32x32x16_bf16 v[48:63], v[224:227], v[216:219], v[48:63]
	ds_read_b128 v[216:219], v96 offset:36928
	v_mfma_f32_32x32x16_bf16 v[16:31], v[224:227], v[220:223], v[16:31]
	ds_read_b128 v[224:227], v176 offset:64
	ds_read_b128 v[220:223], v176 offset:4672
	s_waitcnt lgkmcnt(5)
	v_mfma_f32_32x32x16_bf16 v[32:47], v[228:231], v[244:247], v[32:47]
	s_waitcnt lgkmcnt(4)
	v_mfma_f32_32x32x16_bf16 v[0:15], v[228:231], v[252:255], v[0:15]
	ds_read_b128 v[228:231], v96 offset:41536
	s_waitcnt lgkmcnt(4)
	v_mfma_f32_32x32x16_bf16 v[48:63], v[212:215], v[244:247], v[48:63]
	ds_read_b128 v[244:247], v96 offset:36960
	v_mfma_f32_32x32x16_bf16 v[16:31], v[212:215], v[252:255], v[16:31]
	ds_read_b128 v[212:215], v176 offset:96
	ds_read_b128 v[252:255], v176 offset:4704
	s_waitcnt lgkmcnt(5)
	v_mfma_f32_32x32x16_bf16 v[32:47], v[216:219], v[224:227], v[32:47]
	s_waitcnt vmcnt(15)
	ds_write_b128 v175, v[68:71] offset:18432
	s_waitcnt vmcnt(14)
	ds_write_b128 v175, v[84:87] offset:23040
	s_waitcnt lgkmcnt(6)
	v_mfma_f32_32x32x16_bf16 v[0:15], v[216:219], v[220:223], v[0:15]
	ds_read_b128 v[216:219], v96 offset:41568
	s_waitcnt vmcnt(13)
	ds_write_b128 v175, v[88:91] offset:27648
	s_waitcnt vmcnt(12)
	ds_write_b128 v175, v[92:95] offset:32256
	s_waitcnt lgkmcnt(8)
	v_mfma_f32_32x32x16_bf16 v[48:63], v[228:231], v[224:227], v[48:63]
	s_waitcnt vmcnt(11)
	ds_write_b128 v175, v[98:101] offset:55296
	v_mfma_f32_32x32x16_bf16 v[16:31], v[228:231], v[220:223], v[16:31]
	global_load_dwordx4 v[98:101], v[152:153], off offset:1664
	global_load_dwordx4 v[102:105], v[154:155], off offset:1664
	s_waitcnt vmcnt(12)
	ds_write_b128 v175, v[106:109] offset:59904
	s_waitcnt lgkmcnt(8)
	v_mfma_f32_32x32x16_bf16 v[32:47], v[244:247], v[212:215], v[32:47]
	global_load_dwordx4 v[106:109], v[156:157], off offset:1664
	s_waitcnt vmcnt(12)
	ds_write_b128 v175, v[110:113] offset:64512
	s_waitcnt lgkmcnt(8)
	v_mfma_f32_32x32x16_bf16 v[0:15], v[244:247], v[252:255], v[0:15]
	global_load_dwordx4 v[110:113], v[158:159], off offset:1664
	global_load_dwordx4 v[118:121], v[150:151], off offset:1664
	s_waitcnt lgkmcnt(5)
	v_mfma_f32_32x32x16_bf16 v[48:63], v[216:219], v[212:215], v[48:63]
	s_waitcnt vmcnt(13)
	ds_write_b128 v177, v[130:133] offset:13824
	global_load_dwordx4 v[130:133], v[160:161], off offset:1664
	v_mfma_f32_32x32x16_bf16 v[16:31], v[216:219], v[252:255], v[16:31]
	global_load_dwordx4 v[138:141], v[170:171], off offset:1664
	global_load_dwordx4 v[142:145], v[172:173], off offset:1664
	s_setprio 0
	s_waitcnt lgkmcnt(0)
	s_barrier
	s_setprio 1
	ds_read_b128 v[212:215], v96 offset:55296
	ds_read_b128 v[216:219], v176 offset:18432
	ds_read_b128 v[220:223], v176 offset:23040
	ds_read_b128 v[224:227], v96 offset:59904
	ds_read_b128 v[228:231], v96 offset:55328
	ds_read_b128 v[244:247], v176 offset:18464
	ds_read_b128 v[252:255], v176 offset:23072
	s_waitcnt lgkmcnt(5)
	v_mfma_f32_32x32x16_bf16 v[32:47], v[212:215], v[216:219], v[32:47]
	s_waitcnt lgkmcnt(4)
	v_mfma_f32_32x32x16_bf16 v[0:15], v[212:215], v[220:223], v[0:15]
	ds_read_b128 v[212:215], v96 offset:59936
	s_waitcnt lgkmcnt(4)
	v_mfma_f32_32x32x16_bf16 v[48:63], v[224:227], v[216:219], v[48:63]
	ds_read_b128 v[216:219], v96 offset:55360
	v_mfma_f32_32x32x16_bf16 v[16:31], v[224:227], v[220:223], v[16:31]
	ds_read_b128 v[224:227], v176 offset:18496
	ds_read_b128 v[220:223], v176 offset:23104
	s_waitcnt lgkmcnt(5)
	v_mfma_f32_32x32x16_bf16 v[32:47], v[228:231], v[244:247], v[32:47]
	s_waitcnt lgkmcnt(4)
	v_mfma_f32_32x32x16_bf16 v[0:15], v[228:231], v[252:255], v[0:15]
	ds_read_b128 v[228:231], v96 offset:59968
	s_waitcnt lgkmcnt(4)
	v_mfma_f32_32x32x16_bf16 v[48:63], v[212:215], v[244:247], v[48:63]
	ds_read_b128 v[244:247], v96 offset:55392
	v_mfma_f32_32x32x16_bf16 v[16:31], v[212:215], v[252:255], v[16:31]
	ds_read_b128 v[212:215], v176 offset:18528
	ds_read_b128 v[252:255], v176 offset:23136
	s_waitcnt lgkmcnt(5)
	v_mfma_f32_32x32x16_bf16 v[32:47], v[216:219], v[224:227], v[32:47]
	s_waitcnt vmcnt(15)
	ds_write_b128 v175, v[64:67]
	global_load_dwordx4 v[64:67], v[152:153], off offset:1792
	s_waitcnt lgkmcnt(5)
	v_mfma_f32_32x32x16_bf16 v[0:15], v[216:219], v[220:223], v[0:15]
	ds_read_b128 v[216:219], v96 offset:60000
	s_waitcnt vmcnt(15)
	ds_write_b128 v175, v[72:75] offset:4608
	global_load_dwordx4 v[68:71], v[154:155], off offset:1792
	s_waitcnt lgkmcnt(6)
	v_mfma_f32_32x32x16_bf16 v[48:63], v[228:231], v[224:227], v[48:63]
	s_waitcnt vmcnt(15)
	ds_write_b128 v175, v[76:79] offset:9216
	global_load_dwordx4 v[72:75], v[156:157], off offset:1792
	v_mfma_f32_32x32x16_bf16 v[16:31], v[228:231], v[220:223], v[16:31]
	s_waitcnt vmcnt(15)
	ds_write_b128 v175, v[80:83] offset:13824
	global_load_dwordx4 v[76:79], v[158:159], off offset:1792
	s_waitcnt lgkmcnt(6)
	v_mfma_f32_32x32x16_bf16 v[32:47], v[244:247], v[212:215], v[32:47]
	s_waitcnt vmcnt(15)
	ds_write_b128 v175, v[114:117] offset:36864
	global_load_dwordx4 v[80:83], v[150:151], off offset:1792
	s_waitcnt lgkmcnt(6)
	v_mfma_f32_32x32x16_bf16 v[0:15], v[244:247], v[252:255], v[0:15]
	s_waitcnt vmcnt(15)
	ds_write_b128 v175, v[122:125] offset:41472
	global_load_dwordx4 v[84:87], v[160:161], off offset:1792
	s_waitcnt lgkmcnt(5)
	v_mfma_f32_32x32x16_bf16 v[48:63], v[216:219], v[212:215], v[48:63]
	s_waitcnt vmcnt(15)
	ds_write_b128 v175, v[126:129] offset:46080
	global_load_dwordx4 v[88:91], v[170:171], off offset:1792
	v_mfma_f32_32x32x16_bf16 v[16:31], v[216:219], v[252:255], v[16:31]
	s_waitcnt vmcnt(15)
	ds_write_b128 v175, v[134:137] offset:50688
	global_load_dwordx4 v[92:95], v[172:173], off offset:1792
	s_setprio 0
	s_waitcnt lgkmcnt(0)
	s_barrier
	s_setprio 1
	ds_read_b128 v[212:215], v96 offset:36864
	ds_read_b128 v[216:219], v176
	ds_read_b128 v[220:223], v176 offset:4608
	ds_read_b128 v[224:227], v96 offset:41472
	ds_read_b128 v[228:231], v96 offset:36896
	ds_read_b128 v[244:247], v176 offset:32
	ds_read_b128 v[252:255], v176 offset:4640
	s_waitcnt lgkmcnt(5)
	v_mfma_f32_32x32x16_bf16 v[32:47], v[212:215], v[216:219], v[32:47]
	s_waitcnt lgkmcnt(4)
	v_mfma_f32_32x32x16_bf16 v[0:15], v[212:215], v[220:223], v[0:15]
	ds_read_b128 v[212:215], v96 offset:41504
	s_waitcnt lgkmcnt(4)
	v_mfma_f32_32x32x16_bf16 v[48:63], v[224:227], v[216:219], v[48:63]
	ds_read_b128 v[216:219], v96 offset:36928
	v_mfma_f32_32x32x16_bf16 v[16:31], v[224:227], v[220:223], v[16:31]
	ds_read_b128 v[224:227], v176 offset:64
	ds_read_b128 v[220:223], v176 offset:4672
	s_waitcnt lgkmcnt(5)
	v_mfma_f32_32x32x16_bf16 v[32:47], v[228:231], v[244:247], v[32:47]
	s_waitcnt lgkmcnt(4)
	v_mfma_f32_32x32x16_bf16 v[0:15], v[228:231], v[252:255], v[0:15]
	ds_read_b128 v[228:231], v96 offset:41536
	s_waitcnt lgkmcnt(4)
	v_mfma_f32_32x32x16_bf16 v[48:63], v[212:215], v[244:247], v[48:63]
	ds_read_b128 v[244:247], v96 offset:36960
	v_mfma_f32_32x32x16_bf16 v[16:31], v[212:215], v[252:255], v[16:31]
	ds_read_b128 v[212:215], v176 offset:96
	ds_read_b128 v[252:255], v176 offset:4704
	s_waitcnt lgkmcnt(5)
	v_mfma_f32_32x32x16_bf16 v[32:47], v[216:219], v[224:227], v[32:47]
	s_waitcnt vmcnt(15)
	ds_write_b128 v175, v[98:101] offset:18432
	s_waitcnt vmcnt(14)
	ds_write_b128 v175, v[102:105] offset:23040
	s_waitcnt lgkmcnt(6)
	v_mfma_f32_32x32x16_bf16 v[0:15], v[216:219], v[220:223], v[0:15]
	ds_read_b128 v[216:219], v96 offset:41568
	global_load_dwordx4 v[100:103], v[152:153], off offset:1920
	s_waitcnt vmcnt(14)
	ds_write_b128 v175, v[106:109] offset:27648
	s_waitcnt lgkmcnt(7)
	v_mfma_f32_32x32x16_bf16 v[48:63], v[228:231], v[224:227], v[48:63]
	global_load_dwordx4 v[104:107], v[154:155], off offset:1920
	s_waitcnt vmcnt(14)
	ds_write_b128 v175, v[110:113] offset:32256
	v_mfma_f32_32x32x16_bf16 v[16:31], v[228:231], v[220:223], v[16:31]
	global_load_dwordx4 v[108:111], v[156:157], off offset:1920
	global_load_dwordx4 v[112:115], v[158:159], off offset:1920
	s_waitcnt lgkmcnt(6)
	v_mfma_f32_32x32x16_bf16 v[32:47], v[244:247], v[212:215], v[32:47]
	s_waitcnt vmcnt(15)
	ds_write_b128 v175, v[118:121] offset:55296
	global_load_dwordx4 v[116:119], v[150:151], off offset:1920
	s_waitcnt lgkmcnt(6)
	v_mfma_f32_32x32x16_bf16 v[0:15], v[244:247], v[252:255], v[0:15]
	s_waitcnt vmcnt(15)
	ds_write_b128 v175, v[130:133] offset:59904
	global_load_dwordx4 v[124:127], v[160:161], off offset:1920
	s_waitcnt lgkmcnt(4)
	v_mfma_f32_32x32x16_bf16 v[48:63], v[216:219], v[212:215], v[48:63]
	s_waitcnt vmcnt(15)
	ds_write_b128 v175, v[138:141] offset:64512
	global_load_dwordx4 v[120:123], v[170:171], off offset:1920
	v_mfma_f32_32x32x16_bf16 v[16:31], v[216:219], v[252:255], v[16:31]
	s_waitcnt vmcnt(15)
	ds_write_b128 v177, v[142:145] offset:13824
	global_load_dwordx4 v[128:131], v[172:173], off offset:1920
	s_setprio 0
	s_waitcnt lgkmcnt(0)
	s_barrier
	s_setprio 1
	ds_read_b128 v[212:215], v96 offset:55296
	ds_read_b128 v[216:219], v176 offset:18432
	ds_read_b128 v[220:223], v176 offset:23040
	ds_read_b128 v[224:227], v96 offset:59904
	ds_read_b128 v[228:231], v96 offset:55328
	ds_read_b128 v[244:247], v176 offset:18464
	ds_read_b128 v[252:255], v176 offset:23072
	s_waitcnt lgkmcnt(5)
	v_mfma_f32_32x32x16_bf16 v[32:47], v[212:215], v[216:219], v[32:47]
	s_waitcnt lgkmcnt(4)
	v_mfma_f32_32x32x16_bf16 v[0:15], v[212:215], v[220:223], v[0:15]
	ds_read_b128 v[212:215], v96 offset:59936
	s_waitcnt lgkmcnt(4)
	v_mfma_f32_32x32x16_bf16 v[48:63], v[224:227], v[216:219], v[48:63]
	ds_read_b128 v[216:219], v96 offset:55360
	v_mfma_f32_32x32x16_bf16 v[16:31], v[224:227], v[220:223], v[16:31]
	ds_read_b128 v[224:227], v176 offset:18496
	ds_read_b128 v[220:223], v176 offset:23104
	s_waitcnt lgkmcnt(5)
	v_mfma_f32_32x32x16_bf16 v[32:47], v[228:231], v[244:247], v[32:47]
	s_waitcnt lgkmcnt(4)
	v_mfma_f32_32x32x16_bf16 v[0:15], v[228:231], v[252:255], v[0:15]
	ds_read_b128 v[228:231], v96 offset:59968
	s_waitcnt lgkmcnt(4)
	v_mfma_f32_32x32x16_bf16 v[48:63], v[212:215], v[244:247], v[48:63]
	ds_read_b128 v[244:247], v96 offset:55392
	v_mfma_f32_32x32x16_bf16 v[16:31], v[212:215], v[252:255], v[16:31]
	ds_read_b128 v[212:215], v176 offset:18528
	ds_read_b128 v[252:255], v176 offset:23136
	s_waitcnt lgkmcnt(5)
	v_mfma_f32_32x32x16_bf16 v[32:47], v[216:219], v[224:227], v[32:47]
	s_waitcnt lgkmcnt(4)
	v_mfma_f32_32x32x16_bf16 v[0:15], v[216:219], v[220:223], v[0:15]
	ds_read_b128 v[216:219], v96 offset:60000
	s_waitcnt lgkmcnt(4)
	v_mfma_f32_32x32x16_bf16 v[48:63], v[228:231], v[224:227], v[48:63]
	v_mfma_f32_32x32x16_bf16 v[16:31], v[228:231], v[220:223], v[16:31]
	s_waitcnt lgkmcnt(2)
	v_mfma_f32_32x32x16_bf16 v[32:47], v[244:247], v[212:215], v[32:47]
	s_waitcnt lgkmcnt(1)
	v_mfma_f32_32x32x16_bf16 v[0:15], v[244:247], v[252:255], v[0:15]
	s_waitcnt lgkmcnt(0)
	v_mfma_f32_32x32x16_bf16 v[48:63], v[216:219], v[212:215], v[48:63]
	v_mfma_f32_32x32x16_bf16 v[16:31], v[216:219], v[252:255], v[16:31]
	s_setprio 0
	v_cndmask_b32_e64 v98, 0, 1, s[12:13]
	v_cmp_ne_u32_e64 s[40:41], 1, v98
	s_andn2_b64 vcc, exec, s[12:13]
	s_waitcnt vmcnt(15)
	ds_write_b128 v175, v[64:67]
	s_waitcnt vmcnt(14)
	ds_write_b128 v175, v[68:71] offset:4608
	s_waitcnt vmcnt(13)
	ds_write_b128 v175, v[72:75] offset:9216
	s_waitcnt vmcnt(12)
	ds_write_b128 v175, v[76:79] offset:13824
	s_waitcnt vmcnt(11)
	ds_write_b128 v175, v[80:83] offset:36864
	s_waitcnt vmcnt(10)
	ds_write_b128 v175, v[84:87] offset:41472
	s_waitcnt vmcnt(9)
	ds_write_b128 v175, v[88:91] offset:46080
	s_waitcnt vmcnt(8)
	ds_write_b128 v175, v[92:95] offset:50688
	s_cbranch_vccnz .LBB0_270
	v_add_co_u32_e32 v68, vcc, 0x10000, v148
	global_load_dwordx4 v[64:67], v[148:149], off
	s_nop 0
	v_addc_co_u32_e32 v69, vcc, 0, v149, vcc
	v_add_co_u32_e32 v72, vcc, 0x20000, v148
	s_nop 1
	v_addc_co_u32_e32 v73, vcc, 0, v149, vcc
	v_add_co_u32_e32 v76, vcc, 0x30000, v148
	global_load_dwordx4 v[68:71], v[68:69], off
	global_load_dwordx4 v[72:75], v[72:73], off
	v_addc_co_u32_e32 v77, vcc, 0, v149, vcc
	v_add_co_u32_e32 v84, vcc, 0x10000, v146
	global_load_dwordx4 v[76:79], v[76:77], off
	s_nop 0
	global_load_dwordx4 v[80:83], v[146:147], off
	v_addc_co_u32_e32 v85, vcc, 0, v147, vcc
	v_add_co_u32_e32 v88, vcc, 0x20000, v146
	s_nop 1
	v_addc_co_u32_e32 v89, vcc, 0, v147, vcc
	v_add_co_u32_e32 v92, vcc, 0x30000, v146
	global_load_dwordx4 v[84:87], v[84:85], off
	s_nop 0
	global_load_dwordx4 v[88:91], v[88:89], off
	v_addc_co_u32_e32 v93, vcc, 0, v147, vcc
	global_load_dwordx4 v[92:95], v[92:93], off

.LBB0_472:
	s_ashr_i32 s47, s46, 31
	s_lshl_b64 s[40:41], s[46:47], 18
	s_add_u32 s3, s82, s40
	s_addc_u32 s7, s83, s41
	s_and_b64 s[40:41], s[12:13], exec
	s_cselect_b32 s41, s7, 0
	s_cselect_b32 s40, s3, 0
	s_ashr_i32 s45, s44, 31
	s_lshl_b64 s[42:43], s[44:45], 18
	v_readlane_b32 s14, v251, 56
	v_readlane_b32 s15, v251, 57
	s_add_u32 s3, s14, s42
	s_addc_u32 s7, s15, s43
	s_and_b64 s[42:43], s[12:13], exec
	s_cselect_b32 s43, s7, 0
	s_cselect_b32 s42, s3, 0
	v_lshl_add_u64 v[4:5], s[40:41], 0, v[0:1]
	v_lshl_add_u64 v[0:1], s[42:43], 0, v[0:1]
	v_lshl_add_u64 v[146:147], v[0:1], 0, v[96:97]
	v_lshrrev_b32_e32 v0, 1, v2
	v_and_b32_e32 v1, 31, v2
	v_and_or_b32 v1, v0, s81, v1
	v_lshrrev_b32_e32 v0, 2, v2
	v_and_b32_e32 v0, 8, v0
	v_lshl_add_u64 v[148:149], v[4:5], 0, v[96:97]
	v_mad_u64_u32 v[4:5], s[40:41], v1, s84, v[0:1]
	v_and_b32_e32 v1, 0x5f, v2
	v_mad_u32_u24 v0, v1, s84, v0
	v_lshl_add_u32 v178, v4, 1, 0
	v_lshl_add_u32 v96, v0, 1, 0
	v_add_u32_e32 v179, 0xd800, v177
	s_setprio 1
	ds_read_b128 v[212:215], v96 offset:36864
	ds_read_b128 v[216:219], v178
	ds_read_b128 v[220:223], v178 offset:4608
	ds_read_b128 v[224:227], v96 offset:36896
	ds_read_b128 v[228:231], v178 offset:32
	ds_read_b128 v[244:247], v178 offset:4640
	ds_read_b128 v[252:255], v96 offset:41472
	s_waitcnt lgkmcnt(5)
	v_mfma_f32_32x32x16_bf16 v[48:63], v[212:215], v[216:219], 0
	s_waitcnt lgkmcnt(4)
	v_mfma_f32_32x32x16_bf16 v[32:47], v[212:215], v[220:223], 0
	ds_read_b128 v[212:215], v96 offset:41504
	s_waitcnt lgkmcnt(3)
	v_mfma_f32_32x32x16_bf16 v[48:63], v[224:227], v[228:231], v[48:63]
	s_waitcnt lgkmcnt(2)
	v_mfma_f32_32x32x16_bf16 v[32:47], v[224:227], v[244:247], v[32:47]
	ds_read_b128 v[224:227], v96 offset:36928
	s_waitcnt lgkmcnt(2)
	v_mfma_f32_32x32x16_bf16 v[16:31], v[252:255], v[216:219], 0
	ds_read_b128 v[216:219], v178 offset:64
	v_mfma_f32_32x32x16_bf16 v[0:15], v[252:255], v[220:223], 0
	ds_read_b128 v[252:255], v178 offset:4672
	ds_read_b128 v[220:223], v96 offset:41536
	s_waitcnt lgkmcnt(4)
	v_mfma_f32_32x32x16_bf16 v[16:31], v[212:215], v[228:231], v[16:31]
	ds_read_b128 v[228:231], v96 offset:36960
	v_mfma_f32_32x32x16_bf16 v[0:15], v[212:215], v[244:247], v[0:15]
	ds_read_b128 v[212:215], v178 offset:96
	ds_read_b128 v[244:247], v178 offset:4704
	s_waitcnt lgkmcnt(5)
	v_mfma_f32_32x32x16_bf16 v[48:63], v[224:227], v[216:219], v[48:63]
	s_mov_b32 s3, 0x10000
	v_add_co_u32_e32 v154, vcc, s3, v152
	s_mov_b32 s7, 0x20000
	s_nop 0
	v_addc_co_u32_e32 v155, vcc, 0, v153, vcc
	v_add_co_u32_e32 v156, vcc, s7, v152
	s_mov_b32 s8, 0x30000
	s_nop 0
	s_waitcnt lgkmcnt(4)
	v_mfma_f32_32x32x16_bf16 v[32:47], v[224:227], v[252:255], v[32:47]
	ds_read_b128 v[224:227], v96 offset:41568
	v_addc_co_u32_e32 v157, vcc, 0, v153, vcc
	v_add_co_u32_e32 v158, vcc, s8, v152
	s_waitcnt vmcnt(7)
	ds_write_b128 v177, v[100:103] offset:18432
	s_waitcnt vmcnt(6)
	ds_write_b128 v177, v[104:107] offset:23040
	s_waitcnt lgkmcnt(6)
	v_mfma_f32_32x32x16_bf16 v[16:31], v[220:223], v[216:219], v[16:31]
	s_waitcnt vmcnt(5)
	ds_write_b128 v177, v[108:111] offset:27648
	s_waitcnt vmcnt(4)
	ds_write_b128 v177, v[112:115] offset:32256
	v_mfma_f32_32x32x16_bf16 v[0:15], v[220:223], v[252:255], v[0:15]
	s_waitcnt vmcnt(3)
	ds_write_b128 v177, v[116:119] offset:55296
	s_waitcnt vmcnt(2)
	ds_write_b128 v177, v[120:123] offset:59904
	s_waitcnt vmcnt(1)
	ds_write_b128 v177, v[128:131] offset:64512
	s_waitcnt lgkmcnt(9)
	v_mfma_f32_32x32x16_bf16 v[48:63], v[228:231], v[212:215], v[48:63]
	s_waitcnt vmcnt(0)
	ds_write_b128 v179, v[124:127] offset:13824
	v_addc_co_u32_e32 v159, vcc, 0, v153, vcc
	v_add_co_u32_e32 v160, vcc, s3, v150
	s_waitcnt lgkmcnt(9)
	v_mfma_f32_32x32x16_bf16 v[32:47], v[228:231], v[244:247], v[32:47]
	global_load_dwordx4 v[98:101], v[152:153], off offset:384
	global_load_dwordx4 v[102:105], v[154:155], off offset:384
	v_addc_co_u32_e32 v161, vcc, 0, v151, vcc
	v_add_co_u32_e32 v170, vcc, s7, v150
	global_load_dwordx4 v[106:109], v[156:157], off offset:384
	s_waitcnt lgkmcnt(8)
	v_mfma_f32_32x32x16_bf16 v[16:31], v[224:227], v[212:215], v[16:31]
	s_nop 0
	v_addc_co_u32_e32 v171, vcc, 0, v151, vcc
	v_add_co_u32_e32 v172, vcc, s8, v150
	global_load_dwordx4 v[110:113], v[158:159], off offset:384
	global_load_dwordx4 v[114:117], v[150:151], off offset:384
	v_mfma_f32_32x32x16_bf16 v[0:15], v[224:227], v[244:247], v[0:15]
	v_addc_co_u32_e32 v173, vcc, 0, v151, vcc
	global_load_dwordx4 v[118:121], v[160:161], off offset:384
	global_load_dwordx4 v[122:125], v[170:171], off offset:384
	global_load_dwordx4 v[130:133], v[172:173], off offset:384
	s_setprio 0
	s_waitcnt lgkmcnt(0)
	s_barrier
	s_setprio 1
	ds_read_b128 v[212:215], v96 offset:55296
	ds_read_b128 v[216:219], v178 offset:18432
	ds_read_b128 v[220:223], v178 offset:23040
	ds_read_b128 v[224:227], v96 offset:59904
	ds_read_b128 v[228:231], v96 offset:55328
	ds_read_b128 v[244:247], v178 offset:18464
	ds_read_b128 v[252:255], v178 offset:23072
	s_waitcnt lgkmcnt(5)
	v_mfma_f32_32x32x16_bf16 v[48:63], v[212:215], v[216:219], v[48:63]
	s_waitcnt lgkmcnt(4)
	v_mfma_f32_32x32x16_bf16 v[32:47], v[212:215], v[220:223], v[32:47]
	ds_read_b128 v[212:215], v96 offset:59936
	s_waitcnt lgkmcnt(4)
	v_mfma_f32_32x32x16_bf16 v[16:31], v[224:227], v[216:219], v[16:31]
	ds_read_b128 v[216:219], v96 offset:55360
	v_mfma_f32_32x32x16_bf16 v[0:15], v[224:227], v[220:223], v[0:15]
	ds_read_b128 v[224:227], v178 offset:18496
	ds_read_b128 v[220:223], v178 offset:23104
	s_waitcnt lgkmcnt(5)
	v_mfma_f32_32x32x16_bf16 v[48:63], v[228:231], v[244:247], v[48:63]
	s_waitcnt lgkmcnt(4)
	v_mfma_f32_32x32x16_bf16 v[32:47], v[228:231], v[252:255], v[32:47]
	ds_read_b128 v[228:231], v96 offset:59968
	s_waitcnt lgkmcnt(4)
	v_mfma_f32_32x32x16_bf16 v[16:31], v[212:215], v[244:247], v[16:31]
	ds_read_b128 v[244:247], v96 offset:55392
	v_mfma_f32_32x32x16_bf16 v[0:15], v[212:215], v[252:255], v[0:15]
	ds_read_b128 v[212:215], v178 offset:18528
	ds_read_b128 v[252:255], v178 offset:23136
	s_waitcnt lgkmcnt(5)
	v_mfma_f32_32x32x16_bf16 v[48:63], v[216:219], v[224:227], v[48:63]
	s_nop 0
	ds_write_b128 v177, v[64:67]
	global_load_dwordx4 v[64:67], v[152:153], off offset:512
	s_waitcnt lgkmcnt(5)
	v_mfma_f32_32x32x16_bf16 v[32:47], v[216:219], v[220:223], v[32:47]
	ds_read_b128 v[216:219], v96 offset:60000
	s_nop 0
	ds_write_b128 v177, v[68:71] offset:4608
	s_nop 0
	ds_write_b128 v177, v[72:75] offset:9216
	s_waitcnt lgkmcnt(7)
	v_mfma_f32_32x32x16_bf16 v[16:31], v[228:231], v[224:227], v[16:31]
	global_load_dwordx4 v[72:75], v[154:155], off offset:512
	s_nop 0
	ds_write_b128 v177, v[76:79] offset:13824
	v_mfma_f32_32x32x16_bf16 v[0:15], v[228:231], v[220:223], v[0:15]
	global_load_dwordx4 v[76:79], v[156:157], off offset:512
	s_nop 0
	ds_write_b128 v177, v[80:83] offset:36864
	s_waitcnt lgkmcnt(7)
	v_mfma_f32_32x32x16_bf16 v[48:63], v[244:247], v[212:215], v[48:63]
	global_load_dwordx4 v[80:83], v[158:159], off offset:512
	global_load_dwordx4 v[126:129], v[150:151], off offset:512
	s_waitcnt lgkmcnt(6)
	v_mfma_f32_32x32x16_bf16 v[32:47], v[244:247], v[252:255], v[32:47]
	s_nop 0
	ds_write_b128 v177, v[84:87] offset:41472
	global_load_dwordx4 v[134:137], v[160:161], off offset:512
	s_waitcnt lgkmcnt(5)
	v_mfma_f32_32x32x16_bf16 v[16:31], v[216:219], v[212:215], v[16:31]
	s_nop 0
	ds_write_b128 v177, v[88:91] offset:46080
	global_load_dwordx4 v[138:141], v[170:171], off offset:512
	v_mfma_f32_32x32x16_bf16 v[0:15], v[216:219], v[252:255], v[0:15]
	s_nop 0
	ds_write_b128 v177, v[92:95] offset:50688
	global_load_dwordx4 v[142:145], v[172:173], off offset:512
	s_setprio 0
	s_waitcnt lgkmcnt(0)
	s_barrier
	s_setprio 1
	ds_read_b128 v[212:215], v96 offset:36864
	ds_read_b128 v[216:219], v178
	ds_read_b128 v[220:223], v178 offset:4608
	ds_read_b128 v[224:227], v96 offset:41472
	ds_read_b128 v[228:231], v96 offset:36896
	ds_read_b128 v[244:247], v178 offset:32
	ds_read_b128 v[252:255], v178 offset:4640
	s_waitcnt lgkmcnt(5)
	v_mfma_f32_32x32x16_bf16 v[48:63], v[212:215], v[216:219], v[48:63]
	s_waitcnt lgkmcnt(4)
	v_mfma_f32_32x32x16_bf16 v[32:47], v[212:215], v[220:223], v[32:47]
	ds_read_b128 v[212:215], v96 offset:41504
	s_waitcnt lgkmcnt(4)
	v_mfma_f32_32x32x16_bf16 v[16:31], v[224:227], v[216:219], v[16:31]
	ds_read_b128 v[216:219], v96 offset:36928
	v_mfma_f32_32x32x16_bf16 v[0:15], v[224:227], v[220:223], v[0:15]
	ds_read_b128 v[224:227], v178 offset:64
	ds_read_b128 v[220:223], v178 offset:4672
	s_waitcnt lgkmcnt(5)
	v_mfma_f32_32x32x16_bf16 v[48:63], v[228:231], v[244:247], v[48:63]
	s_waitcnt lgkmcnt(4)
	v_mfma_f32_32x32x16_bf16 v[32:47], v[228:231], v[252:255], v[32:47]
	ds_read_b128 v[228:231], v96 offset:41536
	s_waitcnt lgkmcnt(4)
	v_mfma_f32_32x32x16_bf16 v[16:31], v[212:215], v[244:247], v[16:31]
	ds_read_b128 v[244:247], v96 offset:36960
	v_mfma_f32_32x32x16_bf16 v[0:15], v[212:215], v[252:255], v[0:15]
	ds_read_b128 v[212:215], v178 offset:96
	ds_read_b128 v[252:255], v178 offset:4704
	s_waitcnt lgkmcnt(5)
	v_mfma_f32_32x32x16_bf16 v[48:63], v[216:219], v[224:227], v[48:63]
	s_waitcnt vmcnt(15)
	ds_write_b128 v177, v[98:101] offset:18432
	global_load_dwordx4 v[68:71], v[152:153], off offset:640
	s_waitcnt lgkmcnt(5)
	v_mfma_f32_32x32x16_bf16 v[32:47], v[216:219], v[220:223], v[32:47]
	ds_read_b128 v[216:219], v96 offset:41568
	s_waitcnt vmcnt(15)
	ds_write_b128 v177, v[102:105] offset:23040
	global_load_dwordx4 v[84:87], v[154:155], off offset:640
	s_waitcnt lgkmcnt(6)
	v_mfma_f32_32x32x16_bf16 v[16:31], v[228:231], v[224:227], v[16:31]
	s_waitcnt vmcnt(15)
	ds_write_b128 v177, v[106:109] offset:27648
	global_load_dwordx4 v[88:91], v[156:157], off offset:640
	v_mfma_f32_32x32x16_bf16 v[0:15], v[228:231], v[220:223], v[0:15]
	s_waitcnt vmcnt(15)
	ds_write_b128 v177, v[110:113] offset:32256
	global_load_dwordx4 v[92:95], v[158:159], off offset:640
	s_waitcnt lgkmcnt(6)
	v_mfma_f32_32x32x16_bf16 v[48:63], v[244:247], v[212:215], v[48:63]
	s_waitcnt vmcnt(15)
	ds_write_b128 v177, v[114:117] offset:55296
	global_load_dwordx4 v[98:101], v[150:151], off offset:640
	s_waitcnt lgkmcnt(6)
	v_mfma_f32_32x32x16_bf16 v[32:47], v[244:247], v[252:255], v[32:47]
	s_waitcnt vmcnt(15)
	ds_write_b128 v177, v[118:121] offset:59904
	global_load_dwordx4 v[106:109], v[160:161], off offset:640
	s_waitcnt lgkmcnt(5)
	v_mfma_f32_32x32x16_bf16 v[16:31], v[216:219], v[212:215], v[16:31]
	s_waitcnt vmcnt(15)
	ds_write_b128 v177, v[122:125] offset:64512
	global_load_dwordx4 v[110:113], v[170:171], off offset:640
	v_mfma_f32_32x32x16_bf16 v[0:15], v[216:219], v[252:255], v[0:15]
	s_waitcnt vmcnt(15)
	ds_write_b128 v179, v[130:133] offset:13824
	global_load_dwordx4 v[114:117], v[172:173], off offset:640
	s_setprio 0
	s_waitcnt lgkmcnt(0)
	s_barrier
	s_setprio 1
	ds_read_b128 v[212:215], v96 offset:55296
	ds_read_b128 v[216:219], v178 offset:18432
	ds_read_b128 v[220:223], v178 offset:23040
	ds_read_b128 v[224:227], v96 offset:59904
	ds_read_b128 v[228:231], v96 offset:55328
	ds_read_b128 v[244:247], v178 offset:18464
	ds_read_b128 v[252:255], v178 offset:23072
	s_waitcnt lgkmcnt(5)
	v_mfma_f32_32x32x16_bf16 v[48:63], v[212:215], v[216:219], v[48:63]
	s_waitcnt lgkmcnt(4)
	v_mfma_f32_32x32x16_bf16 v[32:47], v[212:215], v[220:223], v[32:47]
	ds_read_b128 v[212:215], v96 offset:59936
	s_waitcnt lgkmcnt(4)
	v_mfma_f32_32x32x16_bf16 v[16:31], v[224:227], v[216:219], v[16:31]
	ds_read_b128 v[216:219], v96 offset:55360
	v_mfma_f32_32x32x16_bf16 v[0:15], v[224:227], v[220:223], v[0:15]
	ds_read_b128 v[224:227], v178 offset:18496
	ds_read_b128 v[220:223], v178 offset:23104
	s_waitcnt lgkmcnt(5)
	v_mfma_f32_32x32x16_bf16 v[48:63], v[228:231], v[244:247], v[48:63]
	s_waitcnt lgkmcnt(4)
	v_mfma_f32_32x32x16_bf16 v[32:47], v[228:231], v[252:255], v[32:47]
	ds_read_b128 v[228:231], v96 offset:59968
	s_waitcnt lgkmcnt(4)
	v_mfma_f32_32x32x16_bf16 v[16:31], v[212:215], v[244:247], v[16:31]
	ds_read_b128 v[244:247], v96 offset:55392
	v_mfma_f32_32x32x16_bf16 v[0:15], v[212:215], v[252:255], v[0:15]
	ds_read_b128 v[212:215], v178 offset:18528
	ds_read_b128 v[252:255], v178 offset:23136
	s_waitcnt lgkmcnt(5)
	v_mfma_f32_32x32x16_bf16 v[48:63], v[216:219], v[224:227], v[48:63]
	s_waitcnt vmcnt(15)
	ds_write_b128 v177, v[64:67]
	global_load_dwordx4 v[64:67], v[152:153], off offset:768
	s_waitcnt lgkmcnt(5)
	v_mfma_f32_32x32x16_bf16 v[32:47], v[216:219], v[220:223], v[32:47]
	ds_read_b128 v[216:219], v96 offset:60000
	s_waitcnt vmcnt(15)
	ds_write_b128 v177, v[72:75] offset:4608
	global_load_dwordx4 v[72:75], v[154:155], off offset:768
	s_waitcnt lgkmcnt(6)
	v_mfma_f32_32x32x16_bf16 v[16:31], v[228:231], v[224:227], v[16:31]
	s_waitcnt vmcnt(15)
	ds_write_b128 v177, v[76:79] offset:9216
	global_load_dwordx4 v[76:79], v[156:157], off offset:768
	v_mfma_f32_32x32x16_bf16 v[0:15], v[228:231], v[220:223], v[0:15]
	s_waitcnt vmcnt(15)
	ds_write_b128 v177, v[80:83] offset:13824
	global_load_dwordx4 v[80:83], v[158:159], off offset:768
	s_waitcnt lgkmcnt(6)
	v_mfma_f32_32x32x16_bf16 v[48:63], v[244:247], v[212:215], v[48:63]
	s_waitcnt vmcnt(15)
	ds_write_b128 v177, v[126:129] offset:36864
	global_load_dwordx4 v[102:105], v[150:151], off offset:768
	s_waitcnt lgkmcnt(6)
	v_mfma_f32_32x32x16_bf16 v[32:47], v[244:247], v[252:255], v[32:47]
	s_waitcnt vmcnt(15)
	ds_write_b128 v177, v[134:137] offset:41472
	global_load_dwordx4 v[118:121], v[160:161], off offset:768
	s_waitcnt lgkmcnt(5)
	v_mfma_f32_32x32x16_bf16 v[16:31], v[216:219], v[212:215], v[16:31]
	s_waitcnt vmcnt(15)
	ds_write_b128 v177, v[138:141] offset:46080
	global_load_dwordx4 v[122:125], v[170:171], off offset:768
	v_mfma_f32_32x32x16_bf16 v[0:15], v[216:219], v[252:255], v[0:15]
	s_waitcnt vmcnt(15)
	ds_write_b128 v177, v[142:145] offset:50688
	global_load_dwordx4 v[126:129], v[172:173], off offset:768
	s_setprio 0
	s_waitcnt lgkmcnt(0)
	s_barrier
	s_setprio 1
	ds_read_b128 v[212:215], v96 offset:36864
	ds_read_b128 v[216:219], v178
	ds_read_b128 v[220:223], v178 offset:4608
	ds_read_b128 v[224:227], v96 offset:41472
	ds_read_b128 v[228:231], v96 offset:36896
	ds_read_b128 v[244:247], v178 offset:32
	ds_read_b128 v[252:255], v178 offset:4640
	s_waitcnt lgkmcnt(5)
	v_mfma_f32_32x32x16_bf16 v[48:63], v[212:215], v[216:219], v[48:63]
	s_waitcnt lgkmcnt(4)
	v_mfma_f32_32x32x16_bf16 v[32:47], v[212:215], v[220:223], v[32:47]
	ds_read_b128 v[212:215], v96 offset:41504
	s_waitcnt lgkmcnt(4)
	v_mfma_f32_32x32x16_bf16 v[16:31], v[224:227], v[216:219], v[16:31]
	ds_read_b128 v[216:219], v96 offset:36928
	v_mfma_f32_32x32x16_bf16 v[0:15], v[224:227], v[220:223], v[0:15]
	ds_read_b128 v[224:227], v178 offset:64
	ds_read_b128 v[220:223], v178 offset:4672
	s_waitcnt lgkmcnt(5)
	v_mfma_f32_32x32x16_bf16 v[48:63], v[228:231], v[244:247], v[48:63]
	s_waitcnt lgkmcnt(4)
	v_mfma_f32_32x32x16_bf16 v[32:47], v[228:231], v[252:255], v[32:47]
	ds_read_b128 v[228:231], v96 offset:41536
	s_waitcnt lgkmcnt(4)
	v_mfma_f32_32x32x16_bf16 v[16:31], v[212:215], v[244:247], v[16:31]
	ds_read_b128 v[244:247], v96 offset:36960
	v_mfma_f32_32x32x16_bf16 v[0:15], v[212:215], v[252:255], v[0:15]
	ds_read_b128 v[212:215], v178 offset:96
	ds_read_b128 v[252:255], v178 offset:4704
	s_waitcnt lgkmcnt(5)
	v_mfma_f32_32x32x16_bf16 v[48:63], v[216:219], v[224:227], v[48:63]
	s_waitcnt vmcnt(15)
	ds_write_b128 v177, v[68:71] offset:18432
	global_load_dwordx4 v[68:71], v[152:153], off offset:896
	s_waitcnt lgkmcnt(5)
	v_mfma_f32_32x32x16_bf16 v[32:47], v[216:219], v[220:223], v[32:47]
	ds_read_b128 v[216:219], v96 offset:41568
	s_waitcnt vmcnt(15)
	ds_write_b128 v177, v[84:87] offset:23040
	global_load_dwordx4 v[84:87], v[154:155], off offset:896
	s_waitcnt lgkmcnt(6)
	v_mfma_f32_32x32x16_bf16 v[16:31], v[228:231], v[224:227], v[16:31]
	s_waitcnt vmcnt(15)
	ds_write_b128 v177, v[88:91] offset:27648
	global_load_dwordx4 v[88:91], v[156:157], off offset:896
	v_mfma_f32_32x32x16_bf16 v[0:15], v[228:231], v[220:223], v[0:15]
	s_waitcnt vmcnt(15)
	ds_write_b128 v177, v[92:95] offset:32256
	global_load_dwordx4 v[92:95], v[158:159], off offset:896
	s_waitcnt lgkmcnt(6)
	v_mfma_f32_32x32x16_bf16 v[48:63], v[244:247], v[212:215], v[48:63]
	s_waitcnt vmcnt(15)
	ds_write_b128 v177, v[98:101] offset:55296
	global_load_dwordx4 v[98:101], v[150:151], off offset:896
	s_waitcnt lgkmcnt(6)
	v_mfma_f32_32x32x16_bf16 v[32:47], v[244:247], v[252:255], v[32:47]
	s_waitcnt vmcnt(15)
	ds_write_b128 v177, v[106:109] offset:59904
	global_load_dwordx4 v[106:109], v[160:161], off offset:896
	s_waitcnt lgkmcnt(5)
	v_mfma_f32_32x32x16_bf16 v[16:31], v[216:219], v[212:215], v[16:31]
	s_waitcnt vmcnt(15)
	ds_write_b128 v177, v[110:113] offset:64512
	global_load_dwordx4 v[110:113], v[170:171], off offset:896
	v_mfma_f32_32x32x16_bf16 v[0:15], v[216:219], v[252:255], v[0:15]
	s_waitcnt vmcnt(15)
	ds_write_b128 v179, v[114:117] offset:13824
	global_load_dwordx4 v[114:117], v[172:173], off offset:896
	s_setprio 0
	s_waitcnt lgkmcnt(0)
	s_barrier
	s_setprio 1
	ds_read_b128 v[212:215], v96 offset:55296
	ds_read_b128 v[216:219], v178 offset:18432
	ds_read_b128 v[220:223], v178 offset:23040
	ds_read_b128 v[224:227], v96 offset:59904
	ds_read_b128 v[228:231], v96 offset:55328
	ds_read_b128 v[244:247], v178 offset:18464
	ds_read_b128 v[252:255], v178 offset:23072
	s_waitcnt lgkmcnt(5)
	v_mfma_f32_32x32x16_bf16 v[48:63], v[212:215], v[216:219], v[48:63]
	s_waitcnt lgkmcnt(4)
	v_mfma_f32_32x32x16_bf16 v[32:47], v[212:215], v[220:223], v[32:47]
	ds_read_b128 v[212:215], v96 offset:59936
	s_waitcnt lgkmcnt(4)
	v_mfma_f32_32x32x16_bf16 v[16:31], v[224:227], v[216:219], v[16:31]
	ds_read_b128 v[216:219], v96 offset:55360
	v_mfma_f32_32x32x16_bf16 v[0:15], v[224:227], v[220:223], v[0:15]
	ds_read_b128 v[224:227], v178 offset:18496
	ds_read_b128 v[220:223], v178 offset:23104
	s_waitcnt lgkmcnt(5)
	v_mfma_f32_32x32x16_bf16 v[48:63], v[228:231], v[244:247], v[48:63]
	s_waitcnt lgkmcnt(4)
	v_mfma_f32_32x32x16_bf16 v[32:47], v[228:231], v[252:255], v[32:47]
	ds_read_b128 v[228:231], v96 offset:59968
	s_waitcnt lgkmcnt(4)
	v_mfma_f32_32x32x16_bf16 v[16:31], v[212:215], v[244:247], v[16:31]
	ds_read_b128 v[244:247], v96 offset:55392
	v_mfma_f32_32x32x16_bf16 v[0:15], v[212:215], v[252:255], v[0:15]
	ds_read_b128 v[212:215], v178 offset:18528
	ds_read_b128 v[252:255], v178 offset:23136
	s_waitcnt lgkmcnt(5)
	v_mfma_f32_32x32x16_bf16 v[48:63], v[216:219], v[224:227], v[48:63]
	s_waitcnt vmcnt(15)
	ds_write_b128 v177, v[64:67]
	global_load_dwordx4 v[64:67], v[152:153], off offset:1024
	s_waitcnt lgkmcnt(5)
	v_mfma_f32_32x32x16_bf16 v[32:47], v[216:219], v[220:223], v[32:47]
	ds_read_b128 v[216:219], v96 offset:60000
	s_waitcnt vmcnt(15)
	ds_write_b128 v177, v[72:75] offset:4608
	global_load_dwordx4 v[72:75], v[154:155], off offset:1024
	s_waitcnt lgkmcnt(6)
	v_mfma_f32_32x32x16_bf16 v[16:31], v[228:231], v[224:227], v[16:31]
	s_waitcnt vmcnt(15)
	ds_write_b128 v177, v[76:79] offset:9216
	global_load_dwordx4 v[76:79], v[156:157], off offset:1024
	v_mfma_f32_32x32x16_bf16 v[0:15], v[228:231], v[220:223], v[0:15]
	s_waitcnt vmcnt(15)
	ds_write_b128 v177, v[80:83] offset:13824
	global_load_dwordx4 v[80:83], v[158:159], off offset:1024
	s_waitcnt lgkmcnt(6)
	v_mfma_f32_32x32x16_bf16 v[48:63], v[244:247], v[212:215], v[48:63]
	s_waitcnt vmcnt(15)
	ds_write_b128 v177, v[102:105] offset:36864
	global_load_dwordx4 v[102:105], v[150:151], off offset:1024
	s_waitcnt lgkmcnt(6)
	v_mfma_f32_32x32x16_bf16 v[32:47], v[244:247], v[252:255], v[32:47]
	s_waitcnt vmcnt(15)
	ds_write_b128 v177, v[118:121] offset:41472
	global_load_dwordx4 v[118:121], v[160:161], off offset:1024
	s_waitcnt lgkmcnt(5)
	v_mfma_f32_32x32x16_bf16 v[16:31], v[216:219], v[212:215], v[16:31]
	s_waitcnt vmcnt(15)
	ds_write_b128 v177, v[122:125] offset:46080
	global_load_dwordx4 v[122:125], v[170:171], off offset:1024
	v_mfma_f32_32x32x16_bf16 v[0:15], v[216:219], v[252:255], v[0:15]
	s_waitcnt vmcnt(15)
	ds_write_b128 v177, v[126:129] offset:50688
	global_load_dwordx4 v[126:129], v[172:173], off offset:1024
	s_setprio 0
	s_waitcnt lgkmcnt(0)
	s_barrier
	s_setprio 1
	ds_read_b128 v[212:215], v96 offset:36864
	ds_read_b128 v[216:219], v178
	ds_read_b128 v[220:223], v178 offset:4608
	ds_read_b128 v[224:227], v96 offset:41472
	ds_read_b128 v[228:231], v96 offset:36896
	ds_read_b128 v[244:247], v178 offset:32
	ds_read_b128 v[252:255], v178 offset:4640
	s_waitcnt lgkmcnt(5)
	v_mfma_f32_32x32x16_bf16 v[48:63], v[212:215], v[216:219], v[48:63]
	s_waitcnt lgkmcnt(4)
	v_mfma_f32_32x32x16_bf16 v[32:47], v[212:215], v[220:223], v[32:47]
	ds_read_b128 v[212:215], v96 offset:41504
	s_waitcnt lgkmcnt(4)
	v_mfma_f32_32x32x16_bf16 v[16:31], v[224:227], v[216:219], v[16:31]
	ds_read_b128 v[216:219], v96 offset:36928
	v_mfma_f32_32x32x16_bf16 v[0:15], v[224:227], v[220:223], v[0:15]
	ds_read_b128 v[224:227], v178 offset:64
	ds_read_b128 v[220:223], v178 offset:4672
	s_waitcnt lgkmcnt(5)
	v_mfma_f32_32x32x16_bf16 v[48:63], v[228:231], v[244:247], v[48:63]
	s_waitcnt lgkmcnt(4)
	v_mfma_f32_32x32x16_bf16 v[32:47], v[228:231], v[252:255], v[32:47]
	ds_read_b128 v[228:231], v96 offset:41536
	s_waitcnt lgkmcnt(4)
	v_mfma_f32_32x32x16_bf16 v[16:31], v[212:215], v[244:247], v[16:31]
	ds_read_b128 v[244:247], v96 offset:36960
	v_mfma_f32_32x32x16_bf16 v[0:15], v[212:215], v[252:255], v[0:15]
	ds_read_b128 v[212:215], v178 offset:96
	ds_read_b128 v[252:255], v178 offset:4704
	s_waitcnt lgkmcnt(5)
	v_mfma_f32_32x32x16_bf16 v[48:63], v[216:219], v[224:227], v[48:63]
	s_waitcnt vmcnt(15)
	ds_write_b128 v177, v[68:71] offset:18432
	global_load_dwordx4 v[68:71], v[152:153], off offset:1152
	s_waitcnt lgkmcnt(5)
	v_mfma_f32_32x32x16_bf16 v[32:47], v[216:219], v[220:223], v[32:47]
	ds_read_b128 v[216:219], v96 offset:41568
	s_waitcnt vmcnt(15)
	ds_write_b128 v177, v[84:87] offset:23040
	global_load_dwordx4 v[84:87], v[154:155], off offset:1152
	s_waitcnt lgkmcnt(6)
	v_mfma_f32_32x32x16_bf16 v[16:31], v[228:231], v[224:227], v[16:31]
	s_waitcnt vmcnt(15)
	ds_write_b128 v177, v[88:91] offset:27648
	global_load_dwordx4 v[88:91], v[156:157], off offset:1152
	v_mfma_f32_32x32x16_bf16 v[0:15], v[228:231], v[220:223], v[0:15]
	s_waitcnt vmcnt(15)
	ds_write_b128 v177, v[92:95] offset:32256
	global_load_dwordx4 v[92:95], v[158:159], off offset:1152
	s_waitcnt lgkmcnt(6)
	v_mfma_f32_32x32x16_bf16 v[48:63], v[244:247], v[212:215], v[48:63]
	s_waitcnt vmcnt(15)
	ds_write_b128 v177, v[98:101] offset:55296
	global_load_dwordx4 v[98:101], v[150:151], off offset:1152
	s_waitcnt lgkmcnt(6)
	v_mfma_f32_32x32x16_bf16 v[32:47], v[244:247], v[252:255], v[32:47]
	s_waitcnt vmcnt(15)
	ds_write_b128 v177, v[106:109] offset:59904
	global_load_dwordx4 v[106:109], v[160:161], off offset:1152
	s_waitcnt lgkmcnt(5)
	v_mfma_f32_32x32x16_bf16 v[16:31], v[216:219], v[212:215], v[16:31]
	s_waitcnt vmcnt(15)
	ds_write_b128 v177, v[110:113] offset:64512
	global_load_dwordx4 v[110:113], v[170:171], off offset:1152
	v_mfma_f32_32x32x16_bf16 v[0:15], v[216:219], v[252:255], v[0:15]
	s_waitcnt vmcnt(15)
	ds_write_b128 v179, v[114:117] offset:13824
	global_load_dwordx4 v[114:117], v[172:173], off offset:1152
	s_setprio 0
	s_waitcnt lgkmcnt(0)
	s_barrier
	s_setprio 1
	ds_read_b128 v[212:215], v96 offset:55296
	ds_read_b128 v[216:219], v178 offset:18432
	ds_read_b128 v[220:223], v178 offset:23040
	ds_read_b128 v[224:227], v96 offset:59904
	ds_read_b128 v[228:231], v96 offset:55328
	ds_read_b128 v[244:247], v178 offset:18464
	ds_read_b128 v[252:255], v178 offset:23072
	s_waitcnt lgkmcnt(5)
	v_mfma_f32_32x32x16_bf16 v[48:63], v[212:215], v[216:219], v[48:63]
	s_waitcnt lgkmcnt(4)
	v_mfma_f32_32x32x16_bf16 v[32:47], v[212:215], v[220:223], v[32:47]
	ds_read_b128 v[212:215], v96 offset:59936
	s_waitcnt lgkmcnt(4)
	v_mfma_f32_32x32x16_bf16 v[16:31], v[224:227], v[216:219], v[16:31]
	ds_read_b128 v[216:219], v96 offset:55360
	v_mfma_f32_32x32x16_bf16 v[0:15], v[224:227], v[220:223], v[0:15]
	ds_read_b128 v[224:227], v178 offset:18496
	ds_read_b128 v[220:223], v178 offset:23104
	s_waitcnt lgkmcnt(5)
	v_mfma_f32_32x32x16_bf16 v[48:63], v[228:231], v[244:247], v[48:63]
	s_waitcnt lgkmcnt(4)
	v_mfma_f32_32x32x16_bf16 v[32:47], v[228:231], v[252:255], v[32:47]
	ds_read_b128 v[228:231], v96 offset:59968
	s_waitcnt lgkmcnt(4)
	v_mfma_f32_32x32x16_bf16 v[16:31], v[212:215], v[244:247], v[16:31]
	ds_read_b128 v[244:247], v96 offset:55392
	v_mfma_f32_32x32x16_bf16 v[0:15], v[212:215], v[252:255], v[0:15]
	ds_read_b128 v[212:215], v178 offset:18528
	ds_read_b128 v[252:255], v178 offset:23136
	s_waitcnt lgkmcnt(5)
	v_mfma_f32_32x32x16_bf16 v[48:63], v[216:219], v[224:227], v[48:63]
	s_waitcnt vmcnt(15)
	ds_write_b128 v177, v[64:67]
	global_load_dwordx4 v[64:67], v[152:153], off offset:1280
	s_waitcnt lgkmcnt(5)
	v_mfma_f32_32x32x16_bf16 v[32:47], v[216:219], v[220:223], v[32:47]
	ds_read_b128 v[216:219], v96 offset:60000
	s_waitcnt vmcnt(15)
	ds_write_b128 v177, v[72:75] offset:4608
	global_load_dwordx4 v[72:75], v[154:155], off offset:1280
	s_waitcnt lgkmcnt(6)
	v_mfma_f32_32x32x16_bf16 v[16:31], v[228:231], v[224:227], v[16:31]
	s_waitcnt vmcnt(15)
	ds_write_b128 v177, v[76:79] offset:9216
	global_load_dwordx4 v[76:79], v[156:157], off offset:1280
	v_mfma_f32_32x32x16_bf16 v[0:15], v[228:231], v[220:223], v[0:15]
	s_waitcnt vmcnt(15)
	ds_write_b128 v177, v[80:83] offset:13824
	global_load_dwordx4 v[80:83], v[158:159], off offset:1280
	s_waitcnt lgkmcnt(6)
	v_mfma_f32_32x32x16_bf16 v[48:63], v[244:247], v[212:215], v[48:63]
	s_waitcnt vmcnt(15)
	ds_write_b128 v177, v[102:105] offset:36864
	global_load_dwordx4 v[102:105], v[150:151], off offset:1280
	s_waitcnt lgkmcnt(6)
	v_mfma_f32_32x32x16_bf16 v[32:47], v[244:247], v[252:255], v[32:47]
	s_waitcnt vmcnt(15)
	ds_write_b128 v177, v[118:121] offset:41472
	global_load_dwordx4 v[118:121], v[160:161], off offset:1280
	s_waitcnt lgkmcnt(5)
	v_mfma_f32_32x32x16_bf16 v[16:31], v[216:219], v[212:215], v[16:31]
	s_waitcnt vmcnt(15)
	ds_write_b128 v177, v[122:125] offset:46080
	global_load_dwordx4 v[122:125], v[170:171], off offset:1280
	v_mfma_f32_32x32x16_bf16 v[0:15], v[216:219], v[252:255], v[0:15]
	s_waitcnt vmcnt(15)
	ds_write_b128 v177, v[126:129] offset:50688
	global_load_dwordx4 v[126:129], v[172:173], off offset:1280
	s_setprio 0
	s_waitcnt lgkmcnt(0)
	s_barrier
	s_setprio 1
	ds_read_b128 v[212:215], v96 offset:36864
	ds_read_b128 v[216:219], v178
	ds_read_b128 v[220:223], v178 offset:4608
	ds_read_b128 v[224:227], v96 offset:41472
	ds_read_b128 v[228:231], v96 offset:36896
	ds_read_b128 v[244:247], v178 offset:32
	ds_read_b128 v[252:255], v178 offset:4640
	s_waitcnt lgkmcnt(5)
	v_mfma_f32_32x32x16_bf16 v[48:63], v[212:215], v[216:219], v[48:63]
	s_waitcnt lgkmcnt(4)
	v_mfma_f32_32x32x16_bf16 v[32:47], v[212:215], v[220:223], v[32:47]
	ds_read_b128 v[212:215], v96 offset:41504
	s_waitcnt lgkmcnt(4)
	v_mfma_f32_32x32x16_bf16 v[16:31], v[224:227], v[216:219], v[16:31]
	ds_read_b128 v[216:219], v96 offset:36928
	v_mfma_f32_32x32x16_bf16 v[0:15], v[224:227], v[220:223], v[0:15]
	ds_read_b128 v[224:227], v178 offset:64
	ds_read_b128 v[220:223], v178 offset:4672
	s_waitcnt lgkmcnt(5)
	v_mfma_f32_32x32x16_bf16 v[48:63], v[228:231], v[244:247], v[48:63]
	s_waitcnt lgkmcnt(4)
	v_mfma_f32_32x32x16_bf16 v[32:47], v[228:231], v[252:255], v[32:47]
	ds_read_b128 v[228:231], v96 offset:41536
	s_waitcnt lgkmcnt(4)
	v_mfma_f32_32x32x16_bf16 v[16:31], v[212:215], v[244:247], v[16:31]
	ds_read_b128 v[244:247], v96 offset:36960
	v_mfma_f32_32x32x16_bf16 v[0:15], v[212:215], v[252:255], v[0:15]
	ds_read_b128 v[212:215], v178 offset:96
	ds_read_b128 v[252:255], v178 offset:4704
	s_waitcnt lgkmcnt(5)
	v_mfma_f32_32x32x16_bf16 v[48:63], v[216:219], v[224:227], v[48:63]
	s_waitcnt vmcnt(15)
	ds_write_b128 v177, v[68:71] offset:18432
	global_load_dwordx4 v[68:71], v[152:153], off offset:1408
	s_waitcnt lgkmcnt(5)
	v_mfma_f32_32x32x16_bf16 v[32:47], v[216:219], v[220:223], v[32:47]
	ds_read_b128 v[216:219], v96 offset:41568
	s_waitcnt vmcnt(15)
	ds_write_b128 v177, v[84:87] offset:23040
	global_load_dwordx4 v[84:87], v[154:155], off offset:1408
	s_waitcnt lgkmcnt(6)
	v_mfma_f32_32x32x16_bf16 v[16:31], v[228:231], v[224:227], v[16:31]
	s_waitcnt vmcnt(15)
	ds_write_b128 v177, v[88:91] offset:27648
	global_load_dwordx4 v[88:91], v[156:157], off offset:1408
	v_mfma_f32_32x32x16_bf16 v[0:15], v[228:231], v[220:223], v[0:15]
	s_waitcnt vmcnt(15)
	ds_write_b128 v177, v[92:95] offset:32256
	global_load_dwordx4 v[92:95], v[158:159], off offset:1408
	s_waitcnt lgkmcnt(6)
	v_mfma_f32_32x32x16_bf16 v[48:63], v[244:247], v[212:215], v[48:63]
	s_waitcnt vmcnt(15)
	ds_write_b128 v177, v[98:101] offset:55296
	global_load_dwordx4 v[98:101], v[150:151], off offset:1408
	s_waitcnt lgkmcnt(6)
	v_mfma_f32_32x32x16_bf16 v[32:47], v[244:247], v[252:255], v[32:47]
	s_waitcnt vmcnt(15)
	ds_write_b128 v177, v[106:109] offset:59904
	global_load_dwordx4 v[106:109], v[160:161], off offset:1408
	s_waitcnt lgkmcnt(5)
	v_mfma_f32_32x32x16_bf16 v[16:31], v[216:219], v[212:215], v[16:31]
	s_waitcnt vmcnt(15)
	ds_write_b128 v177, v[110:113] offset:64512
	global_load_dwordx4 v[110:113], v[170:171], off offset:1408
	v_mfma_f32_32x32x16_bf16 v[0:15], v[216:219], v[252:255], v[0:15]
	s_waitcnt vmcnt(15)
	ds_write_b128 v179, v[114:117] offset:13824
	global_load_dwordx4 v[130:133], v[172:173], off offset:1408
	s_setprio 0
	s_waitcnt lgkmcnt(0)
	s_barrier
	s_setprio 1
	ds_read_b128 v[212:215], v96 offset:55296
	ds_read_b128 v[216:219], v178 offset:18432
	ds_read_b128 v[220:223], v178 offset:23040
	ds_read_b128 v[224:227], v96 offset:59904
	ds_read_b128 v[228:231], v96 offset:55328
	ds_read_b128 v[244:247], v178 offset:18464
	ds_read_b128 v[252:255], v178 offset:23072
	s_waitcnt lgkmcnt(5)
	v_mfma_f32_32x32x16_bf16 v[48:63], v[212:215], v[216:219], v[48:63]
	s_waitcnt lgkmcnt(4)
	v_mfma_f32_32x32x16_bf16 v[32:47], v[212:215], v[220:223], v[32:47]
	ds_read_b128 v[212:215], v96 offset:59936
	s_waitcnt lgkmcnt(4)
	v_mfma_f32_32x32x16_bf16 v[16:31], v[224:227], v[216:219], v[16:31]
	ds_read_b128 v[216:219], v96 offset:55360
	v_mfma_f32_32x32x16_bf16 v[0:15], v[224:227], v[220:223], v[0:15]
	ds_read_b128 v[224:227], v178 offset:18496
	ds_read_b128 v[220:223], v178 offset:23104
	s_waitcnt lgkmcnt(5)
	v_mfma_f32_32x32x16_bf16 v[48:63], v[228:231], v[244:247], v[48:63]
	s_waitcnt lgkmcnt(4)
	v_mfma_f32_32x32x16_bf16 v[32:47], v[228:231], v[252:255], v[32:47]
	ds_read_b128 v[228:231], v96 offset:59968
	s_waitcnt lgkmcnt(4)
	v_mfma_f32_32x32x16_bf16 v[16:31], v[212:215], v[244:247], v[16:31]
	ds_read_b128 v[244:247], v96 offset:55392
	v_mfma_f32_32x32x16_bf16 v[0:15], v[212:215], v[252:255], v[0:15]
	ds_read_b128 v[212:215], v178 offset:18528
	ds_read_b128 v[252:255], v178 offset:23136
	s_waitcnt lgkmcnt(5)
	v_mfma_f32_32x32x16_bf16 v[48:63], v[216:219], v[224:227], v[48:63]
	s_waitcnt vmcnt(15)
	ds_write_b128 v177, v[64:67]
	global_load_dwordx4 v[64:67], v[152:153], off offset:1536
	s_waitcnt lgkmcnt(5)
	v_mfma_f32_32x32x16_bf16 v[32:47], v[216:219], v[220:223], v[32:47]
	ds_read_b128 v[216:219], v96 offset:60000
	s_waitcnt vmcnt(15)
	ds_write_b128 v177, v[72:75] offset:4608
	global_load_dwordx4 v[72:75], v[154:155], off offset:1536
	s_waitcnt lgkmcnt(6)
	v_mfma_f32_32x32x16_bf16 v[16:31], v[228:231], v[224:227], v[16:31]
	s_waitcnt vmcnt(15)
	ds_write_b128 v177, v[76:79] offset:9216
	global_load_dwordx4 v[76:79], v[156:157], off offset:1536
	v_mfma_f32_32x32x16_bf16 v[0:15], v[228:231], v[220:223], v[0:15]
	s_waitcnt vmcnt(15)
	ds_write_b128 v177, v[80:83] offset:13824
	global_load_dwordx4 v[80:83], v[158:159], off offset:1536
	s_waitcnt lgkmcnt(6)
	v_mfma_f32_32x32x16_bf16 v[48:63], v[244:247], v[212:215], v[48:63]
	s_waitcnt vmcnt(15)
	ds_write_b128 v177, v[102:105] offset:36864
	global_load_dwordx4 v[114:117], v[150:151], off offset:1536
	s_waitcnt lgkmcnt(6)
	v_mfma_f32_32x32x16_bf16 v[32:47], v[244:247], v[252:255], v[32:47]
	s_waitcnt vmcnt(15)
	ds_write_b128 v177, v[118:121] offset:41472
	s_waitcnt vmcnt(14)
	ds_write_b128 v177, v[122:125] offset:46080
	s_waitcnt lgkmcnt(6)
	v_mfma_f32_32x32x16_bf16 v[16:31], v[216:219], v[212:215], v[16:31]
	global_load_dwordx4 v[122:125], v[160:161], off offset:1536
	s_waitcnt vmcnt(14)
	ds_write_b128 v177, v[126:129] offset:50688
	v_mfma_f32_32x32x16_bf16 v[0:15], v[216:219], v[252:255], v[0:15]
	global_load_dwordx4 v[126:129], v[170:171], off offset:1536
	global_load_dwordx4 v[134:137], v[172:173], off offset:1536
	s_setprio 0
	s_waitcnt lgkmcnt(0)
	s_barrier
	s_setprio 1
	ds_read_b128 v[212:215], v96 offset:36864
	ds_read_b128 v[216:219], v178
	ds_read_b128 v[220:223], v178 offset:4608
	ds_read_b128 v[224:227], v96 offset:41472
	ds_read_b128 v[228:231], v96 offset:36896
	ds_read_b128 v[244:247], v178 offset:32
	ds_read_b128 v[252:255], v178 offset:4640
	s_waitcnt lgkmcnt(5)
	v_mfma_f32_32x32x16_bf16 v[48:63], v[212:215], v[216:219], v[48:63]
	s_waitcnt lgkmcnt(4)
	v_mfma_f32_32x32x16_bf16 v[32:47], v[212:215], v[220:223], v[32:47]
	ds_read_b128 v[212:215], v96 offset:41504
	s_waitcnt lgkmcnt(4)
	v_mfma_f32_32x32x16_bf16 v[16:31], v[224:227], v[216:219], v[16:31]
	ds_read_b128 v[216:219], v96 offset:36928
	v_mfma_f32_32x32x16_bf16 v[0:15], v[224:227], v[220:223], v[0:15]
	ds_read_b128 v[224:227], v178 offset:64
	ds_read_b128 v[220:223], v178 offset:4672
	s_waitcnt lgkmcnt(5)
	v_mfma_f32_32x32x16_bf16 v[48:63], v[228:231], v[244:247], v[48:63]
	s_waitcnt lgkmcnt(4)
	v_mfma_f32_32x32x16_bf16 v[32:47], v[228:231], v[252:255], v[32:47]
	ds_read_b128 v[228:231], v96 offset:41536
	s_waitcnt lgkmcnt(4)
	v_mfma_f32_32x32x16_bf16 v[16:31], v[212:215], v[244:247], v[16:31]
	ds_read_b128 v[244:247], v96 offset:36960
	v_mfma_f32_32x32x16_bf16 v[0:15], v[212:215], v[252:255], v[0:15]
	ds_read_b128 v[212:215], v178 offset:96
	ds_read_b128 v[252:255], v178 offset:4704
	s_waitcnt lgkmcnt(5)
	v_mfma_f32_32x32x16_bf16 v[48:63], v[216:219], v[224:227], v[48:63]
	s_waitcnt vmcnt(15)
	ds_write_b128 v177, v[68:71] offset:18432
	s_waitcnt vmcnt(14)
	ds_write_b128 v177, v[84:87] offset:23040
	s_waitcnt lgkmcnt(6)
	v_mfma_f32_32x32x16_bf16 v[32:47], v[216:219], v[220:223], v[32:47]
	ds_read_b128 v[216:219], v96 offset:41568
	s_waitcnt vmcnt(13)
	ds_write_b128 v177, v[88:91] offset:27648
	s_waitcnt vmcnt(12)
	ds_write_b128 v177, v[92:95] offset:32256
	s_waitcnt lgkmcnt(8)
	v_mfma_f32_32x32x16_bf16 v[16:31], v[228:231], v[224:227], v[16:31]
	s_waitcnt vmcnt(11)
	ds_write_b128 v177, v[98:101] offset:55296
	v_mfma_f32_32x32x16_bf16 v[0:15], v[228:231], v[220:223], v[0:15]
	global_load_dwordx4 v[98:101], v[152:153], off offset:1664
	global_load_dwordx4 v[102:105], v[154:155], off offset:1664
	s_waitcnt vmcnt(12)
	ds_write_b128 v177, v[106:109] offset:59904
	s_waitcnt lgkmcnt(8)
	v_mfma_f32_32x32x16_bf16 v[48:63], v[244:247], v[212:215], v[48:63]
	global_load_dwordx4 v[106:109], v[156:157], off offset:1664
	s_waitcnt vmcnt(12)
	ds_write_b128 v177, v[110:113] offset:64512
	s_waitcnt lgkmcnt(8)
	v_mfma_f32_32x32x16_bf16 v[32:47], v[244:247], v[252:255], v[32:47]
	global_load_dwordx4 v[110:113], v[158:159], off offset:1664
	global_load_dwordx4 v[118:121], v[150:151], off offset:1664
	s_waitcnt lgkmcnt(5)
	v_mfma_f32_32x32x16_bf16 v[16:31], v[216:219], v[212:215], v[16:31]
	s_waitcnt vmcnt(13)
	ds_write_b128 v179, v[130:133] offset:13824
	global_load_dwordx4 v[130:133], v[160:161], off offset:1664
	v_mfma_f32_32x32x16_bf16 v[0:15], v[216:219], v[252:255], v[0:15]
	global_load_dwordx4 v[138:141], v[170:171], off offset:1664
	global_load_dwordx4 v[142:145], v[172:173], off offset:1664
	s_setprio 0
	s_waitcnt lgkmcnt(0)
	s_barrier
	s_setprio 1
	ds_read_b128 v[212:215], v96 offset:55296
	ds_read_b128 v[216:219], v178 offset:18432
	ds_read_b128 v[220:223], v178 offset:23040
	ds_read_b128 v[224:227], v96 offset:59904
	ds_read_b128 v[228:231], v96 offset:55328
	ds_read_b128 v[244:247], v178 offset:18464
	ds_read_b128 v[252:255], v178 offset:23072
	s_waitcnt lgkmcnt(5)
	v_mfma_f32_32x32x16_bf16 v[48:63], v[212:215], v[216:219], v[48:63]
	s_waitcnt lgkmcnt(4)
	v_mfma_f32_32x32x16_bf16 v[32:47], v[212:215], v[220:223], v[32:47]
	ds_read_b128 v[212:215], v96 offset:59936
	s_waitcnt lgkmcnt(4)
	v_mfma_f32_32x32x16_bf16 v[16:31], v[224:227], v[216:219], v[16:31]
	ds_read_b128 v[216:219], v96 offset:55360
	v_mfma_f32_32x32x16_bf16 v[0:15], v[224:227], v[220:223], v[0:15]
	ds_read_b128 v[224:227], v178 offset:18496
	ds_read_b128 v[220:223], v178 offset:23104
	s_waitcnt lgkmcnt(5)
	v_mfma_f32_32x32x16_bf16 v[48:63], v[228:231], v[244:247], v[48:63]
	s_waitcnt lgkmcnt(4)
	v_mfma_f32_32x32x16_bf16 v[32:47], v[228:231], v[252:255], v[32:47]
	ds_read_b128 v[228:231], v96 offset:59968
	s_waitcnt lgkmcnt(4)
	v_mfma_f32_32x32x16_bf16 v[16:31], v[212:215], v[244:247], v[16:31]
	ds_read_b128 v[244:247], v96 offset:55392
	v_mfma_f32_32x32x16_bf16 v[0:15], v[212:215], v[252:255], v[0:15]
	ds_read_b128 v[212:215], v178 offset:18528
	ds_read_b128 v[252:255], v178 offset:23136
	s_waitcnt lgkmcnt(5)
	v_mfma_f32_32x32x16_bf16 v[48:63], v[216:219], v[224:227], v[48:63]
	s_waitcnt vmcnt(15)
	ds_write_b128 v177, v[64:67]
	global_load_dwordx4 v[64:67], v[152:153], off offset:1792
	s_waitcnt lgkmcnt(5)
	v_mfma_f32_32x32x16_bf16 v[32:47], v[216:219], v[220:223], v[32:47]
	ds_read_b128 v[216:219], v96 offset:60000
	s_waitcnt vmcnt(15)
	ds_write_b128 v177, v[72:75] offset:4608
	global_load_dwordx4 v[68:71], v[154:155], off offset:1792
	s_waitcnt lgkmcnt(6)
	v_mfma_f32_32x32x16_bf16 v[16:31], v[228:231], v[224:227], v[16:31]
	s_waitcnt vmcnt(15)
	ds_write_b128 v177, v[76:79] offset:9216
	global_load_dwordx4 v[72:75], v[156:157], off offset:1792
	v_mfma_f32_32x32x16_bf16 v[0:15], v[228:231], v[220:223], v[0:15]
	s_waitcnt vmcnt(15)
	ds_write_b128 v177, v[80:83] offset:13824
	global_load_dwordx4 v[76:79], v[158:159], off offset:1792
	s_waitcnt lgkmcnt(6)
	v_mfma_f32_32x32x16_bf16 v[48:63], v[244:247], v[212:215], v[48:63]
	s_waitcnt vmcnt(15)
	ds_write_b128 v177, v[114:117] offset:36864
	global_load_dwordx4 v[80:83], v[150:151], off offset:1792
	s_waitcnt lgkmcnt(6)
	v_mfma_f32_32x32x16_bf16 v[32:47], v[244:247], v[252:255], v[32:47]
	s_waitcnt vmcnt(15)
	ds_write_b128 v177, v[122:125] offset:41472
	global_load_dwordx4 v[84:87], v[160:161], off offset:1792
	s_waitcnt lgkmcnt(5)
	v_mfma_f32_32x32x16_bf16 v[16:31], v[216:219], v[212:215], v[16:31]
	s_waitcnt vmcnt(15)
	ds_write_b128 v177, v[126:129] offset:46080
	global_load_dwordx4 v[88:91], v[170:171], off offset:1792
	v_mfma_f32_32x32x16_bf16 v[0:15], v[216:219], v[252:255], v[0:15]
	s_waitcnt vmcnt(15)
	ds_write_b128 v177, v[134:137] offset:50688
	global_load_dwordx4 v[92:95], v[172:173], off offset:1792
	s_setprio 0
	s_waitcnt lgkmcnt(0)
	s_barrier
	s_setprio 1
	ds_read_b128 v[212:215], v96 offset:36864
	ds_read_b128 v[216:219], v178
	ds_read_b128 v[220:223], v178 offset:4608
	ds_read_b128 v[224:227], v96 offset:41472
	ds_read_b128 v[228:231], v96 offset:36896
	ds_read_b128 v[244:247], v178 offset:32
	ds_read_b128 v[252:255], v178 offset:4640
	s_waitcnt lgkmcnt(5)
	v_mfma_f32_32x32x16_bf16 v[48:63], v[212:215], v[216:219], v[48:63]
	s_waitcnt lgkmcnt(4)
	v_mfma_f32_32x32x16_bf16 v[32:47], v[212:215], v[220:223], v[32:47]
	ds_read_b128 v[212:215], v96 offset:41504
	s_waitcnt lgkmcnt(4)
	v_mfma_f32_32x32x16_bf16 v[16:31], v[224:227], v[216:219], v[16:31]
	ds_read_b128 v[216:219], v96 offset:36928
	v_mfma_f32_32x32x16_bf16 v[0:15], v[224:227], v[220:223], v[0:15]
	ds_read_b128 v[224:227], v178 offset:64
	ds_read_b128 v[220:223], v178 offset:4672
	s_waitcnt lgkmcnt(5)
	v_mfma_f32_32x32x16_bf16 v[48:63], v[228:231], v[244:247], v[48:63]
	s_waitcnt lgkmcnt(4)
	v_mfma_f32_32x32x16_bf16 v[32:47], v[228:231], v[252:255], v[32:47]
	ds_read_b128 v[228:231], v96 offset:41536
	s_waitcnt lgkmcnt(4)
	v_mfma_f32_32x32x16_bf16 v[16:31], v[212:215], v[244:247], v[16:31]
	ds_read_b128 v[244:247], v96 offset:36960
	v_mfma_f32_32x32x16_bf16 v[0:15], v[212:215], v[252:255], v[0:15]
	ds_read_b128 v[212:215], v178 offset:96
	ds_read_b128 v[252:255], v178 offset:4704
	s_waitcnt lgkmcnt(5)
	v_mfma_f32_32x32x16_bf16 v[48:63], v[216:219], v[224:227], v[48:63]
	s_waitcnt vmcnt(15)
	ds_write_b128 v177, v[98:101] offset:18432
	s_waitcnt vmcnt(14)
	ds_write_b128 v177, v[102:105] offset:23040
	s_waitcnt lgkmcnt(6)
	v_mfma_f32_32x32x16_bf16 v[32:47], v[216:219], v[220:223], v[32:47]
	ds_read_b128 v[216:219], v96 offset:41568
	global_load_dwordx4 v[100:103], v[152:153], off offset:1920
	s_waitcnt vmcnt(14)
	ds_write_b128 v177, v[106:109] offset:27648
	s_waitcnt lgkmcnt(7)
	v_mfma_f32_32x32x16_bf16 v[16:31], v[228:231], v[224:227], v[16:31]
	global_load_dwordx4 v[104:107], v[154:155], off offset:1920
	s_waitcnt vmcnt(14)
	ds_write_b128 v177, v[110:113] offset:32256
	v_mfma_f32_32x32x16_bf16 v[0:15], v[228:231], v[220:223], v[0:15]
	global_load_dwordx4 v[108:111], v[156:157], off offset:1920
	global_load_dwordx4 v[112:115], v[158:159], off offset:1920
	s_waitcnt lgkmcnt(6)
	v_mfma_f32_32x32x16_bf16 v[48:63], v[244:247], v[212:215], v[48:63]
	s_waitcnt vmcnt(15)
	ds_write_b128 v177, v[118:121] offset:55296
	global_load_dwordx4 v[116:119], v[150:151], off offset:1920
	s_waitcnt lgkmcnt(6)
	v_mfma_f32_32x32x16_bf16 v[32:47], v[244:247], v[252:255], v[32:47]
	s_waitcnt vmcnt(15)
	ds_write_b128 v177, v[130:133] offset:59904
	global_load_dwordx4 v[120:123], v[160:161], off offset:1920
	s_waitcnt lgkmcnt(4)
	v_mfma_f32_32x32x16_bf16 v[16:31], v[216:219], v[212:215], v[16:31]
	s_waitcnt vmcnt(15)
	ds_write_b128 v177, v[138:141] offset:64512
	global_load_dwordx4 v[128:131], v[170:171], off offset:1920
	v_mfma_f32_32x32x16_bf16 v[0:15], v[216:219], v[252:255], v[0:15]
	s_waitcnt vmcnt(15)
	ds_write_b128 v179, v[142:145] offset:13824
	global_load_dwordx4 v[124:127], v[172:173], off offset:1920
	s_setprio 0
	s_waitcnt lgkmcnt(0)
	s_barrier
	s_setprio 1
	ds_read_b128 v[212:215], v96 offset:55296
	ds_read_b128 v[216:219], v178 offset:18432
	ds_read_b128 v[220:223], v178 offset:23040
	ds_read_b128 v[224:227], v96 offset:59904
	ds_read_b128 v[228:231], v96 offset:55328
	ds_read_b128 v[244:247], v178 offset:18464
	ds_read_b128 v[252:255], v178 offset:23072
	s_waitcnt lgkmcnt(5)
	v_mfma_f32_32x32x16_bf16 v[48:63], v[212:215], v[216:219], v[48:63]
	s_waitcnt lgkmcnt(4)
	v_mfma_f32_32x32x16_bf16 v[32:47], v[212:215], v[220:223], v[32:47]
	ds_read_b128 v[212:215], v96 offset:59936
	s_waitcnt lgkmcnt(4)
	v_mfma_f32_32x32x16_bf16 v[16:31], v[224:227], v[216:219], v[16:31]
	ds_read_b128 v[216:219], v96 offset:55360
	v_mfma_f32_32x32x16_bf16 v[0:15], v[224:227], v[220:223], v[0:15]
	ds_read_b128 v[224:227], v178 offset:18496
	ds_read_b128 v[220:223], v178 offset:23104
	s_waitcnt lgkmcnt(5)
	v_mfma_f32_32x32x16_bf16 v[48:63], v[228:231], v[244:247], v[48:63]
	s_waitcnt lgkmcnt(4)
	v_mfma_f32_32x32x16_bf16 v[32:47], v[228:231], v[252:255], v[32:47]
	ds_read_b128 v[228:231], v96 offset:59968
	s_waitcnt lgkmcnt(4)
	v_mfma_f32_32x32x16_bf16 v[16:31], v[212:215], v[244:247], v[16:31]
	ds_read_b128 v[244:247], v96 offset:55392
	v_mfma_f32_32x32x16_bf16 v[0:15], v[212:215], v[252:255], v[0:15]
	ds_read_b128 v[212:215], v178 offset:18528
	ds_read_b128 v[252:255], v178 offset:23136
	s_waitcnt lgkmcnt(5)
	v_mfma_f32_32x32x16_bf16 v[48:63], v[216:219], v[224:227], v[48:63]
	s_waitcnt lgkmcnt(4)
	v_mfma_f32_32x32x16_bf16 v[32:47], v[216:219], v[220:223], v[32:47]
	ds_read_b128 v[216:219], v96 offset:60000
	s_waitcnt lgkmcnt(4)
	v_mfma_f32_32x32x16_bf16 v[16:31], v[228:231], v[224:227], v[16:31]
	v_mfma_f32_32x32x16_bf16 v[0:15], v[228:231], v[220:223], v[0:15]
	s_waitcnt lgkmcnt(2)
	v_mfma_f32_32x32x16_bf16 v[48:63], v[244:247], v[212:215], v[48:63]
	s_waitcnt lgkmcnt(1)
	v_mfma_f32_32x32x16_bf16 v[32:47], v[244:247], v[252:255], v[32:47]
	s_waitcnt lgkmcnt(0)
	v_mfma_f32_32x32x16_bf16 v[16:31], v[216:219], v[212:215], v[16:31]
	v_mfma_f32_32x32x16_bf16 v[0:15], v[216:219], v[252:255], v[0:15]
	s_setprio 0
	v_cndmask_b32_e64 v98, 0, 1, s[12:13]
	v_cmp_ne_u32_e64 s[40:41], 1, v98
	s_andn2_b64 vcc, exec, s[12:13]
	s_waitcnt vmcnt(15)
	ds_write_b128 v177, v[64:67]
	s_waitcnt vmcnt(14)
	ds_write_b128 v177, v[68:71] offset:4608
	s_waitcnt vmcnt(13)
	ds_write_b128 v177, v[72:75] offset:9216
	s_waitcnt vmcnt(12)
	ds_write_b128 v177, v[76:79] offset:13824
	s_waitcnt vmcnt(11)
	ds_write_b128 v177, v[80:83] offset:36864
	s_waitcnt vmcnt(10)
	ds_write_b128 v177, v[84:87] offset:41472
	s_waitcnt vmcnt(9)
	ds_write_b128 v177, v[88:91] offset:46080
	s_waitcnt vmcnt(8)
	ds_write_b128 v177, v[92:95] offset:50688
	s_cbranch_vccnz .LBB0_474
	v_add_co_u32_e32 v68, vcc, 0x10000, v148
	global_load_dwordx4 v[64:67], v[148:149], off
	s_nop 0
	v_addc_co_u32_e32 v69, vcc, 0, v149, vcc
	v_add_co_u32_e32 v72, vcc, 0x20000, v148
	s_nop 1
	v_addc_co_u32_e32 v73, vcc, 0, v149, vcc
	v_add_co_u32_e32 v76, vcc, 0x30000, v148
	global_load_dwordx4 v[68:71], v[68:69], off
	global_load_dwordx4 v[72:75], v[72:73], off
	v_addc_co_u32_e32 v77, vcc, 0, v149, vcc
	v_add_co_u32_e32 v84, vcc, 0x10000, v146
	global_load_dwordx4 v[76:79], v[76:77], off
	s_nop 0
	global_load_dwordx4 v[80:83], v[146:147], off
	v_addc_co_u32_e32 v85, vcc, 0, v147, vcc
	v_add_co_u32_e32 v88, vcc, 0x20000, v146
	s_nop 1
	v_addc_co_u32_e32 v89, vcc, 0, v147, vcc
	v_add_co_u32_e32 v92, vcc, 0x30000, v146
	global_load_dwordx4 v[84:87], v[84:85], off
	s_nop 0
	global_load_dwordx4 v[88:91], v[88:89], off
	v_addc_co_u32_e32 v93, vcc, 0, v147, vcc
	global_load_dwordx4 v[92:95], v[92:93], off

.LBB0_580:
	v_add_u32_e32 v68, v67, v65
	ds_read_b128 v[72:75], v67 offset:18432
	ds_read_b128 v[76:79], v68
	s_add_i32 s0, s0, 32
	s_cmp_lt_u32 s0, 48
	s_waitcnt lgkmcnt(0)
	v_mfma_f32_32x32x16_bf16 v[48:63], v[76:79], v[72:75], v[48:63]
	ds_read_b128 v[72:75], v67 offset:23040
	s_waitcnt lgkmcnt(0)
	v_mfma_f32_32x32x16_bf16 v[16:31], v[76:79], v[72:75], v[16:31]
	ds_read_b128 v[72:75], v67 offset:27648
	s_waitcnt lgkmcnt(0)
	v_mfma_f32_32x32x16_bf16 v[32:47], v[76:79], v[72:75], v[32:47]
	ds_read_b128 v[72:75], v67 offset:32256
	ds_read_b128 v[80:83], v67 offset:18464
	s_waitcnt lgkmcnt(1)
	v_mfma_f32_32x32x16_bf16 v[0:15], v[76:79], v[72:75], v[0:15]
	ds_read_b128 v[72:75], v68 offset:32
	ds_read_b128 v[76:79], v67 offset:23072
	s_waitcnt lgkmcnt(0)
	v_mfma_f32_32x32x16_bf16 v[16:31], v[72:75], v[76:79], v[16:31]
	ds_read_b128 v[76:79], v67 offset:27680
	s_waitcnt lgkmcnt(0)
	v_mfma_f32_32x32x16_bf16 v[32:47], v[72:75], v[76:79], v[32:47]
	ds_read_b128 v[76:79], v67 offset:32288
	v_add_u32_e32 v67, 64, v67
	v_mfma_f32_32x32x16_bf16 v[48:63], v[72:75], v[80:83], v[48:63]
	s_waitcnt lgkmcnt(0)
	v_mfma_f32_32x32x16_bf16 v[0:15], v[72:75], v[76:79], v[0:15]
	s_cbranch_scc1 .LBB0_580
	s_lshl_b32 s0, s39, 9
	s_or_b32 s6, s0, s3
	v_or_b32_e32 v96, s6, v71
	v_readlane_b32 s8, v251, 20
	v_lshlrev_b32_e32 v67, 11, v64
	v_lshlrev_b64 v[64:65], 2, v[96:97]
	v_readlane_b32 s10, v251, 22
	v_readlane_b32 s11, v251, 23
	s_barrier
	s_nop 0
	v_lshl_add_u64 v[68:69], s[10:11], 0, v[64:65]
	v_readlane_b32 s100, v251, 16
	v_readlane_b32 s101, v251, 17
	s_nop 1
	v_lshl_add_u64 v[220:221], s[100:101], 0, v[64:65]
	v_readlane_b32 s100, v251, 20
	v_readlane_b32 s101, v251, 21
	s_nop 1
	v_lshl_add_u64 v[222:223], s[100:101], 0, v[64:65]
	global_load_dword v224, v[220:221], off
	global_load_dword v225, v[222:223], off
	global_load_dword v226, v[68:69], off offset:128
	global_load_dword v227, v[222:223], off offset:128
	global_load_dword v228, v[220:221], off offset:128
	global_load_dword v68, v[68:69], off
	s_mov_b32 s7, 0x3f2aaaab
	s_mov_b32 s39, 0x3f317218
	v_readlane_b32 s12, v251, 4
	v_readlane_b32 s24, v251, 16
	v_readlane_b32 s25, v251, 17
	v_readlane_b32 s9, v251, 21
	s_mov_b32 s40, 0x7f800000
	s_mov_b32 s41, 0x33800000
	s_mov_b32 s15, 0x43000000
	s_mov_b32 s16, 0x42b17217
	s_mov_b32 s17, 0xf800000
	s_mov_b32 s18, 0xc1880000
	v_add_u32_e32 v96, s6, v71
	s_cmp_eq_u32 s38, 0
	s_mov_b32 s4, 0
	v_readlane_b32 s13, v251, 5
	v_readlane_b32 s14, v251, 6
	v_readlane_b32 s19, v251, 11
	v_readlane_b32 s20, v251, 12
	v_readlane_b32 s21, v251, 13
	v_readlane_b32 s22, v251, 14
	v_readlane_b32 s23, v251, 15
	v_readlane_b32 s26, v251, 18
	v_readlane_b32 s27, v251, 19
	s_waitcnt vmcnt(0)
	v_mul_f32_e32 v68, 0xbfb8aa3b, v68
	v_exp_f32_e32 v70, v68
	s_nop 0
	v_add_f32_e32 v72, 1.0, v70
	v_add_f32_e32 v68, -1.0, v72
	v_sub_f32_e32 v69, v68, v72
	v_add_f32_e32 v69, 1.0, v69
	v_sub_f32_e32 v68, v70, v68
	v_add_f32_e32 v73, v68, v69
	v_frexp_mant_f32_e32 v68, v72
	v_cmp_gt_f32_e32 vcc, s7, v68
	v_cvt_f64_f32_e32 v[68:69], v72
	v_frexp_exp_i32_f64_e32 v68, v[68:69]
	v_subbrev_co_u32_e32 v78, vcc, 0, v68, vcc
	v_sub_u32_e32 v68, 0, v78
	v_ldexp_f32 v69, v72, v68
	v_add_f32_e32 v72, -1.0, v69
	v_add_f32_e32 v74, 1.0, v69
	v_ldexp_f32 v68, v73, v68
	v_add_f32_e32 v73, 1.0, v72
	v_add_f32_e32 v75, -1.0, v74
	v_sub_f32_e32 v73, v69, v73
	v_sub_f32_e32 v69, v69, v75
	v_add_f32_e32 v73, v68, v73
	v_add_f32_e32 v68, v68, v69
	v_add_f32_e32 v79, v74, v68
	v_rcp_f32_e32 v81, v79
	v_sub_f32_e32 v69, v79, v74
	v_sub_f32_e32 v80, v68, v69
	v_add_f32_e32 v69, v72, v73
	v_mul_f32_e32 v83, v69, v81
	v_sub_f32_e32 v68, v69, v72
	v_mul_f32_e32 v72, v79, v83
	v_fma_f32 v74, v83, v79, -v72
	v_fmac_f32_e32 v74, v83, v80
	v_sub_f32_e32 v82, v73, v68
	v_add_f32_e32 v68, v72, v74
	v_sub_f32_e32 v73, v69, v68
	v_pk_add_f32 v[76:77], v[68:69], v[72:73] neg_lo:[0,1] neg_hi:[0,1]
	v_mov_b32_e32 v75, v68
	v_pk_add_f32 v[68:69], v[76:77], v[74:75] neg_lo:[0,1] neg_hi:[0,1]
	v_cmp_neq_f32_e32 vcc, s40, v70
	v_add_f32_e32 v69, v82, v69
	v_add_f32_e32 v68, v68, v69
	v_add_f32_e32 v69, v73, v68
	v_mul_f32_e32 v82, v81, v69
	v_mul_f32_e32 v72, v79, v82
	v_fma_f32 v74, v82, v79, -v72
	v_fmac_f32_e32 v74, v82, v80
	v_sub_f32_e32 v73, v73, v69
	v_add_f32_e32 v79, v68, v73
	v_add_f32_e32 v68, v72, v74
	v_sub_f32_e32 v73, v69, v68
	v_pk_add_f32 v[76:77], v[68:69], v[72:73] neg_lo:[0,1] neg_hi:[0,1]
	v_mov_b32_e32 v75, v68
	v_pk_add_f32 v[68:69], v[76:77], v[74:75] neg_lo:[0,1] neg_hi:[0,1]
	v_add_f32_e32 v69, v79, v69
	v_add_f32_e32 v68, v68, v69
	v_add_f32_e32 v69, v83, v82
	v_add_f32_e32 v68, v73, v68
	v_sub_f32_e32 v72, v69, v83
	v_mul_f32_e32 v68, v81, v68
	v_sub_f32_e32 v72, v82, v72
	v_add_f32_e32 v72, v72, v68
	v_add_f32_e32 v74, v69, v72
	v_mul_f32_e32 v75, v74, v74
	v_fmamk_f32 v68, v75, 0x3e9b6dac, v191
	v_fmaak_f32 v169, v75, v68, 0x3f2aaada
	v_cvt_f32_i32_e32 v68, v78
	v_sub_f32_e32 v69, v74, v69
	v_sub_f32_e32 v69, v72, v69
	v_ldexp_f32 v76, v69, 1
	v_mul_f32_e32 v69, v74, v75
	v_ldexp_f32 v73, v74, 1
	v_pk_mul_f32 v[74:75], v[68:69], v[168:169]
	v_fma_f32 v72, v68, s39, -v74
	v_fmac_f32_e32 v72, 0xb102e308, v68
	v_pk_add_f32 v[68:69], v[74:75], v[72:73]
	v_sub_f32_e32 v73, v69, v73
	v_sub_f32_e32 v73, v75, v73
	v_add_f32_e32 v77, v76, v73
	v_mov_b32_e32 v76, v74
	v_pk_add_f32 v[74:75], v[68:69], v[74:75] neg_lo:[0,1] neg_hi:[0,1]
	v_pk_add_f32 v[78:79], v[68:69], v[76:77]
	v_mov_b32_e32 v73, v68
	v_mov_b32_e32 v75, v79
	v_pk_add_f32 v[80:81], v[72:73], v[74:75] neg_lo:[0,1] neg_hi:[0,1]
	v_pk_add_f32 v[72:73], v[72:73], v[74:75]
	v_mov_b32_e32 v76, v77
	v_pk_add_f32 v[74:75], v[72:73], v[68:69] op_sel:[1,0] op_sel_hi:[0,1] neg_lo:[0,1] neg_hi:[0,1]
	v_pk_add_f32 v[82:83], v[78:79], v[74:75] op_sel_hi:[1,0] neg_lo:[0,1] neg_hi:[0,1]
	v_mov_b32_e32 v78, v79
	v_mov_b32_e32 v79, v73
	v_pk_mov_b32 v[74:75], v[68:69], v[74:75] op_sel:[1,0]
	v_mov_b32_e32 v77, v68
	v_pk_add_f32 v[74:75], v[78:79], v[74:75] neg_lo:[0,1] neg_hi:[0,1]
	v_mov_b32_e32 v82, v80
	v_pk_add_f32 v[68:69], v[76:77], v[74:75] neg_lo:[0,1] neg_hi:[0,1]
	v_mov_b32_e32 v81, v73
	v_pk_add_f32 v[74:75], v[82:83], v[68:69]
	v_pk_add_f32 v[76:77], v[74:75], v[74:75] op_sel:[0,1] op_sel_hi:[1,0]
	v_pk_add_f32 v[72:73], v[72:73], v[76:77] op_sel:[1,0] op_sel_hi:[0,1]
	v_mov_b32_e32 v75, v72
	v_pk_add_f32 v[78:79], v[74:75], v[80:81] neg_lo:[0,1] neg_hi:[0,1]
	v_mov_b32_e32 v69, v76
	v_sub_f32_e32 v73, v74, v78
	v_pk_add_f32 v[68:69], v[68:69], v[78:79] neg_lo:[0,1] neg_hi:[0,1]
	v_sub_f32_e32 v73, v80, v73
	v_add_f32_e32 v68, v68, v73
	v_add_f32_e32 v68, v68, v69
	v_add_f32_e32 v68, v72, v68
	v_mov_b32_e32 v74, v224
	v_mov_b32_e32 v73, v225
	v_cndmask_b32_e32 v68, v199, v68, vcc
	v_cmp_ngt_f32_e32 vcc, -1.0, v70
	v_add_f32_e32 v48, v48, v74
	v_mul_f32_e32 v48, 0xbfb8aa3b, v48
	v_exp_f32_e32 v48, v48
	v_cndmask_b32_e32 v68, v200, v68, vcc
	v_cmp_neq_f32_e32 vcc, -1.0, v70
	v_add_f32_e32 v32, v32, v73
	v_add_f32_e32 v48, 1.0, v48
	v_rcp_f32_e32 v48, v48
	v_cndmask_b32_e32 v68, v201, v68, vcc
	v_cmp_lt_f32_e64 vcc, |v70|, s41
	v_mul_f32_e32 v32, 0xbfb8aa3b, v32
	v_exp_f32_e32 v32, v32
	v_cndmask_b32_e32 v68, v68, v70, vcc
	v_mul_f32_e32 v72, 0xc1000000, v68
	v_mul_f32_e32 v48, v48, v72
	v_mul_f32_e32 v64, 0x3fb8aa3b, v48
	v_add_f32_e32 v48, v48, v48
	v_exp_f32_e32 v68, v64
	v_mul_f32_e32 v64, 0x3fb8aa3b, v48
	v_rndne_f32_e32 v64, v64
	v_fmamk_f32 v65, v64, 0xbf317218, v48
	v_fmac_f32_e32 v65, 0x3102e308, v64
	v_fmamk_f32 v69, v65, 0x395133b1, v192
	v_cmp_eq_f32_e32 vcc, s15, v64
	v_cvt_i32_f32_e32 v64, v64
	v_fmaak_f32 v69, v65, v69, 0x3c0887f9
	v_fmaak_f32 v69, v65, v69, 0x3d2aaa81
	v_fmaak_f32 v69, v65, v69, 0x3e2aaaab
	v_fma_f32 v69, v65, v69, 0.5
	v_ldexp_f32 v64, 1.0, v64
	v_mul_f32_e32 v69, v65, v69
	v_cndmask_b32_e32 v64, v64, v202, vcc
	v_fmac_f32_e32 v65, v65, v69
	v_add_f32_e32 v69, -1.0, v64
	v_fmac_f32_e32 v69, v64, v65
	v_add_f32_e32 v64, v69, v69
	v_cndmask_b32_e32 v64, v69, v64, vcc
	v_cmp_nlt_f32_e32 vcc, s16, v48
	v_add_f32_e32 v32, 1.0, v32
	v_rcp_f32_e32 v32, v32
	v_cndmask_b32_e64 v64, v201, -v64, vcc
	v_cmp_gt_f32_e32 vcc, s17, v64
	v_mul_f32_e32 v65, 0x4f800000, v64
	v_add_f32_e32 v33, v33, v73
	v_cndmask_b32_e32 v64, v64, v65, vcc
	v_sqrt_f32_e32 v65, v64
	v_mul_f32_e32 v33, 0xbfb8aa3b, v33
	v_exp_f32_e32 v33, v33
	v_add_f32_e32 v34, v34, v73
	v_add_u32_e32 v69, -1, v65
	v_fma_f32 v70, -v69, v65, v64
	v_cmp_ge_f32_e64 s[0:1], 0, v70
	v_add_u32_e32 v70, 1, v65
	v_add_f32_e32 v33, 1.0, v33
	v_cndmask_b32_e64 v69, v65, v69, s[0:1]
	v_fma_f32 v65, -v70, v65, v64
	v_cmp_lt_f32_e64 s[0:1], 0, v65
	v_rcp_f32_e32 v33, v33
	v_mul_f32_e32 v34, 0xbfb8aa3b, v34
	v_cndmask_b32_e64 v65, v69, v70, s[0:1]
	v_mul_f32_e32 v69, 0x37800000, v65
	v_cndmask_b32_e32 v65, v65, v69, vcc
	v_cmp_class_f32_e32 vcc, v64, v193
	v_exp_f32_e32 v34, v34
	s_nop 0
	v_cndmask_b32_e32 v64, v65, v64, vcc
	v_cmp_ngt_f32_e32 vcc, s18, v48
	v_add_f32_e32 v34, 1.0, v34
	v_rcp_f32_e32 v34, v34
	v_cndmask_b32_e32 v48, 1.0, v64, vcc
	v_mul_f32_e32 v48, v32, v48
	v_and_b32_e32 v32, 0x100, v66
	v_or3_b32 v32, v67, v71, v32
	v_lshl_add_u32 v70, v32, 2, 0
	v_add_u32_e32 v32, 0x9000, v70
	ds_read2_b32 v[64:65], v32 offset1:32
	s_waitcnt lgkmcnt(0)
	v_mul_f32_e32 v48, v64, v48
	ds_write_b32 v70, v68
	ds_write_b32 v70, v48 offset:36864
	v_add_f32_e32 v48, v49, v74
	v_mul_f32_e32 v48, 0xbfb8aa3b, v48
	v_exp_f32_e32 v48, v48
	s_nop 0
	v_add_f32_e32 v48, 1.0, v48
	v_rcp_f32_e32 v48, v48
	s_nop 0
	v_mul_f32_e32 v48, v48, v72
	v_mul_f32_e32 v49, 0x3fb8aa3b, v48
	v_add_f32_e32 v48, v48, v48
	v_exp_f32_e32 v64, v49
	v_mul_f32_e32 v49, 0x3fb8aa3b, v48
	v_rndne_f32_e32 v49, v49
	v_fmamk_f32 v66, v49, 0xbf317218, v48
	v_fmac_f32_e32 v66, 0x3102e308, v49
	v_fmamk_f32 v67, v66, 0x395133b1, v192
	v_cmp_eq_f32_e32 vcc, s15, v49
	v_cvt_i32_f32_e32 v49, v49
	v_fmaak_f32 v67, v66, v67, 0x3c0887f9
	v_fmaak_f32 v67, v66, v67, 0x3d2aaa81
	v_fmaak_f32 v67, v66, v67, 0x3e2aaaab
	v_fma_f32 v67, v66, v67, 0.5
	v_ldexp_f32 v49, 1.0, v49
	v_mul_f32_e32 v67, v66, v67
	v_cndmask_b32_e32 v49, v49, v202, vcc
	v_fmac_f32_e32 v66, v66, v67
	v_add_f32_e32 v67, -1.0, v49
	v_fmac_f32_e32 v67, v49, v66
	v_add_f32_e32 v49, v67, v67
	v_cndmask_b32_e32 v49, v67, v49, vcc
	v_cmp_nlt_f32_e32 vcc, s16, v48
	s_nop 1
	v_cndmask_b32_e64 v49, v201, -v49, vcc
	v_cmp_gt_f32_e32 vcc, s17, v49
	v_mul_f32_e32 v66, 0x4f800000, v49
	s_nop 0
	v_cndmask_b32_e32 v49, v49, v66, vcc
	v_sqrt_f32_e32 v66, v49
	s_nop 0
	v_add_u32_e32 v67, -1, v66
	v_fma_f32 v68, -v67, v66, v49
	v_cmp_ge_f32_e64 s[0:1], 0, v68
	v_add_u32_e32 v68, 1, v66
	s_nop 0
	v_cndmask_b32_e64 v67, v66, v67, s[0:1]
	v_fma_f32 v66, -v68, v66, v49
	v_cmp_lt_f32_e64 s[0:1], 0, v66
	s_nop 1
	v_cndmask_b32_e64 v66, v67, v68, s[0:1]
	v_mul_f32_e32 v67, 0x37800000, v66
	v_cndmask_b32_e32 v66, v66, v67, vcc
	v_cmp_class_f32_e32 vcc, v49, v193
	s_nop 1
	v_cndmask_b32_e32 v49, v66, v49, vcc
	v_cmp_ngt_f32_e32 vcc, s18, v48
	s_nop 1
	v_cndmask_b32_e32 v48, 1.0, v49, vcc
	v_mul_f32_e32 v33, v33, v48
	ds_read2_b32 v[48:49], v32 offset0:64 offset1:96
	s_waitcnt lgkmcnt(0)
	v_mul_f32_e32 v33, v48, v33
	ds_write_b32 v70, v64 offset:256
	ds_write_b32 v70, v33 offset:37120
	v_add_f32_e32 v33, v50, v74
	v_mul_f32_e32 v33, 0xbfb8aa3b, v33
	v_exp_f32_e32 v33, v33
	s_nop 0
	v_add_f32_e32 v33, 1.0, v33
	v_rcp_f32_e32 v33, v33
	s_nop 0
	v_mul_f32_e32 v33, v33, v72
	v_mul_f32_e32 v48, 0x3fb8aa3b, v33
	v_add_f32_e32 v33, v33, v33
	v_mul_f32_e32 v50, 0x3fb8aa3b, v33
	v_rndne_f32_e32 v50, v50
	v_fmamk_f32 v64, v50, 0xbf317218, v33
	v_fmac_f32_e32 v64, 0x3102e308, v50
	v_fmamk_f32 v66, v64, 0x395133b1, v192
	v_cmp_eq_f32_e32 vcc, s15, v50
	v_cvt_i32_f32_e32 v50, v50
	v_fmaak_f32 v66, v64, v66, 0x3c0887f9
	v_fmaak_f32 v66, v64, v66, 0x3d2aaa81
	v_fmaak_f32 v66, v64, v66, 0x3e2aaaab
	v_fma_f32 v66, v64, v66, 0.5
	v_ldexp_f32 v50, 1.0, v50
	v_mul_f32_e32 v66, v64, v66
	v_cndmask_b32_e32 v50, v50, v202, vcc
	v_fmac_f32_e32 v64, v64, v66
	v_add_f32_e32 v66, -1.0, v50
	v_fmac_f32_e32 v66, v50, v64
	v_add_f32_e32 v50, v66, v66
	v_cndmask_b32_e32 v50, v66, v50, vcc
	v_cmp_nlt_f32_e32 vcc, s16, v33
	v_exp_f32_e32 v48, v48
	s_nop 0
	v_cndmask_b32_e64 v50, v201, -v50, vcc
	v_cmp_gt_f32_e32 vcc, s17, v50
	v_mul_f32_e32 v64, 0x4f800000, v50
	s_nop 0
	v_cndmask_b32_e32 v50, v50, v64, vcc
	v_sqrt_f32_e32 v64, v50
	s_nop 0
	v_add_u32_e32 v66, -1, v64
	v_fma_f32 v67, -v66, v64, v50
	v_cmp_ge_f32_e64 s[0:1], 0, v67
	v_add_u32_e32 v67, 1, v64
	s_nop 0
	v_cndmask_b32_e64 v66, v64, v66, s[0:1]
	v_fma_f32 v64, -v67, v64, v50
	v_cmp_lt_f32_e64 s[0:1], 0, v64
	s_nop 1
	v_cndmask_b32_e64 v64, v66, v67, s[0:1]
	v_mul_f32_e32 v66, 0x37800000, v64
	v_cndmask_b32_e32 v64, v64, v66, vcc
	ds_read2_b32 v[66:67], v32 offset0:128 offset1:160
	v_cmp_class_f32_e32 vcc, v50, v193
	s_nop 1
	v_cndmask_b32_e32 v50, v64, v50, vcc
	v_cmp_ngt_f32_e32 vcc, s18, v33
	s_nop 1
	v_cndmask_b32_e32 v33, 1.0, v50, vcc
	v_mul_f32_e32 v33, v34, v33
	s_waitcnt lgkmcnt(0)
	v_mul_f32_e32 v33, v66, v33
	ds_write_b32 v70, v48 offset:512
	ds_write_b32 v70, v33 offset:37376
	v_add_f32_e32 v33, v51, v74
	v_mul_f32_e32 v33, 0xbfb8aa3b, v33
	v_exp_f32_e32 v33, v33
	v_add_f32_e32 v34, v35, v73
	v_mul_f32_e32 v34, 0xbfb8aa3b, v34
	v_exp_f32_e32 v34, v34
	v_add_f32_e32 v33, 1.0, v33
	v_rcp_f32_e32 v33, v33
	v_add_f32_e32 v34, 1.0, v34
	v_rcp_f32_e32 v34, v34
	v_mul_f32_e32 v33, v33, v72
	v_mul_f32_e32 v35, 0x3fb8aa3b, v33
	v_add_f32_e32 v33, v33, v33
	v_mul_f32_e32 v48, 0x3fb8aa3b, v33
	v_rndne_f32_e32 v48, v48
	v_fmamk_f32 v50, v48, 0xbf317218, v33
	v_fmac_f32_e32 v50, 0x3102e308, v48
	v_fmamk_f32 v51, v50, 0x395133b1, v192
	v_cmp_eq_f32_e32 vcc, s15, v48
	v_cvt_i32_f32_e32 v48, v48
	v_fmaak_f32 v51, v50, v51, 0x3c0887f9
	v_fmaak_f32 v51, v50, v51, 0x3d2aaa81
	v_fmaak_f32 v51, v50, v51, 0x3e2aaaab
	v_fma_f32 v51, v50, v51, 0.5
	v_ldexp_f32 v48, 1.0, v48
	v_mul_f32_e32 v51, v50, v51
	v_cndmask_b32_e32 v48, v48, v202, vcc
	v_fmac_f32_e32 v50, v50, v51
	v_add_f32_e32 v51, -1.0, v48
	v_fmac_f32_e32 v51, v48, v50
	v_add_f32_e32 v48, v51, v51
	v_cndmask_b32_e32 v48, v51, v48, vcc
	v_cmp_nlt_f32_e32 vcc, s16, v33
	v_exp_f32_e32 v35, v35
	s_nop 0
	v_cndmask_b32_e64 v48, v201, -v48, vcc
	v_cmp_gt_f32_e32 vcc, s17, v48
	v_mul_f32_e32 v50, 0x4f800000, v48
	s_nop 0
	v_cndmask_b32_e32 v48, v48, v50, vcc
	v_sqrt_f32_e32 v50, v48
	s_nop 0
	v_add_u32_e32 v51, -1, v50
	v_fma_f32 v64, -v51, v50, v48
	v_cmp_ge_f32_e64 s[0:1], 0, v64
	v_add_u32_e32 v64, 1, v50
	s_nop 0
	v_cndmask_b32_e64 v51, v50, v51, s[0:1]
	v_fma_f32 v50, -v64, v50, v48
	v_cmp_lt_f32_e64 s[0:1], 0, v50
	s_nop 1
	v_cndmask_b32_e64 v50, v51, v64, s[0:1]
	v_mul_f32_e32 v51, 0x37800000, v50
	v_cndmask_b32_e32 v50, v50, v51, vcc
	v_cmp_class_f32_e32 vcc, v48, v193
	s_nop 1
	v_cndmask_b32_e32 v48, v50, v48, vcc
	ds_read2_b32 v[50:51], v32 offset0:192 offset1:224
	v_cmp_ngt_f32_e32 vcc, s18, v33
	s_nop 1
	v_cndmask_b32_e32 v33, 1.0, v48, vcc
	v_mul_f32_e32 v33, v34, v33
	s_waitcnt lgkmcnt(0)
	v_mul_f32_e32 v32, v50, v33
	ds_write_b32 v70, v35 offset:768
	ds_write_b32 v70, v32 offset:37632
	v_add_f32_e32 v32, v52, v74
	v_mul_f32_e32 v32, 0xbfb8aa3b, v32
	v_exp_f32_e32 v32, v32
	v_add_f32_e32 v33, v36, v73
	v_mul_f32_e32 v33, 0xbfb8aa3b, v33
	v_exp_f32_e32 v33, v33
	v_add_f32_e32 v32, 1.0, v32
	v_rcp_f32_e32 v32, v32
	v_add_f32_e32 v33, 1.0, v33
	v_rcp_f32_e32 v33, v33
	v_mul_f32_e32 v32, v32, v72
	v_mul_f32_e32 v34, 0x3fb8aa3b, v32
	v_add_f32_e32 v32, v32, v32
	v_mul_f32_e32 v35, 0x3fb8aa3b, v32
	v_rndne_f32_e32 v35, v35
	v_fmamk_f32 v36, v35, 0xbf317218, v32
	v_fmac_f32_e32 v36, 0x3102e308, v35
	v_fmamk_f32 v48, v36, 0x395133b1, v192
	v_cmp_eq_f32_e32 vcc, s15, v35
	v_cvt_i32_f32_e32 v35, v35
	v_fmaak_f32 v48, v36, v48, 0x3c0887f9
	v_fmaak_f32 v48, v36, v48, 0x3d2aaa81
	v_fmaak_f32 v48, v36, v48, 0x3e2aaaab
	v_fma_f32 v48, v36, v48, 0.5
	v_ldexp_f32 v35, 1.0, v35
	v_mul_f32_e32 v48, v36, v48
	v_cndmask_b32_e32 v35, v35, v202, vcc
	v_fmac_f32_e32 v36, v36, v48
	v_add_f32_e32 v48, -1.0, v35
	v_fmac_f32_e32 v48, v35, v36
	v_add_f32_e32 v35, v48, v48
	v_cndmask_b32_e32 v35, v48, v35, vcc
	v_cmp_nlt_f32_e32 vcc, s16, v32
	v_exp_f32_e32 v34, v34
	s_nop 0
	v_cndmask_b32_e64 v35, v201, -v35, vcc
	v_cmp_gt_f32_e32 vcc, s17, v35
	v_mul_f32_e32 v36, 0x4f800000, v35
	s_nop 0
	v_cndmask_b32_e32 v35, v35, v36, vcc
	v_sqrt_f32_e32 v36, v35
	s_nop 0
	v_add_u32_e32 v48, -1, v36
	v_fma_f32 v50, -v48, v36, v35
	v_cmp_ge_f32_e64 s[0:1], 0, v50
	v_add_u32_e32 v50, 1, v36
	s_nop 0
	v_cndmask_b32_e64 v48, v36, v48, s[0:1]
	v_fma_f32 v36, -v50, v36, v35
	v_cmp_lt_f32_e64 s[0:1], 0, v36
	s_nop 1
	v_cndmask_b32_e64 v36, v48, v50, s[0:1]
	v_mul_f32_e32 v48, 0x37800000, v36
	v_cndmask_b32_e32 v36, v36, v48, vcc
	v_cmp_class_f32_e32 vcc, v35, v193
	s_nop 1
	v_cndmask_b32_e32 v35, v36, v35, vcc
	v_cmp_ngt_f32_e32 vcc, s18, v32
	s_nop 1
	v_cndmask_b32_e32 v32, 1.0, v35, vcc
	v_mul_f32_e32 v33, v33, v32
	v_add_u32_e32 v32, 0x9800, v70
	ds_read2_b32 v[68:69], v32 offset1:32
	s_waitcnt lgkmcnt(0)
	v_mul_f32_e32 v33, v68, v33
	ds_write_b32 v70, v34 offset:2048
	ds_write_b32 v70, v33 offset:38912
	v_add_f32_e32 v33, v53, v74
	v_mul_f32_e32 v33, 0xbfb8aa3b, v33
	v_exp_f32_e32 v33, v33
	v_add_f32_e32 v34, v37, v73
	v_mul_f32_e32 v34, 0xbfb8aa3b, v34
	v_exp_f32_e32 v34, v34
	v_add_f32_e32 v33, 1.0, v33
	v_rcp_f32_e32 v33, v33
	v_add_f32_e32 v34, 1.0, v34
	v_rcp_f32_e32 v34, v34
	v_mul_f32_e32 v33, v33, v72
	v_mul_f32_e32 v35, 0x3fb8aa3b, v33
	v_add_f32_e32 v33, v33, v33
	v_mul_f32_e32 v36, 0x3fb8aa3b, v33
	v_rndne_f32_e32 v36, v36
	v_fmamk_f32 v37, v36, 0xbf317218, v33
	v_fmac_f32_e32 v37, 0x3102e308, v36
	v_fmamk_f32 v48, v37, 0x395133b1, v192
	v_cmp_eq_f32_e32 vcc, s15, v36
	v_cvt_i32_f32_e32 v36, v36
	v_fmaak_f32 v48, v37, v48, 0x3c0887f9
	v_fmaak_f32 v48, v37, v48, 0x3d2aaa81
	v_fmaak_f32 v48, v37, v48, 0x3e2aaaab
	v_fma_f32 v48, v37, v48, 0.5
	v_ldexp_f32 v36, 1.0, v36
	v_mul_f32_e32 v48, v37, v48
	v_cndmask_b32_e32 v36, v36, v202, vcc
	v_fmac_f32_e32 v37, v37, v48
	v_add_f32_e32 v48, -1.0, v36
	v_fmac_f32_e32 v48, v36, v37
	v_add_f32_e32 v36, v48, v48
	v_cndmask_b32_e32 v36, v48, v36, vcc
	v_cmp_nlt_f32_e32 vcc, s16, v33
	v_exp_f32_e32 v35, v35
	s_nop 0
	v_cndmask_b32_e64 v36, v201, -v36, vcc
	v_cmp_gt_f32_e32 vcc, s17, v36
	v_mul_f32_e32 v37, 0x4f800000, v36
	s_nop 0
	v_cndmask_b32_e32 v36, v36, v37, vcc
	v_sqrt_f32_e32 v37, v36
	s_nop 0
	v_add_u32_e32 v48, -1, v37
	v_fma_f32 v50, -v48, v37, v36
	v_cmp_ge_f32_e64 s[0:1], 0, v50
	v_add_u32_e32 v50, 1, v37
	s_nop 0
	v_cndmask_b32_e64 v48, v37, v48, s[0:1]
	v_fma_f32 v37, -v50, v37, v36
	v_cmp_lt_f32_e64 s[0:1], 0, v37
	s_nop 1
	v_cndmask_b32_e64 v37, v48, v50, s[0:1]
	v_mul_f32_e32 v48, 0x37800000, v37
	v_cndmask_b32_e32 v37, v37, v48, vcc
	v_cmp_class_f32_e32 vcc, v36, v193
	s_nop 1
	v_cndmask_b32_e32 v36, v37, v36, vcc
	v_cmp_ngt_f32_e32 vcc, s18, v33
	s_nop 1
	v_cndmask_b32_e32 v33, 1.0, v36, vcc
	ds_read2_b32 v[36:37], v32 offset0:64 offset1:96
	v_mul_f32_e32 v33, v34, v33
	v_add_f32_e32 v34, v38, v73
	v_mul_f32_e32 v34, 0xbfb8aa3b, v34
	v_exp_f32_e32 v34, v34
	s_waitcnt lgkmcnt(0)
	v_mul_f32_e32 v33, v36, v33
	ds_write_b32 v70, v35 offset:2304
	ds_write_b32 v70, v33 offset:39168
	v_add_f32_e32 v33, v54, v74
	v_mul_f32_e32 v33, 0xbfb8aa3b, v33
	v_exp_f32_e32 v33, v33
	v_add_f32_e32 v34, 1.0, v34
	v_rcp_f32_e32 v34, v34
	ds_read2_b32 v[52:53], v32 offset0:128 offset1:160
	v_add_f32_e32 v33, 1.0, v33
	v_rcp_f32_e32 v33, v33
	s_nop 0
	v_mul_f32_e32 v33, v33, v72
	v_mul_f32_e32 v35, 0x3fb8aa3b, v33
	v_add_f32_e32 v33, v33, v33
	v_mul_f32_e32 v36, 0x3fb8aa3b, v33
	v_rndne_f32_e32 v36, v36
	v_fmamk_f32 v38, v36, 0xbf317218, v33
	v_fmac_f32_e32 v38, 0x3102e308, v36
	v_fmamk_f32 v48, v38, 0x395133b1, v192
	v_cmp_eq_f32_e32 vcc, s15, v36
	v_cvt_i32_f32_e32 v36, v36
	v_fmaak_f32 v48, v38, v48, 0x3c0887f9
	v_fmaak_f32 v48, v38, v48, 0x3d2aaa81
	v_fmaak_f32 v48, v38, v48, 0x3e2aaaab
	v_fma_f32 v48, v38, v48, 0.5
	v_ldexp_f32 v36, 1.0, v36
	v_mul_f32_e32 v48, v38, v48
	v_cndmask_b32_e32 v36, v36, v202, vcc
	v_fmac_f32_e32 v38, v38, v48
	v_add_f32_e32 v48, -1.0, v36
	v_fmac_f32_e32 v48, v36, v38
	v_add_f32_e32 v36, v48, v48
	v_cndmask_b32_e32 v36, v48, v36, vcc
	v_cmp_nlt_f32_e32 vcc, s16, v33
	v_exp_f32_e32 v35, v35
	s_nop 0
	v_cndmask_b32_e64 v36, v201, -v36, vcc
	v_cmp_gt_f32_e32 vcc, s17, v36
	v_mul_f32_e32 v38, 0x4f800000, v36
	s_nop 0
	v_cndmask_b32_e32 v36, v36, v38, vcc
	v_sqrt_f32_e32 v38, v36
	s_nop 0
	v_add_u32_e32 v48, -1, v38
	v_fma_f32 v50, -v48, v38, v36
	v_cmp_ge_f32_e64 s[0:1], 0, v50
	v_add_u32_e32 v50, 1, v38
	s_nop 0
	v_cndmask_b32_e64 v48, v38, v48, s[0:1]
	v_fma_f32 v38, -v50, v38, v36
	v_cmp_lt_f32_e64 s[0:1], 0, v38
	s_nop 1
	v_cndmask_b32_e64 v38, v48, v50, s[0:1]
	v_mul_f32_e32 v48, 0x37800000, v38
	v_cndmask_b32_e32 v38, v38, v48, vcc
	v_cmp_class_f32_e32 vcc, v36, v193
	s_nop 1
	v_cndmask_b32_e32 v36, v38, v36, vcc
	v_cmp_ngt_f32_e32 vcc, s18, v33
	s_nop 1
	v_cndmask_b32_e32 v33, 1.0, v36, vcc
	v_mul_f32_e32 v33, v34, v33
	s_waitcnt lgkmcnt(0)
	v_mul_f32_e32 v33, v52, v33
	ds_write_b32 v70, v35 offset:2560
	ds_write_b32 v70, v33 offset:39424
	v_add_f32_e32 v33, v55, v74
	v_mul_f32_e32 v33, 0xbfb8aa3b, v33
	v_exp_f32_e32 v33, v33
	v_add_f32_e32 v34, v39, v73
	v_mul_f32_e32 v34, 0xbfb8aa3b, v34
	v_exp_f32_e32 v34, v34
	v_add_f32_e32 v33, 1.0, v33
	v_rcp_f32_e32 v33, v33
	v_add_f32_e32 v34, 1.0, v34
	v_rcp_f32_e32 v34, v34
	v_mul_f32_e32 v33, v33, v72
	v_mul_f32_e32 v35, 0x3fb8aa3b, v33
	v_add_f32_e32 v33, v33, v33
	v_mul_f32_e32 v36, 0x3fb8aa3b, v33
	v_rndne_f32_e32 v36, v36
	v_fmamk_f32 v38, v36, 0xbf317218, v33
	v_fmac_f32_e32 v38, 0x3102e308, v36
	v_fmamk_f32 v39, v38, 0x395133b1, v192
	v_cmp_eq_f32_e32 vcc, s15, v36
	v_cvt_i32_f32_e32 v36, v36
	v_fmaak_f32 v39, v38, v39, 0x3c0887f9
	v_fmaak_f32 v39, v38, v39, 0x3d2aaa81
	v_fmaak_f32 v39, v38, v39, 0x3e2aaaab
	v_fma_f32 v39, v38, v39, 0.5
	v_ldexp_f32 v36, 1.0, v36
	v_mul_f32_e32 v39, v38, v39
	v_cndmask_b32_e32 v36, v36, v202, vcc
	v_fmac_f32_e32 v38, v38, v39
	v_add_f32_e32 v39, -1.0, v36
	v_fmac_f32_e32 v39, v36, v38
	v_add_f32_e32 v36, v39, v39
	v_cndmask_b32_e32 v36, v39, v36, vcc
	v_cmp_nlt_f32_e32 vcc, s16, v33
	v_exp_f32_e32 v35, v35
	s_nop 0
	v_cndmask_b32_e64 v36, v201, -v36, vcc
	v_cmp_gt_f32_e32 vcc, s17, v36
	v_mul_f32_e32 v38, 0x4f800000, v36
	s_nop 0
	v_cndmask_b32_e32 v36, v36, v38, vcc
	v_sqrt_f32_e32 v38, v36
	s_nop 0
	v_add_u32_e32 v39, -1, v38
	v_fma_f32 v48, -v39, v38, v36
	v_cmp_ge_f32_e64 s[0:1], 0, v48
	v_add_u32_e32 v48, 1, v38
	s_nop 0
	v_cndmask_b32_e64 v39, v38, v39, s[0:1]
	v_fma_f32 v38, -v48, v38, v36
	v_cmp_lt_f32_e64 s[0:1], 0, v38
	s_nop 1
	v_cndmask_b32_e64 v38, v39, v48, s[0:1]
	v_mul_f32_e32 v39, 0x37800000, v38
	v_cndmask_b32_e32 v38, v38, v39, vcc
	v_cmp_class_f32_e32 vcc, v36, v193
	s_nop 1
	v_cndmask_b32_e32 v36, v38, v36, vcc
	ds_read2_b32 v[38:39], v32 offset0:192 offset1:224
	v_cmp_ngt_f32_e32 vcc, s18, v33
	s_nop 1
	v_cndmask_b32_e32 v33, 1.0, v36, vcc
	v_mul_f32_e32 v33, v34, v33
	s_waitcnt lgkmcnt(0)
	v_mul_f32_e32 v32, v38, v33
	ds_write_b32 v70, v35 offset:2816
	ds_write_b32 v70, v32 offset:39680
	v_add_f32_e32 v32, v56, v74
	v_mul_f32_e32 v32, 0xbfb8aa3b, v32
	v_exp_f32_e32 v32, v32
	v_add_f32_e32 v33, v40, v73
	v_mul_f32_e32 v33, 0xbfb8aa3b, v33
	v_exp_f32_e32 v33, v33
	v_add_f32_e32 v32, 1.0, v32
	v_rcp_f32_e32 v32, v32
	v_add_f32_e32 v33, 1.0, v33
	v_rcp_f32_e32 v33, v33
	v_mul_f32_e32 v32, v32, v72
	v_mul_f32_e32 v34, 0x3fb8aa3b, v32
	v_add_f32_e32 v32, v32, v32
	v_mul_f32_e32 v35, 0x3fb8aa3b, v32
	v_rndne_f32_e32 v35, v35
	v_fmamk_f32 v36, v35, 0xbf317218, v32
	v_fmac_f32_e32 v36, 0x3102e308, v35
	v_fmamk_f32 v38, v36, 0x395133b1, v192
	v_cmp_eq_f32_e32 vcc, s15, v35
	v_cvt_i32_f32_e32 v35, v35
	v_fmaak_f32 v38, v36, v38, 0x3c0887f9
	v_fmaak_f32 v38, v36, v38, 0x3d2aaa81
	v_fmaak_f32 v38, v36, v38, 0x3e2aaaab
	v_fma_f32 v38, v36, v38, 0.5
	v_ldexp_f32 v35, 1.0, v35
	v_mul_f32_e32 v38, v36, v38
	v_cndmask_b32_e32 v35, v35, v202, vcc
	v_fmac_f32_e32 v36, v36, v38
	v_add_f32_e32 v38, -1.0, v35
	v_fmac_f32_e32 v38, v35, v36
	v_add_f32_e32 v35, v38, v38
	v_cndmask_b32_e32 v35, v38, v35, vcc
	v_cmp_nlt_f32_e32 vcc, s16, v32
	v_exp_f32_e32 v34, v34
	s_nop 0
	v_cndmask_b32_e64 v35, v201, -v35, vcc
	v_cmp_gt_f32_e32 vcc, s17, v35
	v_mul_f32_e32 v36, 0x4f800000, v35
	s_nop 0
	v_cndmask_b32_e32 v35, v35, v36, vcc
	v_sqrt_f32_e32 v36, v35
	s_nop 0
	v_add_u32_e32 v38, -1, v36
	v_fma_f32 v40, -v38, v36, v35
	v_cmp_ge_f32_e64 s[0:1], 0, v40
	v_add_u32_e32 v40, 1, v36
	s_nop 0
	v_cndmask_b32_e64 v38, v36, v38, s[0:1]
	v_fma_f32 v36, -v40, v36, v35
	v_cmp_lt_f32_e64 s[0:1], 0, v36
	s_nop 1
	v_cndmask_b32_e64 v36, v38, v40, s[0:1]
	v_mul_f32_e32 v38, 0x37800000, v36
	v_cndmask_b32_e32 v36, v36, v38, vcc
	v_cmp_class_f32_e32 vcc, v35, v193
	s_nop 1
	v_cndmask_b32_e32 v35, v36, v35, vcc
	v_cmp_ngt_f32_e32 vcc, s18, v32
	s_nop 1
	v_cndmask_b32_e32 v32, 1.0, v35, vcc
	v_mul_f32_e32 v33, v33, v32
	v_add_u32_e32 v32, 0xa000, v70
	ds_read2_b32 v[54:55], v32 offset1:32
	s_waitcnt lgkmcnt(0)
	v_mul_f32_e32 v33, v54, v33
	ds_write_b32 v70, v34 offset:4096
	ds_write_b32 v70, v33 offset:40960
	v_add_f32_e32 v33, v57, v74
	v_mul_f32_e32 v33, 0xbfb8aa3b, v33
	v_exp_f32_e32 v33, v33
	v_add_f32_e32 v34, v41, v73
	v_mul_f32_e32 v34, 0xbfb8aa3b, v34
	v_exp_f32_e32 v34, v34
	v_add_f32_e32 v33, 1.0, v33
	v_rcp_f32_e32 v33, v33
	v_add_f32_e32 v34, 1.0, v34
	v_rcp_f32_e32 v34, v34
	v_mul_f32_e32 v33, v33, v72
	v_mul_f32_e32 v35, 0x3fb8aa3b, v33
	v_add_f32_e32 v33, v33, v33
	v_mul_f32_e32 v36, 0x3fb8aa3b, v33
	v_rndne_f32_e32 v36, v36
	v_fmamk_f32 v38, v36, 0xbf317218, v33
	v_fmac_f32_e32 v38, 0x3102e308, v36
	v_fmamk_f32 v40, v38, 0x395133b1, v192
	v_cmp_eq_f32_e32 vcc, s15, v36
	v_cvt_i32_f32_e32 v36, v36
	v_fmaak_f32 v40, v38, v40, 0x3c0887f9
	v_fmaak_f32 v40, v38, v40, 0x3d2aaa81
	v_fmaak_f32 v40, v38, v40, 0x3e2aaaab
	v_fma_f32 v40, v38, v40, 0.5
	v_ldexp_f32 v36, 1.0, v36
	v_mul_f32_e32 v40, v38, v40
	v_cndmask_b32_e32 v36, v36, v202, vcc
	v_fmac_f32_e32 v38, v38, v40
	v_add_f32_e32 v40, -1.0, v36
	v_fmac_f32_e32 v40, v36, v38
	v_add_f32_e32 v36, v40, v40
	v_cndmask_b32_e32 v36, v40, v36, vcc
	v_cmp_nlt_f32_e32 vcc, s16, v33
	v_exp_f32_e32 v35, v35
	s_nop 0
	v_cndmask_b32_e64 v36, v201, -v36, vcc
	v_cmp_gt_f32_e32 vcc, s17, v36
	v_mul_f32_e32 v38, 0x4f800000, v36
	s_nop 0
	v_cndmask_b32_e32 v36, v36, v38, vcc
	v_sqrt_f32_e32 v38, v36
	s_nop 0
	v_add_u32_e32 v40, -1, v38
	v_fma_f32 v41, -v40, v38, v36
	v_cmp_ge_f32_e64 s[0:1], 0, v41
	v_add_u32_e32 v41, 1, v38
	s_nop 0
	v_cndmask_b32_e64 v40, v38, v40, s[0:1]
	v_fma_f32 v38, -v41, v38, v36
	v_cmp_lt_f32_e64 s[0:1], 0, v38
	s_nop 1
	v_cndmask_b32_e64 v38, v40, v41, s[0:1]
	v_mul_f32_e32 v40, 0x37800000, v38
	v_cndmask_b32_e32 v38, v38, v40, vcc
	ds_read2_b32 v[40:41], v32 offset0:64 offset1:96
	v_cmp_class_f32_e32 vcc, v36, v193
	s_nop 1
	v_cndmask_b32_e32 v36, v38, v36, vcc
	v_cmp_ngt_f32_e32 vcc, s18, v33
	s_nop 1
	v_cndmask_b32_e32 v33, 1.0, v36, vcc
	v_mul_f32_e32 v33, v34, v33
	s_waitcnt lgkmcnt(0)
	v_mul_f32_e32 v33, v40, v33
	ds_write_b32 v70, v35 offset:4352
	ds_write_b32 v70, v33 offset:41216
	v_add_f32_e32 v33, v58, v74
	v_mul_f32_e32 v33, 0xbfb8aa3b, v33
	v_exp_f32_e32 v33, v33
	v_add_f32_e32 v34, v42, v73
	v_mul_f32_e32 v34, 0xbfb8aa3b, v34
	v_exp_f32_e32 v34, v34
	v_add_f32_e32 v33, 1.0, v33
	v_rcp_f32_e32 v33, v33
	ds_read2_b32 v[56:57], v32 offset0:128 offset1:160
	v_add_f32_e32 v34, 1.0, v34
	v_rcp_f32_e32 v34, v34
	v_mul_f32_e32 v33, v33, v72
	v_mul_f32_e32 v35, 0x3fb8aa3b, v33
	v_add_f32_e32 v33, v33, v33
	v_mul_f32_e32 v36, 0x3fb8aa3b, v33
	v_rndne_f32_e32 v36, v36
	v_fmamk_f32 v38, v36, 0xbf317218, v33
	v_fmac_f32_e32 v38, 0x3102e308, v36
	v_fmamk_f32 v40, v38, 0x395133b1, v192
	v_cmp_eq_f32_e32 vcc, s15, v36
	v_cvt_i32_f32_e32 v36, v36
	v_fmaak_f32 v40, v38, v40, 0x3c0887f9
	v_fmaak_f32 v40, v38, v40, 0x3d2aaa81
	v_fmaak_f32 v40, v38, v40, 0x3e2aaaab
	v_fma_f32 v40, v38, v40, 0.5
	v_ldexp_f32 v36, 1.0, v36
	v_mul_f32_e32 v40, v38, v40
	v_cndmask_b32_e32 v36, v36, v202, vcc
	v_fmac_f32_e32 v38, v38, v40
	v_add_f32_e32 v40, -1.0, v36
	v_fmac_f32_e32 v40, v36, v38
	v_add_f32_e32 v36, v40, v40
	v_cndmask_b32_e32 v36, v40, v36, vcc
	v_cmp_nlt_f32_e32 vcc, s16, v33
	v_exp_f32_e32 v35, v35
	s_nop 0
	v_cndmask_b32_e64 v36, v201, -v36, vcc
	v_cmp_gt_f32_e32 vcc, s17, v36
	v_mul_f32_e32 v38, 0x4f800000, v36
	s_nop 0
	v_cndmask_b32_e32 v36, v36, v38, vcc
	v_sqrt_f32_e32 v38, v36
	s_nop 0
	v_add_u32_e32 v40, -1, v38
	v_fma_f32 v42, -v40, v38, v36
	v_cmp_ge_f32_e64 s[0:1], 0, v42
	v_add_u32_e32 v42, 1, v38
	s_nop 0
	v_cndmask_b32_e64 v40, v38, v40, s[0:1]
	v_fma_f32 v38, -v42, v38, v36
	v_cmp_lt_f32_e64 s[0:1], 0, v38
	s_nop 1
	v_cndmask_b32_e64 v38, v40, v42, s[0:1]
	v_mul_f32_e32 v40, 0x37800000, v38
	v_cndmask_b32_e32 v38, v38, v40, vcc
	v_cmp_class_f32_e32 vcc, v36, v193
	s_nop 1
	v_cndmask_b32_e32 v36, v38, v36, vcc
	v_cmp_ngt_f32_e32 vcc, s18, v33
	s_nop 1
	v_cndmask_b32_e32 v33, 1.0, v36, vcc
	v_mul_f32_e32 v33, v34, v33
	s_waitcnt lgkmcnt(0)
	v_mul_f32_e32 v33, v56, v33
	ds_write_b32 v70, v35 offset:4608
	ds_write_b32 v70, v33 offset:41472
	v_add_f32_e32 v33, v59, v74
	v_mul_f32_e32 v33, 0xbfb8aa3b, v33
	v_exp_f32_e32 v33, v33
	v_add_f32_e32 v34, v43, v73
	v_mul_f32_e32 v34, 0xbfb8aa3b, v34
	v_exp_f32_e32 v34, v34
	v_add_f32_e32 v33, 1.0, v33
	v_rcp_f32_e32 v33, v33
	v_add_f32_e32 v34, 1.0, v34
	v_rcp_f32_e32 v34, v34
	v_mul_f32_e32 v33, v33, v72
	v_mul_f32_e32 v35, 0x3fb8aa3b, v33
	v_add_f32_e32 v33, v33, v33
	v_mul_f32_e32 v36, 0x3fb8aa3b, v33
	v_rndne_f32_e32 v36, v36
	v_fmamk_f32 v38, v36, 0xbf317218, v33
	v_fmac_f32_e32 v38, 0x3102e308, v36
	v_fmamk_f32 v40, v38, 0x395133b1, v192
	v_cmp_eq_f32_e32 vcc, s15, v36
	v_cvt_i32_f32_e32 v36, v36
	v_fmaak_f32 v40, v38, v40, 0x3c0887f9
	v_fmaak_f32 v40, v38, v40, 0x3d2aaa81
	v_fmaak_f32 v40, v38, v40, 0x3e2aaaab
	v_fma_f32 v40, v38, v40, 0.5
	v_ldexp_f32 v36, 1.0, v36
	v_mul_f32_e32 v40, v38, v40
	v_cndmask_b32_e32 v36, v36, v202, vcc
	v_fmac_f32_e32 v38, v38, v40
	v_add_f32_e32 v40, -1.0, v36
	v_fmac_f32_e32 v40, v36, v38
	v_add_f32_e32 v36, v40, v40
	v_cndmask_b32_e32 v36, v40, v36, vcc
	v_cmp_nlt_f32_e32 vcc, s16, v33
	v_exp_f32_e32 v35, v35
	s_nop 0
	v_cndmask_b32_e64 v36, v201, -v36, vcc
	v_cmp_gt_f32_e32 vcc, s17, v36
	v_mul_f32_e32 v38, 0x4f800000, v36
	s_nop 0
	v_cndmask_b32_e32 v36, v36, v38, vcc
	v_sqrt_f32_e32 v38, v36
	s_nop 0
	v_add_u32_e32 v40, -1, v38
	v_fma_f32 v42, -v40, v38, v36
	v_cmp_ge_f32_e64 s[0:1], 0, v42
	v_add_u32_e32 v42, 1, v38
	s_nop 0
	v_cndmask_b32_e64 v40, v38, v40, s[0:1]
	v_fma_f32 v38, -v42, v38, v36
	v_cmp_lt_f32_e64 s[0:1], 0, v38
	s_nop 1
	v_cndmask_b32_e64 v38, v40, v42, s[0:1]
	v_mul_f32_e32 v40, 0x37800000, v38
	ds_read2_b32 v[42:43], v32 offset0:192 offset1:224
	v_cndmask_b32_e32 v38, v38, v40, vcc
	v_cmp_class_f32_e32 vcc, v36, v193
	s_nop 1
	v_cndmask_b32_e32 v36, v38, v36, vcc
	v_cmp_ngt_f32_e32 vcc, s18, v33
	s_nop 1
	v_cndmask_b32_e32 v33, 1.0, v36, vcc
	v_mul_f32_e32 v33, v34, v33
	s_waitcnt lgkmcnt(0)
	v_mul_f32_e32 v32, v42, v33
	ds_write_b32 v70, v35 offset:4864
	ds_write_b32 v70, v32 offset:41728
	v_add_f32_e32 v32, v60, v74
	v_mul_f32_e32 v32, 0xbfb8aa3b, v32
	v_exp_f32_e32 v32, v32
	v_add_f32_e32 v33, v44, v73
	v_mul_f32_e32 v33, 0xbfb8aa3b, v33
	v_exp_f32_e32 v33, v33
	v_add_f32_e32 v32, 1.0, v32
	v_rcp_f32_e32 v32, v32
	v_add_f32_e32 v33, 1.0, v33
	v_rcp_f32_e32 v33, v33
	v_mul_f32_e32 v32, v32, v72
	v_mul_f32_e32 v34, 0x3fb8aa3b, v32
	v_add_f32_e32 v32, v32, v32
	v_mul_f32_e32 v35, 0x3fb8aa3b, v32
	v_rndne_f32_e32 v35, v35
	v_fmamk_f32 v36, v35, 0xbf317218, v32
	v_fmac_f32_e32 v36, 0x3102e308, v35
	v_fmamk_f32 v38, v36, 0x395133b1, v192
	v_cmp_eq_f32_e32 vcc, s15, v35
	v_cvt_i32_f32_e32 v35, v35
	v_fmaak_f32 v38, v36, v38, 0x3c0887f9
	v_fmaak_f32 v38, v36, v38, 0x3d2aaa81
	v_fmaak_f32 v38, v36, v38, 0x3e2aaaab
	v_fma_f32 v38, v36, v38, 0.5
	v_ldexp_f32 v35, 1.0, v35
	v_mul_f32_e32 v38, v36, v38
	v_cndmask_b32_e32 v35, v35, v202, vcc
	v_fmac_f32_e32 v36, v36, v38
	v_add_f32_e32 v38, -1.0, v35
	v_fmac_f32_e32 v38, v35, v36
	v_add_f32_e32 v35, v38, v38
	v_cndmask_b32_e32 v35, v38, v35, vcc
	v_cmp_nlt_f32_e32 vcc, s16, v32
	v_exp_f32_e32 v34, v34
	s_nop 0
	v_cndmask_b32_e64 v35, v201, -v35, vcc
	v_cmp_gt_f32_e32 vcc, s17, v35
	v_mul_f32_e32 v36, 0x4f800000, v35
	s_nop 0
	v_cndmask_b32_e32 v35, v35, v36, vcc
	v_sqrt_f32_e32 v36, v35
	s_nop 0
	v_add_u32_e32 v38, -1, v36
	v_fma_f32 v40, -v38, v36, v35
	v_cmp_ge_f32_e64 s[0:1], 0, v40
	v_add_u32_e32 v40, 1, v36
	s_nop 0
	v_cndmask_b32_e64 v38, v36, v38, s[0:1]
	v_fma_f32 v36, -v40, v36, v35
	v_cmp_lt_f32_e64 s[0:1], 0, v36
	s_nop 1
	v_cndmask_b32_e64 v36, v38, v40, s[0:1]
	v_mul_f32_e32 v38, 0x37800000, v36
	v_cndmask_b32_e32 v36, v36, v38, vcc
	v_cmp_class_f32_e32 vcc, v35, v193
	s_nop 1
	v_cndmask_b32_e32 v35, v36, v35, vcc
	v_cmp_ngt_f32_e32 vcc, s18, v32
	s_nop 1
	v_cndmask_b32_e32 v32, 1.0, v35, vcc
	v_mul_f32_e32 v32, v33, v32
	v_add_u32_e32 v33, 0xa800, v70
	ds_read2_b32 v[58:59], v33 offset1:32
	s_waitcnt lgkmcnt(0)
	v_mul_f32_e32 v32, v58, v32
	ds_write_b32 v70, v34 offset:6144
	ds_write_b32 v70, v32 offset:43008
	v_add_f32_e32 v32, v61, v74
	v_mul_f32_e32 v32, 0xbfb8aa3b, v32
	v_exp_f32_e32 v32, v32
	v_add_f32_e32 v34, v45, v73
	v_mul_f32_e32 v34, 0xbfb8aa3b, v34
	v_exp_f32_e32 v34, v34
	v_add_f32_e32 v32, 1.0, v32
	v_rcp_f32_e32 v32, v32
	ds_read2_b32 v[44:45], v33 offset0:64 offset1:96
	v_add_f32_e32 v34, 1.0, v34
	v_rcp_f32_e32 v34, v34
	v_mul_f32_e32 v32, v32, v72
	v_mul_f32_e32 v35, 0x3fb8aa3b, v32
	v_add_f32_e32 v32, v32, v32
	v_mul_f32_e32 v36, 0x3fb8aa3b, v32
	v_rndne_f32_e32 v36, v36
	v_fmamk_f32 v38, v36, 0xbf317218, v32
	v_fmac_f32_e32 v38, 0x3102e308, v36
	v_fmamk_f32 v40, v38, 0x395133b1, v192
	v_cmp_eq_f32_e32 vcc, s15, v36
	v_cvt_i32_f32_e32 v36, v36
	v_fmaak_f32 v40, v38, v40, 0x3c0887f9
	v_fmaak_f32 v40, v38, v40, 0x3d2aaa81
	v_fmaak_f32 v40, v38, v40, 0x3e2aaaab
	v_fma_f32 v40, v38, v40, 0.5
	v_ldexp_f32 v36, 1.0, v36
	v_mul_f32_e32 v40, v38, v40
	v_cndmask_b32_e32 v36, v36, v202, vcc
	v_fmac_f32_e32 v38, v38, v40
	v_add_f32_e32 v40, -1.0, v36
	v_fmac_f32_e32 v40, v36, v38
	v_add_f32_e32 v36, v40, v40
	v_cndmask_b32_e32 v36, v40, v36, vcc
	v_cmp_nlt_f32_e32 vcc, s16, v32
	v_exp_f32_e32 v35, v35
	s_nop 0
	v_cndmask_b32_e64 v36, v201, -v36, vcc
	v_cmp_gt_f32_e32 vcc, s17, v36
	v_mul_f32_e32 v38, 0x4f800000, v36
	s_nop 0
	v_cndmask_b32_e32 v36, v36, v38, vcc
	v_sqrt_f32_e32 v38, v36
	s_nop 0
	v_add_u32_e32 v40, -1, v38
	v_fma_f32 v42, -v40, v38, v36
	v_cmp_ge_f32_e64 s[0:1], 0, v42
	v_add_u32_e32 v42, 1, v38
	s_nop 0
	v_cndmask_b32_e64 v40, v38, v40, s[0:1]
	v_fma_f32 v38, -v42, v38, v36
	v_cmp_lt_f32_e64 s[0:1], 0, v38
	s_nop 1
	v_cndmask_b32_e64 v38, v40, v42, s[0:1]
	v_mul_f32_e32 v40, 0x37800000, v38
	v_cndmask_b32_e32 v38, v38, v40, vcc
	v_cmp_class_f32_e32 vcc, v36, v193
	s_nop 1
	v_cndmask_b32_e32 v36, v38, v36, vcc
	v_cmp_ngt_f32_e32 vcc, s18, v32
	s_nop 1
	v_cndmask_b32_e32 v32, 1.0, v36, vcc
	v_mul_f32_e32 v32, v34, v32
	s_waitcnt lgkmcnt(0)
	v_mul_f32_e32 v32, v44, v32
	ds_write_b32 v70, v35 offset:6400
	ds_write_b32 v70, v32 offset:43264
	v_add_f32_e32 v32, v62, v74
	v_mul_f32_e32 v32, 0xbfb8aa3b, v32
	v_exp_f32_e32 v32, v32
	v_add_f32_e32 v34, v46, v73
	v_mul_f32_e32 v34, 0xbfb8aa3b, v34
	v_exp_f32_e32 v34, v34
	v_add_f32_e32 v32, 1.0, v32
	v_rcp_f32_e32 v32, v32
	v_add_f32_e32 v34, 1.0, v34
	v_rcp_f32_e32 v34, v34
	v_mul_f32_e32 v32, v32, v72
	v_mul_f32_e32 v35, 0x3fb8aa3b, v32
	v_add_f32_e32 v32, v32, v32
	v_exp_f32_e32 v36, v35
	v_mul_f32_e32 v35, 0x3fb8aa3b, v32
	v_rndne_f32_e32 v35, v35
	v_fmamk_f32 v38, v35, 0xbf317218, v32
	v_fmac_f32_e32 v38, 0x3102e308, v35
	v_fmamk_f32 v40, v38, 0x395133b1, v192
	v_cmp_eq_f32_e32 vcc, s15, v35
	v_cvt_i32_f32_e32 v35, v35
	v_fmaak_f32 v40, v38, v40, 0x3c0887f9
	v_fmaak_f32 v40, v38, v40, 0x3d2aaa81
	v_fmaak_f32 v40, v38, v40, 0x3e2aaaab
	v_fma_f32 v40, v38, v40, 0.5
	v_ldexp_f32 v35, 1.0, v35
	v_mul_f32_e32 v40, v38, v40
	v_cndmask_b32_e32 v35, v35, v202, vcc
	v_fmac_f32_e32 v38, v38, v40
	v_add_f32_e32 v40, -1.0, v35
	v_fmac_f32_e32 v40, v35, v38
	v_add_f32_e32 v35, v40, v40
	v_cndmask_b32_e32 v35, v40, v35, vcc
	v_cmp_nlt_f32_e32 vcc, s16, v32
	s_nop 1
	v_cndmask_b32_e64 v35, v201, -v35, vcc
	v_cmp_gt_f32_e32 vcc, s17, v35
	v_mul_f32_e32 v38, 0x4f800000, v35
	s_nop 0
	v_cndmask_b32_e32 v35, v35, v38, vcc
	v_sqrt_f32_e32 v38, v35
	s_nop 0
	v_add_u32_e32 v40, -1, v38
	v_fma_f32 v42, -v40, v38, v35
	v_cmp_ge_f32_e64 s[0:1], 0, v42
	v_add_u32_e32 v42, 1, v38
	s_nop 0
	v_cndmask_b32_e64 v40, v38, v40, s[0:1]
	v_fma_f32 v38, -v42, v38, v35
	v_cmp_lt_f32_e64 s[0:1], 0, v38
	s_nop 1
	v_cndmask_b32_e64 v38, v40, v42, s[0:1]
	v_mul_f32_e32 v40, 0x37800000, v38
	v_cndmask_b32_e32 v38, v38, v40, vcc
	v_cmp_class_f32_e32 vcc, v35, v193
	s_nop 1
	v_cndmask_b32_e32 v35, v38, v35, vcc
	v_cmp_ngt_f32_e32 vcc, s18, v32
	s_nop 1
	v_cndmask_b32_e32 v32, 1.0, v35, vcc
	v_mul_f32_e32 v32, v34, v32
	ds_read2_b32 v[34:35], v33 offset0:128 offset1:160
	s_waitcnt lgkmcnt(0)
	v_mul_f32_e32 v32, v34, v32
	ds_write_b32 v70, v36 offset:6656
	ds_write_b32 v70, v32 offset:43520
	v_add_f32_e32 v32, v63, v74
	v_mul_f32_e32 v32, 0xbfb8aa3b, v32
	v_exp_f32_e32 v32, v32
	v_add_f32_e32 v34, v47, v73
	v_mul_f32_e32 v34, 0xbfb8aa3b, v34
	v_exp_f32_e32 v34, v34
	v_add_f32_e32 v32, 1.0, v32
	v_rcp_f32_e32 v32, v32
	v_lshlrev_b64 v[46:47], 2, v[96:97]
	v_add_f32_e32 v34, 1.0, v34
	v_rcp_f32_e32 v36, v34
	v_mul_f32_e32 v32, v32, v72
	v_mul_f32_e32 v34, 0x3fb8aa3b, v32
	v_add_f32_e32 v32, v32, v32
	v_mul_f32_e32 v38, 0x3fb8aa3b, v32
	v_rndne_f32_e32 v38, v38
	v_fmamk_f32 v40, v38, 0xbf317218, v32
	v_fmac_f32_e32 v40, 0x3102e308, v38
	v_fmamk_f32 v42, v40, 0x395133b1, v192
	v_cmp_eq_f32_e32 vcc, s15, v38
	v_cvt_i32_f32_e32 v38, v38
	v_fmaak_f32 v42, v40, v42, 0x3c0887f9
	v_fmaak_f32 v42, v40, v42, 0x3d2aaa81
	v_fmaak_f32 v42, v40, v42, 0x3e2aaaab
	v_fma_f32 v42, v40, v42, 0.5
	v_ldexp_f32 v38, 1.0, v38
	v_mul_f32_e32 v42, v40, v42
	v_cndmask_b32_e32 v38, v38, v202, vcc
	v_fmac_f32_e32 v40, v40, v42
	v_add_f32_e32 v42, -1.0, v38
	v_fmac_f32_e32 v42, v38, v40
	v_add_f32_e32 v38, v42, v42
	v_cndmask_b32_e32 v38, v42, v38, vcc
	v_cmp_nlt_f32_e32 vcc, s16, v32
	s_nop 0
	v_exp_f32_e32 v34, v34
	v_cndmask_b32_e64 v38, v201, -v38, vcc
	v_cmp_gt_f32_e32 vcc, s17, v38
	v_mul_f32_e32 v40, 0x4f800000, v38
	s_nop 0
	v_cndmask_b32_e32 v38, v38, v40, vcc
	v_sqrt_f32_e32 v40, v38
	s_nop 0
	v_add_u32_e32 v42, -1, v40
	v_fma_f32 v44, -v42, v40, v38
	v_cmp_ge_f32_e64 s[0:1], 0, v44
	v_add_u32_e32 v44, 1, v40
	s_nop 0
	v_cndmask_b32_e64 v42, v40, v42, s[0:1]
	v_fma_f32 v40, -v44, v40, v38
	v_cmp_lt_f32_e64 s[0:1], 0, v40
	s_nop 1
	v_cndmask_b32_e64 v40, v42, v44, s[0:1]
	v_mul_f32_e32 v42, 0x37800000, v40
	v_cndmask_b32_e32 v40, v40, v42, vcc
	v_cmp_class_f32_e32 vcc, v38, v193
	s_nop 1
	v_cndmask_b32_e32 v38, v40, v38, vcc
	v_cmp_ngt_f32_e32 vcc, s18, v32
	s_nop 1
	v_cndmask_b32_e32 v32, 1.0, v38, vcc
	v_mul_f32_e32 v36, v36, v32
	ds_read2_b32 v[32:33], v33 offset0:192 offset1:224
	s_waitcnt lgkmcnt(0)
	v_mul_f32_e32 v32, v32, v36
	ds_write_b32 v70, v32 offset:43776
	v_mul_f32_e32 v32, 0xbfb8aa3b, v226
	v_exp_f32_e32 v32, v32
	s_nop 0
	v_add_f32_e32 v36, 1.0, v32
	v_add_f32_e32 v38, -1.0, v36
	v_sub_f32_e32 v40, v38, v36
	v_add_f32_e32 v40, 1.0, v40
	v_sub_f32_e32 v38, v32, v38
	v_add_f32_e32 v38, v38, v40
	v_frexp_mant_f32_e32 v40, v36
	v_cvt_f64_f32_e32 v[60:61], v36
	v_cmp_gt_f32_e32 vcc, s7, v40
	v_frexp_exp_i32_f64_e32 v40, v[60:61]
	s_nop 0
	v_subbrev_co_u32_e32 v40, vcc, 0, v40, vcc
	v_sub_u32_e32 v42, 0, v40
	v_ldexp_f32 v36, v36, v42
	v_ldexp_f32 v38, v38, v42
	v_add_f32_e32 v42, -1.0, v36
	v_add_f32_e32 v48, 1.0, v36
	v_add_f32_e32 v44, 1.0, v42
	v_add_f32_e32 v50, -1.0, v48
	v_sub_f32_e32 v44, v36, v44
	v_sub_f32_e32 v36, v36, v50
	v_add_f32_e32 v36, v38, v36
	v_add_f32_e32 v44, v38, v44
	v_add_f32_e32 v38, v48, v36
	v_sub_f32_e32 v48, v38, v48
	v_sub_f32_e32 v36, v36, v48
	v_rcp_f32_e32 v48, v38
	v_add_f32_e32 v61, v42, v44
	v_sub_f32_e32 v42, v61, v42
	v_sub_f32_e32 v42, v44, v42
	v_mul_f32_e32 v44, v61, v48
	v_mul_f32_e32 v62, v38, v44
	v_fma_f32 v72, v44, v38, -v62
	v_fmac_f32_e32 v72, v44, v36
	v_add_f32_e32 v60, v62, v72
	v_sub_f32_e32 v63, v61, v60
	v_pk_add_f32 v[74:75], v[60:61], v[62:63] neg_lo:[0,1] neg_hi:[0,1]
	v_mov_b32_e32 v73, v60
	v_pk_add_f32 v[60:61], v[74:75], v[72:73] neg_lo:[0,1] neg_hi:[0,1]
	v_cmp_neq_f32_e32 vcc, s40, v32
	v_add_f32_e32 v42, v42, v61
	v_add_f32_e32 v42, v60, v42
	v_add_f32_e32 v61, v63, v42
	v_mul_f32_e32 v50, v48, v61
	v_mul_f32_e32 v62, v38, v50
	v_fma_f32 v72, v50, v38, -v62
	v_fmac_f32_e32 v72, v50, v36
	v_add_f32_e32 v60, v62, v72
	v_sub_f32_e32 v36, v63, v61
	v_sub_f32_e32 v63, v61, v60
	v_pk_add_f32 v[74:75], v[60:61], v[62:63] neg_lo:[0,1] neg_hi:[0,1]
	v_mov_b32_e32 v73, v60
	v_add_f32_e32 v36, v42, v36
	v_pk_add_f32 v[60:61], v[74:75], v[72:73] neg_lo:[0,1] neg_hi:[0,1]
	v_add_f32_e32 v38, v44, v50
	v_add_f32_e32 v36, v36, v61
	v_add_f32_e32 v36, v60, v36
	v_add_f32_e32 v36, v63, v36
	v_sub_f32_e32 v42, v38, v44
	v_mul_f32_e32 v36, v48, v36
	v_sub_f32_e32 v42, v50, v42
	v_add_f32_e32 v36, v42, v36
	v_add_f32_e32 v42, v38, v36
	v_cvt_f32_i32_e32 v60, v40
	v_mul_f32_e32 v44, v42, v42
	v_fmamk_f32 v48, v44, 0x3e9b6dac, v191
	v_fmaak_f32 v169, v44, v48, 0x3f2aaada
	v_mul_f32_e32 v61, v42, v44
	v_pk_mul_f32 v[72:73], v[60:61], v[168:169]
	v_ldexp_f32 v63, v42, 1
	v_fma_f32 v62, v60, s39, -v72
	v_fmac_f32_e32 v62, 0xb102e308, v60
	v_sub_f32_e32 v38, v42, v38
	v_pk_add_f32 v[60:61], v[72:73], v[62:63]
	v_sub_f32_e32 v36, v36, v38
	v_sub_f32_e32 v38, v61, v63
	v_ldexp_f32 v36, v36, 1
	v_sub_f32_e32 v38, v73, v38
	v_add_f32_e32 v75, v36, v38
	v_mov_b32_e32 v74, v72
	v_pk_add_f32 v[72:73], v[60:61], v[72:73] neg_lo:[0,1] neg_hi:[0,1]
	v_pk_add_f32 v[76:77], v[60:61], v[74:75]
	v_mov_b32_e32 v63, v60
	v_mov_b32_e32 v73, v77
	v_pk_add_f32 v[78:79], v[62:63], v[72:73] neg_lo:[0,1] neg_hi:[0,1]
	v_pk_add_f32 v[62:63], v[62:63], v[72:73]
	v_mov_b32_e32 v74, v75
	v_pk_add_f32 v[72:73], v[62:63], v[60:61] op_sel:[1,0] op_sel_hi:[0,1] neg_lo:[0,1] neg_hi:[0,1]
	v_pk_add_f32 v[80:81], v[76:77], v[72:73] op_sel_hi:[1,0] neg_lo:[0,1] neg_hi:[0,1]
	v_mov_b32_e32 v76, v77
	v_mov_b32_e32 v77, v63
	v_pk_mov_b32 v[72:73], v[60:61], v[72:73] op_sel:[1,0]
	v_mov_b32_e32 v75, v60
	v_pk_add_f32 v[72:73], v[76:77], v[72:73] neg_lo:[0,1] neg_hi:[0,1]
	v_mov_b32_e32 v80, v78
	v_pk_add_f32 v[60:61], v[74:75], v[72:73] neg_lo:[0,1] neg_hi:[0,1]
	v_mov_b32_e32 v79, v63
	v_pk_add_f32 v[72:73], v[80:81], v[60:61]
	v_pk_add_f32 v[74:75], v[72:73], v[72:73] op_sel:[0,1] op_sel_hi:[1,0]
	v_pk_add_f32 v[62:63], v[62:63], v[74:75] op_sel:[1,0] op_sel_hi:[0,1]
	v_mov_b32_e32 v73, v62
	v_pk_add_f32 v[76:77], v[72:73], v[78:79] neg_lo:[0,1] neg_hi:[0,1]
	v_mov_b32_e32 v61, v74
	v_sub_f32_e32 v36, v72, v76
	v_pk_add_f32 v[60:61], v[60:61], v[76:77] neg_lo:[0,1] neg_hi:[0,1]
	v_sub_f32_e32 v36, v78, v36
	v_add_f32_e32 v36, v60, v36
	v_add_f32_e32 v36, v36, v61
	v_add_f32_e32 v36, v62, v36
	v_cndmask_b32_e32 v36, v199, v36, vcc
	v_cmp_ngt_f32_e32 vcc, -1.0, v32
	v_lshl_add_u64 v[60:61], s[24:25], 0, v[46:47]
	s_nop 0
	v_cndmask_b32_e32 v36, v200, v36, vcc
	v_cmp_neq_f32_e32 vcc, -1.0, v32
	v_mov_b32_e32 v38, v227
	v_add_f32_e32 v0, v0, v38
	v_cndmask_b32_e32 v36, v201, v36, vcc
	v_cmp_lt_f32_e64 vcc, |v32|, s41
	v_mul_f32_e32 v0, 0xbfb8aa3b, v0
	v_exp_f32_e32 v0, v0
	v_cndmask_b32_e32 v32, v36, v32, vcc
	v_mov_b32_e32 v36, v228
	v_mul_f32_e32 v32, 0xc1000000, v32
	v_add_f32_e32 v0, 1.0, v0
	v_rcp_f32_e32 v0, v0
	v_add_f32_e32 v1, v1, v38
	v_mul_f32_e32 v1, 0xbfb8aa3b, v1
	v_exp_f32_e32 v1, v1
	v_add_f32_e32 v16, v16, v36
	v_mul_f32_e32 v16, 0xbfb8aa3b, v16
	v_exp_f32_e32 v16, v16
	v_add_f32_e32 v1, 1.0, v1
	v_rcp_f32_e32 v1, v1
	v_add_f32_e32 v16, 1.0, v16
	v_rcp_f32_e32 v16, v16
	s_nop 0
	v_mul_f32_e32 v16, v16, v32
	v_mul_f32_e32 v40, 0x3fb8aa3b, v16
	v_add_f32_e32 v16, v16, v16
	v_mul_f32_e32 v42, 0x3fb8aa3b, v16
	v_rndne_f32_e32 v42, v42
	v_fmamk_f32 v44, v42, 0xbf317218, v16
	v_fmac_f32_e32 v44, 0x3102e308, v42
	v_fmamk_f32 v46, v44, 0x395133b1, v192
	v_cmp_eq_f32_e32 vcc, s15, v42
	v_cvt_i32_f32_e32 v42, v42
	v_fmaak_f32 v46, v44, v46, 0x3c0887f9
	v_fmaak_f32 v46, v44, v46, 0x3d2aaa81
	v_fmaak_f32 v46, v44, v46, 0x3e2aaaab
	v_fma_f32 v46, v44, v46, 0.5
	v_ldexp_f32 v42, 1.0, v42
	v_mul_f32_e32 v46, v44, v46
	v_cndmask_b32_e32 v42, v42, v202, vcc
	v_fmac_f32_e32 v44, v44, v46
	v_add_f32_e32 v46, -1.0, v42
	v_fmac_f32_e32 v46, v42, v44
	v_add_f32_e32 v42, v46, v46
	v_cndmask_b32_e32 v42, v46, v42, vcc
	v_cmp_nlt_f32_e32 vcc, s16, v16
	v_exp_f32_e32 v40, v40
	s_nop 0
	v_cndmask_b32_e64 v42, v201, -v42, vcc
	v_cmp_gt_f32_e32 vcc, s17, v42
	v_mul_f32_e32 v44, 0x4f800000, v42
	s_nop 0
	v_cndmask_b32_e32 v42, v42, v44, vcc
	v_sqrt_f32_e32 v44, v42
	s_nop 0
	v_add_u32_e32 v46, -1, v44
	v_fma_f32 v47, -v46, v44, v42
	v_cmp_ge_f32_e64 s[0:1], 0, v47
	v_add_u32_e32 v47, 1, v44
	s_nop 0
	v_cndmask_b32_e64 v46, v44, v46, s[0:1]
	v_fma_f32 v44, -v47, v44, v42
	v_cmp_lt_f32_e64 s[0:1], 0, v44
	s_nop 1
	v_cndmask_b32_e64 v44, v46, v47, s[0:1]
	v_mul_f32_e32 v46, 0x37800000, v44
	v_cndmask_b32_e32 v44, v44, v46, vcc
	v_cmp_class_f32_e32 vcc, v42, v193
	s_nop 1
	v_cndmask_b32_e32 v42, v44, v42, vcc
	v_cmp_ngt_f32_e32 vcc, s18, v16
	s_nop 1
	v_cndmask_b32_e32 v16, 1.0, v42, vcc
	v_mul_f32_e32 v0, v0, v16
	v_mul_f32_e32 v0, v65, v0
	ds_write_b32 v70, v40 offset:128
	ds_write_b32 v70, v0 offset:36992
	v_add_f32_e32 v0, v17, v36
	v_mul_f32_e32 v0, 0xbfb8aa3b, v0
	v_exp_f32_e32 v0, v0
	s_nop 0
	v_add_f32_e32 v0, 1.0, v0
	v_rcp_f32_e32 v0, v0
	s_nop 0
	v_mul_f32_e32 v0, v0, v32
	v_mul_f32_e32 v16, 0x3fb8aa3b, v0
	v_add_f32_e32 v0, v0, v0
	v_mul_f32_e32 v17, 0x3fb8aa3b, v0
	v_rndne_f32_e32 v17, v17
	v_fmamk_f32 v40, v17, 0xbf317218, v0
	v_fmac_f32_e32 v40, 0x3102e308, v17
	v_fmamk_f32 v42, v40, 0x395133b1, v192
	v_cmp_eq_f32_e32 vcc, s15, v17
	v_cvt_i32_f32_e32 v17, v17
	v_fmaak_f32 v42, v40, v42, 0x3c0887f9
	v_fmaak_f32 v42, v40, v42, 0x3d2aaa81
	v_fmaak_f32 v42, v40, v42, 0x3e2aaaab
	v_fma_f32 v42, v40, v42, 0.5
	v_ldexp_f32 v17, 1.0, v17
	v_mul_f32_e32 v42, v40, v42
	v_cndmask_b32_e32 v17, v17, v202, vcc
	v_fmac_f32_e32 v40, v40, v42
	v_add_f32_e32 v42, -1.0, v17
	v_fmac_f32_e32 v42, v17, v40
	v_add_f32_e32 v17, v42, v42
	v_cndmask_b32_e32 v17, v42, v17, vcc
	v_cmp_nlt_f32_e32 vcc, s16, v0
	v_exp_f32_e32 v16, v16
	s_nop 0
	v_cndmask_b32_e64 v17, v201, -v17, vcc
	v_cmp_gt_f32_e32 vcc, s17, v17
	v_mul_f32_e32 v40, 0x4f800000, v17
	s_nop 0
	v_cndmask_b32_e32 v17, v17, v40, vcc
	v_sqrt_f32_e32 v40, v17
	s_nop 0
	v_add_u32_e32 v42, -1, v40
	v_fma_f32 v44, -v42, v40, v17
	v_cmp_ge_f32_e64 s[0:1], 0, v44
	v_add_u32_e32 v44, 1, v40
	s_nop 0
	v_cndmask_b32_e64 v42, v40, v42, s[0:1]
	v_fma_f32 v40, -v44, v40, v17
	v_cmp_lt_f32_e64 s[0:1], 0, v40
	s_nop 1
	v_cndmask_b32_e64 v40, v42, v44, s[0:1]
	v_mul_f32_e32 v42, 0x37800000, v40
	v_cndmask_b32_e32 v40, v40, v42, vcc
	v_cmp_class_f32_e32 vcc, v17, v193
	s_nop 1
	v_cndmask_b32_e32 v17, v40, v17, vcc
	v_cmp_ngt_f32_e32 vcc, s18, v0
	s_nop 1
	v_cndmask_b32_e32 v0, 1.0, v17, vcc
	v_mul_f32_e32 v0, v1, v0
	v_mul_f32_e32 v0, v49, v0
	ds_write_b32 v70, v16 offset:384
	ds_write_b32 v70, v0 offset:37248
	v_add_f32_e32 v0, v18, v36
	v_mul_f32_e32 v0, 0xbfb8aa3b, v0
	v_exp_f32_e32 v0, v0
	v_add_f32_e32 v1, v2, v38
	v_mul_f32_e32 v1, 0xbfb8aa3b, v1
	v_exp_f32_e32 v1, v1
	v_add_f32_e32 v0, 1.0, v0
	v_rcp_f32_e32 v0, v0
	v_add_f32_e32 v1, 1.0, v1
	v_rcp_f32_e32 v1, v1
	v_mul_f32_e32 v0, v0, v32
	v_mul_f32_e32 v2, 0x3fb8aa3b, v0
	v_add_f32_e32 v0, v0, v0
	v_mul_f32_e32 v16, 0x3fb8aa3b, v0
	v_rndne_f32_e32 v16, v16
	v_fmamk_f32 v17, v16, 0xbf317218, v0
	v_fmac_f32_e32 v17, 0x3102e308, v16
	v_fmamk_f32 v18, v17, 0x395133b1, v192
	v_cmp_eq_f32_e32 vcc, s15, v16
	v_cvt_i32_f32_e32 v16, v16
	v_fmaak_f32 v18, v17, v18, 0x3c0887f9
	v_fmaak_f32 v18, v17, v18, 0x3d2aaa81
	v_fmaak_f32 v18, v17, v18, 0x3e2aaaab
	v_fma_f32 v18, v17, v18, 0.5
	v_ldexp_f32 v16, 1.0, v16
	v_mul_f32_e32 v18, v17, v18
	v_cndmask_b32_e32 v16, v16, v202, vcc
	v_fmac_f32_e32 v17, v17, v18
	v_add_f32_e32 v18, -1.0, v16
	v_fmac_f32_e32 v18, v16, v17
	v_add_f32_e32 v16, v18, v18
	v_cndmask_b32_e32 v16, v18, v16, vcc
	v_cmp_nlt_f32_e32 vcc, s16, v0
	v_exp_f32_e32 v2, v2
	s_nop 0
	v_cndmask_b32_e64 v16, v201, -v16, vcc
	v_cmp_gt_f32_e32 vcc, s17, v16
	v_mul_f32_e32 v17, 0x4f800000, v16
	s_nop 0
	v_cndmask_b32_e32 v16, v16, v17, vcc
	v_sqrt_f32_e32 v17, v16
	s_nop 0
	v_add_u32_e32 v18, -1, v17
	v_fma_f32 v40, -v18, v17, v16
	v_cmp_ge_f32_e64 s[0:1], 0, v40
	v_add_u32_e32 v40, 1, v17
	s_nop 0
	v_cndmask_b32_e64 v18, v17, v18, s[0:1]
	v_fma_f32 v17, -v40, v17, v16
	v_cmp_lt_f32_e64 s[0:1], 0, v17
	s_nop 1
	v_cndmask_b32_e64 v17, v18, v40, s[0:1]
	v_mul_f32_e32 v18, 0x37800000, v17
	v_cndmask_b32_e32 v17, v17, v18, vcc
	v_cmp_class_f32_e32 vcc, v16, v193
	s_nop 1
	v_cndmask_b32_e32 v16, v17, v16, vcc
	v_cmp_ngt_f32_e32 vcc, s18, v0
	s_nop 1
	v_cndmask_b32_e32 v0, 1.0, v16, vcc
	v_mul_f32_e32 v0, v1, v0
	v_mul_f32_e32 v0, v67, v0
	ds_write_b32 v70, v2 offset:640
	ds_write_b32 v70, v0 offset:37504
	v_add_f32_e32 v0, v19, v36
	v_mul_f32_e32 v0, 0xbfb8aa3b, v0
	v_exp_f32_e32 v0, v0
	v_add_f32_e32 v1, v3, v38
	v_mul_f32_e32 v1, 0xbfb8aa3b, v1
	v_exp_f32_e32 v1, v1
	v_add_f32_e32 v0, 1.0, v0
	v_rcp_f32_e32 v0, v0
	v_add_f32_e32 v1, 1.0, v1
	v_rcp_f32_e32 v1, v1
	v_mul_f32_e32 v0, v0, v32
	v_mul_f32_e32 v2, 0x3fb8aa3b, v0
	v_add_f32_e32 v0, v0, v0
	v_mul_f32_e32 v3, 0x3fb8aa3b, v0
	v_rndne_f32_e32 v3, v3
	v_fmamk_f32 v16, v3, 0xbf317218, v0
	v_fmac_f32_e32 v16, 0x3102e308, v3
	v_fmamk_f32 v17, v16, 0x395133b1, v192
	v_cmp_eq_f32_e32 vcc, s15, v3
	v_cvt_i32_f32_e32 v3, v3
	v_fmaak_f32 v17, v16, v17, 0x3c0887f9
	v_fmaak_f32 v17, v16, v17, 0x3d2aaa81
	v_fmaak_f32 v17, v16, v17, 0x3e2aaaab
	v_fma_f32 v17, v16, v17, 0.5
	v_ldexp_f32 v3, 1.0, v3
	v_mul_f32_e32 v17, v16, v17
	v_cndmask_b32_e32 v3, v3, v202, vcc
	v_fmac_f32_e32 v16, v16, v17
	v_add_f32_e32 v17, -1.0, v3
	v_fmac_f32_e32 v17, v3, v16
	v_add_f32_e32 v3, v17, v17
	v_cndmask_b32_e32 v3, v17, v3, vcc
	v_cmp_nlt_f32_e32 vcc, s16, v0
	v_exp_f32_e32 v2, v2
	s_nop 0
	v_cndmask_b32_e64 v3, v201, -v3, vcc
	v_cmp_gt_f32_e32 vcc, s17, v3
	v_mul_f32_e32 v16, 0x4f800000, v3
	s_nop 0
	v_cndmask_b32_e32 v3, v3, v16, vcc
	v_sqrt_f32_e32 v16, v3
	s_nop 0
	v_add_u32_e32 v17, -1, v16
	v_fma_f32 v18, -v17, v16, v3
	v_cmp_ge_f32_e64 s[0:1], 0, v18
	v_add_u32_e32 v18, 1, v16
	s_nop 0
	v_cndmask_b32_e64 v17, v16, v17, s[0:1]
	v_fma_f32 v16, -v18, v16, v3
	v_cmp_lt_f32_e64 s[0:1], 0, v16
	s_nop 1
	v_cndmask_b32_e64 v16, v17, v18, s[0:1]
	v_mul_f32_e32 v17, 0x37800000, v16
	v_cndmask_b32_e32 v16, v16, v17, vcc
	v_cmp_class_f32_e32 vcc, v3, v193
	s_nop 1
	v_cndmask_b32_e32 v3, v16, v3, vcc
	v_cmp_ngt_f32_e32 vcc, s18, v0
	s_nop 1
	v_cndmask_b32_e32 v0, 1.0, v3, vcc
	v_mul_f32_e32 v0, v1, v0
	v_mul_f32_e32 v0, v51, v0
	ds_write_b32 v70, v2 offset:896
	ds_write_b32 v70, v0 offset:37760
	v_add_f32_e32 v0, v20, v36
	v_mul_f32_e32 v0, 0xbfb8aa3b, v0
	v_exp_f32_e32 v0, v0
	v_add_f32_e32 v1, v4, v38
	v_mul_f32_e32 v1, 0xbfb8aa3b, v1
	v_exp_f32_e32 v1, v1
	v_add_f32_e32 v0, 1.0, v0
	v_rcp_f32_e32 v0, v0
	v_add_f32_e32 v1, 1.0, v1
	v_rcp_f32_e32 v1, v1
	v_mul_f32_e32 v0, v0, v32
	v_mul_f32_e32 v2, 0x3fb8aa3b, v0
	v_add_f32_e32 v0, v0, v0
	v_mul_f32_e32 v3, 0x3fb8aa3b, v0
	v_rndne_f32_e32 v3, v3
	v_fmamk_f32 v4, v3, 0xbf317218, v0
	v_fmac_f32_e32 v4, 0x3102e308, v3
	v_fmamk_f32 v16, v4, 0x395133b1, v192
	v_cmp_eq_f32_e32 vcc, s15, v3
	v_cvt_i32_f32_e32 v3, v3
	v_fmaak_f32 v16, v4, v16, 0x3c0887f9
	v_fmaak_f32 v16, v4, v16, 0x3d2aaa81
	v_fmaak_f32 v16, v4, v16, 0x3e2aaaab
	v_fma_f32 v16, v4, v16, 0.5
	v_ldexp_f32 v3, 1.0, v3
	v_mul_f32_e32 v16, v4, v16
	v_cndmask_b32_e32 v3, v3, v202, vcc
	v_fmac_f32_e32 v4, v4, v16
	v_add_f32_e32 v16, -1.0, v3
	v_fmac_f32_e32 v16, v3, v4
	v_add_f32_e32 v3, v16, v16
	v_cndmask_b32_e32 v3, v16, v3, vcc
	v_cmp_nlt_f32_e32 vcc, s16, v0
	v_exp_f32_e32 v2, v2
	s_nop 0
	v_cndmask_b32_e64 v3, v201, -v3, vcc
	v_cmp_gt_f32_e32 vcc, s17, v3
	v_mul_f32_e32 v4, 0x4f800000, v3
	s_nop 0
	v_cndmask_b32_e32 v3, v3, v4, vcc
	v_sqrt_f32_e32 v4, v3
	s_nop 0
	v_add_u32_e32 v16, -1, v4
	v_fma_f32 v17, -v16, v4, v3
	v_cmp_ge_f32_e64 s[0:1], 0, v17
	v_add_u32_e32 v17, 1, v4
	s_nop 0
	v_cndmask_b32_e64 v16, v4, v16, s[0:1]
	v_fma_f32 v4, -v17, v4, v3
	v_cmp_lt_f32_e64 s[0:1], 0, v4
	s_nop 1
	v_cndmask_b32_e64 v4, v16, v17, s[0:1]
	v_mul_f32_e32 v16, 0x37800000, v4
	v_cndmask_b32_e32 v4, v4, v16, vcc
	v_cmp_class_f32_e32 vcc, v3, v193
	s_nop 1
	v_cndmask_b32_e32 v3, v4, v3, vcc
	v_cmp_ngt_f32_e32 vcc, s18, v0
	s_nop 1
	v_cndmask_b32_e32 v0, 1.0, v3, vcc
	v_mul_f32_e32 v0, v1, v0
	v_mul_f32_e32 v0, v69, v0
	ds_write_b32 v70, v2 offset:2176
	ds_write_b32 v70, v0 offset:39040
	v_add_f32_e32 v0, v21, v36
	v_mul_f32_e32 v0, 0xbfb8aa3b, v0
	v_exp_f32_e32 v0, v0
	v_add_f32_e32 v1, v5, v38
	v_mul_f32_e32 v1, 0xbfb8aa3b, v1
	v_exp_f32_e32 v1, v1
	v_add_f32_e32 v0, 1.0, v0
	v_rcp_f32_e32 v0, v0
	v_add_f32_e32 v1, 1.0, v1
	v_rcp_f32_e32 v1, v1
	v_mul_f32_e32 v0, v0, v32
	v_mul_f32_e32 v2, 0x3fb8aa3b, v0
	v_add_f32_e32 v0, v0, v0
	v_mul_f32_e32 v3, 0x3fb8aa3b, v0
	v_rndne_f32_e32 v3, v3
	v_fmamk_f32 v4, v3, 0xbf317218, v0
	v_fmac_f32_e32 v4, 0x3102e308, v3
	v_fmamk_f32 v5, v4, 0x395133b1, v192
	v_cmp_eq_f32_e32 vcc, s15, v3
	v_cvt_i32_f32_e32 v3, v3
	v_fmaak_f32 v5, v4, v5, 0x3c0887f9
	v_fmaak_f32 v5, v4, v5, 0x3d2aaa81
	v_fmaak_f32 v5, v4, v5, 0x3e2aaaab
	v_fma_f32 v5, v4, v5, 0.5
	v_ldexp_f32 v3, 1.0, v3
	v_mul_f32_e32 v5, v4, v5
	v_cndmask_b32_e32 v3, v3, v202, vcc
	v_fmac_f32_e32 v4, v4, v5
	v_add_f32_e32 v5, -1.0, v3
	v_fmac_f32_e32 v5, v3, v4
	v_add_f32_e32 v3, v5, v5
	v_cndmask_b32_e32 v3, v5, v3, vcc
	v_cmp_nlt_f32_e32 vcc, s16, v0
	v_exp_f32_e32 v2, v2
	s_nop 0
	v_cndmask_b32_e64 v3, v201, -v3, vcc
	v_cmp_gt_f32_e32 vcc, s17, v3
	v_mul_f32_e32 v4, 0x4f800000, v3
	s_nop 0
	v_cndmask_b32_e32 v3, v3, v4, vcc
	v_sqrt_f32_e32 v4, v3
	s_nop 0
	v_add_u32_e32 v5, -1, v4
	v_fma_f32 v16, -v5, v4, v3
	v_cmp_ge_f32_e64 s[0:1], 0, v16
	v_add_u32_e32 v16, 1, v4
	s_nop 0
	v_cndmask_b32_e64 v5, v4, v5, s[0:1]
	v_fma_f32 v4, -v16, v4, v3
	v_cmp_lt_f32_e64 s[0:1], 0, v4
	s_nop 1
	v_cndmask_b32_e64 v4, v5, v16, s[0:1]
	v_mul_f32_e32 v5, 0x37800000, v4
	v_cndmask_b32_e32 v4, v4, v5, vcc
	v_cmp_class_f32_e32 vcc, v3, v193
	s_nop 1
	v_cndmask_b32_e32 v3, v4, v3, vcc
	v_cmp_ngt_f32_e32 vcc, s18, v0
	s_nop 1
	v_cndmask_b32_e32 v0, 1.0, v3, vcc
	v_mul_f32_e32 v0, v1, v0
	v_mul_f32_e32 v0, v37, v0
	ds_write_b32 v70, v2 offset:2432
	ds_write_b32 v70, v0 offset:39296
	v_add_f32_e32 v0, v22, v36
	v_mul_f32_e32 v0, 0xbfb8aa3b, v0
	v_exp_f32_e32 v0, v0
	v_add_f32_e32 v1, v6, v38
	v_mul_f32_e32 v1, 0xbfb8aa3b, v1
	v_exp_f32_e32 v1, v1
	v_add_f32_e32 v0, 1.0, v0
	v_rcp_f32_e32 v0, v0
	v_add_f32_e32 v1, 1.0, v1
	v_rcp_f32_e32 v1, v1
	v_mul_f32_e32 v0, v0, v32
	v_mul_f32_e32 v2, 0x3fb8aa3b, v0
	v_add_f32_e32 v0, v0, v0
	v_mul_f32_e32 v3, 0x3fb8aa3b, v0
	v_rndne_f32_e32 v3, v3
	v_fmamk_f32 v4, v3, 0xbf317218, v0
	v_fmac_f32_e32 v4, 0x3102e308, v3
	v_fmamk_f32 v5, v4, 0x395133b1, v192
	v_cmp_eq_f32_e32 vcc, s15, v3
	v_cvt_i32_f32_e32 v3, v3
	v_fmaak_f32 v5, v4, v5, 0x3c0887f9
	v_fmaak_f32 v5, v4, v5, 0x3d2aaa81
	v_fmaak_f32 v5, v4, v5, 0x3e2aaaab
	v_fma_f32 v5, v4, v5, 0.5
	v_ldexp_f32 v3, 1.0, v3
	v_mul_f32_e32 v5, v4, v5
	v_cndmask_b32_e32 v3, v3, v202, vcc
	v_fmac_f32_e32 v4, v4, v5
	v_add_f32_e32 v5, -1.0, v3
	v_fmac_f32_e32 v5, v3, v4
	v_add_f32_e32 v3, v5, v5
	v_cndmask_b32_e32 v3, v5, v3, vcc
	v_cmp_nlt_f32_e32 vcc, s16, v0
	v_exp_f32_e32 v2, v2
	s_nop 0
	v_cndmask_b32_e64 v3, v201, -v3, vcc
	v_cmp_gt_f32_e32 vcc, s17, v3
	v_mul_f32_e32 v4, 0x4f800000, v3
	s_nop 0
	v_cndmask_b32_e32 v3, v3, v4, vcc
	v_sqrt_f32_e32 v4, v3
	s_nop 0
	v_add_u32_e32 v5, -1, v4
	v_fma_f32 v6, -v5, v4, v3
	v_cmp_ge_f32_e64 s[0:1], 0, v6
	v_add_u32_e32 v6, 1, v4
	s_nop 0
	v_cndmask_b32_e64 v5, v4, v5, s[0:1]
	v_fma_f32 v4, -v6, v4, v3
	v_cmp_lt_f32_e64 s[0:1], 0, v4
	s_nop 1
	v_cndmask_b32_e64 v4, v5, v6, s[0:1]
	v_mul_f32_e32 v5, 0x37800000, v4
	v_cndmask_b32_e32 v4, v4, v5, vcc
	v_cmp_class_f32_e32 vcc, v3, v193
	s_nop 1
	v_cndmask_b32_e32 v3, v4, v3, vcc
	v_cmp_ngt_f32_e32 vcc, s18, v0
	s_nop 1
	v_cndmask_b32_e32 v0, 1.0, v3, vcc
	v_mul_f32_e32 v0, v1, v0
	v_mul_f32_e32 v0, v53, v0
	ds_write_b32 v70, v2 offset:2688
	ds_write_b32 v70, v0 offset:39552
	v_add_f32_e32 v0, v23, v36
	v_mul_f32_e32 v0, 0xbfb8aa3b, v0
	v_exp_f32_e32 v0, v0
	v_add_f32_e32 v1, v7, v38
	v_mul_f32_e32 v1, 0xbfb8aa3b, v1
	v_exp_f32_e32 v1, v1
	v_add_f32_e32 v0, 1.0, v0
	v_rcp_f32_e32 v0, v0
	v_add_f32_e32 v1, 1.0, v1
	v_rcp_f32_e32 v1, v1
	v_mul_f32_e32 v0, v0, v32
	v_mul_f32_e32 v2, 0x3fb8aa3b, v0
	v_add_f32_e32 v0, v0, v0
	v_mul_f32_e32 v3, 0x3fb8aa3b, v0
	v_rndne_f32_e32 v3, v3
	v_fmamk_f32 v4, v3, 0xbf317218, v0
	v_fmac_f32_e32 v4, 0x3102e308, v3
	v_fmamk_f32 v5, v4, 0x395133b1, v192
	v_cmp_eq_f32_e32 vcc, s15, v3
	v_cvt_i32_f32_e32 v3, v3
	v_fmaak_f32 v5, v4, v5, 0x3c0887f9
	v_fmaak_f32 v5, v4, v5, 0x3d2aaa81
	v_fmaak_f32 v5, v4, v5, 0x3e2aaaab
	v_fma_f32 v5, v4, v5, 0.5
	v_ldexp_f32 v3, 1.0, v3
	v_mul_f32_e32 v5, v4, v5
	v_cndmask_b32_e32 v3, v3, v202, vcc
	v_fmac_f32_e32 v4, v4, v5
	v_add_f32_e32 v5, -1.0, v3
	v_fmac_f32_e32 v5, v3, v4
	v_add_f32_e32 v3, v5, v5
	v_cndmask_b32_e32 v3, v5, v3, vcc
	v_cmp_nlt_f32_e32 vcc, s16, v0
	v_exp_f32_e32 v2, v2
	s_nop 0
	v_cndmask_b32_e64 v3, v201, -v3, vcc
	v_cmp_gt_f32_e32 vcc, s17, v3
	v_mul_f32_e32 v4, 0x4f800000, v3
	s_nop 0
	v_cndmask_b32_e32 v3, v3, v4, vcc
	v_sqrt_f32_e32 v4, v3
	s_nop 0
	v_add_u32_e32 v5, -1, v4
	v_fma_f32 v6, -v5, v4, v3
	v_cmp_ge_f32_e64 s[0:1], 0, v6
	v_add_u32_e32 v6, 1, v4
	s_nop 0
	v_cndmask_b32_e64 v5, v4, v5, s[0:1]
	v_fma_f32 v4, -v6, v4, v3
	v_cmp_lt_f32_e64 s[0:1], 0, v4
	s_nop 1
	v_cndmask_b32_e64 v4, v5, v6, s[0:1]
	v_mul_f32_e32 v5, 0x37800000, v4
	v_cndmask_b32_e32 v4, v4, v5, vcc
	v_cmp_class_f32_e32 vcc, v3, v193
	s_nop 1
	v_cndmask_b32_e32 v3, v4, v3, vcc
	v_cmp_ngt_f32_e32 vcc, s18, v0
	s_nop 1
	v_cndmask_b32_e32 v0, 1.0, v3, vcc
	v_mul_f32_e32 v0, v1, v0
	v_mul_f32_e32 v0, v39, v0
	ds_write_b32 v70, v2 offset:2944
	ds_write_b32 v70, v0 offset:39808
	v_add_f32_e32 v0, v24, v36
	v_mul_f32_e32 v0, 0xbfb8aa3b, v0
	v_exp_f32_e32 v0, v0
	v_add_f32_e32 v1, v8, v38
	v_mul_f32_e32 v1, 0xbfb8aa3b, v1
	v_exp_f32_e32 v1, v1
	v_add_f32_e32 v0, 1.0, v0
	v_rcp_f32_e32 v0, v0
	v_add_f32_e32 v1, 1.0, v1
	v_rcp_f32_e32 v1, v1
	v_mul_f32_e32 v0, v0, v32
	v_mul_f32_e32 v2, 0x3fb8aa3b, v0
	v_add_f32_e32 v0, v0, v0
	v_mul_f32_e32 v3, 0x3fb8aa3b, v0
	v_rndne_f32_e32 v3, v3
	v_fmamk_f32 v4, v3, 0xbf317218, v0
	v_fmac_f32_e32 v4, 0x3102e308, v3
	v_fmamk_f32 v5, v4, 0x395133b1, v192
	v_cmp_eq_f32_e32 vcc, s15, v3
	v_cvt_i32_f32_e32 v3, v3
	v_fmaak_f32 v5, v4, v5, 0x3c0887f9
	v_fmaak_f32 v5, v4, v5, 0x3d2aaa81
	v_fmaak_f32 v5, v4, v5, 0x3e2aaaab
	v_fma_f32 v5, v4, v5, 0.5
	v_ldexp_f32 v3, 1.0, v3
	v_mul_f32_e32 v5, v4, v5
	v_cndmask_b32_e32 v3, v3, v202, vcc
	v_fmac_f32_e32 v4, v4, v5
	v_add_f32_e32 v5, -1.0, v3
	v_fmac_f32_e32 v5, v3, v4
	v_add_f32_e32 v3, v5, v5
	v_cndmask_b32_e32 v3, v5, v3, vcc
	v_cmp_nlt_f32_e32 vcc, s16, v0
	v_exp_f32_e32 v2, v2
	s_nop 0
	v_cndmask_b32_e64 v3, v201, -v3, vcc
	v_cmp_gt_f32_e32 vcc, s17, v3
	v_mul_f32_e32 v4, 0x4f800000, v3
	s_nop 0
	v_cndmask_b32_e32 v3, v3, v4, vcc
	v_sqrt_f32_e32 v4, v3
	s_nop 0
	v_add_u32_e32 v5, -1, v4
	v_fma_f32 v6, -v5, v4, v3
	v_cmp_ge_f32_e64 s[0:1], 0, v6
	v_add_u32_e32 v6, 1, v4
	s_nop 0
	v_cndmask_b32_e64 v5, v4, v5, s[0:1]
	v_fma_f32 v4, -v6, v4, v3
	v_cmp_lt_f32_e64 s[0:1], 0, v4
	s_nop 1
	v_cndmask_b32_e64 v4, v5, v6, s[0:1]
	v_mul_f32_e32 v5, 0x37800000, v4
	v_cndmask_b32_e32 v4, v4, v5, vcc
	v_cmp_class_f32_e32 vcc, v3, v193
	s_nop 1
	v_cndmask_b32_e32 v3, v4, v3, vcc
	v_cmp_ngt_f32_e32 vcc, s18, v0
	s_nop 1
	v_cndmask_b32_e32 v0, 1.0, v3, vcc
	v_mul_f32_e32 v0, v1, v0
	v_mul_f32_e32 v0, v55, v0
	ds_write_b32 v70, v2 offset:4224
	ds_write_b32 v70, v0 offset:41088
	v_add_f32_e32 v0, v25, v36
	v_mul_f32_e32 v0, 0xbfb8aa3b, v0
	v_exp_f32_e32 v0, v0
	v_add_f32_e32 v1, v9, v38
	v_mul_f32_e32 v1, 0xbfb8aa3b, v1
	v_exp_f32_e32 v1, v1
	v_add_f32_e32 v0, 1.0, v0
	v_rcp_f32_e32 v0, v0
	v_add_f32_e32 v1, 1.0, v1
	v_rcp_f32_e32 v1, v1
	v_mul_f32_e32 v0, v0, v32
	v_mul_f32_e32 v2, 0x3fb8aa3b, v0
	v_add_f32_e32 v0, v0, v0
	v_mul_f32_e32 v3, 0x3fb8aa3b, v0
	v_rndne_f32_e32 v3, v3
	v_fmamk_f32 v4, v3, 0xbf317218, v0
	v_fmac_f32_e32 v4, 0x3102e308, v3
	v_fmamk_f32 v5, v4, 0x395133b1, v192
	v_cmp_eq_f32_e32 vcc, s15, v3
	v_cvt_i32_f32_e32 v3, v3
	v_fmaak_f32 v5, v4, v5, 0x3c0887f9
	v_fmaak_f32 v5, v4, v5, 0x3d2aaa81
	v_fmaak_f32 v5, v4, v5, 0x3e2aaaab
	v_fma_f32 v5, v4, v5, 0.5
	v_ldexp_f32 v3, 1.0, v3
	v_mul_f32_e32 v5, v4, v5
	v_cndmask_b32_e32 v3, v3, v202, vcc
	v_fmac_f32_e32 v4, v4, v5
	v_add_f32_e32 v5, -1.0, v3
	v_fmac_f32_e32 v5, v3, v4
	v_add_f32_e32 v3, v5, v5
	v_cndmask_b32_e32 v3, v5, v3, vcc
	v_cmp_nlt_f32_e32 vcc, s16, v0
	v_exp_f32_e32 v2, v2
	s_nop 0
	v_cndmask_b32_e64 v3, v201, -v3, vcc
	v_cmp_gt_f32_e32 vcc, s17, v3
	v_mul_f32_e32 v4, 0x4f800000, v3
	s_nop 0
	v_cndmask_b32_e32 v3, v3, v4, vcc
	v_sqrt_f32_e32 v4, v3
	s_nop 0
	v_add_u32_e32 v5, -1, v4
	v_fma_f32 v6, -v5, v4, v3
	v_cmp_ge_f32_e64 s[0:1], 0, v6
	v_add_u32_e32 v6, 1, v4
	s_nop 0
	v_cndmask_b32_e64 v5, v4, v5, s[0:1]
	v_fma_f32 v4, -v6, v4, v3
	v_cmp_lt_f32_e64 s[0:1], 0, v4
	s_nop 1
	v_cndmask_b32_e64 v4, v5, v6, s[0:1]
	v_mul_f32_e32 v5, 0x37800000, v4
	v_cndmask_b32_e32 v4, v4, v5, vcc
	v_cmp_class_f32_e32 vcc, v3, v193
	s_nop 1
	v_cndmask_b32_e32 v3, v4, v3, vcc
	v_cmp_ngt_f32_e32 vcc, s18, v0
	s_nop 1
	v_cndmask_b32_e32 v0, 1.0, v3, vcc
	v_mul_f32_e32 v0, v1, v0
	v_mul_f32_e32 v0, v41, v0
	ds_write_b32 v70, v2 offset:4480
	ds_write_b32 v70, v0 offset:41344
	v_add_f32_e32 v0, v26, v36
	v_mul_f32_e32 v0, 0xbfb8aa3b, v0
	v_exp_f32_e32 v0, v0
	v_add_f32_e32 v1, v10, v38
	v_mul_f32_e32 v1, 0xbfb8aa3b, v1
	v_exp_f32_e32 v1, v1
	v_add_f32_e32 v0, 1.0, v0
	v_rcp_f32_e32 v0, v0
	v_add_f32_e32 v1, 1.0, v1
	v_rcp_f32_e32 v1, v1
	v_mul_f32_e32 v0, v0, v32
	v_mul_f32_e32 v2, 0x3fb8aa3b, v0
	v_add_f32_e32 v0, v0, v0
	v_mul_f32_e32 v3, 0x3fb8aa3b, v0
	v_rndne_f32_e32 v3, v3
	v_fmamk_f32 v4, v3, 0xbf317218, v0
	v_fmac_f32_e32 v4, 0x3102e308, v3
	v_fmamk_f32 v5, v4, 0x395133b1, v192
	v_cmp_eq_f32_e32 vcc, s15, v3
	v_cvt_i32_f32_e32 v3, v3
	v_fmaak_f32 v5, v4, v5, 0x3c0887f9
	v_fmaak_f32 v5, v4, v5, 0x3d2aaa81
	v_fmaak_f32 v5, v4, v5, 0x3e2aaaab
	v_fma_f32 v5, v4, v5, 0.5
	v_ldexp_f32 v3, 1.0, v3
	v_mul_f32_e32 v5, v4, v5
	v_cndmask_b32_e32 v3, v3, v202, vcc
	v_fmac_f32_e32 v4, v4, v5
	v_add_f32_e32 v5, -1.0, v3
	v_fmac_f32_e32 v5, v3, v4
	v_add_f32_e32 v3, v5, v5
	v_cndmask_b32_e32 v3, v5, v3, vcc
	v_cmp_nlt_f32_e32 vcc, s16, v0
	v_exp_f32_e32 v2, v2
	s_nop 0
	v_cndmask_b32_e64 v3, v201, -v3, vcc
	v_cmp_gt_f32_e32 vcc, s17, v3
	v_mul_f32_e32 v4, 0x4f800000, v3
	s_nop 0
	v_cndmask_b32_e32 v3, v3, v4, vcc
	v_sqrt_f32_e32 v4, v3
	s_nop 0
	v_add_u32_e32 v5, -1, v4
	v_fma_f32 v6, -v5, v4, v3
	v_cmp_ge_f32_e64 s[0:1], 0, v6
	v_add_u32_e32 v6, 1, v4
	s_nop 0
	v_cndmask_b32_e64 v5, v4, v5, s[0:1]
	v_fma_f32 v4, -v6, v4, v3
	v_cmp_lt_f32_e64 s[0:1], 0, v4
	s_nop 1
	v_cndmask_b32_e64 v4, v5, v6, s[0:1]
	v_mul_f32_e32 v5, 0x37800000, v4
	v_cndmask_b32_e32 v4, v4, v5, vcc
	v_cmp_class_f32_e32 vcc, v3, v193
	s_nop 1
	v_cndmask_b32_e32 v3, v4, v3, vcc
	v_cmp_ngt_f32_e32 vcc, s18, v0
	s_nop 1
	v_cndmask_b32_e32 v0, 1.0, v3, vcc
	v_mul_f32_e32 v0, v1, v0
	v_mul_f32_e32 v0, v57, v0
	ds_write_b32 v70, v2 offset:4736
	ds_write_b32 v70, v0 offset:41600
	v_add_f32_e32 v0, v27, v36
	v_mul_f32_e32 v0, 0xbfb8aa3b, v0
	v_exp_f32_e32 v0, v0
	v_add_f32_e32 v1, v11, v38
	v_mul_f32_e32 v1, 0xbfb8aa3b, v1
	v_exp_f32_e32 v1, v1
	v_add_f32_e32 v0, 1.0, v0
	v_rcp_f32_e32 v0, v0
	v_add_f32_e32 v1, 1.0, v1
	v_rcp_f32_e32 v1, v1
	v_mul_f32_e32 v0, v0, v32
	v_mul_f32_e32 v2, 0x3fb8aa3b, v0
	v_add_f32_e32 v0, v0, v0
	v_mul_f32_e32 v3, 0x3fb8aa3b, v0
	v_rndne_f32_e32 v3, v3
	v_fmamk_f32 v4, v3, 0xbf317218, v0
	v_fmac_f32_e32 v4, 0x3102e308, v3
	v_fmamk_f32 v5, v4, 0x395133b1, v192
	v_cmp_eq_f32_e32 vcc, s15, v3
	v_cvt_i32_f32_e32 v3, v3
	v_fmaak_f32 v5, v4, v5, 0x3c0887f9
	v_fmaak_f32 v5, v4, v5, 0x3d2aaa81
	v_fmaak_f32 v5, v4, v5, 0x3e2aaaab
	v_fma_f32 v5, v4, v5, 0.5
	v_ldexp_f32 v3, 1.0, v3
	v_mul_f32_e32 v5, v4, v5
	v_cndmask_b32_e32 v3, v3, v202, vcc
	v_fmac_f32_e32 v4, v4, v5
	v_add_f32_e32 v5, -1.0, v3
	v_fmac_f32_e32 v5, v3, v4
	v_add_f32_e32 v3, v5, v5
	v_cndmask_b32_e32 v3, v5, v3, vcc
	v_cmp_nlt_f32_e32 vcc, s16, v0
	v_exp_f32_e32 v2, v2
	s_nop 0
	v_cndmask_b32_e64 v3, v201, -v3, vcc
	v_cmp_gt_f32_e32 vcc, s17, v3
	v_mul_f32_e32 v4, 0x4f800000, v3
	s_nop 0
	v_cndmask_b32_e32 v3, v3, v4, vcc
	v_sqrt_f32_e32 v4, v3
	s_nop 0
	v_add_u32_e32 v5, -1, v4
	v_fma_f32 v6, -v5, v4, v3
	v_cmp_ge_f32_e64 s[0:1], 0, v6
	v_add_u32_e32 v6, 1, v4
	s_nop 0
	v_cndmask_b32_e64 v5, v4, v5, s[0:1]
	v_fma_f32 v4, -v6, v4, v3
	v_cmp_lt_f32_e64 s[0:1], 0, v4
	s_nop 1
	v_cndmask_b32_e64 v4, v5, v6, s[0:1]
	v_mul_f32_e32 v5, 0x37800000, v4
	v_cndmask_b32_e32 v4, v4, v5, vcc
	v_cmp_class_f32_e32 vcc, v3, v193
	s_nop 1
	v_cndmask_b32_e32 v3, v4, v3, vcc
	v_cmp_ngt_f32_e32 vcc, s18, v0
	s_nop 1
	v_cndmask_b32_e32 v0, 1.0, v3, vcc
	v_mul_f32_e32 v0, v1, v0
	v_mul_f32_e32 v0, v43, v0
	ds_write_b32 v70, v2 offset:4992
	ds_write_b32 v70, v0 offset:41856
	v_add_f32_e32 v0, v28, v36
	v_mul_f32_e32 v0, 0xbfb8aa3b, v0
	v_exp_f32_e32 v0, v0
	v_add_f32_e32 v1, v12, v38
	v_mul_f32_e32 v1, 0xbfb8aa3b, v1
	v_exp_f32_e32 v1, v1
	v_add_f32_e32 v0, 1.0, v0
	v_rcp_f32_e32 v0, v0
	v_add_f32_e32 v1, 1.0, v1
	v_rcp_f32_e32 v1, v1
	v_mul_f32_e32 v0, v0, v32
	v_mul_f32_e32 v2, 0x3fb8aa3b, v0
	v_add_f32_e32 v0, v0, v0
	v_mul_f32_e32 v3, 0x3fb8aa3b, v0
	v_rndne_f32_e32 v3, v3
	v_fmamk_f32 v4, v3, 0xbf317218, v0
	v_fmac_f32_e32 v4, 0x3102e308, v3
	v_fmamk_f32 v5, v4, 0x395133b1, v192
	v_cmp_eq_f32_e32 vcc, s15, v3
	v_cvt_i32_f32_e32 v3, v3
	v_fmaak_f32 v5, v4, v5, 0x3c0887f9
	v_fmaak_f32 v5, v4, v5, 0x3d2aaa81
	v_fmaak_f32 v5, v4, v5, 0x3e2aaaab
	v_fma_f32 v5, v4, v5, 0.5
	v_ldexp_f32 v3, 1.0, v3
	v_mul_f32_e32 v5, v4, v5
	v_cndmask_b32_e32 v3, v3, v202, vcc
	v_fmac_f32_e32 v4, v4, v5
	v_add_f32_e32 v5, -1.0, v3
	v_fmac_f32_e32 v5, v3, v4
	v_add_f32_e32 v3, v5, v5
	v_cndmask_b32_e32 v3, v5, v3, vcc
	v_cmp_nlt_f32_e32 vcc, s16, v0
	v_exp_f32_e32 v2, v2
	s_nop 0
	v_cndmask_b32_e64 v3, v201, -v3, vcc
	v_cmp_gt_f32_e32 vcc, s17, v3
	v_mul_f32_e32 v4, 0x4f800000, v3
	s_nop 0
	v_cndmask_b32_e32 v3, v3, v4, vcc
	v_sqrt_f32_e32 v4, v3
	s_nop 0
	v_add_u32_e32 v5, -1, v4
	v_fma_f32 v6, -v5, v4, v3
	v_cmp_ge_f32_e64 s[0:1], 0, v6
	v_add_u32_e32 v6, 1, v4
	s_nop 0
	v_cndmask_b32_e64 v5, v4, v5, s[0:1]
	v_fma_f32 v4, -v6, v4, v3
	v_cmp_lt_f32_e64 s[0:1], 0, v4
	s_nop 1
	v_cndmask_b32_e64 v4, v5, v6, s[0:1]
	v_mul_f32_e32 v5, 0x37800000, v4
	v_cndmask_b32_e32 v4, v4, v5, vcc
	v_cmp_class_f32_e32 vcc, v3, v193
	s_nop 1
	v_cndmask_b32_e32 v3, v4, v3, vcc
	v_cmp_ngt_f32_e32 vcc, s18, v0
	s_nop 1
	v_cndmask_b32_e32 v0, 1.0, v3, vcc
	v_mul_f32_e32 v0, v1, v0
	v_mul_f32_e32 v0, v59, v0
	ds_write_b32 v70, v2 offset:6272
	ds_write_b32 v70, v0 offset:43136
	v_add_f32_e32 v0, v29, v36
	v_mul_f32_e32 v0, 0xbfb8aa3b, v0
	v_exp_f32_e32 v0, v0
	v_add_f32_e32 v1, v13, v38
	v_mul_f32_e32 v1, 0xbfb8aa3b, v1
	v_exp_f32_e32 v1, v1
	v_add_f32_e32 v0, 1.0, v0
	v_rcp_f32_e32 v0, v0
	v_add_f32_e32 v1, 1.0, v1
	v_rcp_f32_e32 v1, v1
	v_mul_f32_e32 v0, v0, v32
	v_mul_f32_e32 v2, 0x3fb8aa3b, v0
	v_add_f32_e32 v0, v0, v0
	v_mul_f32_e32 v3, 0x3fb8aa3b, v0
	v_rndne_f32_e32 v3, v3
	v_fmamk_f32 v4, v3, 0xbf317218, v0
	v_fmac_f32_e32 v4, 0x3102e308, v3
	v_fmamk_f32 v5, v4, 0x395133b1, v192
	v_cmp_eq_f32_e32 vcc, s15, v3
	v_cvt_i32_f32_e32 v3, v3
	v_fmaak_f32 v5, v4, v5, 0x3c0887f9
	v_fmaak_f32 v5, v4, v5, 0x3d2aaa81
	v_fmaak_f32 v5, v4, v5, 0x3e2aaaab
	v_fma_f32 v5, v4, v5, 0.5
	v_ldexp_f32 v3, 1.0, v3
	v_mul_f32_e32 v5, v4, v5
	v_cndmask_b32_e32 v3, v3, v202, vcc
	v_fmac_f32_e32 v4, v4, v5
	v_add_f32_e32 v5, -1.0, v3
	v_fmac_f32_e32 v5, v3, v4
	v_add_f32_e32 v3, v5, v5
	v_cndmask_b32_e32 v3, v5, v3, vcc
	v_cmp_nlt_f32_e32 vcc, s16, v0
	v_exp_f32_e32 v2, v2
	s_nop 0
	v_cndmask_b32_e64 v3, v201, -v3, vcc
	v_cmp_gt_f32_e32 vcc, s17, v3
	v_mul_f32_e32 v4, 0x4f800000, v3
	s_nop 0
	v_cndmask_b32_e32 v3, v3, v4, vcc
	v_sqrt_f32_e32 v4, v3
	s_nop 0
	v_add_u32_e32 v5, -1, v4
	v_fma_f32 v6, -v5, v4, v3
	v_cmp_ge_f32_e64 s[0:1], 0, v6
	v_add_u32_e32 v6, 1, v4
	s_nop 0
	v_cndmask_b32_e64 v5, v4, v5, s[0:1]
	v_fma_f32 v4, -v6, v4, v3
	v_cmp_lt_f32_e64 s[0:1], 0, v4
	s_nop 1
	v_cndmask_b32_e64 v4, v5, v6, s[0:1]
	v_mul_f32_e32 v5, 0x37800000, v4
	v_cndmask_b32_e32 v4, v4, v5, vcc
	v_cmp_class_f32_e32 vcc, v3, v193
	s_nop 1
	v_cndmask_b32_e32 v3, v4, v3, vcc
	v_cmp_ngt_f32_e32 vcc, s18, v0
	s_nop 1
	v_cndmask_b32_e32 v0, 1.0, v3, vcc
	v_mul_f32_e32 v0, v1, v0
	v_mul_f32_e32 v0, v45, v0
	ds_write_b32 v70, v2 offset:6528
	ds_write_b32 v70, v0 offset:43392
	v_add_f32_e32 v0, v30, v36
	v_mul_f32_e32 v0, 0xbfb8aa3b, v0
	v_exp_f32_e32 v0, v0
	v_add_f32_e32 v1, v14, v38
	v_mul_f32_e32 v1, 0xbfb8aa3b, v1
	v_exp_f32_e32 v1, v1
	v_add_f32_e32 v0, 1.0, v0
	v_rcp_f32_e32 v0, v0
	v_add_f32_e32 v1, 1.0, v1
	v_rcp_f32_e32 v1, v1
	v_mul_f32_e32 v0, v0, v32
	v_mul_f32_e32 v2, 0x3fb8aa3b, v0
	v_add_f32_e32 v0, v0, v0
	v_mul_f32_e32 v3, 0x3fb8aa3b, v0
	v_rndne_f32_e32 v3, v3
	v_fmamk_f32 v4, v3, 0xbf317218, v0
	v_fmac_f32_e32 v4, 0x3102e308, v3
	v_fmamk_f32 v5, v4, 0x395133b1, v192
	v_cmp_eq_f32_e32 vcc, s15, v3
	v_cvt_i32_f32_e32 v3, v3
	v_fmaak_f32 v5, v4, v5, 0x3c0887f9
	v_fmaak_f32 v5, v4, v5, 0x3d2aaa81
	v_fmaak_f32 v5, v4, v5, 0x3e2aaaab
	v_fma_f32 v5, v4, v5, 0.5
	v_ldexp_f32 v3, 1.0, v3
	v_mul_f32_e32 v5, v4, v5
	v_cndmask_b32_e32 v3, v3, v202, vcc
	v_fmac_f32_e32 v4, v4, v5
	v_add_f32_e32 v5, -1.0, v3
	v_fmac_f32_e32 v5, v3, v4
	v_add_f32_e32 v3, v5, v5
	v_cndmask_b32_e32 v3, v5, v3, vcc
	v_cmp_nlt_f32_e32 vcc, s16, v0
	v_exp_f32_e32 v2, v2
	s_nop 0
	v_cndmask_b32_e64 v3, v201, -v3, vcc
	v_cmp_gt_f32_e32 vcc, s17, v3
	v_mul_f32_e32 v4, 0x4f800000, v3
	s_nop 0
	v_cndmask_b32_e32 v3, v3, v4, vcc
	v_sqrt_f32_e32 v4, v3
	s_nop 0
	v_add_u32_e32 v5, -1, v4
	v_fma_f32 v6, -v5, v4, v3
	v_cmp_ge_f32_e64 s[0:1], 0, v6
	v_add_u32_e32 v6, 1, v4
	s_nop 0
	v_cndmask_b32_e64 v5, v4, v5, s[0:1]
	v_fma_f32 v4, -v6, v4, v3
	v_cmp_lt_f32_e64 s[0:1], 0, v4
	s_nop 1
	v_cndmask_b32_e64 v4, v5, v6, s[0:1]
	v_mul_f32_e32 v5, 0x37800000, v4
	v_cndmask_b32_e32 v4, v4, v5, vcc
	v_cmp_class_f32_e32 vcc, v3, v193
	s_nop 1
	v_cndmask_b32_e32 v3, v4, v3, vcc
	v_cmp_ngt_f32_e32 vcc, s18, v0
	s_nop 1
	v_cndmask_b32_e32 v0, 1.0, v3, vcc
	v_mul_f32_e32 v0, v1, v0
	v_mul_f32_e32 v0, v35, v0
	v_add_u32_e32 v1, 0x1800, v70
	ds_write2_b32 v1, v2, v34 offset0:160 offset1:192
	ds_write_b32 v70, v0 offset:43648
	v_add_f32_e32 v0, v31, v36
	v_mul_f32_e32 v0, 0xbfb8aa3b, v0
	v_exp_f32_e32 v0, v0
	v_add_f32_e32 v1, v15, v38
	v_mul_f32_e32 v1, 0xbfb8aa3b, v1
	v_exp_f32_e32 v1, v1
	v_add_f32_e32 v0, 1.0, v0
	v_rcp_f32_e32 v0, v0
	v_add_f32_e32 v1, 1.0, v1
	v_rcp_f32_e32 v1, v1
	v_mul_f32_e32 v0, v0, v32
	v_mul_f32_e32 v2, 0x3fb8aa3b, v0
	v_add_f32_e32 v0, v0, v0
	v_mul_f32_e32 v3, 0x3fb8aa3b, v0
	v_rndne_f32_e32 v3, v3
	v_fmamk_f32 v4, v3, 0xbf317218, v0
	v_fmac_f32_e32 v4, 0x3102e308, v3
	v_fmamk_f32 v5, v4, 0x395133b1, v192
	v_cmp_eq_f32_e32 vcc, s15, v3
	v_cvt_i32_f32_e32 v3, v3
	v_fmaak_f32 v5, v4, v5, 0x3c0887f9
	v_fmaak_f32 v5, v4, v5, 0x3d2aaa81
	v_fmaak_f32 v5, v4, v5, 0x3e2aaaab
	v_fma_f32 v5, v4, v5, 0.5
	v_ldexp_f32 v3, 1.0, v3
	v_mul_f32_e32 v5, v4, v5
	v_cndmask_b32_e32 v3, v3, v202, vcc
	v_fmac_f32_e32 v4, v4, v5
	v_add_f32_e32 v5, -1.0, v3
	v_fmac_f32_e32 v5, v3, v4
	v_add_f32_e32 v3, v5, v5
	v_cndmask_b32_e32 v3, v5, v3, vcc
	v_cmp_nlt_f32_e32 vcc, s16, v0
	v_exp_f32_e32 v2, v2
	s_nop 0
	v_cndmask_b32_e64 v3, v201, -v3, vcc
	v_cmp_gt_f32_e32 vcc, s17, v3
	v_mul_f32_e32 v4, 0x4f800000, v3
	s_nop 0
	v_cndmask_b32_e32 v3, v3, v4, vcc
	v_sqrt_f32_e32 v4, v3
	s_nop 0
	v_add_u32_e32 v5, -1, v4
	v_fma_f32 v6, -v5, v4, v3
	v_cmp_ge_f32_e64 s[0:1], 0, v6
	v_add_u32_e32 v6, 1, v4
	s_nop 0
	v_cndmask_b32_e64 v5, v4, v5, s[0:1]
	v_fma_f32 v4, -v6, v4, v3
	v_cmp_lt_f32_e64 s[0:1], 0, v4
	s_nop 1
	v_cndmask_b32_e64 v4, v5, v6, s[0:1]
	v_mul_f32_e32 v5, 0x37800000, v4
	v_cndmask_b32_e32 v4, v4, v5, vcc
	v_cmp_class_f32_e32 vcc, v3, v193
	v_mov_b32_e32 v6, 1.0
	s_mov_b32 s0, 24
	v_cndmask_b32_e32 v3, v4, v3, vcc
	v_cmp_ngt_f32_e32 vcc, s18, v0
	s_nop 1
	v_cndmask_b32_e32 v0, 1.0, v3, vcc
	v_mul_f32_e32 v0, v1, v0
	v_mul_f32_e32 v0, v33, v0
	ds_write_b32 v70, v2 offset:7040
	ds_write_b32 v70, v0 offset:43904
	v_mov_b32_e32 v2, v162
	s_waitcnt lgkmcnt(0)
	s_barrier
	s_cselect_b64 vcc, -1, 0
	v_and_b32_e32 v3, 63, v2
	v_ashrrev_i32_e32 v4, 6, v2
	v_lshl_or_b32 v5, v4, 11, v3
	v_mov_b32_e32 v1, 0

.LBB0_636:
	s_waitcnt vmcnt(3)
	v_add_u32_e32 v82, v69, v67
	ds_read_b128 v[70:73], v69 offset:34816
	ds_read_b128 v[74:77], v82
	s_add_i32 s0, s0, 32
	s_cmpk_lt_u32 s0, 0x70
	s_waitcnt lgkmcnt(0)
	v_mfma_f32_32x32x16_bf16 v[48:63], v[74:77], v[70:73], v[48:63]
	ds_read_b128 v[70:73], v69 offset:43520
	s_waitcnt lgkmcnt(0)
	v_mfma_f32_32x32x16_bf16 v[32:47], v[74:77], v[70:73], v[32:47]
	ds_read_b128 v[70:73], v69 offset:52224
	s_waitcnt lgkmcnt(0)
	v_mfma_f32_32x32x16_bf16 v[16:31], v[74:77], v[70:73], v[16:31]
	ds_read_b128 v[70:73], v69 offset:60928
	ds_read_b128 v[78:81], v69 offset:34848
	s_waitcnt lgkmcnt(1)
	v_mfma_f32_32x32x16_bf16 v[0:15], v[74:77], v[70:73], v[0:15]
	ds_read_b128 v[70:73], v82 offset:32
	ds_read_b128 v[74:77], v69 offset:43552
	s_waitcnt lgkmcnt(0)
	v_mfma_f32_32x32x16_bf16 v[32:47], v[70:73], v[74:77], v[32:47]
	ds_read_b128 v[74:77], v69 offset:52256
	s_waitcnt lgkmcnt(0)
	v_mfma_f32_32x32x16_bf16 v[16:31], v[70:73], v[74:77], v[16:31]
	ds_read_b128 v[74:77], v69 offset:60960
	v_add_u32_e32 v69, 64, v69
	v_mfma_f32_32x32x16_bf16 v[48:63], v[70:73], v[78:81], v[48:63]
	s_waitcnt lgkmcnt(0)
	v_mfma_f32_32x32x16_bf16 v[0:15], v[70:73], v[74:77], v[0:15]
	s_cbranch_scc1 .LBB0_636
	v_lshrrev_b32_e32 v67, 3, v65
	s_ashr_i32 s3, s2, 31
	v_and_or_b32 v66, v67, 4, v66
	s_lshl_b64 s[0:1], s[2:3], 16
	v_lshlrev_b32_e32 v69, 7, v66
	s_add_u32 s0, s56, s0
	v_or_b32_e32 v66, v69, v68
	s_addc_u32 s1, s57, s1
	v_ashrrev_i32_e32 v67, 31, v66
	v_mul_f32_e32 v48, 0x3db504f3, v48
	v_lshl_add_u64 v[70:71], v[66:67], 2, s[0:1]
	v_ashrrev_i32_e32 v67, 31, v69
	global_store_dword v[70:71], v48, off
	v_mul_f32_e32 v70, 0x3db504f3, v49
	v_lshl_add_u64 v[48:49], v[66:67], 2, s[0:1]
	v_mul_f32_e32 v50, 0x3db504f3, v50
	global_store_dword v[48:49], v70, off offset:512
	global_store_dword v[48:49], v50, off offset:1024
	v_mul_f32_e32 v50, 0x3db504f3, v51
	v_or_b32_e32 v70, 0x400, v69
	global_store_dword v[48:49], v50, off offset:1536
	v_or_b32_e32 v50, v70, v68
	v_ashrrev_i32_e32 v51, 31, v50
	v_mul_f32_e32 v52, 0x3db504f3, v52
	v_lshl_add_u64 v[50:51], v[50:51], 2, s[0:1]
	global_store_dword v[50:51], v52, off
	v_mul_f32_e32 v52, 0x3db504f3, v53
	v_or_b32_e32 v53, 0x480, v69
	v_or_b32_e32 v50, v53, v68
	v_ashrrev_i32_e32 v51, 31, v50
	v_lshl_add_u64 v[50:51], v[50:51], 2, s[0:1]
	global_store_dword v[50:51], v52, off
	v_mul_f32_e32 v52, 0x3db504f3, v54
	v_or_b32_e32 v54, 0x500, v69
	v_or_b32_e32 v50, v54, v68
	v_ashrrev_i32_e32 v51, 31, v50
	v_lshl_add_u64 v[50:51], v[50:51], 2, s[0:1]
	global_store_dword v[50:51], v52, off
	v_mul_f32_e32 v52, 0x3db504f3, v55
	v_or_b32_e32 v55, 0x580, v69
	v_or_b32_e32 v50, v55, v68
	v_ashrrev_i32_e32 v51, 31, v50
	v_lshl_add_u64 v[50:51], v[50:51], 2, s[0:1]
	global_store_dword v[50:51], v52, off
	v_mul_f32_e32 v52, 0x3db504f3, v56
	v_or_b32_e32 v56, 0x800, v69
	v_or_b32_e32 v50, v56, v68
	v_ashrrev_i32_e32 v51, 31, v50
	v_lshl_add_u64 v[50:51], v[50:51], 2, s[0:1]
	global_store_dword v[50:51], v52, off
	v_mul_f32_e32 v52, 0x3db504f3, v57
	v_or_b32_e32 v57, 0x880, v69
	v_or_b32_e32 v50, v57, v68
	v_ashrrev_i32_e32 v51, 31, v50
	v_lshl_add_u64 v[50:51], v[50:51], 2, s[0:1]
	global_store_dword v[50:51], v52, off
	v_mul_f32_e32 v52, 0x3db504f3, v58
	v_or_b32_e32 v58, 0x900, v69
	v_or_b32_e32 v50, v58, v68
	v_ashrrev_i32_e32 v51, 31, v50
	v_lshl_add_u64 v[50:51], v[50:51], 2, s[0:1]
	global_store_dword v[50:51], v52, off
	v_mul_f32_e32 v52, 0x3db504f3, v59
	v_or_b32_e32 v59, 0x980, v69
	v_or_b32_e32 v50, v59, v68
	v_ashrrev_i32_e32 v51, 31, v50
	v_lshl_add_u64 v[50:51], v[50:51], 2, s[0:1]
	global_store_dword v[50:51], v52, off
	v_mul_f32_e32 v52, 0x3db504f3, v60
	v_or_b32_e32 v60, 0xc00, v69
	v_or_b32_e32 v50, v60, v68
	v_ashrrev_i32_e32 v51, 31, v50
	v_lshl_add_u64 v[50:51], v[50:51], 2, s[0:1]
	global_store_dword v[50:51], v52, off
	v_mul_f32_e32 v52, 0x3db504f3, v61
	v_or_b32_e32 v61, 0xc80, v69
	v_or_b32_e32 v50, v61, v68
	v_ashrrev_i32_e32 v51, 31, v50
	v_lshl_add_u64 v[50:51], v[50:51], 2, s[0:1]
	global_store_dword v[50:51], v52, off
	v_mul_f32_e32 v52, 0x3db504f3, v62
	v_or_b32_e32 v62, 0xd00, v69
	v_or_b32_e32 v50, v62, v68
	v_ashrrev_i32_e32 v51, 31, v50
	v_lshl_add_u64 v[50:51], v[50:51], 2, s[0:1]
	global_store_dword v[50:51], v52, off
	v_mul_f32_e32 v52, 0x3db504f3, v63
	v_or_b32_e32 v63, 0xd80, v69
	v_or_b32_e32 v50, v63, v68
	v_ashrrev_i32_e32 v51, 31, v50
	v_lshl_add_u64 v[50:51], v[50:51], 2, s[0:1]
	global_store_dword v[50:51], v52, off
	v_or_b32_e32 v50, 32, v68
	v_mul_f32_e32 v32, 0x3db504f3, v32
	v_or_b32_e32 v66, v69, v50
	global_store_dword v[48:49], v32, off offset:128
	v_mul_f32_e32 v51, 0x3db504f3, v33
	v_lshl_add_u64 v[32:33], v[66:67], 2, s[0:1]
	v_mul_f32_e32 v34, 0x3db504f3, v34
	global_store_dword v[32:33], v34, off offset:1024
	v_mul_f32_e32 v34, 0x3db504f3, v35
	global_store_dword v[32:33], v51, off offset:512
	global_store_dword v[32:33], v34, off offset:1536
	v_or_b32_e32 v32, v70, v50
	v_ashrrev_i32_e32 v33, 31, v32
	v_mul_f32_e32 v34, 0x3db504f3, v36
	v_lshl_add_u64 v[32:33], v[32:33], 2, s[0:1]
	global_store_dword v[32:33], v34, off
	v_or_b32_e32 v32, v53, v50
	v_ashrrev_i32_e32 v33, 31, v32
	v_mul_f32_e32 v34, 0x3db504f3, v37
	v_lshl_add_u64 v[32:33], v[32:33], 2, s[0:1]
	global_store_dword v[32:33], v34, off
	v_or_b32_e32 v32, v54, v50
	v_ashrrev_i32_e32 v33, 31, v32
	v_mul_f32_e32 v34, 0x3db504f3, v38
	v_lshl_add_u64 v[32:33], v[32:33], 2, s[0:1]
	global_store_dword v[32:33], v34, off
	v_or_b32_e32 v32, v55, v50
	v_ashrrev_i32_e32 v33, 31, v32
	v_mul_f32_e32 v34, 0x3db504f3, v39
	v_lshl_add_u64 v[32:33], v[32:33], 2, s[0:1]
	global_store_dword v[32:33], v34, off
	v_or_b32_e32 v32, v56, v50
	v_ashrrev_i32_e32 v33, 31, v32
	v_mul_f32_e32 v34, 0x3db504f3, v40
	v_lshl_add_u64 v[32:33], v[32:33], 2, s[0:1]
	global_store_dword v[32:33], v34, off
	v_or_b32_e32 v32, v57, v50
	v_ashrrev_i32_e32 v33, 31, v32
	v_mul_f32_e32 v34, 0x3db504f3, v41
	v_lshl_add_u64 v[32:33], v[32:33], 2, s[0:1]
	global_store_dword v[32:33], v34, off
	v_or_b32_e32 v32, v58, v50
	v_ashrrev_i32_e32 v33, 31, v32
	v_mul_f32_e32 v34, 0x3db504f3, v42
	v_lshl_add_u64 v[32:33], v[32:33], 2, s[0:1]
	global_store_dword v[32:33], v34, off
	v_or_b32_e32 v32, v59, v50
	v_ashrrev_i32_e32 v33, 31, v32
	v_mul_f32_e32 v34, 0x3db504f3, v43
	v_lshl_add_u64 v[32:33], v[32:33], 2, s[0:1]
	global_store_dword v[32:33], v34, off
	v_or_b32_e32 v32, v60, v50
	v_ashrrev_i32_e32 v33, 31, v32
	v_mul_f32_e32 v34, 0x3db504f3, v44
	v_lshl_add_u64 v[32:33], v[32:33], 2, s[0:1]
	global_store_dword v[32:33], v34, off
	v_or_b32_e32 v32, v61, v50
	v_ashrrev_i32_e32 v33, 31, v32
	v_mul_f32_e32 v34, 0x3db504f3, v45
	v_lshl_add_u64 v[32:33], v[32:33], 2, s[0:1]
	global_store_dword v[32:33], v34, off
	v_or_b32_e32 v32, v62, v50
	v_ashrrev_i32_e32 v33, 31, v32
	v_mul_f32_e32 v34, 0x3db504f3, v46
	v_lshl_add_u64 v[32:33], v[32:33], 2, s[0:1]
	global_store_dword v[32:33], v34, off
	v_or_b32_e32 v32, v63, v50
	v_ashrrev_i32_e32 v33, 31, v32
	v_mul_f32_e32 v34, 0x3db504f3, v47
	v_lshl_add_u64 v[32:33], v[32:33], 2, s[0:1]
	global_store_dword v[32:33], v34, off
	v_or_b32_e32 v32, 64, v68
	v_mul_f32_e32 v16, 0x3db504f3, v16
	v_or_b32_e32 v66, v69, v32
	global_store_dword v[48:49], v16, off offset:256
	v_mul_f32_e32 v33, 0x3db504f3, v17
	v_lshl_add_u64 v[16:17], v[66:67], 2, s[0:1]
	v_mul_f32_e32 v18, 0x3db504f3, v18
	global_store_dword v[16:17], v18, off offset:1024
	v_mul_f32_e32 v18, 0x3db504f3, v19
	global_store_dword v[16:17], v33, off offset:512
	global_store_dword v[16:17], v18, off offset:1536
	v_or_b32_e32 v16, v70, v32
	v_ashrrev_i32_e32 v17, 31, v16
	v_mul_f32_e32 v18, 0x3db504f3, v20
	v_lshl_add_u64 v[16:17], v[16:17], 2, s[0:1]
	global_store_dword v[16:17], v18, off
	v_or_b32_e32 v16, v53, v32
	v_ashrrev_i32_e32 v17, 31, v16
	v_mul_f32_e32 v18, 0x3db504f3, v21
	v_lshl_add_u64 v[16:17], v[16:17], 2, s[0:1]
	global_store_dword v[16:17], v18, off
	v_or_b32_e32 v16, v54, v32
	v_ashrrev_i32_e32 v17, 31, v16
	v_mul_f32_e32 v18, 0x3db504f3, v22
	v_lshl_add_u64 v[16:17], v[16:17], 2, s[0:1]
	global_store_dword v[16:17], v18, off
	v_or_b32_e32 v16, v55, v32
	v_ashrrev_i32_e32 v17, 31, v16
	v_mul_f32_e32 v18, 0x3db504f3, v23
	v_lshl_add_u64 v[16:17], v[16:17], 2, s[0:1]
	global_store_dword v[16:17], v18, off
	v_or_b32_e32 v16, v56, v32
	v_ashrrev_i32_e32 v17, 31, v16
	v_mul_f32_e32 v18, 0x3db504f3, v24
	v_lshl_add_u64 v[16:17], v[16:17], 2, s[0:1]
	global_store_dword v[16:17], v18, off
	v_or_b32_e32 v16, v57, v32
	v_ashrrev_i32_e32 v17, 31, v16
	v_mul_f32_e32 v18, 0x3db504f3, v25
	v_lshl_add_u64 v[16:17], v[16:17], 2, s[0:1]
	global_store_dword v[16:17], v18, off
	v_or_b32_e32 v16, v58, v32
	v_ashrrev_i32_e32 v17, 31, v16
	v_mul_f32_e32 v18, 0x3db504f3, v26
	v_lshl_add_u64 v[16:17], v[16:17], 2, s[0:1]
	global_store_dword v[16:17], v18, off
	v_or_b32_e32 v16, v59, v32
	v_ashrrev_i32_e32 v17, 31, v16
	v_mul_f32_e32 v18, 0x3db504f3, v27
	v_lshl_add_u64 v[16:17], v[16:17], 2, s[0:1]
	global_store_dword v[16:17], v18, off
	v_or_b32_e32 v16, v60, v32
	v_ashrrev_i32_e32 v17, 31, v16
	v_mul_f32_e32 v18, 0x3db504f3, v28
	v_lshl_add_u64 v[16:17], v[16:17], 2, s[0:1]
	global_store_dword v[16:17], v18, off
	v_or_b32_e32 v16, v61, v32
	v_ashrrev_i32_e32 v17, 31, v16
	v_mul_f32_e32 v18, 0x3db504f3, v29
	v_lshl_add_u64 v[16:17], v[16:17], 2, s[0:1]
	global_store_dword v[16:17], v18, off
	v_or_b32_e32 v16, v62, v32
	v_ashrrev_i32_e32 v17, 31, v16
	v_mul_f32_e32 v18, 0x3db504f3, v30
	v_lshl_add_u64 v[16:17], v[16:17], 2, s[0:1]
	global_store_dword v[16:17], v18, off
	v_or_b32_e32 v16, v63, v32
	v_ashrrev_i32_e32 v17, 31, v16
	v_mul_f32_e32 v18, 0x3db504f3, v31
	v_lshl_add_u64 v[16:17], v[16:17], 2, s[0:1]
	global_store_dword v[16:17], v18, off
	v_or_b32_e32 v16, 0x60, v68
	v_mul_f32_e32 v0, 0x3db504f3, v0
	v_or_b32_e32 v66, v69, v16
	global_store_dword v[48:49], v0, off offset:384
	v_mul_f32_e32 v17, 0x3db504f3, v1
	v_lshl_add_u64 v[0:1], v[66:67], 2, s[0:1]
	v_mul_f32_e32 v2, 0x3db504f3, v2
	global_store_dword v[0:1], v2, off offset:1024
	v_mul_f32_e32 v2, 0x3db504f3, v3
	global_store_dword v[0:1], v17, off offset:512
	global_store_dword v[0:1], v2, off offset:1536
	v_or_b32_e32 v0, v70, v16
	v_ashrrev_i32_e32 v1, 31, v0
	v_mul_f32_e32 v2, 0x3db504f3, v4
	v_lshl_add_u64 v[0:1], v[0:1], 2, s[0:1]
	global_store_dword v[0:1], v2, off
	v_or_b32_e32 v0, v53, v16
	v_ashrrev_i32_e32 v1, 31, v0
	v_mul_f32_e32 v2, 0x3db504f3, v5
	v_lshl_add_u64 v[0:1], v[0:1], 2, s[0:1]
	global_store_dword v[0:1], v2, off
	v_or_b32_e32 v0, v54, v16
	v_ashrrev_i32_e32 v1, 31, v0
	v_mul_f32_e32 v2, 0x3db504f3, v6
	v_lshl_add_u64 v[0:1], v[0:1], 2, s[0:1]
	global_store_dword v[0:1], v2, off
	v_or_b32_e32 v0, v55, v16
	v_ashrrev_i32_e32 v1, 31, v0
	v_mul_f32_e32 v2, 0x3db504f3, v7
	v_lshl_add_u64 v[0:1], v[0:1], 2, s[0:1]
	global_store_dword v[0:1], v2, off
	v_or_b32_e32 v0, v56, v16
	v_ashrrev_i32_e32 v1, 31, v0
	v_mul_f32_e32 v2, 0x3db504f3, v8
	v_lshl_add_u64 v[0:1], v[0:1], 2, s[0:1]
	global_store_dword v[0:1], v2, off
	v_or_b32_e32 v0, v57, v16
	v_ashrrev_i32_e32 v1, 31, v0
	v_mul_f32_e32 v2, 0x3db504f3, v9
	v_lshl_add_u64 v[0:1], v[0:1], 2, s[0:1]
	global_store_dword v[0:1], v2, off
	v_or_b32_e32 v0, v58, v16
	v_ashrrev_i32_e32 v1, 31, v0
	v_mul_f32_e32 v2, 0x3db504f3, v10
	v_lshl_add_u64 v[0:1], v[0:1], 2, s[0:1]
	global_store_dword v[0:1], v2, off
	v_or_b32_e32 v0, v59, v16
	v_ashrrev_i32_e32 v1, 31, v0
	v_mul_f32_e32 v2, 0x3db504f3, v11
	v_lshl_add_u64 v[0:1], v[0:1], 2, s[0:1]
	global_store_dword v[0:1], v2, off
	v_or_b32_e32 v0, v60, v16
	v_ashrrev_i32_e32 v1, 31, v0
	v_mul_f32_e32 v2, 0x3db504f3, v12
	v_lshl_add_u64 v[0:1], v[0:1], 2, s[0:1]
	global_store_dword v[0:1], v2, off
	v_or_b32_e32 v0, v61, v16
	v_ashrrev_i32_e32 v1, 31, v0
	v_mul_f32_e32 v2, 0x3db504f3, v13
	v_lshl_add_u64 v[0:1], v[0:1], 2, s[0:1]
	global_store_dword v[0:1], v2, off
	v_or_b32_e32 v0, v62, v16
	v_ashrrev_i32_e32 v1, 31, v0
	v_mul_f32_e32 v2, 0x3db504f3, v14
	v_lshl_add_u64 v[0:1], v[0:1], 2, s[0:1]
	global_store_dword v[0:1], v2, off
	v_or_b32_e32 v0, v63, v16
	v_ashrrev_i32_e32 v1, 31, v0
	v_mul_f32_e32 v2, 0x3db504f3, v15
	v_lshl_add_u64 v[0:1], v[0:1], 2, s[0:1]
	v_and_b32_e32 v4, 1, v65
	global_store_dword v[0:1], v2, off
	v_mul_lo_u32 v0, v64, s87
	v_lshlrev_b32_e32 v1, 7, v4
	v_add3_u32 v7, 0, v0, v1
	v_lshl_add_u32 v6, v4, 8, 0
	ds_read_b128 v[8:11], v7 offset:34816
	ds_read_b128 v[12:15], v7 offset:34832
	ds_read_b128 v[16:19], v7 offset:34848
	ds_read_b128 v[0:3], v7 offset:34864
	v_add_u32_e32 v6, 0x11600, v6
	ds_read_b128 v[20:23], v6
	ds_read_b128 v[24:27], v6 offset:16
	ds_read_b128 v[28:31], v6 offset:32
	ds_read_b128 v[32:35], v6 offset:48
	s_waitcnt lgkmcnt(7)
	v_lshlrev_b32_e32 v5, 16, v8
	s_waitcnt lgkmcnt(3)
	v_fma_f32 v5, v20, v5, 0
	v_and_b32_e32 v8, 0xffff0000, v8
	v_fmac_f32_e32 v5, v21, v8
	v_lshlrev_b32_e32 v8, 16, v9
	v_fmac_f32_e32 v5, v22, v8
	v_and_b32_e32 v8, 0xffff0000, v9
	v_fmac_f32_e32 v5, v23, v8
	v_lshlrev_b32_e32 v8, 16, v10
	s_waitcnt lgkmcnt(2)
	v_fmac_f32_e32 v5, v24, v8
	v_and_b32_e32 v8, 0xffff0000, v10
	v_fmac_f32_e32 v5, v25, v8
	v_lshlrev_b32_e32 v8, 16, v11
	v_fmac_f32_e32 v5, v26, v8
	v_and_b32_e32 v8, 0xffff0000, v11
	v_fmac_f32_e32 v5, v27, v8
	v_lshlrev_b32_e32 v8, 16, v12
	s_waitcnt lgkmcnt(1)
	v_fmac_f32_e32 v5, v28, v8
	v_and_b32_e32 v8, 0xffff0000, v12
	v_fmac_f32_e32 v5, v29, v8
	v_lshlrev_b32_e32 v8, 16, v13
	v_fmac_f32_e32 v5, v30, v8
	v_and_b32_e32 v8, 0xffff0000, v13
	v_fmac_f32_e32 v5, v31, v8
	v_lshlrev_b32_e32 v8, 16, v14
	s_waitcnt lgkmcnt(0)
	v_fmac_f32_e32 v5, v32, v8
	v_and_b32_e32 v8, 0xffff0000, v14
	v_fmac_f32_e32 v5, v33, v8
	v_lshlrev_b32_e32 v8, 16, v15
	v_fmac_f32_e32 v5, v34, v8
	v_and_b32_e32 v8, 0xffff0000, v15
	v_fmac_f32_e32 v5, v35, v8
	ds_read_b128 v[8:11], v6 offset:64
	v_lshlrev_b32_e32 v12, 16, v16
	s_waitcnt lgkmcnt(0)
	v_fmac_f32_e32 v5, v8, v12
	v_and_b32_e32 v8, 0xffff0000, v16
	v_fmac_f32_e32 v5, v9, v8
	v_lshlrev_b32_e32 v8, 16, v17
	v_fmac_f32_e32 v5, v10, v8
	v_and_b32_e32 v8, 0xffff0000, v17
	v_fmac_f32_e32 v5, v11, v8
	ds_read_b128 v[8:11], v6 offset:80
	v_lshlrev_b32_e32 v12, 16, v18
	s_waitcnt lgkmcnt(0)
	v_fmac_f32_e32 v5, v8, v12
	v_and_b32_e32 v8, 0xffff0000, v18
	v_fmac_f32_e32 v5, v9, v8
	v_lshlrev_b32_e32 v8, 16, v19
	v_fmac_f32_e32 v5, v10, v8
	v_and_b32_e32 v8, 0xffff0000, v19
	v_fmac_f32_e32 v5, v11, v8
	ds_read_b128 v[8:11], v6 offset:96
	v_lshlrev_b32_e32 v12, 16, v0
	v_and_b32_e32 v0, 0xffff0000, v0
	s_waitcnt lgkmcnt(0)
	v_fmac_f32_e32 v5, v8, v12
	v_fmac_f32_e32 v5, v9, v0
	v_lshlrev_b32_e32 v0, 16, v1
	v_fmac_f32_e32 v5, v10, v0
	v_and_b32_e32 v0, 0xffff0000, v1
	v_fmac_f32_e32 v5, v11, v0
	ds_read_b128 v[8:11], v6 offset:112
	v_lshlrev_b32_e32 v0, 16, v2
	s_waitcnt lgkmcnt(0)
	v_fmac_f32_e32 v5, v8, v0
	v_and_b32_e32 v0, 0xffff0000, v2
	v_fmac_f32_e32 v5, v9, v0
	v_lshlrev_b32_e32 v0, 16, v3
	v_fmac_f32_e32 v5, v10, v0
	v_and_b32_e32 v0, 0xffff0000, v3
	v_fmac_f32_e32 v5, v11, v0
	ds_read_b128 v[0:3], v7 offset:34880
	ds_read_b128 v[8:11], v6 offset:128
	s_waitcnt lgkmcnt(1)
	v_lshlrev_b32_e32 v12, 16, v0
	s_waitcnt lgkmcnt(0)
	v_fmac_f32_e32 v5, v8, v12
	v_and_b32_e32 v0, 0xffff0000, v0
	v_fmac_f32_e32 v5, v9, v0
	v_lshlrev_b32_e32 v0, 16, v1
	v_fmac_f32_e32 v5, v10, v0
	v_and_b32_e32 v0, 0xffff0000, v1
	v_fmac_f32_e32 v5, v11, v0
	ds_read_b128 v[8:11], v6 offset:144
	v_lshlrev_b32_e32 v0, 16, v2
	s_waitcnt lgkmcnt(0)
	v_fmac_f32_e32 v5, v8, v0
	v_and_b32_e32 v0, 0xffff0000, v2
	v_fmac_f32_e32 v5, v9, v0
	v_lshlrev_b32_e32 v0, 16, v3
	v_fmac_f32_e32 v5, v10, v0
	v_and_b32_e32 v0, 0xffff0000, v3
	v_fmac_f32_e32 v5, v11, v0
	ds_read_b128 v[0:3], v7 offset:34896
	ds_read_b128 v[8:11], v6 offset:160
	s_waitcnt lgkmcnt(1)
	v_lshlrev_b32_e32 v12, 16, v0
	s_waitcnt lgkmcnt(0)
	v_fmac_f32_e32 v5, v8, v12
	v_and_b32_e32 v0, 0xffff0000, v0
	v_fmac_f32_e32 v5, v9, v0
	v_lshlrev_b32_e32 v0, 16, v1
	v_fmac_f32_e32 v5, v10, v0
	v_and_b32_e32 v0, 0xffff0000, v1
	v_fmac_f32_e32 v5, v11, v0
	ds_read_b128 v[8:11], v6 offset:176
	v_lshlrev_b32_e32 v0, 16, v2
	s_waitcnt lgkmcnt(0)
	v_fmac_f32_e32 v5, v8, v0
	v_and_b32_e32 v0, 0xffff0000, v2
	v_fmac_f32_e32 v5, v9, v0
	v_lshlrev_b32_e32 v0, 16, v3
	v_fmac_f32_e32 v5, v10, v0
	v_and_b32_e32 v0, 0xffff0000, v3
	v_fmac_f32_e32 v5, v11, v0
	ds_read_b128 v[0:3], v7 offset:34912
	ds_read_b128 v[8:11], v6 offset:192
	s_waitcnt lgkmcnt(1)
	v_lshlrev_b32_e32 v12, 16, v0
	s_waitcnt lgkmcnt(0)
	v_fmac_f32_e32 v5, v8, v12
	v_and_b32_e32 v0, 0xffff0000, v0
	v_fmac_f32_e32 v5, v9, v0
	v_lshlrev_b32_e32 v0, 16, v1
	v_fmac_f32_e32 v5, v10, v0
	v_and_b32_e32 v0, 0xffff0000, v1
	v_fmac_f32_e32 v5, v11, v0
	ds_read_b128 v[8:11], v6 offset:208
	v_lshlrev_b32_e32 v0, 16, v2
	s_waitcnt lgkmcnt(0)
	v_fmac_f32_e32 v5, v8, v0
	v_and_b32_e32 v0, 0xffff0000, v2
	v_fmac_f32_e32 v5, v9, v0
	v_lshlrev_b32_e32 v0, 16, v3
	v_fmac_f32_e32 v5, v10, v0
	v_and_b32_e32 v0, 0xffff0000, v3
	v_fmac_f32_e32 v5, v11, v0
	ds_read_b128 v[0:3], v7 offset:34928
	ds_read_b128 v[8:11], v6 offset:224
	s_waitcnt lgkmcnt(1)
	v_lshlrev_b32_e32 v7, 16, v0
	s_waitcnt lgkmcnt(0)
	v_fmac_f32_e32 v5, v8, v7
	v_and_b32_e32 v0, 0xffff0000, v0
	v_fmac_f32_e32 v5, v9, v0
	ds_read_b128 v[6:9], v6 offset:240
	v_lshlrev_b32_e32 v0, 16, v1
	v_fmac_f32_e32 v5, v10, v0
	v_and_b32_e32 v0, 0xffff0000, v1
	v_fmac_f32_e32 v5, v11, v0
	v_lshlrev_b32_e32 v0, 16, v2
	s_waitcnt lgkmcnt(0)
	v_fmac_f32_e32 v5, v6, v0
	v_and_b32_e32 v0, 0xffff0000, v2
	v_fmac_f32_e32 v5, v7, v0
	v_lshlrev_b32_e32 v0, 16, v3
	v_fmac_f32_e32 v5, v8, v0
	v_and_b32_e32 v0, 0xffff0000, v3
	v_fmac_f32_e32 v5, v9, v0
	v_mbcnt_hi_u32_b32 v0, -1, v195
	v_and_b32_e32 v2, 64, v0
	v_xor_b32_e32 v1, 1, v0
	v_add_u32_e32 v2, 64, v2
	v_cmp_lt_i32_e32 vcc, v1, v2
	s_nop 1
	v_cndmask_b32_e32 v0, v0, v1, vcc
	v_lshlrev_b32_e32 v0, 2, v0
	v_mov_b32_dpp v0, v5 quad_perm:[1,0,3,2] row_mask:0xf bank_mask:0xf
	v_cmp_eq_u32_e32 vcc, 0, v4
	s_and_saveexec_b64 s[0:1], vcc
	s_cbranch_execz .LBB0_535
	s_lshl_b64 s[6:7], s[2:3], 9
	v_readlane_b32 s8, v249, 21
	v_readlane_b32 s9, v249, 22
	s_add_u32 s6, s8, s6
	s_addc_u32 s7, s9, s7
	v_ashrrev_i32_e32 v65, 31, v64
	s_nop 0
	v_add_f32_e32 v0, v5, v0
	v_lshl_add_u64 v[2:3], v[64:65], 2, s[6:7]
	v_mul_f32_e32 v0, 0x3db504f3, v0
	global_store_dword v[2:3], v0, off
	s_branch .LBB0_535

.LBB0_859:
	v_add_u32_e32 v67, v65, v64
	ds_read_b128 v[76:79], v65 offset:18432
	ds_read_b128 v[80:83], v67
	s_add_i32 s0, s0, 32
	s_cmp_lt_u32 s0, 48
	s_waitcnt lgkmcnt(0)
	v_mfma_f32_32x32x16_bf16 v[48:63], v[80:83], v[76:79], v[48:63]
	ds_read_b128 v[76:79], v65 offset:23040
	s_waitcnt lgkmcnt(0)
	v_mfma_f32_32x32x16_bf16 v[16:31], v[80:83], v[76:79], v[16:31]
	ds_read_b128 v[76:79], v65 offset:27648
	s_waitcnt lgkmcnt(0)
	v_mfma_f32_32x32x16_bf16 v[32:47], v[80:83], v[76:79], v[32:47]
	ds_read_b128 v[76:79], v65 offset:32256
	ds_read_b128 v[84:87], v65 offset:18464
	s_waitcnt lgkmcnt(1)
	v_mfma_f32_32x32x16_bf16 v[0:15], v[80:83], v[76:79], v[0:15]
	ds_read_b128 v[76:79], v67 offset:32
	ds_read_b128 v[80:83], v65 offset:23072
	s_waitcnt lgkmcnt(0)
	v_mfma_f32_32x32x16_bf16 v[16:31], v[76:79], v[80:83], v[16:31]
	ds_read_b128 v[80:83], v65 offset:27680
	s_waitcnt lgkmcnt(0)
	v_mfma_f32_32x32x16_bf16 v[32:47], v[76:79], v[80:83], v[32:47]
	ds_read_b128 v[80:83], v65 offset:32288
	v_add_u32_e32 v65, 64, v65
	v_mfma_f32_32x32x16_bf16 v[48:63], v[76:79], v[84:87], v[48:63]
	s_waitcnt lgkmcnt(0)
	v_mfma_f32_32x32x16_bf16 v[0:15], v[76:79], v[80:83], v[0:15]
	s_cbranch_scc1 .LBB0_859
	v_and_b32_e32 v141, 63, v72
	v_or_b32_e32 v140, s13, v141
	v_readlane_b32 s0, v249, 15
	v_lshlrev_b32_e32 v96, 3, v140
	v_readlane_b32 s1, v249, 16
	v_readlane_b32 s16, v251, 20
	v_lshlrev_b32_e32 v69, 11, v66
	v_lshl_add_u64 v[64:65], s[0:1], 0, v[96:97]
	v_readlane_b32 s0, v248, 25
	s_or_b32 s3, s13, s0
	v_or_b32_e32 v96, s3, v74
	v_lshlrev_b64 v[66:67], 2, v[96:97]
	v_readlane_b32 s18, v251, 22
	v_readlane_b32 s19, v251, 23
	s_barrier
	s_nop 0
	v_lshl_add_u64 v[70:71], s[18:19], 0, v[66:67]
	v_readlane_b32 s100, v251, 16
	v_readlane_b32 s101, v251, 17
	s_nop 1
	v_lshl_add_u64 v[220:221], s[100:101], 0, v[66:67]
	v_readlane_b32 s100, v251, 20
	v_readlane_b32 s101, v251, 21
	s_nop 1
	v_lshl_add_u64 v[222:223], s[100:101], 0, v[66:67]
	global_load_dword v224, v[220:221], off
	global_load_dword v225, v[222:223], off
	global_load_dword v226, v[70:71], off offset:128
	global_load_dword v227, v[222:223], off offset:128
	global_load_dword v228, v[220:221], off offset:128
	global_load_dword v70, v[70:71], off
	s_mov_b32 s4, 0x3f2aaaab
	s_mov_b32 s8, 0x3f317218
	v_readlane_b32 s40, v251, 4
	v_readlane_b32 s52, v251, 16
	v_readlane_b32 s53, v251, 17
	v_readlane_b32 s17, v251, 21
	s_mov_b32 s9, 0x7f800000
	s_mov_b32 s10, 0x33800000
	s_mov_b32 s20, 0x43000000
	s_mov_b32 s21, 0x42b17217
	s_mov_b32 s22, 0xf800000
	s_mov_b32 s23, 0xc1880000
	s_mov_b32 s2, 0
	s_cmp_eq_u32 s12, 0
	v_readlane_b32 s24, v251, 28
	v_readlane_b32 s25, v251, 29
	v_readlane_b32 s26, v251, 30
	v_readlane_b32 s27, v251, 31
	v_readlane_b32 s28, v251, 32
	v_readlane_b32 s29, v251, 33
	v_readlane_b32 s30, v251, 34
	v_readlane_b32 s31, v251, 35
	v_readlane_b32 s41, v251, 5
	v_readlane_b32 s42, v251, 6
	v_readlane_b32 s43, v251, 7
	v_readlane_b32 s44, v251, 8
	v_readlane_b32 s45, v251, 9
	v_readlane_b32 s46, v251, 10
	v_readlane_b32 s47, v251, 11
	v_readlane_b32 s48, v251, 12
	v_readlane_b32 s49, v251, 13
	v_readlane_b32 s50, v251, 14
	v_readlane_b32 s51, v251, 15
	v_readlane_b32 s54, v251, 18
	v_readlane_b32 s55, v251, 19
	s_waitcnt vmcnt(0)
	v_mul_f32_e32 v70, 0xbfb8aa3b, v70
	v_exp_f32_e32 v73, v70
	s_nop 0
	v_add_f32_e32 v75, 1.0, v73
	v_add_f32_e32 v70, -1.0, v75
	v_sub_f32_e32 v71, v70, v75
	v_add_f32_e32 v71, 1.0, v71
	v_sub_f32_e32 v70, v73, v70
	v_add_f32_e32 v76, v70, v71
	v_frexp_mant_f32_e32 v70, v75
	v_cmp_gt_f32_e32 vcc, s4, v70
	v_cvt_f64_f32_e32 v[70:71], v75
	v_frexp_exp_i32_f64_e32 v70, v[70:71]
	v_subbrev_co_u32_e32 v82, vcc, 0, v70, vcc
	v_sub_u32_e32 v70, 0, v82
	v_ldexp_f32 v71, v75, v70
	v_add_f32_e32 v75, -1.0, v71
	v_add_f32_e32 v77, 1.0, v71
	v_ldexp_f32 v70, v76, v70
	v_add_f32_e32 v76, 1.0, v75
	v_add_f32_e32 v78, -1.0, v77
	v_sub_f32_e32 v76, v71, v76
	v_sub_f32_e32 v71, v71, v78
	v_add_f32_e32 v76, v70, v76
	v_add_f32_e32 v70, v70, v71
	v_add_f32_e32 v83, v77, v70
	v_rcp_f32_e32 v85, v83
	v_sub_f32_e32 v71, v83, v77
	v_sub_f32_e32 v84, v70, v71
	v_add_f32_e32 v71, v75, v76
	v_sub_f32_e32 v70, v71, v75
	v_mul_f32_e32 v86, v71, v85
	v_sub_f32_e32 v75, v76, v70
	v_mul_f32_e32 v76, v83, v86
	v_fma_f32 v78, v86, v83, -v76
	v_fmac_f32_e32 v78, v86, v84
	v_add_f32_e32 v70, v76, v78
	v_sub_f32_e32 v77, v71, v70
	v_pk_add_f32 v[80:81], v[70:71], v[76:77] neg_lo:[0,1] neg_hi:[0,1]
	v_mov_b32_e32 v79, v70
	v_pk_add_f32 v[70:71], v[80:81], v[78:79] neg_lo:[0,1] neg_hi:[0,1]
	v_cmp_neq_f32_e32 vcc, s9, v73
	v_add_f32_e32 v71, v75, v71
	v_add_f32_e32 v70, v70, v71
	v_add_f32_e32 v71, v77, v70
	v_mul_f32_e32 v75, v85, v71
	v_mul_f32_e32 v76, v83, v75
	v_fma_f32 v78, v75, v83, -v76
	v_fmac_f32_e32 v78, v75, v84
	v_sub_f32_e32 v77, v77, v71
	v_add_f32_e32 v83, v70, v77
	v_add_f32_e32 v70, v76, v78
	v_sub_f32_e32 v77, v71, v70
	v_pk_add_f32 v[80:81], v[70:71], v[76:77] neg_lo:[0,1] neg_hi:[0,1]
	v_mov_b32_e32 v79, v70
	v_pk_add_f32 v[70:71], v[80:81], v[78:79] neg_lo:[0,1] neg_hi:[0,1]
	v_add_f32_e32 v71, v83, v71
	v_add_f32_e32 v70, v70, v71
	v_add_f32_e32 v71, v86, v75
	v_add_f32_e32 v70, v77, v70
	v_sub_f32_e32 v76, v71, v86
	v_mul_f32_e32 v70, v85, v70
	v_sub_f32_e32 v75, v75, v76
	v_add_f32_e32 v75, v75, v70
	v_add_f32_e32 v76, v71, v75
	v_mul_f32_e32 v78, v76, v76
	v_fmamk_f32 v70, v78, 0x3e9b6dac, v191
	v_fmaak_f32 v169, v78, v70, 0x3f2aaada
	v_cvt_f32_i32_e32 v70, v82
	v_sub_f32_e32 v71, v76, v71
	v_sub_f32_e32 v71, v75, v71
	v_ldexp_f32 v75, v71, 1
	v_mul_f32_e32 v71, v76, v78
	v_pk_mul_f32 v[78:79], v[70:71], v[168:169]
	v_ldexp_f32 v77, v76, 1
	v_fma_f32 v76, v70, s8, -v78
	v_fmac_f32_e32 v76, 0xb102e308, v70
	v_pk_add_f32 v[70:71], v[78:79], v[76:77]
	v_mov_b32_e32 v80, v78
	v_sub_f32_e32 v77, v71, v77
	v_sub_f32_e32 v77, v79, v77
	v_add_f32_e32 v81, v75, v77
	v_pk_add_f32 v[78:79], v[70:71], v[78:79] neg_lo:[0,1] neg_hi:[0,1]
	v_pk_add_f32 v[82:83], v[70:71], v[80:81]
	v_mov_b32_e32 v77, v70
	v_mov_b32_e32 v79, v83
	v_pk_add_f32 v[84:85], v[76:77], v[78:79] neg_lo:[0,1] neg_hi:[0,1]
	v_pk_add_f32 v[76:77], v[76:77], v[78:79]
	v_mov_b32_e32 v80, v81
	v_pk_add_f32 v[78:79], v[76:77], v[70:71] op_sel:[1,0] op_sel_hi:[0,1] neg_lo:[0,1] neg_hi:[0,1]
	v_pk_add_f32 v[86:87], v[82:83], v[78:79] op_sel_hi:[1,0] neg_lo:[0,1] neg_hi:[0,1]
	v_mov_b32_e32 v82, v83
	v_mov_b32_e32 v83, v77
	v_pk_mov_b32 v[78:79], v[70:71], v[78:79] op_sel:[1,0]
	v_mov_b32_e32 v81, v70
	v_pk_add_f32 v[78:79], v[82:83], v[78:79] neg_lo:[0,1] neg_hi:[0,1]
	v_mov_b32_e32 v86, v84
	v_pk_add_f32 v[70:71], v[80:81], v[78:79] neg_lo:[0,1] neg_hi:[0,1]
	v_mov_b32_e32 v85, v77
	v_pk_add_f32 v[78:79], v[86:87], v[70:71]
	v_pk_add_f32 v[80:81], v[78:79], v[78:79] op_sel:[0,1] op_sel_hi:[1,0]
	v_pk_add_f32 v[76:77], v[76:77], v[80:81] op_sel:[1,0] op_sel_hi:[0,1]
	v_mov_b32_e32 v79, v76
	v_pk_add_f32 v[82:83], v[78:79], v[84:85] neg_lo:[0,1] neg_hi:[0,1]
	v_mov_b32_e32 v71, v80
	v_sub_f32_e32 v75, v78, v82
	v_pk_add_f32 v[70:71], v[70:71], v[82:83] neg_lo:[0,1] neg_hi:[0,1]
	v_sub_f32_e32 v75, v84, v75
	v_add_f32_e32 v70, v70, v75
	v_add_f32_e32 v70, v70, v71
	v_add_f32_e32 v70, v76, v70
	v_mov_b32_e32 v77, v224
	v_mov_b32_e32 v76, v225
	v_cndmask_b32_e32 v70, v199, v70, vcc
	v_cmp_ngt_f32_e32 vcc, -1.0, v73
	v_add_f32_e32 v48, v48, v77
	v_mul_f32_e32 v48, 0xbfb8aa3b, v48
	v_exp_f32_e32 v48, v48
	v_cndmask_b32_e32 v70, v200, v70, vcc
	v_cmp_neq_f32_e32 vcc, -1.0, v73
	v_add_f32_e32 v32, v32, v76
	v_add_f32_e32 v48, 1.0, v48
	v_rcp_f32_e32 v48, v48
	v_cndmask_b32_e32 v70, v201, v70, vcc
	v_cmp_lt_f32_e64 vcc, |v73|, s10
	v_mul_f32_e32 v32, 0xbfb8aa3b, v32
	v_exp_f32_e32 v32, v32
	v_cndmask_b32_e32 v70, v70, v73, vcc
	v_mul_f32_e32 v75, 0xc1000000, v70
	v_mul_f32_e32 v48, v48, v75
	v_mul_f32_e32 v66, 0x3fb8aa3b, v48
	v_add_f32_e32 v48, v48, v48
	v_exp_f32_e32 v70, v66
	v_mul_f32_e32 v66, 0x3fb8aa3b, v48
	v_rndne_f32_e32 v66, v66
	v_fmamk_f32 v67, v66, 0xbf317218, v48
	v_fmac_f32_e32 v67, 0x3102e308, v66
	v_fmamk_f32 v71, v67, 0x395133b1, v192
	v_cmp_eq_f32_e32 vcc, s20, v66
	v_cvt_i32_f32_e32 v66, v66
	v_fmaak_f32 v71, v67, v71, 0x3c0887f9
	v_fmaak_f32 v71, v67, v71, 0x3d2aaa81
	v_fmaak_f32 v71, v67, v71, 0x3e2aaaab
	v_fma_f32 v71, v67, v71, 0.5
	v_ldexp_f32 v66, 1.0, v66
	v_mul_f32_e32 v71, v67, v71
	v_cndmask_b32_e32 v66, v66, v202, vcc
	v_fmac_f32_e32 v67, v67, v71
	v_add_f32_e32 v71, -1.0, v66
	v_fmac_f32_e32 v71, v66, v67
	v_add_f32_e32 v66, v71, v71
	v_cndmask_b32_e32 v66, v71, v66, vcc
	v_cmp_nlt_f32_e32 vcc, s21, v48
	v_add_f32_e32 v32, 1.0, v32
	v_rcp_f32_e32 v32, v32
	v_cndmask_b32_e64 v66, v201, -v66, vcc
	v_cmp_gt_f32_e32 vcc, s22, v66
	v_mul_f32_e32 v67, 0x4f800000, v66
	v_add_f32_e32 v33, v33, v76
	v_cndmask_b32_e32 v66, v66, v67, vcc
	v_sqrt_f32_e32 v67, v66
	v_mul_f32_e32 v33, 0xbfb8aa3b, v33
	v_exp_f32_e32 v33, v33
	v_add_f32_e32 v34, v34, v76
	v_add_u32_e32 v71, -1, v67
	v_fma_f32 v73, -v71, v67, v66
	v_cmp_ge_f32_e64 s[0:1], 0, v73
	v_add_u32_e32 v73, 1, v67
	v_add_f32_e32 v33, 1.0, v33
	v_cndmask_b32_e64 v71, v67, v71, s[0:1]
	v_fma_f32 v67, -v73, v67, v66
	v_cmp_lt_f32_e64 s[0:1], 0, v67
	v_rcp_f32_e32 v33, v33
	v_mul_f32_e32 v34, 0xbfb8aa3b, v34
	v_cndmask_b32_e64 v67, v71, v73, s[0:1]
	v_mul_f32_e32 v71, 0x37800000, v67
	v_cndmask_b32_e32 v67, v67, v71, vcc
	v_cmp_class_f32_e32 vcc, v66, v193
	v_exp_f32_e32 v34, v34
	s_nop 0
	v_cndmask_b32_e32 v66, v67, v66, vcc
	v_cmp_ngt_f32_e32 vcc, s23, v48
	v_add_f32_e32 v34, 1.0, v34
	v_rcp_f32_e32 v34, v34
	v_cndmask_b32_e32 v48, 1.0, v66, vcc
	v_mul_f32_e32 v48, v32, v48
	v_and_b32_e32 v32, 0x100, v68
	v_or3_b32 v32, v69, v74, v32
	v_lshl_add_u32 v73, v32, 2, 0
	v_add_u32_e32 v32, 0x9000, v73
	ds_read2_b32 v[66:67], v32 offset1:32
	s_waitcnt lgkmcnt(0)
	v_mul_f32_e32 v48, v66, v48
	ds_write_b32 v73, v70
	ds_write_b32 v73, v48 offset:36864
	v_add_f32_e32 v48, v49, v77
	v_mul_f32_e32 v48, 0xbfb8aa3b, v48
	v_exp_f32_e32 v48, v48
	s_nop 0
	v_add_f32_e32 v48, 1.0, v48
	v_rcp_f32_e32 v48, v48
	s_nop 0
	v_mul_f32_e32 v48, v48, v75
	v_mul_f32_e32 v49, 0x3fb8aa3b, v48
	v_add_f32_e32 v48, v48, v48
	v_exp_f32_e32 v66, v49
	v_mul_f32_e32 v49, 0x3fb8aa3b, v48
	v_rndne_f32_e32 v49, v49
	v_fmamk_f32 v68, v49, 0xbf317218, v48
	v_fmac_f32_e32 v68, 0x3102e308, v49
	v_fmamk_f32 v69, v68, 0x395133b1, v192
	v_cmp_eq_f32_e32 vcc, s20, v49
	v_cvt_i32_f32_e32 v49, v49
	v_fmaak_f32 v69, v68, v69, 0x3c0887f9
	v_fmaak_f32 v69, v68, v69, 0x3d2aaa81
	v_fmaak_f32 v69, v68, v69, 0x3e2aaaab
	v_fma_f32 v69, v68, v69, 0.5
	v_ldexp_f32 v49, 1.0, v49
	v_mul_f32_e32 v69, v68, v69
	v_cndmask_b32_e32 v49, v49, v202, vcc
	v_fmac_f32_e32 v68, v68, v69
	v_add_f32_e32 v69, -1.0, v49
	v_fmac_f32_e32 v69, v49, v68
	v_add_f32_e32 v49, v69, v69
	v_cndmask_b32_e32 v49, v69, v49, vcc
	v_cmp_nlt_f32_e32 vcc, s21, v48
	s_nop 1
	v_cndmask_b32_e64 v49, v201, -v49, vcc
	v_cmp_gt_f32_e32 vcc, s22, v49
	v_mul_f32_e32 v68, 0x4f800000, v49
	s_nop 0
	v_cndmask_b32_e32 v49, v49, v68, vcc
	v_sqrt_f32_e32 v68, v49
	s_nop 0
	v_add_u32_e32 v69, -1, v68
	v_fma_f32 v70, -v69, v68, v49
	v_cmp_ge_f32_e64 s[0:1], 0, v70
	v_add_u32_e32 v70, 1, v68
	s_nop 0
	v_cndmask_b32_e64 v69, v68, v69, s[0:1]
	v_fma_f32 v68, -v70, v68, v49
	v_cmp_lt_f32_e64 s[0:1], 0, v68
	s_nop 1
	v_cndmask_b32_e64 v68, v69, v70, s[0:1]
	v_mul_f32_e32 v69, 0x37800000, v68
	v_cndmask_b32_e32 v68, v68, v69, vcc
	v_cmp_class_f32_e32 vcc, v49, v193
	s_nop 1
	v_cndmask_b32_e32 v49, v68, v49, vcc
	v_cmp_ngt_f32_e32 vcc, s23, v48
	s_nop 1
	v_cndmask_b32_e32 v48, 1.0, v49, vcc
	v_mul_f32_e32 v33, v33, v48
	ds_read2_b32 v[48:49], v32 offset0:64 offset1:96
	s_waitcnt lgkmcnt(0)
	v_mul_f32_e32 v33, v48, v33
	ds_write_b32 v73, v66 offset:256
	ds_write_b32 v73, v33 offset:37120
	v_add_f32_e32 v33, v50, v77
	v_mul_f32_e32 v33, 0xbfb8aa3b, v33
	v_exp_f32_e32 v33, v33
	s_nop 0
	v_add_f32_e32 v33, 1.0, v33
	v_rcp_f32_e32 v33, v33
	s_nop 0
	v_mul_f32_e32 v33, v33, v75
	v_mul_f32_e32 v48, 0x3fb8aa3b, v33
	v_add_f32_e32 v33, v33, v33
	v_mul_f32_e32 v50, 0x3fb8aa3b, v33
	v_rndne_f32_e32 v50, v50
	v_fmamk_f32 v66, v50, 0xbf317218, v33
	v_fmac_f32_e32 v66, 0x3102e308, v50
	v_fmamk_f32 v68, v66, 0x395133b1, v192
	v_cmp_eq_f32_e32 vcc, s20, v50
	v_cvt_i32_f32_e32 v50, v50
	v_fmaak_f32 v68, v66, v68, 0x3c0887f9
	v_fmaak_f32 v68, v66, v68, 0x3d2aaa81
	v_fmaak_f32 v68, v66, v68, 0x3e2aaaab
	v_fma_f32 v68, v66, v68, 0.5
	v_ldexp_f32 v50, 1.0, v50
	v_mul_f32_e32 v68, v66, v68
	v_cndmask_b32_e32 v50, v50, v202, vcc
	v_fmac_f32_e32 v66, v66, v68
	v_add_f32_e32 v68, -1.0, v50
	v_fmac_f32_e32 v68, v50, v66
	v_add_f32_e32 v50, v68, v68
	v_cndmask_b32_e32 v50, v68, v50, vcc
	v_cmp_nlt_f32_e32 vcc, s21, v33
	v_exp_f32_e32 v48, v48
	s_nop 0
	v_cndmask_b32_e64 v50, v201, -v50, vcc
	v_cmp_gt_f32_e32 vcc, s22, v50
	v_mul_f32_e32 v66, 0x4f800000, v50
	s_nop 0
	v_cndmask_b32_e32 v50, v50, v66, vcc
	v_sqrt_f32_e32 v66, v50
	s_nop 0
	v_add_u32_e32 v68, -1, v66
	v_fma_f32 v69, -v68, v66, v50
	v_cmp_ge_f32_e64 s[0:1], 0, v69
	v_add_u32_e32 v69, 1, v66
	s_nop 0
	v_cndmask_b32_e64 v68, v66, v68, s[0:1]
	v_fma_f32 v66, -v69, v66, v50
	v_cmp_lt_f32_e64 s[0:1], 0, v66
	s_nop 1
	v_cndmask_b32_e64 v66, v68, v69, s[0:1]
	v_mul_f32_e32 v68, 0x37800000, v66
	v_cndmask_b32_e32 v66, v66, v68, vcc
	ds_read2_b32 v[68:69], v32 offset0:128 offset1:160
	v_cmp_class_f32_e32 vcc, v50, v193
	s_nop 1
	v_cndmask_b32_e32 v50, v66, v50, vcc
	v_cmp_ngt_f32_e32 vcc, s23, v33
	s_nop 1
	v_cndmask_b32_e32 v33, 1.0, v50, vcc
	v_mul_f32_e32 v33, v34, v33
	s_waitcnt lgkmcnt(0)
	v_mul_f32_e32 v33, v68, v33
	ds_write_b32 v73, v48 offset:512
	ds_write_b32 v73, v33 offset:37376
	v_add_f32_e32 v33, v51, v77
	v_mul_f32_e32 v33, 0xbfb8aa3b, v33
	v_exp_f32_e32 v33, v33
	v_add_f32_e32 v34, v35, v76
	v_mul_f32_e32 v34, 0xbfb8aa3b, v34
	v_exp_f32_e32 v34, v34
	v_add_f32_e32 v33, 1.0, v33
	v_rcp_f32_e32 v33, v33
	v_add_f32_e32 v34, 1.0, v34
	v_rcp_f32_e32 v34, v34
	v_mul_f32_e32 v33, v33, v75
	v_mul_f32_e32 v35, 0x3fb8aa3b, v33
	v_add_f32_e32 v33, v33, v33
	v_mul_f32_e32 v48, 0x3fb8aa3b, v33
	v_rndne_f32_e32 v48, v48
	v_fmamk_f32 v50, v48, 0xbf317218, v33
	v_fmac_f32_e32 v50, 0x3102e308, v48
	v_fmamk_f32 v51, v50, 0x395133b1, v192
	v_cmp_eq_f32_e32 vcc, s20, v48
	v_cvt_i32_f32_e32 v48, v48
	v_fmaak_f32 v51, v50, v51, 0x3c0887f9
	v_fmaak_f32 v51, v50, v51, 0x3d2aaa81
	v_fmaak_f32 v51, v50, v51, 0x3e2aaaab
	v_fma_f32 v51, v50, v51, 0.5
	v_ldexp_f32 v48, 1.0, v48
	v_mul_f32_e32 v51, v50, v51
	v_cndmask_b32_e32 v48, v48, v202, vcc
	v_fmac_f32_e32 v50, v50, v51
	v_add_f32_e32 v51, -1.0, v48
	v_fmac_f32_e32 v51, v48, v50
	v_add_f32_e32 v48, v51, v51
	v_cndmask_b32_e32 v48, v51, v48, vcc
	v_cmp_nlt_f32_e32 vcc, s21, v33
	v_exp_f32_e32 v35, v35
	s_nop 0
	v_cndmask_b32_e64 v48, v201, -v48, vcc
	v_cmp_gt_f32_e32 vcc, s22, v48
	v_mul_f32_e32 v50, 0x4f800000, v48
	s_nop 0
	v_cndmask_b32_e32 v48, v48, v50, vcc
	v_sqrt_f32_e32 v50, v48
	s_nop 0
	v_add_u32_e32 v51, -1, v50
	v_fma_f32 v66, -v51, v50, v48
	v_cmp_ge_f32_e64 s[0:1], 0, v66
	v_add_u32_e32 v66, 1, v50
	s_nop 0
	v_cndmask_b32_e64 v51, v50, v51, s[0:1]
	v_fma_f32 v50, -v66, v50, v48
	v_cmp_lt_f32_e64 s[0:1], 0, v50
	s_nop 1
	v_cndmask_b32_e64 v50, v51, v66, s[0:1]
	v_mul_f32_e32 v51, 0x37800000, v50
	v_cndmask_b32_e32 v50, v50, v51, vcc
	v_cmp_class_f32_e32 vcc, v48, v193
	s_nop 1
	v_cndmask_b32_e32 v48, v50, v48, vcc
	ds_read2_b32 v[50:51], v32 offset0:192 offset1:224
	v_cmp_ngt_f32_e32 vcc, s23, v33
	s_nop 1
	v_cndmask_b32_e32 v33, 1.0, v48, vcc
	v_mul_f32_e32 v33, v34, v33
	s_waitcnt lgkmcnt(0)
	v_mul_f32_e32 v32, v50, v33
	ds_write_b32 v73, v35 offset:768
	ds_write_b32 v73, v32 offset:37632
	v_add_f32_e32 v32, v52, v77
	v_mul_f32_e32 v32, 0xbfb8aa3b, v32
	v_exp_f32_e32 v32, v32
	v_add_f32_e32 v33, v36, v76
	v_mul_f32_e32 v33, 0xbfb8aa3b, v33
	v_exp_f32_e32 v33, v33
	v_add_f32_e32 v32, 1.0, v32
	v_rcp_f32_e32 v32, v32
	v_add_f32_e32 v33, 1.0, v33
	v_rcp_f32_e32 v33, v33
	v_mul_f32_e32 v32, v32, v75
	v_mul_f32_e32 v34, 0x3fb8aa3b, v32
	v_add_f32_e32 v32, v32, v32
	v_mul_f32_e32 v35, 0x3fb8aa3b, v32
	v_rndne_f32_e32 v35, v35
	v_fmamk_f32 v36, v35, 0xbf317218, v32
	v_fmac_f32_e32 v36, 0x3102e308, v35
	v_fmamk_f32 v48, v36, 0x395133b1, v192
	v_cmp_eq_f32_e32 vcc, s20, v35
	v_cvt_i32_f32_e32 v35, v35
	v_fmaak_f32 v48, v36, v48, 0x3c0887f9
	v_fmaak_f32 v48, v36, v48, 0x3d2aaa81
	v_fmaak_f32 v48, v36, v48, 0x3e2aaaab
	v_fma_f32 v48, v36, v48, 0.5
	v_ldexp_f32 v35, 1.0, v35
	v_mul_f32_e32 v48, v36, v48
	v_cndmask_b32_e32 v35, v35, v202, vcc
	v_fmac_f32_e32 v36, v36, v48
	v_add_f32_e32 v48, -1.0, v35
	v_fmac_f32_e32 v48, v35, v36
	v_add_f32_e32 v35, v48, v48
	v_cndmask_b32_e32 v35, v48, v35, vcc
	v_cmp_nlt_f32_e32 vcc, s21, v32
	v_exp_f32_e32 v34, v34
	s_nop 0
	v_cndmask_b32_e64 v35, v201, -v35, vcc
	v_cmp_gt_f32_e32 vcc, s22, v35
	v_mul_f32_e32 v36, 0x4f800000, v35
	s_nop 0
	v_cndmask_b32_e32 v35, v35, v36, vcc
	v_sqrt_f32_e32 v36, v35
	s_nop 0
	v_add_u32_e32 v48, -1, v36
	v_fma_f32 v50, -v48, v36, v35
	v_cmp_ge_f32_e64 s[0:1], 0, v50
	v_add_u32_e32 v50, 1, v36
	s_nop 0
	v_cndmask_b32_e64 v48, v36, v48, s[0:1]
	v_fma_f32 v36, -v50, v36, v35
	v_cmp_lt_f32_e64 s[0:1], 0, v36
	s_nop 1
	v_cndmask_b32_e64 v36, v48, v50, s[0:1]
	v_mul_f32_e32 v48, 0x37800000, v36
	v_cndmask_b32_e32 v36, v36, v48, vcc
	v_cmp_class_f32_e32 vcc, v35, v193
	s_nop 1
	v_cndmask_b32_e32 v35, v36, v35, vcc
	v_cmp_ngt_f32_e32 vcc, s23, v32
	s_nop 1
	v_cndmask_b32_e32 v32, 1.0, v35, vcc
	v_mul_f32_e32 v33, v33, v32
	v_add_u32_e32 v32, 0x9800, v73
	ds_read2_b32 v[70:71], v32 offset1:32
	s_waitcnt lgkmcnt(0)
	v_mul_f32_e32 v33, v70, v33
	ds_write_b32 v73, v34 offset:2048
	ds_write_b32 v73, v33 offset:38912
	v_add_f32_e32 v33, v53, v77
	v_mul_f32_e32 v33, 0xbfb8aa3b, v33
	v_exp_f32_e32 v33, v33
	v_add_f32_e32 v34, v37, v76
	v_mul_f32_e32 v34, 0xbfb8aa3b, v34
	v_exp_f32_e32 v34, v34
	v_add_f32_e32 v33, 1.0, v33
	v_rcp_f32_e32 v33, v33
	v_add_f32_e32 v34, 1.0, v34
	v_rcp_f32_e32 v34, v34
	v_mul_f32_e32 v33, v33, v75
	v_mul_f32_e32 v35, 0x3fb8aa3b, v33
	v_add_f32_e32 v33, v33, v33
	v_mul_f32_e32 v36, 0x3fb8aa3b, v33
	v_rndne_f32_e32 v36, v36
	v_fmamk_f32 v37, v36, 0xbf317218, v33
	v_fmac_f32_e32 v37, 0x3102e308, v36
	v_fmamk_f32 v48, v37, 0x395133b1, v192
	v_cmp_eq_f32_e32 vcc, s20, v36
	v_cvt_i32_f32_e32 v36, v36
	v_fmaak_f32 v48, v37, v48, 0x3c0887f9
	v_fmaak_f32 v48, v37, v48, 0x3d2aaa81
	v_fmaak_f32 v48, v37, v48, 0x3e2aaaab
	v_fma_f32 v48, v37, v48, 0.5
	v_ldexp_f32 v36, 1.0, v36
	v_mul_f32_e32 v48, v37, v48
	v_cndmask_b32_e32 v36, v36, v202, vcc
	v_fmac_f32_e32 v37, v37, v48
	v_add_f32_e32 v48, -1.0, v36
	v_fmac_f32_e32 v48, v36, v37
	v_add_f32_e32 v36, v48, v48
	v_cndmask_b32_e32 v36, v48, v36, vcc
	v_cmp_nlt_f32_e32 vcc, s21, v33
	v_exp_f32_e32 v35, v35
	s_nop 0
	v_cndmask_b32_e64 v36, v201, -v36, vcc
	v_cmp_gt_f32_e32 vcc, s22, v36
	v_mul_f32_e32 v37, 0x4f800000, v36
	s_nop 0
	v_cndmask_b32_e32 v36, v36, v37, vcc
	v_sqrt_f32_e32 v37, v36
	s_nop 0
	v_add_u32_e32 v48, -1, v37
	v_fma_f32 v50, -v48, v37, v36
	v_cmp_ge_f32_e64 s[0:1], 0, v50
	v_add_u32_e32 v50, 1, v37
	s_nop 0
	v_cndmask_b32_e64 v48, v37, v48, s[0:1]
	v_fma_f32 v37, -v50, v37, v36
	v_cmp_lt_f32_e64 s[0:1], 0, v37
	s_nop 1
	v_cndmask_b32_e64 v37, v48, v50, s[0:1]
	v_mul_f32_e32 v48, 0x37800000, v37
	v_cndmask_b32_e32 v37, v37, v48, vcc
	v_cmp_class_f32_e32 vcc, v36, v193
	s_nop 1
	v_cndmask_b32_e32 v36, v37, v36, vcc
	v_cmp_ngt_f32_e32 vcc, s23, v33
	s_nop 1
	v_cndmask_b32_e32 v33, 1.0, v36, vcc
	ds_read2_b32 v[36:37], v32 offset0:64 offset1:96
	v_mul_f32_e32 v33, v34, v33
	v_add_f32_e32 v34, v38, v76
	v_mul_f32_e32 v34, 0xbfb8aa3b, v34
	v_exp_f32_e32 v34, v34
	s_waitcnt lgkmcnt(0)
	v_mul_f32_e32 v33, v36, v33
	ds_write_b32 v73, v35 offset:2304
	ds_write_b32 v73, v33 offset:39168
	v_add_f32_e32 v33, v54, v77
	v_mul_f32_e32 v33, 0xbfb8aa3b, v33
	v_exp_f32_e32 v33, v33
	v_add_f32_e32 v34, 1.0, v34
	v_rcp_f32_e32 v34, v34
	ds_read2_b32 v[52:53], v32 offset0:128 offset1:160
	v_add_f32_e32 v33, 1.0, v33
	v_rcp_f32_e32 v33, v33
	s_nop 0
	v_mul_f32_e32 v33, v33, v75
	v_mul_f32_e32 v35, 0x3fb8aa3b, v33
	v_add_f32_e32 v33, v33, v33
	v_mul_f32_e32 v36, 0x3fb8aa3b, v33
	v_rndne_f32_e32 v36, v36
	v_fmamk_f32 v38, v36, 0xbf317218, v33
	v_fmac_f32_e32 v38, 0x3102e308, v36
	v_fmamk_f32 v48, v38, 0x395133b1, v192
	v_cmp_eq_f32_e32 vcc, s20, v36
	v_cvt_i32_f32_e32 v36, v36
	v_fmaak_f32 v48, v38, v48, 0x3c0887f9
	v_fmaak_f32 v48, v38, v48, 0x3d2aaa81
	v_fmaak_f32 v48, v38, v48, 0x3e2aaaab
	v_fma_f32 v48, v38, v48, 0.5
	v_ldexp_f32 v36, 1.0, v36
	v_mul_f32_e32 v48, v38, v48
	v_cndmask_b32_e32 v36, v36, v202, vcc
	v_fmac_f32_e32 v38, v38, v48
	v_add_f32_e32 v48, -1.0, v36
	v_fmac_f32_e32 v48, v36, v38
	v_add_f32_e32 v36, v48, v48
	v_cndmask_b32_e32 v36, v48, v36, vcc
	v_cmp_nlt_f32_e32 vcc, s21, v33
	v_exp_f32_e32 v35, v35
	s_nop 0
	v_cndmask_b32_e64 v36, v201, -v36, vcc
	v_cmp_gt_f32_e32 vcc, s22, v36
	v_mul_f32_e32 v38, 0x4f800000, v36
	s_nop 0
	v_cndmask_b32_e32 v36, v36, v38, vcc
	v_sqrt_f32_e32 v38, v36
	s_nop 0
	v_add_u32_e32 v48, -1, v38
	v_fma_f32 v50, -v48, v38, v36
	v_cmp_ge_f32_e64 s[0:1], 0, v50
	v_add_u32_e32 v50, 1, v38
	s_nop 0
	v_cndmask_b32_e64 v48, v38, v48, s[0:1]
	v_fma_f32 v38, -v50, v38, v36
	v_cmp_lt_f32_e64 s[0:1], 0, v38
	s_nop 1
	v_cndmask_b32_e64 v38, v48, v50, s[0:1]
	v_mul_f32_e32 v48, 0x37800000, v38
	v_cndmask_b32_e32 v38, v38, v48, vcc
	v_cmp_class_f32_e32 vcc, v36, v193
	s_nop 1
	v_cndmask_b32_e32 v36, v38, v36, vcc
	v_cmp_ngt_f32_e32 vcc, s23, v33
	s_nop 1
	v_cndmask_b32_e32 v33, 1.0, v36, vcc
	v_mul_f32_e32 v33, v34, v33
	s_waitcnt lgkmcnt(0)
	v_mul_f32_e32 v33, v52, v33
	ds_write_b32 v73, v35 offset:2560
	ds_write_b32 v73, v33 offset:39424
	v_add_f32_e32 v33, v55, v77
	v_mul_f32_e32 v33, 0xbfb8aa3b, v33
	v_exp_f32_e32 v33, v33
	v_add_f32_e32 v34, v39, v76
	v_mul_f32_e32 v34, 0xbfb8aa3b, v34
	v_exp_f32_e32 v34, v34
	v_add_f32_e32 v33, 1.0, v33
	v_rcp_f32_e32 v33, v33
	v_add_f32_e32 v34, 1.0, v34
	v_rcp_f32_e32 v34, v34
	v_mul_f32_e32 v33, v33, v75
	v_mul_f32_e32 v35, 0x3fb8aa3b, v33
	v_add_f32_e32 v33, v33, v33
	v_mul_f32_e32 v36, 0x3fb8aa3b, v33
	v_rndne_f32_e32 v36, v36
	v_fmamk_f32 v38, v36, 0xbf317218, v33
	v_fmac_f32_e32 v38, 0x3102e308, v36
	v_fmamk_f32 v39, v38, 0x395133b1, v192
	v_cmp_eq_f32_e32 vcc, s20, v36
	v_cvt_i32_f32_e32 v36, v36
	v_fmaak_f32 v39, v38, v39, 0x3c0887f9
	v_fmaak_f32 v39, v38, v39, 0x3d2aaa81
	v_fmaak_f32 v39, v38, v39, 0x3e2aaaab
	v_fma_f32 v39, v38, v39, 0.5
	v_ldexp_f32 v36, 1.0, v36
	v_mul_f32_e32 v39, v38, v39
	v_cndmask_b32_e32 v36, v36, v202, vcc
	v_fmac_f32_e32 v38, v38, v39
	v_add_f32_e32 v39, -1.0, v36
	v_fmac_f32_e32 v39, v36, v38
	v_add_f32_e32 v36, v39, v39
	v_cndmask_b32_e32 v36, v39, v36, vcc
	v_cmp_nlt_f32_e32 vcc, s21, v33
	v_exp_f32_e32 v35, v35
	s_nop 0
	v_cndmask_b32_e64 v36, v201, -v36, vcc
	v_cmp_gt_f32_e32 vcc, s22, v36
	v_mul_f32_e32 v38, 0x4f800000, v36
	s_nop 0
	v_cndmask_b32_e32 v36, v36, v38, vcc
	v_sqrt_f32_e32 v38, v36
	s_nop 0
	v_add_u32_e32 v39, -1, v38
	v_fma_f32 v48, -v39, v38, v36
	v_cmp_ge_f32_e64 s[0:1], 0, v48
	v_add_u32_e32 v48, 1, v38
	s_nop 0
	v_cndmask_b32_e64 v39, v38, v39, s[0:1]
	v_fma_f32 v38, -v48, v38, v36
	v_cmp_lt_f32_e64 s[0:1], 0, v38
	s_nop 1
	v_cndmask_b32_e64 v38, v39, v48, s[0:1]
	v_mul_f32_e32 v39, 0x37800000, v38
	v_cndmask_b32_e32 v38, v38, v39, vcc
	v_cmp_class_f32_e32 vcc, v36, v193
	s_nop 1
	v_cndmask_b32_e32 v36, v38, v36, vcc
	ds_read2_b32 v[38:39], v32 offset0:192 offset1:224
	v_cmp_ngt_f32_e32 vcc, s23, v33
	s_nop 1
	v_cndmask_b32_e32 v33, 1.0, v36, vcc
	v_mul_f32_e32 v33, v34, v33
	s_waitcnt lgkmcnt(0)
	v_mul_f32_e32 v32, v38, v33
	ds_write_b32 v73, v35 offset:2816
	ds_write_b32 v73, v32 offset:39680
	v_add_f32_e32 v32, v56, v77
	v_mul_f32_e32 v32, 0xbfb8aa3b, v32
	v_exp_f32_e32 v32, v32
	v_add_f32_e32 v33, v40, v76
	v_mul_f32_e32 v33, 0xbfb8aa3b, v33
	v_exp_f32_e32 v33, v33
	v_add_f32_e32 v32, 1.0, v32
	v_rcp_f32_e32 v32, v32
	v_add_f32_e32 v33, 1.0, v33
	v_rcp_f32_e32 v33, v33
	v_mul_f32_e32 v32, v32, v75
	v_mul_f32_e32 v34, 0x3fb8aa3b, v32
	v_add_f32_e32 v32, v32, v32
	v_mul_f32_e32 v35, 0x3fb8aa3b, v32
	v_rndne_f32_e32 v35, v35
	v_fmamk_f32 v36, v35, 0xbf317218, v32
	v_fmac_f32_e32 v36, 0x3102e308, v35
	v_fmamk_f32 v38, v36, 0x395133b1, v192
	v_cmp_eq_f32_e32 vcc, s20, v35
	v_cvt_i32_f32_e32 v35, v35
	v_fmaak_f32 v38, v36, v38, 0x3c0887f9
	v_fmaak_f32 v38, v36, v38, 0x3d2aaa81
	v_fmaak_f32 v38, v36, v38, 0x3e2aaaab
	v_fma_f32 v38, v36, v38, 0.5
	v_ldexp_f32 v35, 1.0, v35
	v_mul_f32_e32 v38, v36, v38
	v_cndmask_b32_e32 v35, v35, v202, vcc
	v_fmac_f32_e32 v36, v36, v38
	v_add_f32_e32 v38, -1.0, v35
	v_fmac_f32_e32 v38, v35, v36
	v_add_f32_e32 v35, v38, v38
	v_cndmask_b32_e32 v35, v38, v35, vcc
	v_cmp_nlt_f32_e32 vcc, s21, v32
	v_exp_f32_e32 v34, v34
	s_nop 0
	v_cndmask_b32_e64 v35, v201, -v35, vcc
	v_cmp_gt_f32_e32 vcc, s22, v35
	v_mul_f32_e32 v36, 0x4f800000, v35
	s_nop 0
	v_cndmask_b32_e32 v35, v35, v36, vcc
	v_sqrt_f32_e32 v36, v35
	s_nop 0
	v_add_u32_e32 v38, -1, v36
	v_fma_f32 v40, -v38, v36, v35
	v_cmp_ge_f32_e64 s[0:1], 0, v40
	v_add_u32_e32 v40, 1, v36
	s_nop 0
	v_cndmask_b32_e64 v38, v36, v38, s[0:1]
	v_fma_f32 v36, -v40, v36, v35
	v_cmp_lt_f32_e64 s[0:1], 0, v36
	s_nop 1
	v_cndmask_b32_e64 v36, v38, v40, s[0:1]
	v_mul_f32_e32 v38, 0x37800000, v36
	v_cndmask_b32_e32 v36, v36, v38, vcc
	v_cmp_class_f32_e32 vcc, v35, v193
	s_nop 1
	v_cndmask_b32_e32 v35, v36, v35, vcc
	v_cmp_ngt_f32_e32 vcc, s23, v32
	s_nop 1
	v_cndmask_b32_e32 v32, 1.0, v35, vcc
	v_mul_f32_e32 v33, v33, v32
	v_add_u32_e32 v32, 0xa000, v73
	ds_read2_b32 v[54:55], v32 offset1:32
	s_waitcnt lgkmcnt(0)
	v_mul_f32_e32 v33, v54, v33
	ds_write_b32 v73, v34 offset:4096
	ds_write_b32 v73, v33 offset:40960
	v_add_f32_e32 v33, v57, v77
	v_mul_f32_e32 v33, 0xbfb8aa3b, v33
	v_exp_f32_e32 v33, v33
	v_add_f32_e32 v34, v41, v76
	v_mul_f32_e32 v34, 0xbfb8aa3b, v34
	v_exp_f32_e32 v34, v34
	v_add_f32_e32 v33, 1.0, v33
	v_rcp_f32_e32 v33, v33
	v_add_f32_e32 v34, 1.0, v34
	v_rcp_f32_e32 v34, v34
	v_mul_f32_e32 v33, v33, v75
	v_mul_f32_e32 v35, 0x3fb8aa3b, v33
	v_add_f32_e32 v33, v33, v33
	v_mul_f32_e32 v36, 0x3fb8aa3b, v33
	v_rndne_f32_e32 v36, v36
	v_fmamk_f32 v38, v36, 0xbf317218, v33
	v_fmac_f32_e32 v38, 0x3102e308, v36
	v_fmamk_f32 v40, v38, 0x395133b1, v192
	v_cmp_eq_f32_e32 vcc, s20, v36
	v_cvt_i32_f32_e32 v36, v36
	v_fmaak_f32 v40, v38, v40, 0x3c0887f9
	v_fmaak_f32 v40, v38, v40, 0x3d2aaa81
	v_fmaak_f32 v40, v38, v40, 0x3e2aaaab
	v_fma_f32 v40, v38, v40, 0.5
	v_ldexp_f32 v36, 1.0, v36
	v_mul_f32_e32 v40, v38, v40
	v_cndmask_b32_e32 v36, v36, v202, vcc
	v_fmac_f32_e32 v38, v38, v40
	v_add_f32_e32 v40, -1.0, v36
	v_fmac_f32_e32 v40, v36, v38
	v_add_f32_e32 v36, v40, v40
	v_cndmask_b32_e32 v36, v40, v36, vcc
	v_cmp_nlt_f32_e32 vcc, s21, v33
	v_exp_f32_e32 v35, v35
	s_nop 0
	v_cndmask_b32_e64 v36, v201, -v36, vcc
	v_cmp_gt_f32_e32 vcc, s22, v36
	v_mul_f32_e32 v38, 0x4f800000, v36
	s_nop 0
	v_cndmask_b32_e32 v36, v36, v38, vcc
	v_sqrt_f32_e32 v38, v36
	s_nop 0
	v_add_u32_e32 v40, -1, v38
	v_fma_f32 v41, -v40, v38, v36
	v_cmp_ge_f32_e64 s[0:1], 0, v41
	v_add_u32_e32 v41, 1, v38
	s_nop 0
	v_cndmask_b32_e64 v40, v38, v40, s[0:1]
	v_fma_f32 v38, -v41, v38, v36
	v_cmp_lt_f32_e64 s[0:1], 0, v38
	s_nop 1
	v_cndmask_b32_e64 v38, v40, v41, s[0:1]
	v_mul_f32_e32 v40, 0x37800000, v38
	v_cndmask_b32_e32 v38, v38, v40, vcc
	ds_read2_b32 v[40:41], v32 offset0:64 offset1:96
	v_cmp_class_f32_e32 vcc, v36, v193
	s_nop 1
	v_cndmask_b32_e32 v36, v38, v36, vcc
	v_cmp_ngt_f32_e32 vcc, s23, v33
	s_nop 1
	v_cndmask_b32_e32 v33, 1.0, v36, vcc
	v_mul_f32_e32 v33, v34, v33
	s_waitcnt lgkmcnt(0)
	v_mul_f32_e32 v33, v40, v33
	ds_write_b32 v73, v35 offset:4352
	ds_write_b32 v73, v33 offset:41216
	v_add_f32_e32 v33, v58, v77
	v_mul_f32_e32 v33, 0xbfb8aa3b, v33
	v_exp_f32_e32 v33, v33
	v_add_f32_e32 v34, v42, v76
	v_mul_f32_e32 v34, 0xbfb8aa3b, v34
	v_exp_f32_e32 v34, v34
	v_add_f32_e32 v33, 1.0, v33
	v_rcp_f32_e32 v33, v33
	ds_read2_b32 v[56:57], v32 offset0:128 offset1:160
	v_add_f32_e32 v34, 1.0, v34
	v_rcp_f32_e32 v34, v34
	v_mul_f32_e32 v33, v33, v75
	v_mul_f32_e32 v35, 0x3fb8aa3b, v33
	v_add_f32_e32 v33, v33, v33
	v_mul_f32_e32 v36, 0x3fb8aa3b, v33
	v_rndne_f32_e32 v36, v36
	v_fmamk_f32 v38, v36, 0xbf317218, v33
	v_fmac_f32_e32 v38, 0x3102e308, v36
	v_fmamk_f32 v40, v38, 0x395133b1, v192
	v_cmp_eq_f32_e32 vcc, s20, v36
	v_cvt_i32_f32_e32 v36, v36
	v_fmaak_f32 v40, v38, v40, 0x3c0887f9
	v_fmaak_f32 v40, v38, v40, 0x3d2aaa81
	v_fmaak_f32 v40, v38, v40, 0x3e2aaaab
	v_fma_f32 v40, v38, v40, 0.5
	v_ldexp_f32 v36, 1.0, v36
	v_mul_f32_e32 v40, v38, v40
	v_cndmask_b32_e32 v36, v36, v202, vcc
	v_fmac_f32_e32 v38, v38, v40
	v_add_f32_e32 v40, -1.0, v36
	v_fmac_f32_e32 v40, v36, v38
	v_add_f32_e32 v36, v40, v40
	v_cndmask_b32_e32 v36, v40, v36, vcc
	v_cmp_nlt_f32_e32 vcc, s21, v33
	v_exp_f32_e32 v35, v35
	s_nop 0
	v_cndmask_b32_e64 v36, v201, -v36, vcc
	v_cmp_gt_f32_e32 vcc, s22, v36
	v_mul_f32_e32 v38, 0x4f800000, v36
	s_nop 0
	v_cndmask_b32_e32 v36, v36, v38, vcc
	v_sqrt_f32_e32 v38, v36
	s_nop 0
	v_add_u32_e32 v40, -1, v38
	v_fma_f32 v42, -v40, v38, v36
	v_cmp_ge_f32_e64 s[0:1], 0, v42
	v_add_u32_e32 v42, 1, v38
	s_nop 0
	v_cndmask_b32_e64 v40, v38, v40, s[0:1]
	v_fma_f32 v38, -v42, v38, v36
	v_cmp_lt_f32_e64 s[0:1], 0, v38
	s_nop 1
	v_cndmask_b32_e64 v38, v40, v42, s[0:1]
	v_mul_f32_e32 v40, 0x37800000, v38
	v_cndmask_b32_e32 v38, v38, v40, vcc
	v_cmp_class_f32_e32 vcc, v36, v193
	s_nop 1
	v_cndmask_b32_e32 v36, v38, v36, vcc
	v_cmp_ngt_f32_e32 vcc, s23, v33
	s_nop 1
	v_cndmask_b32_e32 v33, 1.0, v36, vcc
	v_mul_f32_e32 v33, v34, v33
	s_waitcnt lgkmcnt(0)
	v_mul_f32_e32 v33, v56, v33
	ds_write_b32 v73, v35 offset:4608
	ds_write_b32 v73, v33 offset:41472
	v_add_f32_e32 v33, v59, v77
	v_mul_f32_e32 v33, 0xbfb8aa3b, v33
	v_exp_f32_e32 v33, v33
	v_add_f32_e32 v34, v43, v76
	v_mul_f32_e32 v34, 0xbfb8aa3b, v34
	v_exp_f32_e32 v34, v34
	v_add_f32_e32 v33, 1.0, v33
	v_rcp_f32_e32 v33, v33
	v_add_f32_e32 v34, 1.0, v34
	v_rcp_f32_e32 v34, v34
	v_mul_f32_e32 v33, v33, v75
	v_mul_f32_e32 v35, 0x3fb8aa3b, v33
	v_add_f32_e32 v33, v33, v33
	v_mul_f32_e32 v36, 0x3fb8aa3b, v33
	v_rndne_f32_e32 v36, v36
	v_fmamk_f32 v38, v36, 0xbf317218, v33
	v_fmac_f32_e32 v38, 0x3102e308, v36
	v_fmamk_f32 v40, v38, 0x395133b1, v192
	v_cmp_eq_f32_e32 vcc, s20, v36
	v_cvt_i32_f32_e32 v36, v36
	v_fmaak_f32 v40, v38, v40, 0x3c0887f9
	v_fmaak_f32 v40, v38, v40, 0x3d2aaa81
	v_fmaak_f32 v40, v38, v40, 0x3e2aaaab
	v_fma_f32 v40, v38, v40, 0.5
	v_ldexp_f32 v36, 1.0, v36
	v_mul_f32_e32 v40, v38, v40
	v_cndmask_b32_e32 v36, v36, v202, vcc
	v_fmac_f32_e32 v38, v38, v40
	v_add_f32_e32 v40, -1.0, v36
	v_fmac_f32_e32 v40, v36, v38
	v_add_f32_e32 v36, v40, v40
	v_cndmask_b32_e32 v36, v40, v36, vcc
	v_cmp_nlt_f32_e32 vcc, s21, v33
	v_exp_f32_e32 v35, v35
	s_nop 0
	v_cndmask_b32_e64 v36, v201, -v36, vcc
	v_cmp_gt_f32_e32 vcc, s22, v36
	v_mul_f32_e32 v38, 0x4f800000, v36
	s_nop 0
	v_cndmask_b32_e32 v36, v36, v38, vcc
	v_sqrt_f32_e32 v38, v36
	s_nop 0
	v_add_u32_e32 v40, -1, v38
	v_fma_f32 v42, -v40, v38, v36
	v_cmp_ge_f32_e64 s[0:1], 0, v42
	v_add_u32_e32 v42, 1, v38
	s_nop 0
	v_cndmask_b32_e64 v40, v38, v40, s[0:1]
	v_fma_f32 v38, -v42, v38, v36
	v_cmp_lt_f32_e64 s[0:1], 0, v38
	s_nop 1
	v_cndmask_b32_e64 v38, v40, v42, s[0:1]
	v_mul_f32_e32 v40, 0x37800000, v38
	ds_read2_b32 v[42:43], v32 offset0:192 offset1:224
	v_cndmask_b32_e32 v38, v38, v40, vcc
	v_cmp_class_f32_e32 vcc, v36, v193
	s_nop 1
	v_cndmask_b32_e32 v36, v38, v36, vcc
	v_cmp_ngt_f32_e32 vcc, s23, v33
	s_nop 1
	v_cndmask_b32_e32 v33, 1.0, v36, vcc
	v_mul_f32_e32 v33, v34, v33
	s_waitcnt lgkmcnt(0)
	v_mul_f32_e32 v32, v42, v33
	ds_write_b32 v73, v35 offset:4864
	ds_write_b32 v73, v32 offset:41728
	v_add_f32_e32 v32, v60, v77
	v_mul_f32_e32 v32, 0xbfb8aa3b, v32
	v_exp_f32_e32 v32, v32
	v_add_f32_e32 v33, v44, v76
	v_mul_f32_e32 v33, 0xbfb8aa3b, v33
	v_exp_f32_e32 v33, v33
	v_add_f32_e32 v32, 1.0, v32
	v_rcp_f32_e32 v32, v32
	v_add_f32_e32 v33, 1.0, v33
	v_rcp_f32_e32 v33, v33
	v_mul_f32_e32 v32, v32, v75
	v_mul_f32_e32 v34, 0x3fb8aa3b, v32
	v_add_f32_e32 v32, v32, v32
	v_mul_f32_e32 v35, 0x3fb8aa3b, v32
	v_rndne_f32_e32 v35, v35
	v_fmamk_f32 v36, v35, 0xbf317218, v32
	v_fmac_f32_e32 v36, 0x3102e308, v35
	v_fmamk_f32 v38, v36, 0x395133b1, v192
	v_cmp_eq_f32_e32 vcc, s20, v35
	v_cvt_i32_f32_e32 v35, v35
	v_fmaak_f32 v38, v36, v38, 0x3c0887f9
	v_fmaak_f32 v38, v36, v38, 0x3d2aaa81
	v_fmaak_f32 v38, v36, v38, 0x3e2aaaab
	v_fma_f32 v38, v36, v38, 0.5
	v_ldexp_f32 v35, 1.0, v35
	v_mul_f32_e32 v38, v36, v38
	v_cndmask_b32_e32 v35, v35, v202, vcc
	v_fmac_f32_e32 v36, v36, v38
	v_add_f32_e32 v38, -1.0, v35
	v_fmac_f32_e32 v38, v35, v36
	v_add_f32_e32 v35, v38, v38
	v_cndmask_b32_e32 v35, v38, v35, vcc
	v_cmp_nlt_f32_e32 vcc, s21, v32
	v_exp_f32_e32 v34, v34
	s_nop 0
	v_cndmask_b32_e64 v35, v201, -v35, vcc
	v_cmp_gt_f32_e32 vcc, s22, v35
	v_mul_f32_e32 v36, 0x4f800000, v35
	s_nop 0
	v_cndmask_b32_e32 v35, v35, v36, vcc
	v_sqrt_f32_e32 v36, v35
	s_nop 0
	v_add_u32_e32 v38, -1, v36
	v_fma_f32 v40, -v38, v36, v35
	v_cmp_ge_f32_e64 s[0:1], 0, v40
	v_add_u32_e32 v40, 1, v36
	s_nop 0
	v_cndmask_b32_e64 v38, v36, v38, s[0:1]
	v_fma_f32 v36, -v40, v36, v35
	v_cmp_lt_f32_e64 s[0:1], 0, v36
	s_nop 1
	v_cndmask_b32_e64 v36, v38, v40, s[0:1]
	v_mul_f32_e32 v38, 0x37800000, v36
	v_cndmask_b32_e32 v36, v36, v38, vcc
	v_cmp_class_f32_e32 vcc, v35, v193
	s_nop 1
	v_cndmask_b32_e32 v35, v36, v35, vcc
	v_cmp_ngt_f32_e32 vcc, s23, v32
	s_nop 1
	v_cndmask_b32_e32 v32, 1.0, v35, vcc
	v_mul_f32_e32 v32, v33, v32
	v_add_u32_e32 v33, 0xa800, v73
	ds_read2_b32 v[58:59], v33 offset1:32
	s_waitcnt lgkmcnt(0)
	v_mul_f32_e32 v32, v58, v32
	ds_write_b32 v73, v34 offset:6144
	ds_write_b32 v73, v32 offset:43008
	v_add_f32_e32 v32, v61, v77
	v_mul_f32_e32 v32, 0xbfb8aa3b, v32
	v_exp_f32_e32 v32, v32
	v_add_f32_e32 v34, v45, v76
	v_mul_f32_e32 v34, 0xbfb8aa3b, v34
	v_exp_f32_e32 v34, v34
	v_add_f32_e32 v32, 1.0, v32
	v_rcp_f32_e32 v32, v32
	ds_read2_b32 v[44:45], v33 offset0:64 offset1:96
	v_add_f32_e32 v34, 1.0, v34
	v_rcp_f32_e32 v34, v34
	v_mul_f32_e32 v32, v32, v75
	v_mul_f32_e32 v35, 0x3fb8aa3b, v32
	v_add_f32_e32 v32, v32, v32
	v_mul_f32_e32 v36, 0x3fb8aa3b, v32
	v_rndne_f32_e32 v36, v36
	v_fmamk_f32 v38, v36, 0xbf317218, v32
	v_fmac_f32_e32 v38, 0x3102e308, v36
	v_fmamk_f32 v40, v38, 0x395133b1, v192
	v_cmp_eq_f32_e32 vcc, s20, v36
	v_cvt_i32_f32_e32 v36, v36
	v_fmaak_f32 v40, v38, v40, 0x3c0887f9
	v_fmaak_f32 v40, v38, v40, 0x3d2aaa81
	v_fmaak_f32 v40, v38, v40, 0x3e2aaaab
	v_fma_f32 v40, v38, v40, 0.5
	v_ldexp_f32 v36, 1.0, v36
	v_mul_f32_e32 v40, v38, v40
	v_cndmask_b32_e32 v36, v36, v202, vcc
	v_fmac_f32_e32 v38, v38, v40
	v_add_f32_e32 v40, -1.0, v36
	v_fmac_f32_e32 v40, v36, v38
	v_add_f32_e32 v36, v40, v40
	v_cndmask_b32_e32 v36, v40, v36, vcc
	v_cmp_nlt_f32_e32 vcc, s21, v32
	v_exp_f32_e32 v35, v35
	s_nop 0
	v_cndmask_b32_e64 v36, v201, -v36, vcc
	v_cmp_gt_f32_e32 vcc, s22, v36
	v_mul_f32_e32 v38, 0x4f800000, v36
	s_nop 0
	v_cndmask_b32_e32 v36, v36, v38, vcc
	v_sqrt_f32_e32 v38, v36
	s_nop 0
	v_add_u32_e32 v40, -1, v38
	v_fma_f32 v42, -v40, v38, v36
	v_cmp_ge_f32_e64 s[0:1], 0, v42
	v_add_u32_e32 v42, 1, v38
	s_nop 0
	v_cndmask_b32_e64 v40, v38, v40, s[0:1]
	v_fma_f32 v38, -v42, v38, v36
	v_cmp_lt_f32_e64 s[0:1], 0, v38
	s_nop 1
	v_cndmask_b32_e64 v38, v40, v42, s[0:1]
	v_mul_f32_e32 v40, 0x37800000, v38
	v_cndmask_b32_e32 v38, v38, v40, vcc
	v_cmp_class_f32_e32 vcc, v36, v193
	s_nop 1
	v_cndmask_b32_e32 v36, v38, v36, vcc
	v_cmp_ngt_f32_e32 vcc, s23, v32
	s_nop 1
	v_cndmask_b32_e32 v32, 1.0, v36, vcc
	v_mul_f32_e32 v32, v34, v32
	s_waitcnt lgkmcnt(0)
	v_mul_f32_e32 v32, v44, v32
	ds_write_b32 v73, v35 offset:6400
	ds_write_b32 v73, v32 offset:43264
	v_add_f32_e32 v32, v62, v77
	v_mul_f32_e32 v32, 0xbfb8aa3b, v32
	v_exp_f32_e32 v32, v32
	v_add_f32_e32 v34, v46, v76
	v_mul_f32_e32 v34, 0xbfb8aa3b, v34
	v_exp_f32_e32 v34, v34
	v_add_f32_e32 v32, 1.0, v32
	v_rcp_f32_e32 v32, v32
	v_add_f32_e32 v34, 1.0, v34
	v_rcp_f32_e32 v34, v34
	v_mul_f32_e32 v32, v32, v75
	v_mul_f32_e32 v35, 0x3fb8aa3b, v32
	v_add_f32_e32 v32, v32, v32
	v_exp_f32_e32 v36, v35
	v_mul_f32_e32 v35, 0x3fb8aa3b, v32
	v_rndne_f32_e32 v35, v35
	v_fmamk_f32 v38, v35, 0xbf317218, v32
	v_fmac_f32_e32 v38, 0x3102e308, v35
	v_fmamk_f32 v40, v38, 0x395133b1, v192
	v_cmp_eq_f32_e32 vcc, s20, v35
	v_cvt_i32_f32_e32 v35, v35
	v_fmaak_f32 v40, v38, v40, 0x3c0887f9
	v_fmaak_f32 v40, v38, v40, 0x3d2aaa81
	v_fmaak_f32 v40, v38, v40, 0x3e2aaaab
	v_fma_f32 v40, v38, v40, 0.5
	v_ldexp_f32 v35, 1.0, v35
	v_mul_f32_e32 v40, v38, v40
	v_cndmask_b32_e32 v35, v35, v202, vcc
	v_fmac_f32_e32 v38, v38, v40
	v_add_f32_e32 v40, -1.0, v35
	v_fmac_f32_e32 v40, v35, v38
	v_add_f32_e32 v35, v40, v40
	v_cndmask_b32_e32 v35, v40, v35, vcc
	v_cmp_nlt_f32_e32 vcc, s21, v32
	s_nop 1
	v_cndmask_b32_e64 v35, v201, -v35, vcc
	v_cmp_gt_f32_e32 vcc, s22, v35
	v_mul_f32_e32 v38, 0x4f800000, v35
	s_nop 0
	v_cndmask_b32_e32 v35, v35, v38, vcc
	v_sqrt_f32_e32 v38, v35
	s_nop 0
	v_add_u32_e32 v40, -1, v38
	v_fma_f32 v42, -v40, v38, v35
	v_cmp_ge_f32_e64 s[0:1], 0, v42
	v_add_u32_e32 v42, 1, v38
	s_nop 0
	v_cndmask_b32_e64 v40, v38, v40, s[0:1]
	v_fma_f32 v38, -v42, v38, v35
	v_cmp_lt_f32_e64 s[0:1], 0, v38
	s_nop 1
	v_cndmask_b32_e64 v38, v40, v42, s[0:1]
	v_mul_f32_e32 v40, 0x37800000, v38
	v_cndmask_b32_e32 v38, v38, v40, vcc
	v_cmp_class_f32_e32 vcc, v35, v193
	s_nop 1
	v_cndmask_b32_e32 v35, v38, v35, vcc
	v_cmp_ngt_f32_e32 vcc, s23, v32
	s_nop 1
	v_cndmask_b32_e32 v32, 1.0, v35, vcc
	v_mul_f32_e32 v32, v34, v32
	ds_read2_b32 v[34:35], v33 offset0:128 offset1:160
	s_waitcnt lgkmcnt(0)
	v_mul_f32_e32 v32, v34, v32
	ds_write_b32 v73, v36 offset:6656
	ds_write_b32 v73, v32 offset:43520
	v_add_f32_e32 v32, v63, v77
	v_mul_f32_e32 v32, 0xbfb8aa3b, v32
	v_exp_f32_e32 v32, v32
	v_add_f32_e32 v34, v47, v76
	v_mul_f32_e32 v34, 0xbfb8aa3b, v34
	v_exp_f32_e32 v34, v34
	v_add_f32_e32 v32, 1.0, v32
	v_rcp_f32_e32 v32, v32
	v_add_f32_e32 v34, 1.0, v34
	v_rcp_f32_e32 v36, v34
	v_mul_f32_e32 v32, v32, v75
	v_mul_f32_e32 v34, 0x3fb8aa3b, v32
	v_add_f32_e32 v32, v32, v32
	v_mul_f32_e32 v38, 0x3fb8aa3b, v32
	v_rndne_f32_e32 v38, v38
	v_fmamk_f32 v40, v38, 0xbf317218, v32
	v_fmac_f32_e32 v40, 0x3102e308, v38
	v_fmamk_f32 v42, v40, 0x395133b1, v192
	v_cmp_eq_f32_e32 vcc, s20, v38
	v_cvt_i32_f32_e32 v38, v38
	v_fmaak_f32 v42, v40, v42, 0x3c0887f9
	v_fmaak_f32 v42, v40, v42, 0x3d2aaa81
	v_fmaak_f32 v42, v40, v42, 0x3e2aaaab
	v_fma_f32 v42, v40, v42, 0.5
	v_ldexp_f32 v38, 1.0, v38
	v_mul_f32_e32 v42, v40, v42
	v_cndmask_b32_e32 v38, v38, v202, vcc
	v_fmac_f32_e32 v40, v40, v42
	v_add_f32_e32 v42, -1.0, v38
	v_fmac_f32_e32 v42, v38, v40
	v_add_f32_e32 v38, v42, v42
	v_cndmask_b32_e32 v38, v42, v38, vcc
	v_cmp_nlt_f32_e32 vcc, s21, v32
	s_nop 0
	v_exp_f32_e32 v34, v34
	v_cndmask_b32_e64 v38, v201, -v38, vcc
	v_cmp_gt_f32_e32 vcc, s22, v38
	v_mul_f32_e32 v40, 0x4f800000, v38
	s_nop 0
	v_cndmask_b32_e32 v38, v38, v40, vcc
	v_sqrt_f32_e32 v40, v38
	s_nop 0
	v_add_u32_e32 v42, -1, v40
	v_fma_f32 v44, -v42, v40, v38
	v_cmp_ge_f32_e64 s[0:1], 0, v44
	v_add_u32_e32 v44, 1, v40
	s_nop 0
	v_cndmask_b32_e64 v42, v40, v42, s[0:1]
	v_fma_f32 v40, -v44, v40, v38
	v_cmp_lt_f32_e64 s[0:1], 0, v40
	s_nop 1
	v_cndmask_b32_e64 v40, v42, v44, s[0:1]
	v_mul_f32_e32 v42, 0x37800000, v40
	v_cndmask_b32_e32 v40, v40, v42, vcc
	v_cmp_class_f32_e32 vcc, v38, v193
	s_nop 1
	v_cndmask_b32_e32 v38, v40, v38, vcc
	v_cmp_ngt_f32_e32 vcc, s23, v32
	s_nop 1
	v_cndmask_b32_e32 v32, 1.0, v38, vcc
	v_mul_f32_e32 v36, v36, v32
	ds_read2_b32 v[32:33], v33 offset0:192 offset1:224
	s_waitcnt lgkmcnt(0)
	v_mul_f32_e32 v32, v32, v36
	ds_write_b32 v73, v32 offset:43776
	v_mul_f32_e32 v32, 0xbfb8aa3b, v226
	v_exp_f32_e32 v32, v32
	s_nop 0
	v_add_f32_e32 v36, 1.0, v32
	v_add_f32_e32 v38, -1.0, v36
	v_sub_f32_e32 v40, v38, v36
	v_add_f32_e32 v40, 1.0, v40
	v_sub_f32_e32 v38, v32, v38
	v_add_f32_e32 v38, v38, v40
	v_frexp_mant_f32_e32 v40, v36
	v_cvt_f64_f32_e32 v[60:61], v36
	v_cmp_gt_f32_e32 vcc, s4, v40
	v_frexp_exp_i32_f64_e32 v40, v[60:61]
	s_mul_i32 s4, s11, 0x24000
	v_subbrev_co_u32_e32 v40, vcc, 0, v40, vcc
	v_sub_u32_e32 v42, 0, v40
	v_ldexp_f32 v36, v36, v42
	v_ldexp_f32 v38, v38, v42
	v_add_f32_e32 v42, -1.0, v36
	v_add_f32_e32 v48, 1.0, v36
	v_add_f32_e32 v44, 1.0, v42
	v_add_f32_e32 v50, -1.0, v48
	v_sub_f32_e32 v44, v36, v44
	v_sub_f32_e32 v36, v36, v50
	v_add_f32_e32 v36, v38, v36
	v_add_f32_e32 v44, v38, v44
	v_add_f32_e32 v38, v48, v36
	v_sub_f32_e32 v48, v38, v48
	v_sub_f32_e32 v36, v36, v48
	v_rcp_f32_e32 v48, v38
	v_add_f32_e32 v61, v42, v44
	v_sub_f32_e32 v42, v61, v42
	v_sub_f32_e32 v42, v44, v42
	v_mul_f32_e32 v44, v61, v48
	v_mul_f32_e32 v62, v38, v44
	v_fma_f32 v74, v44, v38, -v62
	v_fmac_f32_e32 v74, v44, v36
	v_add_f32_e32 v60, v62, v74
	v_sub_f32_e32 v63, v61, v60
	v_pk_add_f32 v[76:77], v[60:61], v[62:63] neg_lo:[0,1] neg_hi:[0,1]
	v_mov_b32_e32 v75, v60
	v_pk_add_f32 v[60:61], v[76:77], v[74:75] neg_lo:[0,1] neg_hi:[0,1]
	v_cmp_neq_f32_e32 vcc, s9, v32
	v_add_f32_e32 v42, v42, v61
	v_add_f32_e32 v42, v60, v42
	v_add_f32_e32 v61, v63, v42
	v_mul_f32_e32 v50, v48, v61
	v_mul_f32_e32 v62, v38, v50
	v_fma_f32 v74, v50, v38, -v62
	v_fmac_f32_e32 v74, v50, v36
	v_add_f32_e32 v60, v62, v74
	v_sub_f32_e32 v36, v63, v61
	v_sub_f32_e32 v63, v61, v60
	v_pk_add_f32 v[76:77], v[60:61], v[62:63] neg_lo:[0,1] neg_hi:[0,1]
	v_mov_b32_e32 v75, v60
	v_add_f32_e32 v36, v42, v36
	v_pk_add_f32 v[60:61], v[76:77], v[74:75] neg_lo:[0,1] neg_hi:[0,1]
	v_add_f32_e32 v38, v44, v50
	v_add_f32_e32 v36, v36, v61
	v_add_f32_e32 v36, v60, v36
	v_add_f32_e32 v36, v63, v36
	v_sub_f32_e32 v42, v38, v44
	v_mul_f32_e32 v36, v48, v36
	v_sub_f32_e32 v42, v50, v42
	v_add_f32_e32 v36, v42, v36
	v_add_f32_e32 v42, v38, v36
	v_cvt_f32_i32_e32 v60, v40
	v_mul_f32_e32 v44, v42, v42
	v_fmamk_f32 v48, v44, 0x3e9b6dac, v191
	v_fmaak_f32 v169, v44, v48, 0x3f2aaada
	v_mul_f32_e32 v61, v42, v44
	v_pk_mul_f32 v[74:75], v[60:61], v[168:169]
	v_ldexp_f32 v63, v42, 1
	v_fma_f32 v62, v60, s8, -v74
	v_fmac_f32_e32 v62, 0xb102e308, v60
	v_sub_f32_e32 v38, v42, v38
	v_pk_add_f32 v[60:61], v[74:75], v[62:63]
	v_sub_f32_e32 v36, v36, v38
	v_sub_f32_e32 v38, v61, v63
	v_ldexp_f32 v36, v36, 1
	v_sub_f32_e32 v38, v75, v38
	v_add_f32_e32 v77, v36, v38
	v_mov_b32_e32 v76, v74
	v_pk_add_f32 v[74:75], v[60:61], v[74:75] neg_lo:[0,1] neg_hi:[0,1]
	v_pk_add_f32 v[78:79], v[60:61], v[76:77]
	v_mov_b32_e32 v63, v60
	v_mov_b32_e32 v75, v79
	v_pk_add_f32 v[80:81], v[62:63], v[74:75] neg_lo:[0,1] neg_hi:[0,1]
	v_pk_add_f32 v[62:63], v[62:63], v[74:75]
	v_mov_b32_e32 v76, v77
	v_pk_add_f32 v[74:75], v[62:63], v[60:61] op_sel:[1,0] op_sel_hi:[0,1] neg_lo:[0,1] neg_hi:[0,1]
	v_pk_add_f32 v[82:83], v[78:79], v[74:75] op_sel_hi:[1,0] neg_lo:[0,1] neg_hi:[0,1]
	v_mov_b32_e32 v78, v79
	v_mov_b32_e32 v79, v63
	v_pk_mov_b32 v[74:75], v[60:61], v[74:75] op_sel:[1,0]
	v_mov_b32_e32 v77, v60
	v_pk_add_f32 v[74:75], v[78:79], v[74:75] neg_lo:[0,1] neg_hi:[0,1]
	v_mov_b32_e32 v82, v80
	v_pk_add_f32 v[60:61], v[76:77], v[74:75] neg_lo:[0,1] neg_hi:[0,1]
	v_mov_b32_e32 v81, v63
	v_pk_add_f32 v[74:75], v[82:83], v[60:61]
	v_pk_add_f32 v[76:77], v[74:75], v[74:75] op_sel:[0,1] op_sel_hi:[1,0]
	v_pk_add_f32 v[62:63], v[62:63], v[76:77] op_sel:[1,0] op_sel_hi:[0,1]
	v_mov_b32_e32 v75, v62
	v_pk_add_f32 v[78:79], v[74:75], v[80:81] neg_lo:[0,1] neg_hi:[0,1]
	v_mov_b32_e32 v61, v76
	v_sub_f32_e32 v36, v74, v78
	v_pk_add_f32 v[60:61], v[60:61], v[78:79] neg_lo:[0,1] neg_hi:[0,1]
	v_sub_f32_e32 v36, v80, v36
	v_add_f32_e32 v36, v60, v36
	v_add_f32_e32 v36, v36, v61
	v_add_f32_e32 v36, v62, v36
	v_cndmask_b32_e32 v36, v199, v36, vcc
	v_cmp_ngt_f32_e32 vcc, -1.0, v32
	s_nop 0
	s_nop 0
	v_cndmask_b32_e32 v36, v200, v36, vcc
	v_cmp_neq_f32_e32 vcc, -1.0, v32
	v_mov_b32_e32 v38, v227
	v_add_f32_e32 v0, v0, v38
	v_cndmask_b32_e32 v36, v201, v36, vcc
	v_cmp_lt_f32_e64 vcc, |v32|, s10
	v_mul_f32_e32 v0, 0xbfb8aa3b, v0
	v_exp_f32_e32 v0, v0
	v_cndmask_b32_e32 v32, v36, v32, vcc
	v_mov_b32_e32 v36, v228
	v_mul_f32_e32 v32, 0xc1000000, v32
	v_add_f32_e32 v0, 1.0, v0
	v_rcp_f32_e32 v0, v0
	v_add_f32_e32 v1, v1, v38
	v_mul_f32_e32 v1, 0xbfb8aa3b, v1
	v_exp_f32_e32 v1, v1
	v_add_f32_e32 v16, v16, v36
	v_mul_f32_e32 v16, 0xbfb8aa3b, v16
	v_exp_f32_e32 v16, v16
	v_add_f32_e32 v1, 1.0, v1
	v_rcp_f32_e32 v1, v1
	v_add_f32_e32 v16, 1.0, v16
	v_rcp_f32_e32 v16, v16
	s_nop 0
	v_mul_f32_e32 v16, v16, v32
	v_mul_f32_e32 v40, 0x3fb8aa3b, v16
	v_add_f32_e32 v16, v16, v16
	v_mul_f32_e32 v42, 0x3fb8aa3b, v16
	v_rndne_f32_e32 v42, v42
	v_fmamk_f32 v44, v42, 0xbf317218, v16
	v_fmac_f32_e32 v44, 0x3102e308, v42
	v_fmamk_f32 v46, v44, 0x395133b1, v192
	v_cmp_eq_f32_e32 vcc, s20, v42
	v_cvt_i32_f32_e32 v42, v42
	v_fmaak_f32 v46, v44, v46, 0x3c0887f9
	v_fmaak_f32 v46, v44, v46, 0x3d2aaa81
	v_fmaak_f32 v46, v44, v46, 0x3e2aaaab
	v_fma_f32 v46, v44, v46, 0.5
	v_ldexp_f32 v42, 1.0, v42
	v_mul_f32_e32 v46, v44, v46
	v_cndmask_b32_e32 v42, v42, v202, vcc
	v_fmac_f32_e32 v44, v44, v46
	v_add_f32_e32 v46, -1.0, v42
	v_fmac_f32_e32 v46, v42, v44
	v_add_f32_e32 v42, v46, v46
	v_cndmask_b32_e32 v42, v46, v42, vcc
	v_cmp_nlt_f32_e32 vcc, s21, v16
	v_exp_f32_e32 v40, v40
	s_nop 0
	v_cndmask_b32_e64 v42, v201, -v42, vcc
	v_cmp_gt_f32_e32 vcc, s22, v42
	v_mul_f32_e32 v44, 0x4f800000, v42
	s_nop 0
	v_cndmask_b32_e32 v42, v42, v44, vcc
	v_sqrt_f32_e32 v44, v42
	s_nop 0
	v_add_u32_e32 v46, -1, v44
	v_fma_f32 v47, -v46, v44, v42
	v_cmp_ge_f32_e64 s[0:1], 0, v47
	v_add_u32_e32 v47, 1, v44
	s_nop 0
	v_cndmask_b32_e64 v46, v44, v46, s[0:1]
	v_fma_f32 v44, -v47, v44, v42
	v_cmp_lt_f32_e64 s[0:1], 0, v44
	s_nop 1
	v_cndmask_b32_e64 v44, v46, v47, s[0:1]
	v_mul_f32_e32 v46, 0x37800000, v44
	v_cndmask_b32_e32 v44, v44, v46, vcc
	v_cmp_class_f32_e32 vcc, v42, v193
	s_nop 1
	v_cndmask_b32_e32 v42, v44, v42, vcc
	v_cmp_ngt_f32_e32 vcc, s23, v16
	s_nop 1
	v_cndmask_b32_e32 v16, 1.0, v42, vcc
	v_mul_f32_e32 v0, v0, v16
	v_mul_f32_e32 v0, v67, v0
	ds_write_b32 v73, v40 offset:128
	ds_write_b32 v73, v0 offset:36992
	v_add_f32_e32 v0, v17, v36
	v_mul_f32_e32 v0, 0xbfb8aa3b, v0
	v_exp_f32_e32 v0, v0
	s_nop 0
	v_add_f32_e32 v0, 1.0, v0
	v_rcp_f32_e32 v0, v0
	s_nop 0
	v_mul_f32_e32 v0, v0, v32
	v_mul_f32_e32 v16, 0x3fb8aa3b, v0
	v_add_f32_e32 v0, v0, v0
	v_mul_f32_e32 v17, 0x3fb8aa3b, v0
	v_rndne_f32_e32 v17, v17
	v_fmamk_f32 v40, v17, 0xbf317218, v0
	v_fmac_f32_e32 v40, 0x3102e308, v17
	v_fmamk_f32 v42, v40, 0x395133b1, v192
	v_cmp_eq_f32_e32 vcc, s20, v17
	v_cvt_i32_f32_e32 v17, v17
	v_fmaak_f32 v42, v40, v42, 0x3c0887f9
	v_fmaak_f32 v42, v40, v42, 0x3d2aaa81
	v_fmaak_f32 v42, v40, v42, 0x3e2aaaab
	v_fma_f32 v42, v40, v42, 0.5
	v_ldexp_f32 v17, 1.0, v17
	v_mul_f32_e32 v42, v40, v42
	v_cndmask_b32_e32 v17, v17, v202, vcc
	v_fmac_f32_e32 v40, v40, v42
	v_add_f32_e32 v42, -1.0, v17
	v_fmac_f32_e32 v42, v17, v40
	v_add_f32_e32 v17, v42, v42
	v_cndmask_b32_e32 v17, v42, v17, vcc
	v_cmp_nlt_f32_e32 vcc, s21, v0
	v_exp_f32_e32 v16, v16
	s_nop 0
	v_cndmask_b32_e64 v17, v201, -v17, vcc
	v_cmp_gt_f32_e32 vcc, s22, v17
	v_mul_f32_e32 v40, 0x4f800000, v17
	s_nop 0
	v_cndmask_b32_e32 v17, v17, v40, vcc
	v_sqrt_f32_e32 v40, v17
	s_nop 0
	v_add_u32_e32 v42, -1, v40
	v_fma_f32 v44, -v42, v40, v17
	v_cmp_ge_f32_e64 s[0:1], 0, v44
	v_add_u32_e32 v44, 1, v40
	s_nop 0
	v_cndmask_b32_e64 v42, v40, v42, s[0:1]
	v_fma_f32 v40, -v44, v40, v17
	v_cmp_lt_f32_e64 s[0:1], 0, v40
	s_nop 1
	v_cndmask_b32_e64 v40, v42, v44, s[0:1]
	v_mul_f32_e32 v42, 0x37800000, v40
	v_cndmask_b32_e32 v40, v40, v42, vcc
	v_cmp_class_f32_e32 vcc, v17, v193
	s_nop 1
	v_cndmask_b32_e32 v17, v40, v17, vcc
	v_cmp_ngt_f32_e32 vcc, s23, v0
	s_nop 1
	v_cndmask_b32_e32 v0, 1.0, v17, vcc
	v_mul_f32_e32 v0, v1, v0
	v_mul_f32_e32 v0, v49, v0
	ds_write_b32 v73, v16 offset:384
	ds_write_b32 v73, v0 offset:37248
	v_add_f32_e32 v0, v18, v36
	v_mul_f32_e32 v0, 0xbfb8aa3b, v0
	v_exp_f32_e32 v0, v0
	v_add_f32_e32 v1, v2, v38
	v_mul_f32_e32 v1, 0xbfb8aa3b, v1
	v_exp_f32_e32 v1, v1
	v_add_f32_e32 v0, 1.0, v0
	v_rcp_f32_e32 v0, v0
	v_add_f32_e32 v1, 1.0, v1
	v_rcp_f32_e32 v1, v1
	v_mul_f32_e32 v0, v0, v32
	v_mul_f32_e32 v2, 0x3fb8aa3b, v0
	v_add_f32_e32 v0, v0, v0
	v_mul_f32_e32 v16, 0x3fb8aa3b, v0
	v_rndne_f32_e32 v16, v16
	v_fmamk_f32 v17, v16, 0xbf317218, v0
	v_fmac_f32_e32 v17, 0x3102e308, v16
	v_fmamk_f32 v18, v17, 0x395133b1, v192
	v_cmp_eq_f32_e32 vcc, s20, v16
	v_cvt_i32_f32_e32 v16, v16
	v_fmaak_f32 v18, v17, v18, 0x3c0887f9
	v_fmaak_f32 v18, v17, v18, 0x3d2aaa81
	v_fmaak_f32 v18, v17, v18, 0x3e2aaaab
	v_fma_f32 v18, v17, v18, 0.5
	v_ldexp_f32 v16, 1.0, v16
	v_mul_f32_e32 v18, v17, v18
	v_cndmask_b32_e32 v16, v16, v202, vcc
	v_fmac_f32_e32 v17, v17, v18
	v_add_f32_e32 v18, -1.0, v16
	v_fmac_f32_e32 v18, v16, v17
	v_add_f32_e32 v16, v18, v18
	v_cndmask_b32_e32 v16, v18, v16, vcc
	v_cmp_nlt_f32_e32 vcc, s21, v0
	v_exp_f32_e32 v2, v2
	s_nop 0
	v_cndmask_b32_e64 v16, v201, -v16, vcc
	v_cmp_gt_f32_e32 vcc, s22, v16
	v_mul_f32_e32 v17, 0x4f800000, v16
	s_nop 0
	v_cndmask_b32_e32 v16, v16, v17, vcc
	v_sqrt_f32_e32 v17, v16
	s_nop 0
	v_add_u32_e32 v18, -1, v17
	v_fma_f32 v40, -v18, v17, v16
	v_cmp_ge_f32_e64 s[0:1], 0, v40
	v_add_u32_e32 v40, 1, v17
	s_nop 0
	v_cndmask_b32_e64 v18, v17, v18, s[0:1]
	v_fma_f32 v17, -v40, v17, v16
	v_cmp_lt_f32_e64 s[0:1], 0, v17
	s_nop 1
	v_cndmask_b32_e64 v17, v18, v40, s[0:1]
	v_mul_f32_e32 v18, 0x37800000, v17
	v_cndmask_b32_e32 v17, v17, v18, vcc
	v_cmp_class_f32_e32 vcc, v16, v193
	s_nop 1
	v_cndmask_b32_e32 v16, v17, v16, vcc
	v_cmp_ngt_f32_e32 vcc, s23, v0
	s_nop 1
	v_cndmask_b32_e32 v0, 1.0, v16, vcc
	v_mul_f32_e32 v0, v1, v0
	v_mul_f32_e32 v0, v69, v0
	ds_write_b32 v73, v2 offset:640
	ds_write_b32 v73, v0 offset:37504
	v_add_f32_e32 v0, v19, v36
	v_mul_f32_e32 v0, 0xbfb8aa3b, v0
	v_exp_f32_e32 v0, v0
	v_add_f32_e32 v1, v3, v38
	v_mul_f32_e32 v1, 0xbfb8aa3b, v1
	v_exp_f32_e32 v1, v1
	v_add_f32_e32 v0, 1.0, v0
	v_rcp_f32_e32 v0, v0
	v_add_f32_e32 v1, 1.0, v1
	v_rcp_f32_e32 v1, v1
	v_mul_f32_e32 v0, v0, v32
	v_mul_f32_e32 v2, 0x3fb8aa3b, v0
	v_add_f32_e32 v0, v0, v0
	v_mul_f32_e32 v3, 0x3fb8aa3b, v0
	v_rndne_f32_e32 v3, v3
	v_fmamk_f32 v16, v3, 0xbf317218, v0
	v_fmac_f32_e32 v16, 0x3102e308, v3
	v_fmamk_f32 v17, v16, 0x395133b1, v192
	v_cmp_eq_f32_e32 vcc, s20, v3
	v_cvt_i32_f32_e32 v3, v3
	v_fmaak_f32 v17, v16, v17, 0x3c0887f9
	v_fmaak_f32 v17, v16, v17, 0x3d2aaa81
	v_fmaak_f32 v17, v16, v17, 0x3e2aaaab
	v_fma_f32 v17, v16, v17, 0.5
	v_ldexp_f32 v3, 1.0, v3
	v_mul_f32_e32 v17, v16, v17
	v_cndmask_b32_e32 v3, v3, v202, vcc
	v_fmac_f32_e32 v16, v16, v17
	v_add_f32_e32 v17, -1.0, v3
	v_fmac_f32_e32 v17, v3, v16
	v_add_f32_e32 v3, v17, v17
	v_cndmask_b32_e32 v3, v17, v3, vcc
	v_cmp_nlt_f32_e32 vcc, s21, v0
	v_exp_f32_e32 v2, v2
	s_nop 0
	v_cndmask_b32_e64 v3, v201, -v3, vcc
	v_cmp_gt_f32_e32 vcc, s22, v3
	v_mul_f32_e32 v16, 0x4f800000, v3
	s_nop 0
	v_cndmask_b32_e32 v3, v3, v16, vcc
	v_sqrt_f32_e32 v16, v3
	s_nop 0
	v_add_u32_e32 v17, -1, v16
	v_fma_f32 v18, -v17, v16, v3
	v_cmp_ge_f32_e64 s[0:1], 0, v18
	v_add_u32_e32 v18, 1, v16
	s_nop 0
	v_cndmask_b32_e64 v17, v16, v17, s[0:1]
	v_fma_f32 v16, -v18, v16, v3
	v_cmp_lt_f32_e64 s[0:1], 0, v16
	s_nop 1
	v_cndmask_b32_e64 v16, v17, v18, s[0:1]
	v_mul_f32_e32 v17, 0x37800000, v16
	v_cndmask_b32_e32 v16, v16, v17, vcc
	v_cmp_class_f32_e32 vcc, v3, v193
	s_nop 1
	v_cndmask_b32_e32 v3, v16, v3, vcc
	v_cmp_ngt_f32_e32 vcc, s23, v0
	s_nop 1
	v_cndmask_b32_e32 v0, 1.0, v3, vcc
	v_mul_f32_e32 v0, v1, v0
	v_mul_f32_e32 v0, v51, v0
	ds_write_b32 v73, v2 offset:896
	ds_write_b32 v73, v0 offset:37760
	v_add_f32_e32 v0, v20, v36
	v_mul_f32_e32 v0, 0xbfb8aa3b, v0
	v_exp_f32_e32 v0, v0
	v_add_f32_e32 v1, v4, v38
	v_mul_f32_e32 v1, 0xbfb8aa3b, v1
	v_exp_f32_e32 v1, v1
	v_add_f32_e32 v0, 1.0, v0
	v_rcp_f32_e32 v0, v0
	v_add_f32_e32 v1, 1.0, v1
	v_rcp_f32_e32 v1, v1
	v_mul_f32_e32 v0, v0, v32
	v_mul_f32_e32 v2, 0x3fb8aa3b, v0
	v_add_f32_e32 v0, v0, v0
	v_mul_f32_e32 v3, 0x3fb8aa3b, v0
	v_rndne_f32_e32 v3, v3
	v_fmamk_f32 v4, v3, 0xbf317218, v0
	v_fmac_f32_e32 v4, 0x3102e308, v3
	v_fmamk_f32 v16, v4, 0x395133b1, v192
	v_cmp_eq_f32_e32 vcc, s20, v3
	v_cvt_i32_f32_e32 v3, v3
	v_fmaak_f32 v16, v4, v16, 0x3c0887f9
	v_fmaak_f32 v16, v4, v16, 0x3d2aaa81
	v_fmaak_f32 v16, v4, v16, 0x3e2aaaab
	v_fma_f32 v16, v4, v16, 0.5
	v_ldexp_f32 v3, 1.0, v3
	v_mul_f32_e32 v16, v4, v16
	v_cndmask_b32_e32 v3, v3, v202, vcc
	v_fmac_f32_e32 v4, v4, v16
	v_add_f32_e32 v16, -1.0, v3
	v_fmac_f32_e32 v16, v3, v4
	v_add_f32_e32 v3, v16, v16
	v_cndmask_b32_e32 v3, v16, v3, vcc
	v_cmp_nlt_f32_e32 vcc, s21, v0
	v_exp_f32_e32 v2, v2
	s_nop 0
	v_cndmask_b32_e64 v3, v201, -v3, vcc
	v_cmp_gt_f32_e32 vcc, s22, v3
	v_mul_f32_e32 v4, 0x4f800000, v3
	s_nop 0
	v_cndmask_b32_e32 v3, v3, v4, vcc
	v_sqrt_f32_e32 v4, v3
	s_nop 0
	v_add_u32_e32 v16, -1, v4
	v_fma_f32 v17, -v16, v4, v3
	v_cmp_ge_f32_e64 s[0:1], 0, v17
	v_add_u32_e32 v17, 1, v4
	s_nop 0
	v_cndmask_b32_e64 v16, v4, v16, s[0:1]
	v_fma_f32 v4, -v17, v4, v3
	v_cmp_lt_f32_e64 s[0:1], 0, v4
	s_nop 1
	v_cndmask_b32_e64 v4, v16, v17, s[0:1]
	v_mul_f32_e32 v16, 0x37800000, v4
	v_cndmask_b32_e32 v4, v4, v16, vcc
	v_cmp_class_f32_e32 vcc, v3, v193
	s_nop 1
	v_cndmask_b32_e32 v3, v4, v3, vcc
	v_cmp_ngt_f32_e32 vcc, s23, v0
	s_nop 1
	v_cndmask_b32_e32 v0, 1.0, v3, vcc
	v_mul_f32_e32 v0, v1, v0
	v_mul_f32_e32 v0, v71, v0
	ds_write_b32 v73, v2 offset:2176
	ds_write_b32 v73, v0 offset:39040
	v_add_f32_e32 v0, v21, v36
	v_mul_f32_e32 v0, 0xbfb8aa3b, v0
	v_exp_f32_e32 v0, v0
	v_add_f32_e32 v1, v5, v38
	v_mul_f32_e32 v1, 0xbfb8aa3b, v1
	v_exp_f32_e32 v1, v1
	v_add_f32_e32 v0, 1.0, v0
	v_rcp_f32_e32 v0, v0
	v_add_f32_e32 v1, 1.0, v1
	v_rcp_f32_e32 v1, v1
	v_mul_f32_e32 v0, v0, v32
	v_mul_f32_e32 v2, 0x3fb8aa3b, v0
	v_add_f32_e32 v0, v0, v0
	v_mul_f32_e32 v3, 0x3fb8aa3b, v0
	v_rndne_f32_e32 v3, v3
	v_fmamk_f32 v4, v3, 0xbf317218, v0
	v_fmac_f32_e32 v4, 0x3102e308, v3
	v_fmamk_f32 v5, v4, 0x395133b1, v192
	v_cmp_eq_f32_e32 vcc, s20, v3
	v_cvt_i32_f32_e32 v3, v3
	v_fmaak_f32 v5, v4, v5, 0x3c0887f9
	v_fmaak_f32 v5, v4, v5, 0x3d2aaa81
	v_fmaak_f32 v5, v4, v5, 0x3e2aaaab
	v_fma_f32 v5, v4, v5, 0.5
	v_ldexp_f32 v3, 1.0, v3
	v_mul_f32_e32 v5, v4, v5
	v_cndmask_b32_e32 v3, v3, v202, vcc
	v_fmac_f32_e32 v4, v4, v5
	v_add_f32_e32 v5, -1.0, v3
	v_fmac_f32_e32 v5, v3, v4
	v_add_f32_e32 v3, v5, v5
	v_cndmask_b32_e32 v3, v5, v3, vcc
	v_cmp_nlt_f32_e32 vcc, s21, v0
	v_exp_f32_e32 v2, v2
	s_nop 0
	v_cndmask_b32_e64 v3, v201, -v3, vcc
	v_cmp_gt_f32_e32 vcc, s22, v3
	v_mul_f32_e32 v4, 0x4f800000, v3
	s_nop 0
	v_cndmask_b32_e32 v3, v3, v4, vcc
	v_sqrt_f32_e32 v4, v3
	s_nop 0
	v_add_u32_e32 v5, -1, v4
	v_fma_f32 v16, -v5, v4, v3
	v_cmp_ge_f32_e64 s[0:1], 0, v16
	v_add_u32_e32 v16, 1, v4
	s_nop 0
	v_cndmask_b32_e64 v5, v4, v5, s[0:1]
	v_fma_f32 v4, -v16, v4, v3
	v_cmp_lt_f32_e64 s[0:1], 0, v4
	s_nop 1
	v_cndmask_b32_e64 v4, v5, v16, s[0:1]
	v_mul_f32_e32 v5, 0x37800000, v4
	v_cndmask_b32_e32 v4, v4, v5, vcc
	v_cmp_class_f32_e32 vcc, v3, v193
	s_nop 1
	v_cndmask_b32_e32 v3, v4, v3, vcc
	v_cmp_ngt_f32_e32 vcc, s23, v0
	s_nop 1
	v_cndmask_b32_e32 v0, 1.0, v3, vcc
	v_mul_f32_e32 v0, v1, v0
	v_mul_f32_e32 v0, v37, v0
	ds_write_b32 v73, v2 offset:2432
	ds_write_b32 v73, v0 offset:39296
	v_add_f32_e32 v0, v22, v36
	v_mul_f32_e32 v0, 0xbfb8aa3b, v0
	v_exp_f32_e32 v0, v0
	v_add_f32_e32 v1, v6, v38
	v_mul_f32_e32 v1, 0xbfb8aa3b, v1
	v_exp_f32_e32 v1, v1
	v_add_f32_e32 v0, 1.0, v0
	v_rcp_f32_e32 v0, v0
	v_add_f32_e32 v1, 1.0, v1
	v_rcp_f32_e32 v1, v1
	v_mul_f32_e32 v0, v0, v32
	v_mul_f32_e32 v2, 0x3fb8aa3b, v0
	v_add_f32_e32 v0, v0, v0
	v_mul_f32_e32 v3, 0x3fb8aa3b, v0
	v_rndne_f32_e32 v3, v3
	v_fmamk_f32 v4, v3, 0xbf317218, v0
	v_fmac_f32_e32 v4, 0x3102e308, v3
	v_fmamk_f32 v5, v4, 0x395133b1, v192
	v_cmp_eq_f32_e32 vcc, s20, v3
	v_cvt_i32_f32_e32 v3, v3
	v_fmaak_f32 v5, v4, v5, 0x3c0887f9
	v_fmaak_f32 v5, v4, v5, 0x3d2aaa81
	v_fmaak_f32 v5, v4, v5, 0x3e2aaaab
	v_fma_f32 v5, v4, v5, 0.5
	v_ldexp_f32 v3, 1.0, v3
	v_mul_f32_e32 v5, v4, v5
	v_cndmask_b32_e32 v3, v3, v202, vcc
	v_fmac_f32_e32 v4, v4, v5
	v_add_f32_e32 v5, -1.0, v3
	v_fmac_f32_e32 v5, v3, v4
	v_add_f32_e32 v3, v5, v5
	v_cndmask_b32_e32 v3, v5, v3, vcc
	v_cmp_nlt_f32_e32 vcc, s21, v0
	v_exp_f32_e32 v2, v2
	s_nop 0
	v_cndmask_b32_e64 v3, v201, -v3, vcc
	v_cmp_gt_f32_e32 vcc, s22, v3
	v_mul_f32_e32 v4, 0x4f800000, v3
	s_nop 0
	v_cndmask_b32_e32 v3, v3, v4, vcc
	v_sqrt_f32_e32 v4, v3
	s_nop 0
	v_add_u32_e32 v5, -1, v4
	v_fma_f32 v6, -v5, v4, v3
	v_cmp_ge_f32_e64 s[0:1], 0, v6
	v_add_u32_e32 v6, 1, v4
	s_nop 0
	v_cndmask_b32_e64 v5, v4, v5, s[0:1]
	v_fma_f32 v4, -v6, v4, v3
	v_cmp_lt_f32_e64 s[0:1], 0, v4
	s_nop 1
	v_cndmask_b32_e64 v4, v5, v6, s[0:1]
	v_mul_f32_e32 v5, 0x37800000, v4
	v_cndmask_b32_e32 v4, v4, v5, vcc
	v_cmp_class_f32_e32 vcc, v3, v193
	s_nop 1
	v_cndmask_b32_e32 v3, v4, v3, vcc
	v_cmp_ngt_f32_e32 vcc, s23, v0
	s_nop 1
	v_cndmask_b32_e32 v0, 1.0, v3, vcc
	v_mul_f32_e32 v0, v1, v0
	v_mul_f32_e32 v0, v53, v0
	ds_write_b32 v73, v2 offset:2688
	ds_write_b32 v73, v0 offset:39552
	v_add_f32_e32 v0, v23, v36
	v_mul_f32_e32 v0, 0xbfb8aa3b, v0
	v_exp_f32_e32 v0, v0
	v_add_f32_e32 v1, v7, v38
	v_mul_f32_e32 v1, 0xbfb8aa3b, v1
	v_exp_f32_e32 v1, v1
	v_add_f32_e32 v0, 1.0, v0
	v_rcp_f32_e32 v0, v0
	v_add_f32_e32 v1, 1.0, v1
	v_rcp_f32_e32 v1, v1
	v_mul_f32_e32 v0, v0, v32
	v_mul_f32_e32 v2, 0x3fb8aa3b, v0
	v_add_f32_e32 v0, v0, v0
	v_mul_f32_e32 v3, 0x3fb8aa3b, v0
	v_rndne_f32_e32 v3, v3
	v_fmamk_f32 v4, v3, 0xbf317218, v0
	v_fmac_f32_e32 v4, 0x3102e308, v3
	v_fmamk_f32 v5, v4, 0x395133b1, v192
	v_cmp_eq_f32_e32 vcc, s20, v3
	v_cvt_i32_f32_e32 v3, v3
	v_fmaak_f32 v5, v4, v5, 0x3c0887f9
	v_fmaak_f32 v5, v4, v5, 0x3d2aaa81
	v_fmaak_f32 v5, v4, v5, 0x3e2aaaab
	v_fma_f32 v5, v4, v5, 0.5
	v_ldexp_f32 v3, 1.0, v3
	v_mul_f32_e32 v5, v4, v5
	v_cndmask_b32_e32 v3, v3, v202, vcc
	v_fmac_f32_e32 v4, v4, v5
	v_add_f32_e32 v5, -1.0, v3
	v_fmac_f32_e32 v5, v3, v4
	v_add_f32_e32 v3, v5, v5
	v_cndmask_b32_e32 v3, v5, v3, vcc
	v_cmp_nlt_f32_e32 vcc, s21, v0
	v_exp_f32_e32 v2, v2
	s_nop 0
	v_cndmask_b32_e64 v3, v201, -v3, vcc
	v_cmp_gt_f32_e32 vcc, s22, v3
	v_mul_f32_e32 v4, 0x4f800000, v3
	s_nop 0
	v_cndmask_b32_e32 v3, v3, v4, vcc
	v_sqrt_f32_e32 v4, v3
	s_nop 0
	v_add_u32_e32 v5, -1, v4
	v_fma_f32 v6, -v5, v4, v3
	v_cmp_ge_f32_e64 s[0:1], 0, v6
	v_add_u32_e32 v6, 1, v4
	s_nop 0
	v_cndmask_b32_e64 v5, v4, v5, s[0:1]
	v_fma_f32 v4, -v6, v4, v3
	v_cmp_lt_f32_e64 s[0:1], 0, v4
	s_nop 1
	v_cndmask_b32_e64 v4, v5, v6, s[0:1]
	v_mul_f32_e32 v5, 0x37800000, v4
	v_cndmask_b32_e32 v4, v4, v5, vcc
	v_cmp_class_f32_e32 vcc, v3, v193
	s_nop 1
	v_cndmask_b32_e32 v3, v4, v3, vcc
	v_cmp_ngt_f32_e32 vcc, s23, v0
	s_nop 1
	v_cndmask_b32_e32 v0, 1.0, v3, vcc
	v_mul_f32_e32 v0, v1, v0
	v_mul_f32_e32 v0, v39, v0
	ds_write_b32 v73, v2 offset:2944
	ds_write_b32 v73, v0 offset:39808
	v_add_f32_e32 v0, v24, v36
	v_mul_f32_e32 v0, 0xbfb8aa3b, v0
	v_exp_f32_e32 v0, v0
	v_add_f32_e32 v1, v8, v38
	v_mul_f32_e32 v1, 0xbfb8aa3b, v1
	v_exp_f32_e32 v1, v1
	v_add_f32_e32 v0, 1.0, v0
	v_rcp_f32_e32 v0, v0
	v_add_f32_e32 v1, 1.0, v1
	v_rcp_f32_e32 v1, v1
	v_mul_f32_e32 v0, v0, v32
	v_mul_f32_e32 v2, 0x3fb8aa3b, v0
	v_add_f32_e32 v0, v0, v0
	v_mul_f32_e32 v3, 0x3fb8aa3b, v0
	v_rndne_f32_e32 v3, v3
	v_fmamk_f32 v4, v3, 0xbf317218, v0
	v_fmac_f32_e32 v4, 0x3102e308, v3
	v_fmamk_f32 v5, v4, 0x395133b1, v192
	v_cmp_eq_f32_e32 vcc, s20, v3
	v_cvt_i32_f32_e32 v3, v3
	v_fmaak_f32 v5, v4, v5, 0x3c0887f9
	v_fmaak_f32 v5, v4, v5, 0x3d2aaa81
	v_fmaak_f32 v5, v4, v5, 0x3e2aaaab
	v_fma_f32 v5, v4, v5, 0.5
	v_ldexp_f32 v3, 1.0, v3
	v_mul_f32_e32 v5, v4, v5
	v_cndmask_b32_e32 v3, v3, v202, vcc
	v_fmac_f32_e32 v4, v4, v5
	v_add_f32_e32 v5, -1.0, v3
	v_fmac_f32_e32 v5, v3, v4
	v_add_f32_e32 v3, v5, v5
	v_cndmask_b32_e32 v3, v5, v3, vcc
	v_cmp_nlt_f32_e32 vcc, s21, v0
	v_exp_f32_e32 v2, v2
	s_nop 0
	v_cndmask_b32_e64 v3, v201, -v3, vcc
	v_cmp_gt_f32_e32 vcc, s22, v3
	v_mul_f32_e32 v4, 0x4f800000, v3
	s_nop 0
	v_cndmask_b32_e32 v3, v3, v4, vcc
	v_sqrt_f32_e32 v4, v3
	s_nop 0
	v_add_u32_e32 v5, -1, v4
	v_fma_f32 v6, -v5, v4, v3
	v_cmp_ge_f32_e64 s[0:1], 0, v6
	v_add_u32_e32 v6, 1, v4
	s_nop 0
	v_cndmask_b32_e64 v5, v4, v5, s[0:1]
	v_fma_f32 v4, -v6, v4, v3
	v_cmp_lt_f32_e64 s[0:1], 0, v4
	s_nop 1
	v_cndmask_b32_e64 v4, v5, v6, s[0:1]
	v_mul_f32_e32 v5, 0x37800000, v4
	v_cndmask_b32_e32 v4, v4, v5, vcc
	v_cmp_class_f32_e32 vcc, v3, v193
	s_nop 1
	v_cndmask_b32_e32 v3, v4, v3, vcc
	v_cmp_ngt_f32_e32 vcc, s23, v0
	s_nop 1
	v_cndmask_b32_e32 v0, 1.0, v3, vcc
	v_mul_f32_e32 v0, v1, v0
	v_mul_f32_e32 v0, v55, v0
	ds_write_b32 v73, v2 offset:4224
	ds_write_b32 v73, v0 offset:41088
	v_add_f32_e32 v0, v25, v36
	v_mul_f32_e32 v0, 0xbfb8aa3b, v0
	v_exp_f32_e32 v0, v0
	v_add_f32_e32 v1, v9, v38
	v_mul_f32_e32 v1, 0xbfb8aa3b, v1
	v_exp_f32_e32 v1, v1
	v_add_f32_e32 v0, 1.0, v0
	v_rcp_f32_e32 v0, v0
	v_add_f32_e32 v1, 1.0, v1
	v_rcp_f32_e32 v1, v1
	v_mul_f32_e32 v0, v0, v32
	v_mul_f32_e32 v2, 0x3fb8aa3b, v0
	v_add_f32_e32 v0, v0, v0
	v_mul_f32_e32 v3, 0x3fb8aa3b, v0
	v_rndne_f32_e32 v3, v3
	v_fmamk_f32 v4, v3, 0xbf317218, v0
	v_fmac_f32_e32 v4, 0x3102e308, v3
	v_fmamk_f32 v5, v4, 0x395133b1, v192
	v_cmp_eq_f32_e32 vcc, s20, v3
	v_cvt_i32_f32_e32 v3, v3
	v_fmaak_f32 v5, v4, v5, 0x3c0887f9
	v_fmaak_f32 v5, v4, v5, 0x3d2aaa81
	v_fmaak_f32 v5, v4, v5, 0x3e2aaaab
	v_fma_f32 v5, v4, v5, 0.5
	v_ldexp_f32 v3, 1.0, v3
	v_mul_f32_e32 v5, v4, v5
	v_cndmask_b32_e32 v3, v3, v202, vcc
	v_fmac_f32_e32 v4, v4, v5
	v_add_f32_e32 v5, -1.0, v3
	v_fmac_f32_e32 v5, v3, v4
	v_add_f32_e32 v3, v5, v5
	v_cndmask_b32_e32 v3, v5, v3, vcc
	v_cmp_nlt_f32_e32 vcc, s21, v0
	v_exp_f32_e32 v2, v2
	s_nop 0
	v_cndmask_b32_e64 v3, v201, -v3, vcc
	v_cmp_gt_f32_e32 vcc, s22, v3
	v_mul_f32_e32 v4, 0x4f800000, v3
	s_nop 0
	v_cndmask_b32_e32 v3, v3, v4, vcc
	v_sqrt_f32_e32 v4, v3
	s_nop 0
	v_add_u32_e32 v5, -1, v4
	v_fma_f32 v6, -v5, v4, v3
	v_cmp_ge_f32_e64 s[0:1], 0, v6
	v_add_u32_e32 v6, 1, v4
	s_nop 0
	v_cndmask_b32_e64 v5, v4, v5, s[0:1]
	v_fma_f32 v4, -v6, v4, v3
	v_cmp_lt_f32_e64 s[0:1], 0, v4
	s_nop 1
	v_cndmask_b32_e64 v4, v5, v6, s[0:1]
	v_mul_f32_e32 v5, 0x37800000, v4
	v_cndmask_b32_e32 v4, v4, v5, vcc
	v_cmp_class_f32_e32 vcc, v3, v193
	s_nop 1
	v_cndmask_b32_e32 v3, v4, v3, vcc
	v_cmp_ngt_f32_e32 vcc, s23, v0
	s_nop 1
	v_cndmask_b32_e32 v0, 1.0, v3, vcc
	v_mul_f32_e32 v0, v1, v0
	v_mul_f32_e32 v0, v41, v0
	ds_write_b32 v73, v2 offset:4480
	ds_write_b32 v73, v0 offset:41344
	v_add_f32_e32 v0, v26, v36
	v_mul_f32_e32 v0, 0xbfb8aa3b, v0
	v_exp_f32_e32 v0, v0
	v_add_f32_e32 v1, v10, v38
	v_mul_f32_e32 v1, 0xbfb8aa3b, v1
	v_exp_f32_e32 v1, v1
	v_add_f32_e32 v0, 1.0, v0
	v_rcp_f32_e32 v0, v0
	v_add_f32_e32 v1, 1.0, v1
	v_rcp_f32_e32 v1, v1
	v_mul_f32_e32 v0, v0, v32
	v_mul_f32_e32 v2, 0x3fb8aa3b, v0
	v_add_f32_e32 v0, v0, v0
	v_mul_f32_e32 v3, 0x3fb8aa3b, v0
	v_rndne_f32_e32 v3, v3
	v_fmamk_f32 v4, v3, 0xbf317218, v0
	v_fmac_f32_e32 v4, 0x3102e308, v3
	v_fmamk_f32 v5, v4, 0x395133b1, v192
	v_cmp_eq_f32_e32 vcc, s20, v3
	v_cvt_i32_f32_e32 v3, v3
	v_fmaak_f32 v5, v4, v5, 0x3c0887f9
	v_fmaak_f32 v5, v4, v5, 0x3d2aaa81
	v_fmaak_f32 v5, v4, v5, 0x3e2aaaab
	v_fma_f32 v5, v4, v5, 0.5
	v_ldexp_f32 v3, 1.0, v3
	v_mul_f32_e32 v5, v4, v5
	v_cndmask_b32_e32 v3, v3, v202, vcc
	v_fmac_f32_e32 v4, v4, v5
	v_add_f32_e32 v5, -1.0, v3
	v_fmac_f32_e32 v5, v3, v4
	v_add_f32_e32 v3, v5, v5
	v_cndmask_b32_e32 v3, v5, v3, vcc
	v_cmp_nlt_f32_e32 vcc, s21, v0
	v_exp_f32_e32 v2, v2
	s_nop 0
	v_cndmask_b32_e64 v3, v201, -v3, vcc
	v_cmp_gt_f32_e32 vcc, s22, v3
	v_mul_f32_e32 v4, 0x4f800000, v3
	s_nop 0
	v_cndmask_b32_e32 v3, v3, v4, vcc
	v_sqrt_f32_e32 v4, v3
	s_nop 0
	v_add_u32_e32 v5, -1, v4
	v_fma_f32 v6, -v5, v4, v3
	v_cmp_ge_f32_e64 s[0:1], 0, v6
	v_add_u32_e32 v6, 1, v4
	s_nop 0
	v_cndmask_b32_e64 v5, v4, v5, s[0:1]
	v_fma_f32 v4, -v6, v4, v3
	v_cmp_lt_f32_e64 s[0:1], 0, v4
	s_nop 1
	v_cndmask_b32_e64 v4, v5, v6, s[0:1]
	v_mul_f32_e32 v5, 0x37800000, v4
	v_cndmask_b32_e32 v4, v4, v5, vcc
	v_cmp_class_f32_e32 vcc, v3, v193
	s_nop 1
	v_cndmask_b32_e32 v3, v4, v3, vcc
	v_cmp_ngt_f32_e32 vcc, s23, v0
	s_nop 1
	v_cndmask_b32_e32 v0, 1.0, v3, vcc
	v_mul_f32_e32 v0, v1, v0
	v_mul_f32_e32 v0, v57, v0
	ds_write_b32 v73, v2 offset:4736
	ds_write_b32 v73, v0 offset:41600
	v_add_f32_e32 v0, v27, v36
	v_mul_f32_e32 v0, 0xbfb8aa3b, v0
	v_exp_f32_e32 v0, v0
	v_add_f32_e32 v1, v11, v38
	v_mul_f32_e32 v1, 0xbfb8aa3b, v1
	v_exp_f32_e32 v1, v1
	v_add_f32_e32 v0, 1.0, v0
	v_rcp_f32_e32 v0, v0
	v_add_f32_e32 v1, 1.0, v1
	v_rcp_f32_e32 v1, v1
	v_mul_f32_e32 v0, v0, v32
	v_mul_f32_e32 v2, 0x3fb8aa3b, v0
	v_add_f32_e32 v0, v0, v0
	v_mul_f32_e32 v3, 0x3fb8aa3b, v0
	v_rndne_f32_e32 v3, v3
	v_fmamk_f32 v4, v3, 0xbf317218, v0
	v_fmac_f32_e32 v4, 0x3102e308, v3
	v_fmamk_f32 v5, v4, 0x395133b1, v192
	v_cmp_eq_f32_e32 vcc, s20, v3
	v_cvt_i32_f32_e32 v3, v3
	v_fmaak_f32 v5, v4, v5, 0x3c0887f9
	v_fmaak_f32 v5, v4, v5, 0x3d2aaa81
	v_fmaak_f32 v5, v4, v5, 0x3e2aaaab
	v_fma_f32 v5, v4, v5, 0.5
	v_ldexp_f32 v3, 1.0, v3
	v_mul_f32_e32 v5, v4, v5
	v_cndmask_b32_e32 v3, v3, v202, vcc
	v_fmac_f32_e32 v4, v4, v5
	v_add_f32_e32 v5, -1.0, v3
	v_fmac_f32_e32 v5, v3, v4
	v_add_f32_e32 v3, v5, v5
	v_cndmask_b32_e32 v3, v5, v3, vcc
	v_cmp_nlt_f32_e32 vcc, s21, v0
	v_exp_f32_e32 v2, v2
	s_nop 0
	v_cndmask_b32_e64 v3, v201, -v3, vcc
	v_cmp_gt_f32_e32 vcc, s22, v3
	v_mul_f32_e32 v4, 0x4f800000, v3
	s_nop 0
	v_cndmask_b32_e32 v3, v3, v4, vcc
	v_sqrt_f32_e32 v4, v3
	s_nop 0
	v_add_u32_e32 v5, -1, v4
	v_fma_f32 v6, -v5, v4, v3
	v_cmp_ge_f32_e64 s[0:1], 0, v6
	v_add_u32_e32 v6, 1, v4
	s_nop 0
	v_cndmask_b32_e64 v5, v4, v5, s[0:1]
	v_fma_f32 v4, -v6, v4, v3
	v_cmp_lt_f32_e64 s[0:1], 0, v4
	s_nop 1
	v_cndmask_b32_e64 v4, v5, v6, s[0:1]
	v_mul_f32_e32 v5, 0x37800000, v4
	v_cndmask_b32_e32 v4, v4, v5, vcc
	v_cmp_class_f32_e32 vcc, v3, v193
	s_nop 1
	v_cndmask_b32_e32 v3, v4, v3, vcc
	v_cmp_ngt_f32_e32 vcc, s23, v0
	s_nop 1
	v_cndmask_b32_e32 v0, 1.0, v3, vcc
	v_mul_f32_e32 v0, v1, v0
	v_mul_f32_e32 v0, v43, v0
	ds_write_b32 v73, v2 offset:4992
	ds_write_b32 v73, v0 offset:41856
	v_add_f32_e32 v0, v28, v36
	v_mul_f32_e32 v0, 0xbfb8aa3b, v0
	v_exp_f32_e32 v0, v0
	v_add_f32_e32 v1, v12, v38
	v_mul_f32_e32 v1, 0xbfb8aa3b, v1
	v_exp_f32_e32 v1, v1
	v_add_f32_e32 v0, 1.0, v0
	v_rcp_f32_e32 v0, v0
	v_add_f32_e32 v1, 1.0, v1
	v_rcp_f32_e32 v1, v1
	v_mul_f32_e32 v0, v0, v32
	v_mul_f32_e32 v2, 0x3fb8aa3b, v0
	v_add_f32_e32 v0, v0, v0
	v_mul_f32_e32 v3, 0x3fb8aa3b, v0
	v_rndne_f32_e32 v3, v3
	v_fmamk_f32 v4, v3, 0xbf317218, v0
	v_fmac_f32_e32 v4, 0x3102e308, v3
	v_fmamk_f32 v5, v4, 0x395133b1, v192
	v_cmp_eq_f32_e32 vcc, s20, v3
	v_cvt_i32_f32_e32 v3, v3
	v_fmaak_f32 v5, v4, v5, 0x3c0887f9
	v_fmaak_f32 v5, v4, v5, 0x3d2aaa81
	v_fmaak_f32 v5, v4, v5, 0x3e2aaaab
	v_fma_f32 v5, v4, v5, 0.5
	v_ldexp_f32 v3, 1.0, v3
	v_mul_f32_e32 v5, v4, v5
	v_cndmask_b32_e32 v3, v3, v202, vcc
	v_fmac_f32_e32 v4, v4, v5
	v_add_f32_e32 v5, -1.0, v3
	v_fmac_f32_e32 v5, v3, v4
	v_add_f32_e32 v3, v5, v5
	v_cndmask_b32_e32 v3, v5, v3, vcc
	v_cmp_nlt_f32_e32 vcc, s21, v0
	v_exp_f32_e32 v2, v2
	s_nop 0
	v_cndmask_b32_e64 v3, v201, -v3, vcc
	v_cmp_gt_f32_e32 vcc, s22, v3
	v_mul_f32_e32 v4, 0x4f800000, v3
	s_nop 0
	v_cndmask_b32_e32 v3, v3, v4, vcc
	v_sqrt_f32_e32 v4, v3
	s_nop 0
	v_add_u32_e32 v5, -1, v4
	v_fma_f32 v6, -v5, v4, v3
	v_cmp_ge_f32_e64 s[0:1], 0, v6
	v_add_u32_e32 v6, 1, v4
	s_nop 0
	v_cndmask_b32_e64 v5, v4, v5, s[0:1]
	v_fma_f32 v4, -v6, v4, v3
	v_cmp_lt_f32_e64 s[0:1], 0, v4
	s_nop 1
	v_cndmask_b32_e64 v4, v5, v6, s[0:1]
	v_mul_f32_e32 v5, 0x37800000, v4
	v_cndmask_b32_e32 v4, v4, v5, vcc
	v_cmp_class_f32_e32 vcc, v3, v193
	s_nop 1
	v_cndmask_b32_e32 v3, v4, v3, vcc
	v_cmp_ngt_f32_e32 vcc, s23, v0
	s_nop 1
	v_cndmask_b32_e32 v0, 1.0, v3, vcc
	v_mul_f32_e32 v0, v1, v0
	v_mul_f32_e32 v0, v59, v0
	ds_write_b32 v73, v2 offset:6272
	ds_write_b32 v73, v0 offset:43136
	v_add_f32_e32 v0, v29, v36
	v_mul_f32_e32 v0, 0xbfb8aa3b, v0
	v_exp_f32_e32 v0, v0
	v_add_f32_e32 v1, v13, v38
	v_mul_f32_e32 v1, 0xbfb8aa3b, v1
	v_exp_f32_e32 v1, v1
	v_add_f32_e32 v0, 1.0, v0
	v_rcp_f32_e32 v0, v0
	v_add_f32_e32 v1, 1.0, v1
	v_rcp_f32_e32 v1, v1
	v_mul_f32_e32 v0, v0, v32
	v_mul_f32_e32 v2, 0x3fb8aa3b, v0
	v_add_f32_e32 v0, v0, v0
	v_mul_f32_e32 v3, 0x3fb8aa3b, v0
	v_rndne_f32_e32 v3, v3
	v_fmamk_f32 v4, v3, 0xbf317218, v0
	v_fmac_f32_e32 v4, 0x3102e308, v3
	v_fmamk_f32 v5, v4, 0x395133b1, v192
	v_cmp_eq_f32_e32 vcc, s20, v3
	v_cvt_i32_f32_e32 v3, v3
	v_fmaak_f32 v5, v4, v5, 0x3c0887f9
	v_fmaak_f32 v5, v4, v5, 0x3d2aaa81
	v_fmaak_f32 v5, v4, v5, 0x3e2aaaab
	v_fma_f32 v5, v4, v5, 0.5
	v_ldexp_f32 v3, 1.0, v3
	v_mul_f32_e32 v5, v4, v5
	v_cndmask_b32_e32 v3, v3, v202, vcc
	v_fmac_f32_e32 v4, v4, v5
	v_add_f32_e32 v5, -1.0, v3
	v_fmac_f32_e32 v5, v3, v4
	v_add_f32_e32 v3, v5, v5
	v_cndmask_b32_e32 v3, v5, v3, vcc
	v_cmp_nlt_f32_e32 vcc, s21, v0
	v_exp_f32_e32 v2, v2
	s_nop 0
	v_cndmask_b32_e64 v3, v201, -v3, vcc
	v_cmp_gt_f32_e32 vcc, s22, v3
	v_mul_f32_e32 v4, 0x4f800000, v3
	s_nop 0
	v_cndmask_b32_e32 v3, v3, v4, vcc
	v_sqrt_f32_e32 v4, v3
	s_nop 0
	v_add_u32_e32 v5, -1, v4
	v_fma_f32 v6, -v5, v4, v3
	v_cmp_ge_f32_e64 s[0:1], 0, v6
	v_add_u32_e32 v6, 1, v4
	s_nop 0
	v_cndmask_b32_e64 v5, v4, v5, s[0:1]
	v_fma_f32 v4, -v6, v4, v3
	v_cmp_lt_f32_e64 s[0:1], 0, v4
	s_nop 1
	v_cndmask_b32_e64 v4, v5, v6, s[0:1]
	v_mul_f32_e32 v5, 0x37800000, v4
	v_cndmask_b32_e32 v4, v4, v5, vcc
	v_cmp_class_f32_e32 vcc, v3, v193
	s_nop 1
	v_cndmask_b32_e32 v3, v4, v3, vcc
	v_cmp_ngt_f32_e32 vcc, s23, v0
	s_nop 1
	v_cndmask_b32_e32 v0, 1.0, v3, vcc
	v_mul_f32_e32 v0, v1, v0
	v_mul_f32_e32 v0, v45, v0
	ds_write_b32 v73, v2 offset:6528
	ds_write_b32 v73, v0 offset:43392
	v_add_f32_e32 v0, v30, v36
	v_mul_f32_e32 v0, 0xbfb8aa3b, v0
	v_exp_f32_e32 v0, v0
	v_add_f32_e32 v1, v14, v38
	v_mul_f32_e32 v1, 0xbfb8aa3b, v1
	v_exp_f32_e32 v1, v1
	v_add_f32_e32 v0, 1.0, v0
	v_rcp_f32_e32 v0, v0
	v_add_f32_e32 v1, 1.0, v1
	v_rcp_f32_e32 v1, v1
	v_mul_f32_e32 v0, v0, v32
	v_mul_f32_e32 v2, 0x3fb8aa3b, v0
	v_add_f32_e32 v0, v0, v0
	v_mul_f32_e32 v3, 0x3fb8aa3b, v0
	v_rndne_f32_e32 v3, v3
	v_fmamk_f32 v4, v3, 0xbf317218, v0
	v_fmac_f32_e32 v4, 0x3102e308, v3
	v_fmamk_f32 v5, v4, 0x395133b1, v192
	v_cmp_eq_f32_e32 vcc, s20, v3
	v_cvt_i32_f32_e32 v3, v3
	v_fmaak_f32 v5, v4, v5, 0x3c0887f9
	v_fmaak_f32 v5, v4, v5, 0x3d2aaa81
	v_fmaak_f32 v5, v4, v5, 0x3e2aaaab
	v_fma_f32 v5, v4, v5, 0.5
	v_ldexp_f32 v3, 1.0, v3
	v_mul_f32_e32 v5, v4, v5
	v_cndmask_b32_e32 v3, v3, v202, vcc
	v_fmac_f32_e32 v4, v4, v5
	v_add_f32_e32 v5, -1.0, v3
	v_fmac_f32_e32 v5, v3, v4
	v_add_f32_e32 v3, v5, v5
	v_cndmask_b32_e32 v3, v5, v3, vcc
	v_cmp_nlt_f32_e32 vcc, s21, v0
	v_exp_f32_e32 v2, v2
	s_nop 0
	v_cndmask_b32_e64 v3, v201, -v3, vcc
	v_cmp_gt_f32_e32 vcc, s22, v3
	v_mul_f32_e32 v4, 0x4f800000, v3
	s_nop 0
	v_cndmask_b32_e32 v3, v3, v4, vcc
	v_sqrt_f32_e32 v4, v3
	s_nop 0
	v_add_u32_e32 v5, -1, v4
	v_fma_f32 v6, -v5, v4, v3
	v_cmp_ge_f32_e64 s[0:1], 0, v6
	v_add_u32_e32 v6, 1, v4
	s_nop 0
	v_cndmask_b32_e64 v5, v4, v5, s[0:1]
	v_fma_f32 v4, -v6, v4, v3
	v_cmp_lt_f32_e64 s[0:1], 0, v4
	s_nop 1
	v_cndmask_b32_e64 v4, v5, v6, s[0:1]
	v_mul_f32_e32 v5, 0x37800000, v4
	v_cndmask_b32_e32 v4, v4, v5, vcc
	v_cmp_class_f32_e32 vcc, v3, v193
	s_nop 1
	v_cndmask_b32_e32 v3, v4, v3, vcc
	v_cmp_ngt_f32_e32 vcc, s23, v0
	s_nop 1
	v_cndmask_b32_e32 v0, 1.0, v3, vcc
	v_mul_f32_e32 v0, v1, v0
	v_mul_f32_e32 v0, v35, v0
	v_add_u32_e32 v1, 0x1800, v73
	ds_write2_b32 v1, v2, v34 offset0:160 offset1:192
	ds_write_b32 v73, v0 offset:43648
	v_add_f32_e32 v0, v31, v36
	v_mul_f32_e32 v0, 0xbfb8aa3b, v0
	v_exp_f32_e32 v0, v0
	v_add_f32_e32 v1, v15, v38
	v_mul_f32_e32 v1, 0xbfb8aa3b, v1
	v_exp_f32_e32 v1, v1
	v_add_f32_e32 v0, 1.0, v0
	v_rcp_f32_e32 v0, v0
	v_add_f32_e32 v1, 1.0, v1
	v_rcp_f32_e32 v1, v1
	v_mul_f32_e32 v0, v0, v32
	v_mul_f32_e32 v2, 0x3fb8aa3b, v0
	v_add_f32_e32 v0, v0, v0
	v_mul_f32_e32 v3, 0x3fb8aa3b, v0
	v_rndne_f32_e32 v3, v3
	v_fmamk_f32 v4, v3, 0xbf317218, v0
	v_fmac_f32_e32 v4, 0x3102e308, v3
	v_fmamk_f32 v5, v4, 0x395133b1, v192
	v_cmp_eq_f32_e32 vcc, s20, v3
	v_cvt_i32_f32_e32 v3, v3
	v_fmaak_f32 v5, v4, v5, 0x3c0887f9
	v_fmaak_f32 v5, v4, v5, 0x3d2aaa81
	v_fmaak_f32 v5, v4, v5, 0x3e2aaaab
	v_fma_f32 v5, v4, v5, 0.5
	v_ldexp_f32 v3, 1.0, v3
	v_mul_f32_e32 v5, v4, v5
	v_cndmask_b32_e32 v3, v3, v202, vcc
	v_fmac_f32_e32 v4, v4, v5
	v_add_f32_e32 v5, -1.0, v3
	v_fmac_f32_e32 v5, v3, v4
	v_add_f32_e32 v3, v5, v5
	v_cndmask_b32_e32 v3, v5, v3, vcc
	v_cmp_nlt_f32_e32 vcc, s21, v0
	v_exp_f32_e32 v2, v2
	s_nop 0
	v_cndmask_b32_e64 v3, v201, -v3, vcc
	v_cmp_gt_f32_e32 vcc, s22, v3
	v_mul_f32_e32 v4, 0x4f800000, v3
	s_nop 0
	v_cndmask_b32_e32 v3, v3, v4, vcc
	v_sqrt_f32_e32 v4, v3
	s_nop 0
	v_add_u32_e32 v5, -1, v4
	v_fma_f32 v6, -v5, v4, v3
	v_cmp_ge_f32_e64 s[0:1], 0, v6
	v_add_u32_e32 v6, 1, v4
	s_nop 0
	v_cndmask_b32_e64 v5, v4, v5, s[0:1]
	v_fma_f32 v4, -v6, v4, v3
	v_cmp_lt_f32_e64 s[0:1], 0, v4
	s_nop 1
	v_cndmask_b32_e64 v4, v5, v6, s[0:1]
	v_mul_f32_e32 v5, 0x37800000, v4
	v_cndmask_b32_e32 v4, v4, v5, vcc
	v_cmp_class_f32_e32 vcc, v3, v193
	s_nop 1
	v_cndmask_b32_e32 v3, v4, v3, vcc
	v_cmp_ngt_f32_e32 vcc, s23, v0
	s_nop 1
	v_cndmask_b32_e32 v0, 1.0, v3, vcc
	v_mul_f32_e32 v0, v1, v0
	v_mul_f32_e32 v0, v33, v0
	ds_write_b32 v73, v2 offset:7040
	ds_write_b32 v73, v0 offset:43904
	s_waitcnt lgkmcnt(0)
	s_barrier
	s_cbranch_scc1 .LBB0_866
	v_lshl_add_u64 v[0:1], v[64:65], 0, s[4:5]
	global_load_dwordx2 v[98:99], v[0:1], off
	s_cmp_eq_u32 s12, 1
	s_waitcnt vmcnt(0)
	v_fmac_f32_e32 v99, 0, v98
	s_cbranch_scc1 .LBB0_867
	v_add_co_u32_e32 v0, vcc, 0x1000, v0
	s_cmp_eq_u32 s12, 2
	s_nop 0
	v_addc_co_u32_e32 v1, vcc, 0, v1, vcc
	global_load_dwordx2 v[0:1], v[0:1], off
	s_waitcnt vmcnt(0)
	v_fmac_f32_e32 v1, v99, v0
	s_cbranch_scc1 .LBB0_865
	v_readlane_b32 s0, v248, 32
	s_mul_i32 s46, s11, 36
	s_add_i32 s0, s0, s75
	s_mov_b32 s47, s5
	s_sub_i32 s0, s0, s70
	s_lshl_b64 s[44:45], s[46:47], 12
	v_readlane_b32 s1, v249, 45
	s_add_u32 s44, s1, s44
	v_readlane_b32 s1, v249, 46
	v_add_lshl_u32 v96, s13, v141, 3
	s_addc_u32 s45, s1, s45
	v_lshl_add_u64 v[2:3], s[44:45], 0, v[96:97]
	s_mov_b64 s[8:9], 0x1000

.LBB0_908:
	v_add_u32_e32 v137, v135, v134
	ds_read_b128 v[146:149], v135 offset:18432
	ds_read_b128 v[150:153], v137
	s_add_i32 s0, s0, 32
	s_cmp_lt_u32 s0, 48
	s_waitcnt lgkmcnt(0)
	v_mfma_f32_32x32x16_bf16 v[48:63], v[150:153], v[146:149], v[48:63]
	ds_read_b128 v[146:149], v135 offset:23040
	s_waitcnt lgkmcnt(0)
	v_mfma_f32_32x32x16_bf16 v[16:31], v[150:153], v[146:149], v[16:31]
	ds_read_b128 v[146:149], v135 offset:27648
	s_waitcnt lgkmcnt(0)
	v_mfma_f32_32x32x16_bf16 v[32:47], v[150:153], v[146:149], v[32:47]
	ds_read_b128 v[146:149], v135 offset:32256
	ds_read_b128 v[154:157], v135 offset:18464
	s_waitcnt lgkmcnt(1)
	v_mfma_f32_32x32x16_bf16 v[0:15], v[150:153], v[146:149], v[0:15]
	ds_read_b128 v[146:149], v137 offset:32
	ds_read_b128 v[150:153], v135 offset:23072
	s_waitcnt lgkmcnt(0)
	v_mfma_f32_32x32x16_bf16 v[16:31], v[146:149], v[150:153], v[16:31]
	ds_read_b128 v[150:153], v135 offset:27680
	s_waitcnt lgkmcnt(0)
	v_mfma_f32_32x32x16_bf16 v[32:47], v[146:149], v[150:153], v[32:47]
	ds_read_b128 v[150:153], v135 offset:32288
	v_add_u32_e32 v135, 64, v135
	v_mfma_f32_32x32x16_bf16 v[48:63], v[146:149], v[154:157], v[48:63]
	s_waitcnt lgkmcnt(0)
	v_mfma_f32_32x32x16_bf16 v[0:15], v[146:149], v[150:153], v[0:15]
	s_cbranch_scc1 .LBB0_908
	s_cmp_gt_u32 s12, 1
	v_readlane_b32 s0, v248, 27
	s_cselect_b32 s2, 19, 1
	s_or_b32 s3, s13, s0
	v_lshlrev_b32_e32 v137, 11, v96
	v_or_b32_e32 v96, s3, v145
	s_nop 0
	v_lshlrev_b64 v[134:135], 2, v[96:97]
	v_readlane_b32 s18, v251, 22
	v_readlane_b32 s19, v251, 23
	s_barrier
	s_nop 0
	v_lshl_add_u64 v[138:139], s[18:19], 0, v[134:135]
	v_readlane_b32 s100, v251, 16
	v_readlane_b32 s101, v251, 17
	s_nop 1
	v_lshl_add_u64 v[220:221], s[100:101], 0, v[134:135]
	v_readlane_b32 s100, v251, 20
	v_readlane_b32 s101, v251, 21
	s_nop 1
	v_lshl_add_u64 v[222:223], s[100:101], 0, v[134:135]
	global_load_dword v224, v[220:221], off
	global_load_dword v225, v[222:223], off
	global_load_dword v226, v[138:139], off offset:128
	global_load_dword v227, v[222:223], off offset:128
	global_load_dword v228, v[220:221], off offset:128
	global_load_dword v96, v[138:139], off
	s_mov_b32 s8, 0x3f2aaaab
	s_mov_b32 s9, 0x3f317218
	s_mov_b32 s10, 0x7f800000
	s_mov_b32 s20, 0x33800000
	v_readlane_b32 s40, v251, 4
	v_readlane_b32 s52, v251, 16
	v_readlane_b32 s53, v251, 17
	s_mov_b32 s21, 0x43000000
	s_mov_b32 s22, 0x42b17217
	s_mov_b32 s23, 0xf800000
	s_mov_b32 s24, 0xc1880000
	v_readlane_b32 s30, v248, 2
	s_cmp_eq_u32 s2, s12
	v_readlane_b32 s31, v248, 3
	s_mov_b32 s28, 0x4800000
	s_movk_i32 s29, 0x47ff
	s_mov_b32 s25, 0x85000
	v_readlane_b32 s27, v248, 10
	v_readlane_b32 s26, v251, 30
	v_readlane_b32 s41, v251, 5
	v_readlane_b32 s42, v251, 6
	v_readlane_b32 s43, v251, 7
	v_readlane_b32 s44, v251, 8
	v_readlane_b32 s45, v251, 9
	v_readlane_b32 s46, v251, 10
	v_readlane_b32 s47, v251, 11
	v_readlane_b32 s48, v251, 12
	v_readlane_b32 s49, v251, 13
	v_readlane_b32 s50, v251, 14
	v_readlane_b32 s51, v251, 15
	v_readlane_b32 s54, v251, 18
	v_readlane_b32 s55, v251, 19
	s_waitcnt vmcnt(0)
	v_mul_f32_e32 v96, 0xbfb8aa3b, v96
	v_exp_f32_e32 v96, v96
	s_nop 0
	v_add_f32_e32 v144, 1.0, v96
	v_add_f32_e32 v138, -1.0, v144
	v_sub_f32_e32 v139, v138, v144
	v_add_f32_e32 v139, 1.0, v139
	v_sub_f32_e32 v138, v96, v138
	v_add_f32_e32 v146, v138, v139
	v_frexp_mant_f32_e32 v138, v144
	v_cmp_gt_f32_e32 vcc, s8, v138
	v_cvt_f64_f32_e32 v[138:139], v144
	v_frexp_exp_i32_f64_e32 v138, v[138:139]
	v_subbrev_co_u32_e32 v152, vcc, 0, v138, vcc
	v_sub_u32_e32 v138, 0, v152
	v_ldexp_f32 v139, v144, v138
	v_add_f32_e32 v144, -1.0, v139
	v_add_f32_e32 v147, 1.0, v139
	v_ldexp_f32 v138, v146, v138
	v_add_f32_e32 v146, 1.0, v144
	v_add_f32_e32 v148, -1.0, v147
	v_sub_f32_e32 v146, v139, v146
	v_sub_f32_e32 v139, v139, v148
	v_add_f32_e32 v146, v138, v146
	v_add_f32_e32 v138, v138, v139
	v_add_f32_e32 v153, v147, v138
	v_rcp_f32_e32 v155, v153
	v_sub_f32_e32 v139, v153, v147
	v_sub_f32_e32 v154, v138, v139
	v_add_f32_e32 v139, v144, v146
	v_sub_f32_e32 v138, v139, v144
	v_mul_f32_e32 v156, v139, v155
	v_sub_f32_e32 v144, v146, v138
	v_mul_f32_e32 v146, v153, v156
	v_fma_f32 v148, v156, v153, -v146
	v_fmac_f32_e32 v148, v156, v154
	v_add_f32_e32 v138, v146, v148
	v_sub_f32_e32 v147, v139, v138
	v_pk_add_f32 v[150:151], v[138:139], v[146:147] neg_lo:[0,1] neg_hi:[0,1]
	v_mov_b32_e32 v149, v138
	v_pk_add_f32 v[138:139], v[150:151], v[148:149] neg_lo:[0,1] neg_hi:[0,1]
	v_cmp_neq_f32_e32 vcc, s10, v96
	v_add_f32_e32 v139, v144, v139
	v_add_f32_e32 v138, v138, v139
	v_add_f32_e32 v139, v147, v138
	v_mul_f32_e32 v144, v155, v139
	v_mul_f32_e32 v146, v153, v144
	v_fma_f32 v148, v144, v153, -v146
	v_fmac_f32_e32 v148, v144, v154
	v_sub_f32_e32 v147, v147, v139
	v_add_f32_e32 v153, v138, v147
	v_add_f32_e32 v138, v146, v148
	v_sub_f32_e32 v147, v139, v138
	v_pk_add_f32 v[150:151], v[138:139], v[146:147] neg_lo:[0,1] neg_hi:[0,1]
	v_mov_b32_e32 v149, v138
	v_pk_add_f32 v[138:139], v[150:151], v[148:149] neg_lo:[0,1] neg_hi:[0,1]
	v_add_f32_e32 v139, v153, v139
	v_add_f32_e32 v138, v138, v139
	v_add_f32_e32 v139, v156, v144
	v_add_f32_e32 v138, v147, v138
	v_sub_f32_e32 v146, v139, v156
	v_mul_f32_e32 v138, v155, v138
	v_sub_f32_e32 v144, v144, v146
	v_add_f32_e32 v144, v144, v138
	v_add_f32_e32 v146, v139, v144
	v_mul_f32_e32 v148, v146, v146
	v_fmamk_f32 v138, v148, 0x3e9b6dac, v191
	v_fmaak_f32 v169, v148, v138, 0x3f2aaada
	v_cvt_f32_i32_e32 v138, v152
	v_sub_f32_e32 v139, v146, v139
	v_sub_f32_e32 v139, v144, v139
	v_ldexp_f32 v144, v139, 1
	v_mul_f32_e32 v139, v146, v148
	v_pk_mul_f32 v[148:149], v[138:139], v[168:169]
	v_ldexp_f32 v147, v146, 1
	v_fma_f32 v146, v138, s9, -v148
	v_fmac_f32_e32 v146, 0xb102e308, v138
	v_pk_add_f32 v[138:139], v[148:149], v[146:147]
	v_mov_b32_e32 v150, v148
	v_sub_f32_e32 v147, v139, v147
	v_sub_f32_e32 v147, v149, v147
	v_add_f32_e32 v151, v144, v147
	v_pk_add_f32 v[148:149], v[138:139], v[148:149] neg_lo:[0,1] neg_hi:[0,1]
	v_pk_add_f32 v[152:153], v[138:139], v[150:151]
	v_mov_b32_e32 v147, v138
	v_mov_b32_e32 v149, v153
	v_pk_add_f32 v[154:155], v[146:147], v[148:149] neg_lo:[0,1] neg_hi:[0,1]
	v_pk_add_f32 v[146:147], v[146:147], v[148:149]
	v_mov_b32_e32 v150, v151
	v_pk_add_f32 v[148:149], v[146:147], v[138:139] op_sel:[1,0] op_sel_hi:[0,1] neg_lo:[0,1] neg_hi:[0,1]
	v_pk_add_f32 v[156:157], v[152:153], v[148:149] op_sel_hi:[1,0] neg_lo:[0,1] neg_hi:[0,1]
	v_mov_b32_e32 v152, v153
	v_mov_b32_e32 v153, v147
	v_pk_mov_b32 v[148:149], v[138:139], v[148:149] op_sel:[1,0]
	v_mov_b32_e32 v151, v138
	v_pk_add_f32 v[148:149], v[152:153], v[148:149] neg_lo:[0,1] neg_hi:[0,1]
	v_mov_b32_e32 v156, v154
	v_pk_add_f32 v[138:139], v[150:151], v[148:149] neg_lo:[0,1] neg_hi:[0,1]
	v_mov_b32_e32 v155, v147
	v_pk_add_f32 v[148:149], v[156:157], v[138:139]
	v_pk_add_f32 v[150:151], v[148:149], v[148:149] op_sel:[0,1] op_sel_hi:[1,0]
	v_pk_add_f32 v[146:147], v[146:147], v[150:151] op_sel:[1,0] op_sel_hi:[0,1]
	v_mov_b32_e32 v149, v146
	v_pk_add_f32 v[152:153], v[148:149], v[154:155] neg_lo:[0,1] neg_hi:[0,1]
	v_mov_b32_e32 v139, v150
	v_sub_f32_e32 v144, v148, v152
	v_pk_add_f32 v[138:139], v[138:139], v[152:153] neg_lo:[0,1] neg_hi:[0,1]
	v_sub_f32_e32 v144, v154, v144
	v_add_f32_e32 v138, v138, v144
	v_add_f32_e32 v138, v138, v139
	v_add_f32_e32 v138, v146, v138
	v_cndmask_b32_e32 v138, v199, v138, vcc
	v_cmp_ngt_f32_e32 vcc, -1.0, v96
	s_nop 1
	v_cndmask_b32_e32 v138, v200, v138, vcc
	v_cmp_neq_f32_e32 vcc, -1.0, v96
	s_nop 1
	v_cndmask_b32_e32 v138, v201, v138, vcc
	v_cmp_lt_f32_e64 vcc, |v96|, s20
	s_nop 1
	v_cndmask_b32_e32 v96, v138, v96, vcc
	v_mov_b32_e32 v147, v224
	v_mov_b32_e32 v146, v225
	v_mul_f32_e32 v96, 0xc1000000, v96
	v_add_f32_e32 v48, v48, v147
	v_mul_f32_e32 v48, 0xbfb8aa3b, v48
	v_exp_f32_e32 v48, v48
	v_add_f32_e32 v32, v32, v146
	v_mul_f32_e32 v32, 0xbfb8aa3b, v32
	v_exp_f32_e32 v32, v32
	v_add_f32_e32 v48, 1.0, v48
	v_rcp_f32_e32 v48, v48
	v_add_f32_e32 v33, v33, v146
	v_add_f32_e32 v32, 1.0, v32
	v_rcp_f32_e32 v32, v32
	v_mul_f32_e32 v48, v48, v96
	v_mul_f32_e32 v134, 0x3fb8aa3b, v48
	v_add_f32_e32 v48, v48, v48
	v_exp_f32_e32 v138, v134
	v_mul_f32_e32 v134, 0x3fb8aa3b, v48
	v_rndne_f32_e32 v134, v134
	v_fmamk_f32 v135, v134, 0xbf317218, v48
	v_fmac_f32_e32 v135, 0x3102e308, v134
	v_fmamk_f32 v139, v135, 0x395133b1, v192
	v_cmp_eq_f32_e32 vcc, s21, v134
	v_cvt_i32_f32_e32 v134, v134
	v_fmaak_f32 v139, v135, v139, 0x3c0887f9
	v_fmaak_f32 v139, v135, v139, 0x3d2aaa81
	v_fmaak_f32 v139, v135, v139, 0x3e2aaaab
	v_fma_f32 v139, v135, v139, 0.5
	v_ldexp_f32 v134, 1.0, v134
	v_mul_f32_e32 v139, v135, v139
	v_cndmask_b32_e32 v134, v134, v202, vcc
	v_fmac_f32_e32 v135, v135, v139
	v_add_f32_e32 v139, -1.0, v134
	v_fmac_f32_e32 v139, v134, v135
	v_add_f32_e32 v134, v139, v139
	v_cndmask_b32_e32 v134, v139, v134, vcc
	v_cmp_nlt_f32_e32 vcc, s22, v48
	v_mul_f32_e32 v33, 0xbfb8aa3b, v33
	v_exp_f32_e32 v33, v33
	v_cndmask_b32_e64 v134, v201, -v134, vcc
	v_cmp_gt_f32_e32 vcc, s23, v134
	v_mul_f32_e32 v135, 0x4f800000, v134
	v_add_f32_e32 v33, 1.0, v33
	v_cndmask_b32_e32 v134, v134, v135, vcc
	v_sqrt_f32_e32 v135, v134
	v_rcp_f32_e32 v33, v33
	v_add_f32_e32 v34, v34, v146
	v_mul_f32_e32 v34, 0xbfb8aa3b, v34
	v_add_u32_e32 v139, -1, v135
	v_fma_f32 v144, -v139, v135, v134
	v_cmp_ge_f32_e64 s[0:1], 0, v144
	v_add_u32_e32 v144, 1, v135
	v_exp_f32_e32 v34, v34
	v_cndmask_b32_e64 v139, v135, v139, s[0:1]
	v_fma_f32 v135, -v144, v135, v134
	v_cmp_lt_f32_e64 s[0:1], 0, v135
	v_add_f32_e32 v34, 1.0, v34
	v_rcp_f32_e32 v34, v34
	v_cndmask_b32_e64 v135, v139, v144, s[0:1]
	v_mul_f32_e32 v139, 0x37800000, v135
	v_cndmask_b32_e32 v135, v135, v139, vcc
	v_cmp_class_f32_e32 vcc, v134, v193
	s_nop 1
	v_cndmask_b32_e32 v134, v135, v134, vcc
	v_cmp_ngt_f32_e32 vcc, s24, v48
	s_nop 1
	v_cndmask_b32_e32 v48, 1.0, v134, vcc
	v_mul_f32_e32 v48, v32, v48
	v_and_b32_e32 v32, 0x100, v136
	v_or3_b32 v32, v137, v145, v32
	v_lshl_add_u32 v144, v32, 2, 0
	v_add_u32_e32 v32, 0x9000, v144
	ds_read2_b32 v[134:135], v32 offset1:32
	s_waitcnt lgkmcnt(0)
	v_mul_f32_e32 v48, v134, v48
	ds_write_b32 v144, v138
	ds_write_b32 v144, v48 offset:36864
	v_add_f32_e32 v48, v49, v147
	v_mul_f32_e32 v48, 0xbfb8aa3b, v48
	v_exp_f32_e32 v48, v48
	s_nop 0
	v_add_f32_e32 v48, 1.0, v48
	v_rcp_f32_e32 v48, v48
	s_nop 0
	v_mul_f32_e32 v48, v48, v96
	v_mul_f32_e32 v49, 0x3fb8aa3b, v48
	v_add_f32_e32 v48, v48, v48
	v_exp_f32_e32 v134, v49
	v_mul_f32_e32 v49, 0x3fb8aa3b, v48
	v_rndne_f32_e32 v49, v49
	v_fmamk_f32 v136, v49, 0xbf317218, v48
	v_fmac_f32_e32 v136, 0x3102e308, v49
	v_fmamk_f32 v137, v136, 0x395133b1, v192
	v_cmp_eq_f32_e32 vcc, s21, v49
	v_cvt_i32_f32_e32 v49, v49
	v_fmaak_f32 v137, v136, v137, 0x3c0887f9
	v_fmaak_f32 v137, v136, v137, 0x3d2aaa81
	v_fmaak_f32 v137, v136, v137, 0x3e2aaaab
	v_fma_f32 v137, v136, v137, 0.5
	v_ldexp_f32 v49, 1.0, v49
	v_mul_f32_e32 v137, v136, v137
	v_cndmask_b32_e32 v49, v49, v202, vcc
	v_fmac_f32_e32 v136, v136, v137
	v_add_f32_e32 v137, -1.0, v49
	v_fmac_f32_e32 v137, v49, v136
	v_add_f32_e32 v49, v137, v137
	v_cndmask_b32_e32 v49, v137, v49, vcc
	v_cmp_nlt_f32_e32 vcc, s22, v48
	s_nop 1
	v_cndmask_b32_e64 v49, v201, -v49, vcc
	v_cmp_gt_f32_e32 vcc, s23, v49
	v_mul_f32_e32 v136, 0x4f800000, v49
	s_nop 0
	v_cndmask_b32_e32 v49, v49, v136, vcc
	v_sqrt_f32_e32 v136, v49
	s_nop 0
	v_add_u32_e32 v137, -1, v136
	v_fma_f32 v138, -v137, v136, v49
	v_cmp_ge_f32_e64 s[0:1], 0, v138
	v_add_u32_e32 v138, 1, v136
	s_nop 0
	v_cndmask_b32_e64 v137, v136, v137, s[0:1]
	v_fma_f32 v136, -v138, v136, v49
	v_cmp_lt_f32_e64 s[0:1], 0, v136
	s_nop 1
	v_cndmask_b32_e64 v136, v137, v138, s[0:1]
	v_mul_f32_e32 v137, 0x37800000, v136
	v_cndmask_b32_e32 v136, v136, v137, vcc
	v_cmp_class_f32_e32 vcc, v49, v193
	s_nop 1
	v_cndmask_b32_e32 v49, v136, v49, vcc
	v_cmp_ngt_f32_e32 vcc, s24, v48
	s_nop 1
	v_cndmask_b32_e32 v48, 1.0, v49, vcc
	v_mul_f32_e32 v33, v33, v48
	ds_read2_b32 v[48:49], v32 offset0:64 offset1:96
	s_waitcnt lgkmcnt(0)
	v_mul_f32_e32 v33, v48, v33
	ds_write_b32 v144, v134 offset:256
	ds_write_b32 v144, v33 offset:37120
	v_add_f32_e32 v33, v50, v147
	v_mul_f32_e32 v33, 0xbfb8aa3b, v33
	v_exp_f32_e32 v33, v33
	s_nop 0
	v_add_f32_e32 v33, 1.0, v33
	v_rcp_f32_e32 v33, v33
	s_nop 0
	v_mul_f32_e32 v33, v33, v96
	v_mul_f32_e32 v48, 0x3fb8aa3b, v33
	v_add_f32_e32 v33, v33, v33
	v_mul_f32_e32 v50, 0x3fb8aa3b, v33
	v_rndne_f32_e32 v50, v50
	v_fmamk_f32 v134, v50, 0xbf317218, v33
	v_fmac_f32_e32 v134, 0x3102e308, v50
	v_fmamk_f32 v136, v134, 0x395133b1, v192
	v_cmp_eq_f32_e32 vcc, s21, v50
	v_cvt_i32_f32_e32 v50, v50
	v_fmaak_f32 v136, v134, v136, 0x3c0887f9
	v_fmaak_f32 v136, v134, v136, 0x3d2aaa81
	v_fmaak_f32 v136, v134, v136, 0x3e2aaaab
	v_fma_f32 v136, v134, v136, 0.5
	v_ldexp_f32 v50, 1.0, v50
	v_mul_f32_e32 v136, v134, v136
	v_cndmask_b32_e32 v50, v50, v202, vcc
	v_fmac_f32_e32 v134, v134, v136
	v_add_f32_e32 v136, -1.0, v50
	v_fmac_f32_e32 v136, v50, v134
	v_add_f32_e32 v50, v136, v136
	v_cndmask_b32_e32 v50, v136, v50, vcc
	v_cmp_nlt_f32_e32 vcc, s22, v33
	v_exp_f32_e32 v48, v48
	s_nop 0
	v_cndmask_b32_e64 v50, v201, -v50, vcc
	v_cmp_gt_f32_e32 vcc, s23, v50
	v_mul_f32_e32 v134, 0x4f800000, v50
	s_nop 0
	v_cndmask_b32_e32 v50, v50, v134, vcc
	v_sqrt_f32_e32 v134, v50
	s_nop 0
	v_add_u32_e32 v136, -1, v134
	v_fma_f32 v137, -v136, v134, v50
	v_cmp_ge_f32_e64 s[0:1], 0, v137
	v_add_u32_e32 v137, 1, v134
	s_nop 0
	v_cndmask_b32_e64 v136, v134, v136, s[0:1]
	v_fma_f32 v134, -v137, v134, v50
	v_cmp_lt_f32_e64 s[0:1], 0, v134
	s_nop 1
	v_cndmask_b32_e64 v134, v136, v137, s[0:1]
	v_mul_f32_e32 v136, 0x37800000, v134
	v_cndmask_b32_e32 v134, v134, v136, vcc
	ds_read2_b32 v[136:137], v32 offset0:128 offset1:160
	v_cmp_class_f32_e32 vcc, v50, v193
	s_nop 1
	v_cndmask_b32_e32 v50, v134, v50, vcc
	v_cmp_ngt_f32_e32 vcc, s24, v33
	s_nop 1
	v_cndmask_b32_e32 v33, 1.0, v50, vcc
	v_mul_f32_e32 v33, v34, v33
	s_waitcnt lgkmcnt(0)
	v_mul_f32_e32 v33, v136, v33
	ds_write_b32 v144, v48 offset:512
	ds_write_b32 v144, v33 offset:37376
	v_add_f32_e32 v33, v51, v147
	v_mul_f32_e32 v33, 0xbfb8aa3b, v33
	v_exp_f32_e32 v33, v33
	v_add_f32_e32 v34, v35, v146
	v_mul_f32_e32 v34, 0xbfb8aa3b, v34
	v_exp_f32_e32 v34, v34
	v_add_f32_e32 v33, 1.0, v33
	v_rcp_f32_e32 v33, v33
	v_add_f32_e32 v34, 1.0, v34
	v_rcp_f32_e32 v34, v34
	v_mul_f32_e32 v33, v33, v96
	v_mul_f32_e32 v35, 0x3fb8aa3b, v33
	v_add_f32_e32 v33, v33, v33
	v_mul_f32_e32 v48, 0x3fb8aa3b, v33
	v_rndne_f32_e32 v48, v48
	v_fmamk_f32 v50, v48, 0xbf317218, v33
	v_fmac_f32_e32 v50, 0x3102e308, v48
	v_fmamk_f32 v51, v50, 0x395133b1, v192
	v_cmp_eq_f32_e32 vcc, s21, v48
	v_cvt_i32_f32_e32 v48, v48
	v_fmaak_f32 v51, v50, v51, 0x3c0887f9
	v_fmaak_f32 v51, v50, v51, 0x3d2aaa81
	v_fmaak_f32 v51, v50, v51, 0x3e2aaaab
	v_fma_f32 v51, v50, v51, 0.5
	v_ldexp_f32 v48, 1.0, v48
	v_mul_f32_e32 v51, v50, v51
	v_cndmask_b32_e32 v48, v48, v202, vcc
	v_fmac_f32_e32 v50, v50, v51
	v_add_f32_e32 v51, -1.0, v48
	v_fmac_f32_e32 v51, v48, v50
	v_add_f32_e32 v48, v51, v51
	v_cndmask_b32_e32 v48, v51, v48, vcc
	v_cmp_nlt_f32_e32 vcc, s22, v33
	v_exp_f32_e32 v35, v35
	s_nop 0
	v_cndmask_b32_e64 v48, v201, -v48, vcc
	v_cmp_gt_f32_e32 vcc, s23, v48
	v_mul_f32_e32 v50, 0x4f800000, v48
	s_nop 0
	v_cndmask_b32_e32 v48, v48, v50, vcc
	v_sqrt_f32_e32 v50, v48
	s_nop 0
	v_add_u32_e32 v51, -1, v50
	v_fma_f32 v134, -v51, v50, v48
	v_cmp_ge_f32_e64 s[0:1], 0, v134
	v_add_u32_e32 v134, 1, v50
	s_nop 0
	v_cndmask_b32_e64 v51, v50, v51, s[0:1]
	v_fma_f32 v50, -v134, v50, v48
	v_cmp_lt_f32_e64 s[0:1], 0, v50
	s_nop 1
	v_cndmask_b32_e64 v50, v51, v134, s[0:1]
	v_mul_f32_e32 v51, 0x37800000, v50
	v_cndmask_b32_e32 v50, v50, v51, vcc
	v_cmp_class_f32_e32 vcc, v48, v193
	s_nop 1
	v_cndmask_b32_e32 v48, v50, v48, vcc
	ds_read2_b32 v[50:51], v32 offset0:192 offset1:224
	v_cmp_ngt_f32_e32 vcc, s24, v33
	s_nop 1
	v_cndmask_b32_e32 v33, 1.0, v48, vcc
	v_mul_f32_e32 v33, v34, v33
	s_waitcnt lgkmcnt(0)
	v_mul_f32_e32 v32, v50, v33
	ds_write_b32 v144, v35 offset:768
	ds_write_b32 v144, v32 offset:37632
	v_add_f32_e32 v32, v52, v147
	v_mul_f32_e32 v32, 0xbfb8aa3b, v32
	v_exp_f32_e32 v32, v32
	v_add_f32_e32 v33, v36, v146
	v_mul_f32_e32 v33, 0xbfb8aa3b, v33
	v_exp_f32_e32 v33, v33
	v_add_f32_e32 v32, 1.0, v32
	v_rcp_f32_e32 v32, v32
	v_add_f32_e32 v33, 1.0, v33
	v_rcp_f32_e32 v33, v33
	v_mul_f32_e32 v32, v32, v96
	v_mul_f32_e32 v34, 0x3fb8aa3b, v32
	v_add_f32_e32 v32, v32, v32
	v_mul_f32_e32 v35, 0x3fb8aa3b, v32
	v_rndne_f32_e32 v35, v35
	v_fmamk_f32 v36, v35, 0xbf317218, v32
	v_fmac_f32_e32 v36, 0x3102e308, v35
	v_fmamk_f32 v48, v36, 0x395133b1, v192
	v_cmp_eq_f32_e32 vcc, s21, v35
	v_cvt_i32_f32_e32 v35, v35
	v_fmaak_f32 v48, v36, v48, 0x3c0887f9
	v_fmaak_f32 v48, v36, v48, 0x3d2aaa81
	v_fmaak_f32 v48, v36, v48, 0x3e2aaaab
	v_fma_f32 v48, v36, v48, 0.5
	v_ldexp_f32 v35, 1.0, v35
	v_mul_f32_e32 v48, v36, v48
	v_cndmask_b32_e32 v35, v35, v202, vcc
	v_fmac_f32_e32 v36, v36, v48
	v_add_f32_e32 v48, -1.0, v35
	v_fmac_f32_e32 v48, v35, v36
	v_add_f32_e32 v35, v48, v48
	v_cndmask_b32_e32 v35, v48, v35, vcc
	v_cmp_nlt_f32_e32 vcc, s22, v32
	v_exp_f32_e32 v34, v34
	s_nop 0
	v_cndmask_b32_e64 v35, v201, -v35, vcc
	v_cmp_gt_f32_e32 vcc, s23, v35
	v_mul_f32_e32 v36, 0x4f800000, v35
	s_nop 0
	v_cndmask_b32_e32 v35, v35, v36, vcc
	v_sqrt_f32_e32 v36, v35
	s_nop 0
	v_add_u32_e32 v48, -1, v36
	v_fma_f32 v50, -v48, v36, v35
	v_cmp_ge_f32_e64 s[0:1], 0, v50
	v_add_u32_e32 v50, 1, v36
	s_nop 0
	v_cndmask_b32_e64 v48, v36, v48, s[0:1]
	v_fma_f32 v36, -v50, v36, v35
	v_cmp_lt_f32_e64 s[0:1], 0, v36
	s_nop 1
	v_cndmask_b32_e64 v36, v48, v50, s[0:1]
	v_mul_f32_e32 v48, 0x37800000, v36
	v_cndmask_b32_e32 v36, v36, v48, vcc
	v_cmp_class_f32_e32 vcc, v35, v193
	s_nop 1
	v_cndmask_b32_e32 v35, v36, v35, vcc
	v_cmp_ngt_f32_e32 vcc, s24, v32
	s_nop 1
	v_cndmask_b32_e32 v32, 1.0, v35, vcc
	v_mul_f32_e32 v33, v33, v32
	v_add_u32_e32 v32, 0x9800, v144
	ds_read2_b32 v[138:139], v32 offset1:32
	s_waitcnt lgkmcnt(0)
	v_mul_f32_e32 v33, v138, v33
	ds_write_b32 v144, v34 offset:2048
	ds_write_b32 v144, v33 offset:38912
	v_add_f32_e32 v33, v53, v147
	v_mul_f32_e32 v33, 0xbfb8aa3b, v33
	v_exp_f32_e32 v33, v33
	v_add_f32_e32 v34, v37, v146
	v_mul_f32_e32 v34, 0xbfb8aa3b, v34
	v_exp_f32_e32 v34, v34
	v_add_f32_e32 v33, 1.0, v33
	v_rcp_f32_e32 v33, v33
	v_add_f32_e32 v34, 1.0, v34
	v_rcp_f32_e32 v34, v34
	v_mul_f32_e32 v33, v33, v96
	v_mul_f32_e32 v35, 0x3fb8aa3b, v33
	v_add_f32_e32 v33, v33, v33
	v_mul_f32_e32 v36, 0x3fb8aa3b, v33
	v_rndne_f32_e32 v36, v36
	v_fmamk_f32 v37, v36, 0xbf317218, v33
	v_fmac_f32_e32 v37, 0x3102e308, v36
	v_fmamk_f32 v48, v37, 0x395133b1, v192
	v_cmp_eq_f32_e32 vcc, s21, v36
	v_cvt_i32_f32_e32 v36, v36
	v_fmaak_f32 v48, v37, v48, 0x3c0887f9
	v_fmaak_f32 v48, v37, v48, 0x3d2aaa81
	v_fmaak_f32 v48, v37, v48, 0x3e2aaaab
	v_fma_f32 v48, v37, v48, 0.5
	v_ldexp_f32 v36, 1.0, v36
	v_mul_f32_e32 v48, v37, v48
	v_cndmask_b32_e32 v36, v36, v202, vcc
	v_fmac_f32_e32 v37, v37, v48
	v_add_f32_e32 v48, -1.0, v36
	v_fmac_f32_e32 v48, v36, v37
	v_add_f32_e32 v36, v48, v48
	v_cndmask_b32_e32 v36, v48, v36, vcc
	v_cmp_nlt_f32_e32 vcc, s22, v33
	v_exp_f32_e32 v35, v35
	s_nop 0
	v_cndmask_b32_e64 v36, v201, -v36, vcc
	v_cmp_gt_f32_e32 vcc, s23, v36
	v_mul_f32_e32 v37, 0x4f800000, v36
	s_nop 0
	v_cndmask_b32_e32 v36, v36, v37, vcc
	v_sqrt_f32_e32 v37, v36
	s_nop 0
	v_add_u32_e32 v48, -1, v37
	v_fma_f32 v50, -v48, v37, v36
	v_cmp_ge_f32_e64 s[0:1], 0, v50
	v_add_u32_e32 v50, 1, v37
	s_nop 0
	v_cndmask_b32_e64 v48, v37, v48, s[0:1]
	v_fma_f32 v37, -v50, v37, v36
	v_cmp_lt_f32_e64 s[0:1], 0, v37
	s_nop 1
	v_cndmask_b32_e64 v37, v48, v50, s[0:1]
	v_mul_f32_e32 v48, 0x37800000, v37
	v_cndmask_b32_e32 v37, v37, v48, vcc
	v_cmp_class_f32_e32 vcc, v36, v193
	s_nop 1
	v_cndmask_b32_e32 v36, v37, v36, vcc
	v_cmp_ngt_f32_e32 vcc, s24, v33
	s_nop 1
	v_cndmask_b32_e32 v33, 1.0, v36, vcc
	ds_read2_b32 v[36:37], v32 offset0:64 offset1:96
	v_mul_f32_e32 v33, v34, v33
	v_add_f32_e32 v34, v38, v146
	v_mul_f32_e32 v34, 0xbfb8aa3b, v34
	v_exp_f32_e32 v34, v34
	s_waitcnt lgkmcnt(0)
	v_mul_f32_e32 v33, v36, v33
	ds_write_b32 v144, v35 offset:2304
	ds_write_b32 v144, v33 offset:39168
	v_add_f32_e32 v33, v54, v147
	v_mul_f32_e32 v33, 0xbfb8aa3b, v33
	v_exp_f32_e32 v33, v33
	v_add_f32_e32 v34, 1.0, v34
	v_rcp_f32_e32 v34, v34
	ds_read2_b32 v[52:53], v32 offset0:128 offset1:160
	v_add_f32_e32 v33, 1.0, v33
	v_rcp_f32_e32 v33, v33
	s_nop 0
	v_mul_f32_e32 v33, v33, v96
	v_mul_f32_e32 v35, 0x3fb8aa3b, v33
	v_add_f32_e32 v33, v33, v33
	v_mul_f32_e32 v36, 0x3fb8aa3b, v33
	v_rndne_f32_e32 v36, v36
	v_fmamk_f32 v38, v36, 0xbf317218, v33
	v_fmac_f32_e32 v38, 0x3102e308, v36
	v_fmamk_f32 v48, v38, 0x395133b1, v192
	v_cmp_eq_f32_e32 vcc, s21, v36
	v_cvt_i32_f32_e32 v36, v36
	v_fmaak_f32 v48, v38, v48, 0x3c0887f9
	v_fmaak_f32 v48, v38, v48, 0x3d2aaa81
	v_fmaak_f32 v48, v38, v48, 0x3e2aaaab
	v_fma_f32 v48, v38, v48, 0.5
	v_ldexp_f32 v36, 1.0, v36
	v_mul_f32_e32 v48, v38, v48
	v_cndmask_b32_e32 v36, v36, v202, vcc
	v_fmac_f32_e32 v38, v38, v48
	v_add_f32_e32 v48, -1.0, v36
	v_fmac_f32_e32 v48, v36, v38
	v_add_f32_e32 v36, v48, v48
	v_cndmask_b32_e32 v36, v48, v36, vcc
	v_cmp_nlt_f32_e32 vcc, s22, v33
	v_exp_f32_e32 v35, v35
	s_nop 0
	v_cndmask_b32_e64 v36, v201, -v36, vcc
	v_cmp_gt_f32_e32 vcc, s23, v36
	v_mul_f32_e32 v38, 0x4f800000, v36
	s_nop 0
	v_cndmask_b32_e32 v36, v36, v38, vcc
	v_sqrt_f32_e32 v38, v36
	s_nop 0
	v_add_u32_e32 v48, -1, v38
	v_fma_f32 v50, -v48, v38, v36
	v_cmp_ge_f32_e64 s[0:1], 0, v50
	v_add_u32_e32 v50, 1, v38
	s_nop 0
	v_cndmask_b32_e64 v48, v38, v48, s[0:1]
	v_fma_f32 v38, -v50, v38, v36
	v_cmp_lt_f32_e64 s[0:1], 0, v38
	s_nop 1
	v_cndmask_b32_e64 v38, v48, v50, s[0:1]
	v_mul_f32_e32 v48, 0x37800000, v38
	v_cndmask_b32_e32 v38, v38, v48, vcc
	v_cmp_class_f32_e32 vcc, v36, v193
	s_nop 1
	v_cndmask_b32_e32 v36, v38, v36, vcc
	v_cmp_ngt_f32_e32 vcc, s24, v33
	s_nop 1
	v_cndmask_b32_e32 v33, 1.0, v36, vcc
	v_mul_f32_e32 v33, v34, v33
	s_waitcnt lgkmcnt(0)
	v_mul_f32_e32 v33, v52, v33
	ds_write_b32 v144, v35 offset:2560
	ds_write_b32 v144, v33 offset:39424
	v_add_f32_e32 v33, v55, v147
	v_mul_f32_e32 v33, 0xbfb8aa3b, v33
	v_exp_f32_e32 v33, v33
	v_add_f32_e32 v34, v39, v146
	v_mul_f32_e32 v34, 0xbfb8aa3b, v34
	v_exp_f32_e32 v34, v34
	v_add_f32_e32 v33, 1.0, v33
	v_rcp_f32_e32 v33, v33
	v_add_f32_e32 v34, 1.0, v34
	v_rcp_f32_e32 v34, v34
	v_mul_f32_e32 v33, v33, v96
	v_mul_f32_e32 v35, 0x3fb8aa3b, v33
	v_add_f32_e32 v33, v33, v33
	v_mul_f32_e32 v36, 0x3fb8aa3b, v33
	v_rndne_f32_e32 v36, v36
	v_fmamk_f32 v38, v36, 0xbf317218, v33
	v_fmac_f32_e32 v38, 0x3102e308, v36
	v_fmamk_f32 v39, v38, 0x395133b1, v192
	v_cmp_eq_f32_e32 vcc, s21, v36
	v_cvt_i32_f32_e32 v36, v36
	v_fmaak_f32 v39, v38, v39, 0x3c0887f9
	v_fmaak_f32 v39, v38, v39, 0x3d2aaa81
	v_fmaak_f32 v39, v38, v39, 0x3e2aaaab
	v_fma_f32 v39, v38, v39, 0.5
	v_ldexp_f32 v36, 1.0, v36
	v_mul_f32_e32 v39, v38, v39
	v_cndmask_b32_e32 v36, v36, v202, vcc
	v_fmac_f32_e32 v38, v38, v39
	v_add_f32_e32 v39, -1.0, v36
	v_fmac_f32_e32 v39, v36, v38
	v_add_f32_e32 v36, v39, v39
	v_cndmask_b32_e32 v36, v39, v36, vcc
	v_cmp_nlt_f32_e32 vcc, s22, v33
	v_exp_f32_e32 v35, v35
	s_nop 0
	v_cndmask_b32_e64 v36, v201, -v36, vcc
	v_cmp_gt_f32_e32 vcc, s23, v36
	v_mul_f32_e32 v38, 0x4f800000, v36
	s_nop 0
	v_cndmask_b32_e32 v36, v36, v38, vcc
	v_sqrt_f32_e32 v38, v36
	s_nop 0
	v_add_u32_e32 v39, -1, v38
	v_fma_f32 v48, -v39, v38, v36
	v_cmp_ge_f32_e64 s[0:1], 0, v48
	v_add_u32_e32 v48, 1, v38
	s_nop 0
	v_cndmask_b32_e64 v39, v38, v39, s[0:1]
	v_fma_f32 v38, -v48, v38, v36
	v_cmp_lt_f32_e64 s[0:1], 0, v38
	s_nop 1
	v_cndmask_b32_e64 v38, v39, v48, s[0:1]
	v_mul_f32_e32 v39, 0x37800000, v38
	v_cndmask_b32_e32 v38, v38, v39, vcc
	v_cmp_class_f32_e32 vcc, v36, v193
	s_nop 1
	v_cndmask_b32_e32 v36, v38, v36, vcc
	ds_read2_b32 v[38:39], v32 offset0:192 offset1:224
	v_cmp_ngt_f32_e32 vcc, s24, v33
	s_nop 1
	v_cndmask_b32_e32 v33, 1.0, v36, vcc
	v_mul_f32_e32 v33, v34, v33
	s_waitcnt lgkmcnt(0)
	v_mul_f32_e32 v32, v38, v33
	ds_write_b32 v144, v35 offset:2816
	ds_write_b32 v144, v32 offset:39680
	v_add_f32_e32 v32, v56, v147
	v_mul_f32_e32 v32, 0xbfb8aa3b, v32
	v_exp_f32_e32 v32, v32
	v_add_f32_e32 v33, v40, v146
	v_mul_f32_e32 v33, 0xbfb8aa3b, v33
	v_exp_f32_e32 v33, v33
	v_add_f32_e32 v32, 1.0, v32
	v_rcp_f32_e32 v32, v32
	v_add_f32_e32 v33, 1.0, v33
	v_rcp_f32_e32 v33, v33
	v_mul_f32_e32 v32, v32, v96
	v_mul_f32_e32 v34, 0x3fb8aa3b, v32
	v_add_f32_e32 v32, v32, v32
	v_mul_f32_e32 v35, 0x3fb8aa3b, v32
	v_rndne_f32_e32 v35, v35
	v_fmamk_f32 v36, v35, 0xbf317218, v32
	v_fmac_f32_e32 v36, 0x3102e308, v35
	v_fmamk_f32 v38, v36, 0x395133b1, v192
	v_cmp_eq_f32_e32 vcc, s21, v35
	v_cvt_i32_f32_e32 v35, v35
	v_fmaak_f32 v38, v36, v38, 0x3c0887f9
	v_fmaak_f32 v38, v36, v38, 0x3d2aaa81
	v_fmaak_f32 v38, v36, v38, 0x3e2aaaab
	v_fma_f32 v38, v36, v38, 0.5
	v_ldexp_f32 v35, 1.0, v35
	v_mul_f32_e32 v38, v36, v38
	v_cndmask_b32_e32 v35, v35, v202, vcc
	v_fmac_f32_e32 v36, v36, v38
	v_add_f32_e32 v38, -1.0, v35
	v_fmac_f32_e32 v38, v35, v36
	v_add_f32_e32 v35, v38, v38
	v_cndmask_b32_e32 v35, v38, v35, vcc
	v_cmp_nlt_f32_e32 vcc, s22, v32
	v_exp_f32_e32 v34, v34
	s_nop 0
	v_cndmask_b32_e64 v35, v201, -v35, vcc
	v_cmp_gt_f32_e32 vcc, s23, v35
	v_mul_f32_e32 v36, 0x4f800000, v35
	s_nop 0
	v_cndmask_b32_e32 v35, v35, v36, vcc
	v_sqrt_f32_e32 v36, v35
	s_nop 0
	v_add_u32_e32 v38, -1, v36
	v_fma_f32 v40, -v38, v36, v35
	v_cmp_ge_f32_e64 s[0:1], 0, v40
	v_add_u32_e32 v40, 1, v36
	s_nop 0
	v_cndmask_b32_e64 v38, v36, v38, s[0:1]
	v_fma_f32 v36, -v40, v36, v35
	v_cmp_lt_f32_e64 s[0:1], 0, v36
	s_nop 1
	v_cndmask_b32_e64 v36, v38, v40, s[0:1]
	v_mul_f32_e32 v38, 0x37800000, v36
	v_cndmask_b32_e32 v36, v36, v38, vcc
	v_cmp_class_f32_e32 vcc, v35, v193
	s_nop 1
	v_cndmask_b32_e32 v35, v36, v35, vcc
	v_cmp_ngt_f32_e32 vcc, s24, v32
	s_nop 1
	v_cndmask_b32_e32 v32, 1.0, v35, vcc
	v_mul_f32_e32 v33, v33, v32
	v_add_u32_e32 v32, 0xa000, v144
	ds_read2_b32 v[54:55], v32 offset1:32
	s_waitcnt lgkmcnt(0)
	v_mul_f32_e32 v33, v54, v33
	ds_write_b32 v144, v34 offset:4096
	ds_write_b32 v144, v33 offset:40960
	v_add_f32_e32 v33, v57, v147
	v_mul_f32_e32 v33, 0xbfb8aa3b, v33
	v_exp_f32_e32 v33, v33
	v_add_f32_e32 v34, v41, v146
	v_mul_f32_e32 v34, 0xbfb8aa3b, v34
	v_exp_f32_e32 v34, v34
	v_add_f32_e32 v33, 1.0, v33
	v_rcp_f32_e32 v33, v33
	v_add_f32_e32 v34, 1.0, v34
	v_rcp_f32_e32 v34, v34
	v_mul_f32_e32 v33, v33, v96
	v_mul_f32_e32 v35, 0x3fb8aa3b, v33
	v_add_f32_e32 v33, v33, v33
	v_mul_f32_e32 v36, 0x3fb8aa3b, v33
	v_rndne_f32_e32 v36, v36
	v_fmamk_f32 v38, v36, 0xbf317218, v33
	v_fmac_f32_e32 v38, 0x3102e308, v36
	v_fmamk_f32 v40, v38, 0x395133b1, v192
	v_cmp_eq_f32_e32 vcc, s21, v36
	v_cvt_i32_f32_e32 v36, v36
	v_fmaak_f32 v40, v38, v40, 0x3c0887f9
	v_fmaak_f32 v40, v38, v40, 0x3d2aaa81
	v_fmaak_f32 v40, v38, v40, 0x3e2aaaab
	v_fma_f32 v40, v38, v40, 0.5
	v_ldexp_f32 v36, 1.0, v36
	v_mul_f32_e32 v40, v38, v40
	v_cndmask_b32_e32 v36, v36, v202, vcc
	v_fmac_f32_e32 v38, v38, v40
	v_add_f32_e32 v40, -1.0, v36
	v_fmac_f32_e32 v40, v36, v38
	v_add_f32_e32 v36, v40, v40
	v_cndmask_b32_e32 v36, v40, v36, vcc
	v_cmp_nlt_f32_e32 vcc, s22, v33
	v_exp_f32_e32 v35, v35
	s_nop 0
	v_cndmask_b32_e64 v36, v201, -v36, vcc
	v_cmp_gt_f32_e32 vcc, s23, v36
	v_mul_f32_e32 v38, 0x4f800000, v36
	s_nop 0
	v_cndmask_b32_e32 v36, v36, v38, vcc
	v_sqrt_f32_e32 v38, v36
	s_nop 0
	v_add_u32_e32 v40, -1, v38
	v_fma_f32 v41, -v40, v38, v36
	v_cmp_ge_f32_e64 s[0:1], 0, v41
	v_add_u32_e32 v41, 1, v38
	s_nop 0
	v_cndmask_b32_e64 v40, v38, v40, s[0:1]
	v_fma_f32 v38, -v41, v38, v36
	v_cmp_lt_f32_e64 s[0:1], 0, v38
	s_nop 1
	v_cndmask_b32_e64 v38, v40, v41, s[0:1]
	v_mul_f32_e32 v40, 0x37800000, v38
	v_cndmask_b32_e32 v38, v38, v40, vcc
	ds_read2_b32 v[40:41], v32 offset0:64 offset1:96
	v_cmp_class_f32_e32 vcc, v36, v193
	s_nop 1
	v_cndmask_b32_e32 v36, v38, v36, vcc
	v_cmp_ngt_f32_e32 vcc, s24, v33
	s_nop 1
	v_cndmask_b32_e32 v33, 1.0, v36, vcc
	v_mul_f32_e32 v33, v34, v33
	s_waitcnt lgkmcnt(0)
	v_mul_f32_e32 v33, v40, v33
	ds_write_b32 v144, v35 offset:4352
	ds_write_b32 v144, v33 offset:41216
	v_add_f32_e32 v33, v58, v147
	v_mul_f32_e32 v33, 0xbfb8aa3b, v33
	v_exp_f32_e32 v33, v33
	v_add_f32_e32 v34, v42, v146
	v_mul_f32_e32 v34, 0xbfb8aa3b, v34
	v_exp_f32_e32 v34, v34
	v_add_f32_e32 v33, 1.0, v33
	v_rcp_f32_e32 v33, v33
	ds_read2_b32 v[56:57], v32 offset0:128 offset1:160
	v_add_f32_e32 v34, 1.0, v34
	v_rcp_f32_e32 v34, v34
	v_mul_f32_e32 v33, v33, v96
	v_mul_f32_e32 v35, 0x3fb8aa3b, v33
	v_add_f32_e32 v33, v33, v33
	v_mul_f32_e32 v36, 0x3fb8aa3b, v33
	v_rndne_f32_e32 v36, v36
	v_fmamk_f32 v38, v36, 0xbf317218, v33
	v_fmac_f32_e32 v38, 0x3102e308, v36
	v_fmamk_f32 v40, v38, 0x395133b1, v192
	v_cmp_eq_f32_e32 vcc, s21, v36
	v_cvt_i32_f32_e32 v36, v36
	v_fmaak_f32 v40, v38, v40, 0x3c0887f9
	v_fmaak_f32 v40, v38, v40, 0x3d2aaa81
	v_fmaak_f32 v40, v38, v40, 0x3e2aaaab
	v_fma_f32 v40, v38, v40, 0.5
	v_ldexp_f32 v36, 1.0, v36
	v_mul_f32_e32 v40, v38, v40
	v_cndmask_b32_e32 v36, v36, v202, vcc
	v_fmac_f32_e32 v38, v38, v40
	v_add_f32_e32 v40, -1.0, v36
	v_fmac_f32_e32 v40, v36, v38
	v_add_f32_e32 v36, v40, v40
	v_cndmask_b32_e32 v36, v40, v36, vcc
	v_cmp_nlt_f32_e32 vcc, s22, v33
	v_exp_f32_e32 v35, v35
	s_nop 0
	v_cndmask_b32_e64 v36, v201, -v36, vcc
	v_cmp_gt_f32_e32 vcc, s23, v36
	v_mul_f32_e32 v38, 0x4f800000, v36
	s_nop 0
	v_cndmask_b32_e32 v36, v36, v38, vcc
	v_sqrt_f32_e32 v38, v36
	s_nop 0
	v_add_u32_e32 v40, -1, v38
	v_fma_f32 v42, -v40, v38, v36
	v_cmp_ge_f32_e64 s[0:1], 0, v42
	v_add_u32_e32 v42, 1, v38
	s_nop 0
	v_cndmask_b32_e64 v40, v38, v40, s[0:1]
	v_fma_f32 v38, -v42, v38, v36
	v_cmp_lt_f32_e64 s[0:1], 0, v38
	s_nop 1
	v_cndmask_b32_e64 v38, v40, v42, s[0:1]
	v_mul_f32_e32 v40, 0x37800000, v38
	v_cndmask_b32_e32 v38, v38, v40, vcc
	v_cmp_class_f32_e32 vcc, v36, v193
	s_nop 1
	v_cndmask_b32_e32 v36, v38, v36, vcc
	v_cmp_ngt_f32_e32 vcc, s24, v33
	s_nop 1
	v_cndmask_b32_e32 v33, 1.0, v36, vcc
	v_mul_f32_e32 v33, v34, v33
	s_waitcnt lgkmcnt(0)
	v_mul_f32_e32 v33, v56, v33
	ds_write_b32 v144, v35 offset:4608
	ds_write_b32 v144, v33 offset:41472
	v_add_f32_e32 v33, v59, v147
	v_mul_f32_e32 v33, 0xbfb8aa3b, v33
	v_exp_f32_e32 v33, v33
	v_add_f32_e32 v34, v43, v146
	v_mul_f32_e32 v34, 0xbfb8aa3b, v34
	v_exp_f32_e32 v34, v34
	v_add_f32_e32 v33, 1.0, v33
	v_rcp_f32_e32 v33, v33
	v_add_f32_e32 v34, 1.0, v34
	v_rcp_f32_e32 v34, v34
	v_mul_f32_e32 v33, v33, v96
	v_mul_f32_e32 v35, 0x3fb8aa3b, v33
	v_add_f32_e32 v33, v33, v33
	v_mul_f32_e32 v36, 0x3fb8aa3b, v33
	v_rndne_f32_e32 v36, v36
	v_fmamk_f32 v38, v36, 0xbf317218, v33
	v_fmac_f32_e32 v38, 0x3102e308, v36
	v_fmamk_f32 v40, v38, 0x395133b1, v192
	v_cmp_eq_f32_e32 vcc, s21, v36
	v_cvt_i32_f32_e32 v36, v36
	v_fmaak_f32 v40, v38, v40, 0x3c0887f9
	v_fmaak_f32 v40, v38, v40, 0x3d2aaa81
	v_fmaak_f32 v40, v38, v40, 0x3e2aaaab
	v_fma_f32 v40, v38, v40, 0.5
	v_ldexp_f32 v36, 1.0, v36
	v_mul_f32_e32 v40, v38, v40
	v_cndmask_b32_e32 v36, v36, v202, vcc
	v_fmac_f32_e32 v38, v38, v40
	v_add_f32_e32 v40, -1.0, v36
	v_fmac_f32_e32 v40, v36, v38
	v_add_f32_e32 v36, v40, v40
	v_cndmask_b32_e32 v36, v40, v36, vcc
	v_cmp_nlt_f32_e32 vcc, s22, v33
	v_exp_f32_e32 v35, v35
	s_nop 0
	v_cndmask_b32_e64 v36, v201, -v36, vcc
	v_cmp_gt_f32_e32 vcc, s23, v36
	v_mul_f32_e32 v38, 0x4f800000, v36
	s_nop 0
	v_cndmask_b32_e32 v36, v36, v38, vcc
	v_sqrt_f32_e32 v38, v36
	s_nop 0
	v_add_u32_e32 v40, -1, v38
	v_fma_f32 v42, -v40, v38, v36
	v_cmp_ge_f32_e64 s[0:1], 0, v42
	v_add_u32_e32 v42, 1, v38
	s_nop 0
	v_cndmask_b32_e64 v40, v38, v40, s[0:1]
	v_fma_f32 v38, -v42, v38, v36
	v_cmp_lt_f32_e64 s[0:1], 0, v38
	s_nop 1
	v_cndmask_b32_e64 v38, v40, v42, s[0:1]
	v_mul_f32_e32 v40, 0x37800000, v38
	ds_read2_b32 v[42:43], v32 offset0:192 offset1:224
	v_cndmask_b32_e32 v38, v38, v40, vcc
	v_cmp_class_f32_e32 vcc, v36, v193
	s_nop 1
	v_cndmask_b32_e32 v36, v38, v36, vcc
	v_cmp_ngt_f32_e32 vcc, s24, v33
	s_nop 1
	v_cndmask_b32_e32 v33, 1.0, v36, vcc
	v_mul_f32_e32 v33, v34, v33
	s_waitcnt lgkmcnt(0)
	v_mul_f32_e32 v32, v42, v33
	ds_write_b32 v144, v35 offset:4864
	ds_write_b32 v144, v32 offset:41728
	v_add_f32_e32 v32, v60, v147
	v_mul_f32_e32 v32, 0xbfb8aa3b, v32
	v_exp_f32_e32 v32, v32
	v_add_f32_e32 v33, v44, v146
	v_mul_f32_e32 v33, 0xbfb8aa3b, v33
	v_exp_f32_e32 v33, v33
	v_add_f32_e32 v32, 1.0, v32
	v_rcp_f32_e32 v32, v32
	v_add_f32_e32 v33, 1.0, v33
	v_rcp_f32_e32 v33, v33
	v_mul_f32_e32 v32, v32, v96
	v_mul_f32_e32 v34, 0x3fb8aa3b, v32
	v_add_f32_e32 v32, v32, v32
	v_mul_f32_e32 v35, 0x3fb8aa3b, v32
	v_rndne_f32_e32 v35, v35
	v_fmamk_f32 v36, v35, 0xbf317218, v32
	v_fmac_f32_e32 v36, 0x3102e308, v35
	v_fmamk_f32 v38, v36, 0x395133b1, v192
	v_cmp_eq_f32_e32 vcc, s21, v35
	v_cvt_i32_f32_e32 v35, v35
	v_fmaak_f32 v38, v36, v38, 0x3c0887f9
	v_fmaak_f32 v38, v36, v38, 0x3d2aaa81
	v_fmaak_f32 v38, v36, v38, 0x3e2aaaab
	v_fma_f32 v38, v36, v38, 0.5
	v_ldexp_f32 v35, 1.0, v35
	v_mul_f32_e32 v38, v36, v38
	v_cndmask_b32_e32 v35, v35, v202, vcc
	v_fmac_f32_e32 v36, v36, v38
	v_add_f32_e32 v38, -1.0, v35
	v_fmac_f32_e32 v38, v35, v36
	v_add_f32_e32 v35, v38, v38
	v_cndmask_b32_e32 v35, v38, v35, vcc
	v_cmp_nlt_f32_e32 vcc, s22, v32
	v_exp_f32_e32 v34, v34
	s_nop 0
	v_cndmask_b32_e64 v35, v201, -v35, vcc
	v_cmp_gt_f32_e32 vcc, s23, v35
	v_mul_f32_e32 v36, 0x4f800000, v35
	s_nop 0
	v_cndmask_b32_e32 v35, v35, v36, vcc
	v_sqrt_f32_e32 v36, v35
	s_nop 0
	v_add_u32_e32 v38, -1, v36
	v_fma_f32 v40, -v38, v36, v35
	v_cmp_ge_f32_e64 s[0:1], 0, v40
	v_add_u32_e32 v40, 1, v36
	s_nop 0
	v_cndmask_b32_e64 v38, v36, v38, s[0:1]
	v_fma_f32 v36, -v40, v36, v35
	v_cmp_lt_f32_e64 s[0:1], 0, v36
	s_nop 1
	v_cndmask_b32_e64 v36, v38, v40, s[0:1]
	v_mul_f32_e32 v38, 0x37800000, v36
	v_cndmask_b32_e32 v36, v36, v38, vcc
	v_cmp_class_f32_e32 vcc, v35, v193
	s_nop 1
	v_cndmask_b32_e32 v35, v36, v35, vcc
	v_cmp_ngt_f32_e32 vcc, s24, v32
	s_nop 1
	v_cndmask_b32_e32 v32, 1.0, v35, vcc
	v_mul_f32_e32 v32, v33, v32
	v_add_u32_e32 v33, 0xa800, v144
	ds_read2_b32 v[58:59], v33 offset1:32
	s_waitcnt lgkmcnt(0)
	v_mul_f32_e32 v32, v58, v32
	ds_write_b32 v144, v34 offset:6144
	ds_write_b32 v144, v32 offset:43008
	v_add_f32_e32 v32, v61, v147
	v_mul_f32_e32 v32, 0xbfb8aa3b, v32
	v_exp_f32_e32 v32, v32
	v_add_f32_e32 v34, v45, v146
	v_mul_f32_e32 v34, 0xbfb8aa3b, v34
	v_exp_f32_e32 v34, v34
	v_add_f32_e32 v32, 1.0, v32
	v_rcp_f32_e32 v32, v32
	ds_read2_b32 v[44:45], v33 offset0:64 offset1:96
	v_add_f32_e32 v34, 1.0, v34
	v_rcp_f32_e32 v34, v34
	v_mul_f32_e32 v32, v32, v96
	v_mul_f32_e32 v35, 0x3fb8aa3b, v32
	v_add_f32_e32 v32, v32, v32
	v_mul_f32_e32 v36, 0x3fb8aa3b, v32
	v_rndne_f32_e32 v36, v36
	v_fmamk_f32 v38, v36, 0xbf317218, v32
	v_fmac_f32_e32 v38, 0x3102e308, v36
	v_fmamk_f32 v40, v38, 0x395133b1, v192
	v_cmp_eq_f32_e32 vcc, s21, v36
	v_cvt_i32_f32_e32 v36, v36
	v_fmaak_f32 v40, v38, v40, 0x3c0887f9
	v_fmaak_f32 v40, v38, v40, 0x3d2aaa81
	v_fmaak_f32 v40, v38, v40, 0x3e2aaaab
	v_fma_f32 v40, v38, v40, 0.5
	v_ldexp_f32 v36, 1.0, v36
	v_mul_f32_e32 v40, v38, v40
	v_cndmask_b32_e32 v36, v36, v202, vcc
	v_fmac_f32_e32 v38, v38, v40
	v_add_f32_e32 v40, -1.0, v36
	v_fmac_f32_e32 v40, v36, v38
	v_add_f32_e32 v36, v40, v40
	v_cndmask_b32_e32 v36, v40, v36, vcc
	v_cmp_nlt_f32_e32 vcc, s22, v32
	v_exp_f32_e32 v35, v35
	s_nop 0
	v_cndmask_b32_e64 v36, v201, -v36, vcc
	v_cmp_gt_f32_e32 vcc, s23, v36
	v_mul_f32_e32 v38, 0x4f800000, v36
	s_nop 0
	v_cndmask_b32_e32 v36, v36, v38, vcc
	v_sqrt_f32_e32 v38, v36
	s_nop 0
	v_add_u32_e32 v40, -1, v38
	v_fma_f32 v42, -v40, v38, v36
	v_cmp_ge_f32_e64 s[0:1], 0, v42
	v_add_u32_e32 v42, 1, v38
	s_nop 0
	v_cndmask_b32_e64 v40, v38, v40, s[0:1]
	v_fma_f32 v38, -v42, v38, v36
	v_cmp_lt_f32_e64 s[0:1], 0, v38
	s_nop 1
	v_cndmask_b32_e64 v38, v40, v42, s[0:1]
	v_mul_f32_e32 v40, 0x37800000, v38
	v_cndmask_b32_e32 v38, v38, v40, vcc
	v_cmp_class_f32_e32 vcc, v36, v193
	s_nop 1
	v_cndmask_b32_e32 v36, v38, v36, vcc
	v_cmp_ngt_f32_e32 vcc, s24, v32
	s_nop 1
	v_cndmask_b32_e32 v32, 1.0, v36, vcc
	v_mul_f32_e32 v32, v34, v32
	s_waitcnt lgkmcnt(0)
	v_mul_f32_e32 v32, v44, v32
	ds_write_b32 v144, v35 offset:6400
	ds_write_b32 v144, v32 offset:43264
	v_add_f32_e32 v32, v62, v147
	v_mul_f32_e32 v32, 0xbfb8aa3b, v32
	v_exp_f32_e32 v32, v32
	v_add_f32_e32 v34, v46, v146
	v_mul_f32_e32 v34, 0xbfb8aa3b, v34
	v_exp_f32_e32 v34, v34
	v_add_f32_e32 v32, 1.0, v32
	v_rcp_f32_e32 v32, v32
	v_add_f32_e32 v34, 1.0, v34
	v_rcp_f32_e32 v34, v34
	v_mul_f32_e32 v32, v32, v96
	v_mul_f32_e32 v35, 0x3fb8aa3b, v32
	v_add_f32_e32 v32, v32, v32
	v_exp_f32_e32 v36, v35
	v_mul_f32_e32 v35, 0x3fb8aa3b, v32
	v_rndne_f32_e32 v35, v35
	v_fmamk_f32 v38, v35, 0xbf317218, v32
	v_fmac_f32_e32 v38, 0x3102e308, v35
	v_fmamk_f32 v40, v38, 0x395133b1, v192
	v_cmp_eq_f32_e32 vcc, s21, v35
	v_cvt_i32_f32_e32 v35, v35
	v_fmaak_f32 v40, v38, v40, 0x3c0887f9
	v_fmaak_f32 v40, v38, v40, 0x3d2aaa81
	v_fmaak_f32 v40, v38, v40, 0x3e2aaaab
	v_fma_f32 v40, v38, v40, 0.5
	v_ldexp_f32 v35, 1.0, v35
	v_mul_f32_e32 v40, v38, v40
	v_cndmask_b32_e32 v35, v35, v202, vcc
	v_fmac_f32_e32 v38, v38, v40
	v_add_f32_e32 v40, -1.0, v35
	v_fmac_f32_e32 v40, v35, v38
	v_add_f32_e32 v35, v40, v40
	v_cndmask_b32_e32 v35, v40, v35, vcc
	v_cmp_nlt_f32_e32 vcc, s22, v32
	s_nop 1
	v_cndmask_b32_e64 v35, v201, -v35, vcc
	v_cmp_gt_f32_e32 vcc, s23, v35
	v_mul_f32_e32 v38, 0x4f800000, v35
	s_nop 0
	v_cndmask_b32_e32 v35, v35, v38, vcc
	v_sqrt_f32_e32 v38, v35
	s_nop 0
	v_add_u32_e32 v40, -1, v38
	v_fma_f32 v42, -v40, v38, v35
	v_cmp_ge_f32_e64 s[0:1], 0, v42
	v_add_u32_e32 v42, 1, v38
	s_nop 0
	v_cndmask_b32_e64 v40, v38, v40, s[0:1]
	v_fma_f32 v38, -v42, v38, v35
	v_cmp_lt_f32_e64 s[0:1], 0, v38
	s_nop 1
	v_cndmask_b32_e64 v38, v40, v42, s[0:1]
	v_mul_f32_e32 v40, 0x37800000, v38
	v_cndmask_b32_e32 v38, v38, v40, vcc
	v_cmp_class_f32_e32 vcc, v35, v193
	s_nop 1
	v_cndmask_b32_e32 v35, v38, v35, vcc
	v_cmp_ngt_f32_e32 vcc, s24, v32
	s_nop 1
	v_cndmask_b32_e32 v32, 1.0, v35, vcc
	v_mul_f32_e32 v32, v34, v32
	ds_read2_b32 v[34:35], v33 offset0:128 offset1:160
	s_waitcnt lgkmcnt(0)
	v_mul_f32_e32 v32, v34, v32
	ds_write_b32 v144, v36 offset:6656
	ds_write_b32 v144, v32 offset:43520
	v_add_f32_e32 v32, v63, v147
	v_mul_f32_e32 v32, 0xbfb8aa3b, v32
	v_exp_f32_e32 v32, v32
	v_add_f32_e32 v34, v47, v146
	v_mul_f32_e32 v34, 0xbfb8aa3b, v34
	v_exp_f32_e32 v34, v34
	v_add_f32_e32 v32, 1.0, v32
	v_rcp_f32_e32 v32, v32
	v_add_f32_e32 v34, 1.0, v34
	v_rcp_f32_e32 v36, v34
	v_mul_f32_e32 v32, v32, v96
	v_mul_f32_e32 v34, 0x3fb8aa3b, v32
	v_add_f32_e32 v32, v32, v32
	v_mul_f32_e32 v38, 0x3fb8aa3b, v32
	v_rndne_f32_e32 v38, v38
	v_fmamk_f32 v40, v38, 0xbf317218, v32
	v_fmac_f32_e32 v40, 0x3102e308, v38
	v_fmamk_f32 v42, v40, 0x395133b1, v192
	v_cmp_eq_f32_e32 vcc, s21, v38
	v_cvt_i32_f32_e32 v38, v38
	v_fmaak_f32 v42, v40, v42, 0x3c0887f9
	v_fmaak_f32 v42, v40, v42, 0x3d2aaa81
	v_fmaak_f32 v42, v40, v42, 0x3e2aaaab
	v_fma_f32 v42, v40, v42, 0.5
	v_ldexp_f32 v38, 1.0, v38
	v_mul_f32_e32 v42, v40, v42
	v_cndmask_b32_e32 v38, v38, v202, vcc
	v_fmac_f32_e32 v40, v40, v42
	v_add_f32_e32 v42, -1.0, v38
	v_fmac_f32_e32 v42, v38, v40
	v_add_f32_e32 v38, v42, v42
	v_cndmask_b32_e32 v38, v42, v38, vcc
	v_cmp_nlt_f32_e32 vcc, s22, v32
	v_add_u32_e32 v96, s3, v145
	v_lshlrev_b64 v[46:47], 2, v[96:97]
	v_cndmask_b32_e64 v38, v201, -v38, vcc
	v_cmp_gt_f32_e32 vcc, s23, v38
	v_mul_f32_e32 v40, 0x4f800000, v38
	s_nop 0
	v_cndmask_b32_e32 v38, v38, v40, vcc
	v_sqrt_f32_e32 v40, v38
	v_exp_f32_e32 v34, v34
	s_movk_i32 s18, 0x1600
	s_mov_b32 s19, 0x2c000
	v_add_u32_e32 v42, -1, v40
	v_fma_f32 v44, -v42, v40, v38
	v_cmp_ge_f32_e64 s[0:1], 0, v44
	v_add_u32_e32 v44, 1, v40
	s_nop 0
	v_cndmask_b32_e64 v42, v40, v42, s[0:1]
	v_fma_f32 v40, -v44, v40, v38
	v_cmp_lt_f32_e64 s[0:1], 0, v40
	s_nop 1
	v_cndmask_b32_e64 v40, v42, v44, s[0:1]
	v_mul_f32_e32 v42, 0x37800000, v40
	v_cndmask_b32_e32 v40, v40, v42, vcc
	v_cmp_class_f32_e32 vcc, v38, v193
	s_nop 1
	v_cndmask_b32_e32 v38, v40, v38, vcc
	v_cmp_ngt_f32_e32 vcc, s24, v32
	s_nop 1
	v_cndmask_b32_e32 v32, 1.0, v38, vcc
	v_mul_f32_e32 v36, v36, v32
	ds_read2_b32 v[32:33], v33 offset0:192 offset1:224
	s_waitcnt lgkmcnt(0)
	v_mul_f32_e32 v32, v32, v36
	ds_write_b32 v144, v32 offset:43776
	v_mul_f32_e32 v32, 0xbfb8aa3b, v226
	v_exp_f32_e32 v32, v32
	s_nop 0
	v_add_f32_e32 v36, 1.0, v32
	v_add_f32_e32 v38, -1.0, v36
	v_sub_f32_e32 v40, v38, v36
	v_add_f32_e32 v40, 1.0, v40
	v_sub_f32_e32 v38, v32, v38
	v_add_f32_e32 v38, v38, v40
	v_frexp_mant_f32_e32 v40, v36
	v_cvt_f64_f32_e32 v[60:61], v36
	v_cmp_gt_f32_e32 vcc, s8, v40
	v_frexp_exp_i32_f64_e32 v40, v[60:61]
	s_nop 0
	v_subbrev_co_u32_e32 v40, vcc, 0, v40, vcc
	v_sub_u32_e32 v42, 0, v40
	v_ldexp_f32 v36, v36, v42
	v_ldexp_f32 v38, v38, v42
	v_add_f32_e32 v42, -1.0, v36
	v_add_f32_e32 v48, 1.0, v36
	v_add_f32_e32 v44, 1.0, v42
	v_add_f32_e32 v50, -1.0, v48
	v_sub_f32_e32 v44, v36, v44
	v_sub_f32_e32 v36, v36, v50
	v_add_f32_e32 v36, v38, v36
	v_add_f32_e32 v44, v38, v44
	v_add_f32_e32 v38, v48, v36
	v_sub_f32_e32 v48, v38, v48
	v_sub_f32_e32 v36, v36, v48
	v_rcp_f32_e32 v48, v38
	v_add_f32_e32 v61, v42, v44
	v_sub_f32_e32 v42, v61, v42
	v_sub_f32_e32 v42, v44, v42
	v_mul_f32_e32 v44, v61, v48
	v_mul_f32_e32 v62, v38, v44
	v_fma_f32 v146, v44, v38, -v62
	v_fmac_f32_e32 v146, v44, v36
	v_add_f32_e32 v60, v62, v146
	v_sub_f32_e32 v63, v61, v60
	v_pk_add_f32 v[148:149], v[60:61], v[62:63] neg_lo:[0,1] neg_hi:[0,1]
	v_mov_b32_e32 v147, v60
	v_pk_add_f32 v[60:61], v[148:149], v[146:147] neg_lo:[0,1] neg_hi:[0,1]
	v_cmp_neq_f32_e32 vcc, s10, v32
	v_add_f32_e32 v42, v42, v61
	v_add_f32_e32 v42, v60, v42
	v_add_f32_e32 v61, v63, v42
	v_mul_f32_e32 v50, v48, v61
	v_mul_f32_e32 v62, v38, v50
	v_fma_f32 v146, v50, v38, -v62
	v_fmac_f32_e32 v146, v50, v36
	v_add_f32_e32 v60, v62, v146
	v_sub_f32_e32 v36, v63, v61
	v_sub_f32_e32 v63, v61, v60
	v_pk_add_f32 v[148:149], v[60:61], v[62:63] neg_lo:[0,1] neg_hi:[0,1]
	v_mov_b32_e32 v147, v60
	v_add_f32_e32 v36, v42, v36
	v_pk_add_f32 v[60:61], v[148:149], v[146:147] neg_lo:[0,1] neg_hi:[0,1]
	v_add_f32_e32 v38, v44, v50
	v_add_f32_e32 v36, v36, v61
	v_add_f32_e32 v36, v60, v36
	v_add_f32_e32 v36, v63, v36
	v_sub_f32_e32 v42, v38, v44
	v_mul_f32_e32 v36, v48, v36
	v_sub_f32_e32 v42, v50, v42
	v_add_f32_e32 v36, v42, v36
	v_add_f32_e32 v42, v38, v36
	v_cvt_f32_i32_e32 v60, v40
	v_mul_f32_e32 v44, v42, v42
	v_fmamk_f32 v48, v44, 0x3e9b6dac, v191
	v_fmaak_f32 v169, v44, v48, 0x3f2aaada
	v_mul_f32_e32 v61, v42, v44
	v_pk_mul_f32 v[146:147], v[60:61], v[168:169]
	v_ldexp_f32 v63, v42, 1
	v_fma_f32 v62, v60, s9, -v146
	v_fmac_f32_e32 v62, 0xb102e308, v60
	v_sub_f32_e32 v38, v42, v38
	v_pk_add_f32 v[60:61], v[146:147], v[62:63]
	v_sub_f32_e32 v36, v36, v38
	v_sub_f32_e32 v38, v61, v63
	v_ldexp_f32 v36, v36, 1
	v_sub_f32_e32 v38, v147, v38
	v_add_f32_e32 v149, v36, v38
	v_mov_b32_e32 v148, v146
	v_pk_add_f32 v[146:147], v[60:61], v[146:147] neg_lo:[0,1] neg_hi:[0,1]
	v_pk_add_f32 v[150:151], v[60:61], v[148:149]
	v_mov_b32_e32 v63, v60
	v_mov_b32_e32 v147, v151
	v_pk_add_f32 v[152:153], v[62:63], v[146:147] neg_lo:[0,1] neg_hi:[0,1]
	v_pk_add_f32 v[62:63], v[62:63], v[146:147]
	v_mov_b32_e32 v148, v149
	v_pk_add_f32 v[146:147], v[62:63], v[60:61] op_sel:[1,0] op_sel_hi:[0,1] neg_lo:[0,1] neg_hi:[0,1]
	v_pk_add_f32 v[154:155], v[150:151], v[146:147] op_sel_hi:[1,0] neg_lo:[0,1] neg_hi:[0,1]
	v_mov_b32_e32 v150, v151
	v_mov_b32_e32 v151, v63
	v_pk_mov_b32 v[146:147], v[60:61], v[146:147] op_sel:[1,0]
	v_mov_b32_e32 v149, v60
	v_pk_add_f32 v[146:147], v[150:151], v[146:147] neg_lo:[0,1] neg_hi:[0,1]
	v_mov_b32_e32 v154, v152
	v_pk_add_f32 v[60:61], v[148:149], v[146:147] neg_lo:[0,1] neg_hi:[0,1]
	v_mov_b32_e32 v153, v63
	v_pk_add_f32 v[146:147], v[154:155], v[60:61]
	v_readlane_b32 s10, v248, 33
	v_pk_add_f32 v[148:149], v[146:147], v[146:147] op_sel:[0,1] op_sel_hi:[1,0]
	v_pk_add_f32 v[62:63], v[62:63], v[148:149] op_sel:[1,0] op_sel_hi:[0,1]
	v_mov_b32_e32 v147, v62
	v_pk_add_f32 v[150:151], v[146:147], v[152:153] neg_lo:[0,1] neg_hi:[0,1]
	v_mov_b32_e32 v61, v148
	v_sub_f32_e32 v36, v146, v150
	v_pk_add_f32 v[60:61], v[60:61], v[150:151] neg_lo:[0,1] neg_hi:[0,1]
	v_sub_f32_e32 v36, v152, v36
	v_add_f32_e32 v36, v60, v36
	v_add_f32_e32 v36, v36, v61
	v_add_f32_e32 v36, v62, v36
	v_cndmask_b32_e32 v36, v199, v36, vcc
	v_cmp_ngt_f32_e32 vcc, -1.0, v32
	v_lshl_add_u64 v[60:61], s[52:53], 0, v[46:47]
	s_nop 0
	v_cndmask_b32_e32 v36, v200, v36, vcc
	v_cmp_neq_f32_e32 vcc, -1.0, v32
	v_mov_b32_e32 v38, v227
	s_mov_b64 s[16:17], s[82:83]
	v_cndmask_b32_e32 v36, v201, v36, vcc
	v_cmp_lt_f32_e64 vcc, |v32|, s20
	s_mov_b32 s20, 0x58000
	v_add_f32_e32 v0, v0, v38
	v_cndmask_b32_e32 v32, v36, v32, vcc
	v_mov_b32_e32 v36, v228
	v_mul_f32_e32 v32, 0xc1000000, v32
	v_mul_f32_e32 v0, 0xbfb8aa3b, v0
	v_exp_f32_e32 v0, v0
	v_add_f32_e32 v1, v1, v38
	v_mul_f32_e32 v1, 0xbfb8aa3b, v1
	v_exp_f32_e32 v1, v1
	v_add_f32_e32 v0, 1.0, v0
	v_rcp_f32_e32 v0, v0
	v_add_f32_e32 v1, 1.0, v1
	v_rcp_f32_e32 v1, v1
	v_add_f32_e32 v16, v16, v36
	v_mul_f32_e32 v16, 0xbfb8aa3b, v16
	v_exp_f32_e32 v16, v16
	s_nop 0
	v_add_f32_e32 v16, 1.0, v16
	v_rcp_f32_e32 v16, v16
	s_nop 0
	v_mul_f32_e32 v16, v16, v32
	v_mul_f32_e32 v40, 0x3fb8aa3b, v16
	v_add_f32_e32 v16, v16, v16
	v_mul_f32_e32 v42, 0x3fb8aa3b, v16
	v_rndne_f32_e32 v42, v42
	v_fmamk_f32 v44, v42, 0xbf317218, v16
	v_fmac_f32_e32 v44, 0x3102e308, v42
	v_fmamk_f32 v46, v44, 0x395133b1, v192
	v_cmp_eq_f32_e32 vcc, s21, v42
	v_cvt_i32_f32_e32 v42, v42
	v_fmaak_f32 v46, v44, v46, 0x3c0887f9
	v_fmaak_f32 v46, v44, v46, 0x3d2aaa81
	v_fmaak_f32 v46, v44, v46, 0x3e2aaaab
	v_fma_f32 v46, v44, v46, 0.5
	v_ldexp_f32 v42, 1.0, v42
	v_mul_f32_e32 v46, v44, v46
	v_cndmask_b32_e32 v42, v42, v202, vcc
	v_fmac_f32_e32 v44, v44, v46
	v_add_f32_e32 v46, -1.0, v42
	v_fmac_f32_e32 v46, v42, v44
	v_add_f32_e32 v42, v46, v46
	v_cndmask_b32_e32 v42, v46, v42, vcc
	v_cmp_nlt_f32_e32 vcc, s22, v16
	v_exp_f32_e32 v40, v40
	s_nop 0
	v_cndmask_b32_e64 v42, v201, -v42, vcc
	v_cmp_gt_f32_e32 vcc, s23, v42
	v_mul_f32_e32 v44, 0x4f800000, v42
	s_nop 0
	v_cndmask_b32_e32 v42, v42, v44, vcc
	v_sqrt_f32_e32 v44, v42
	s_nop 0
	v_add_u32_e32 v46, -1, v44
	v_fma_f32 v47, -v46, v44, v42
	v_cmp_ge_f32_e64 s[0:1], 0, v47
	v_add_u32_e32 v47, 1, v44
	s_nop 0
	v_cndmask_b32_e64 v46, v44, v46, s[0:1]
	v_fma_f32 v44, -v47, v44, v42
	v_cmp_lt_f32_e64 s[0:1], 0, v44
	s_nop 1
	v_cndmask_b32_e64 v44, v46, v47, s[0:1]
	v_mul_f32_e32 v46, 0x37800000, v44
	v_cndmask_b32_e32 v44, v44, v46, vcc
	v_cmp_class_f32_e32 vcc, v42, v193
	s_nop 1
	v_cndmask_b32_e32 v42, v44, v42, vcc
	v_cmp_ngt_f32_e32 vcc, s24, v16
	s_nop 1
	v_cndmask_b32_e32 v16, 1.0, v42, vcc
	v_mul_f32_e32 v0, v0, v16
	v_mul_f32_e32 v0, v135, v0
	ds_write_b32 v144, v40 offset:128
	ds_write_b32 v144, v0 offset:36992
	v_add_f32_e32 v0, v17, v36
	v_mul_f32_e32 v0, 0xbfb8aa3b, v0
	v_exp_f32_e32 v0, v0
	s_nop 0
	v_add_f32_e32 v0, 1.0, v0
	v_rcp_f32_e32 v0, v0
	s_nop 0
	v_mul_f32_e32 v0, v0, v32
	v_mul_f32_e32 v16, 0x3fb8aa3b, v0
	v_add_f32_e32 v0, v0, v0
	v_mul_f32_e32 v17, 0x3fb8aa3b, v0
	v_rndne_f32_e32 v17, v17
	v_fmamk_f32 v40, v17, 0xbf317218, v0
	v_fmac_f32_e32 v40, 0x3102e308, v17
	v_fmamk_f32 v42, v40, 0x395133b1, v192
	v_cmp_eq_f32_e32 vcc, s21, v17
	v_cvt_i32_f32_e32 v17, v17
	v_fmaak_f32 v42, v40, v42, 0x3c0887f9
	v_fmaak_f32 v42, v40, v42, 0x3d2aaa81
	v_fmaak_f32 v42, v40, v42, 0x3e2aaaab
	v_fma_f32 v42, v40, v42, 0.5
	v_ldexp_f32 v17, 1.0, v17
	v_mul_f32_e32 v42, v40, v42
	v_cndmask_b32_e32 v17, v17, v202, vcc
	v_fmac_f32_e32 v40, v40, v42
	v_add_f32_e32 v42, -1.0, v17
	v_fmac_f32_e32 v42, v17, v40
	v_add_f32_e32 v17, v42, v42
	v_cndmask_b32_e32 v17, v42, v17, vcc
	v_cmp_nlt_f32_e32 vcc, s22, v0
	v_exp_f32_e32 v16, v16
	s_nop 0
	v_cndmask_b32_e64 v17, v201, -v17, vcc
	v_cmp_gt_f32_e32 vcc, s23, v17
	v_mul_f32_e32 v40, 0x4f800000, v17
	s_nop 0
	v_cndmask_b32_e32 v17, v17, v40, vcc
	v_sqrt_f32_e32 v40, v17
	s_nop 0
	v_add_u32_e32 v42, -1, v40
	v_fma_f32 v44, -v42, v40, v17
	v_cmp_ge_f32_e64 s[0:1], 0, v44
	v_add_u32_e32 v44, 1, v40
	s_nop 0
	v_cndmask_b32_e64 v42, v40, v42, s[0:1]
	v_fma_f32 v40, -v44, v40, v17
	v_cmp_lt_f32_e64 s[0:1], 0, v40
	s_nop 1
	v_cndmask_b32_e64 v40, v42, v44, s[0:1]
	v_mul_f32_e32 v42, 0x37800000, v40
	v_cndmask_b32_e32 v40, v40, v42, vcc
	v_cmp_class_f32_e32 vcc, v17, v193
	s_nop 1
	v_cndmask_b32_e32 v17, v40, v17, vcc
	v_cmp_ngt_f32_e32 vcc, s24, v0
	s_nop 1
	v_cndmask_b32_e32 v0, 1.0, v17, vcc
	v_mul_f32_e32 v0, v1, v0
	v_mul_f32_e32 v0, v49, v0
	ds_write_b32 v144, v16 offset:384
	ds_write_b32 v144, v0 offset:37248
	v_add_f32_e32 v0, v18, v36
	v_mul_f32_e32 v0, 0xbfb8aa3b, v0
	v_exp_f32_e32 v0, v0
	v_add_f32_e32 v1, v2, v38
	v_mul_f32_e32 v1, 0xbfb8aa3b, v1
	v_exp_f32_e32 v1, v1
	v_add_f32_e32 v0, 1.0, v0
	v_rcp_f32_e32 v0, v0
	v_add_f32_e32 v1, 1.0, v1
	v_rcp_f32_e32 v1, v1
	v_mul_f32_e32 v0, v0, v32
	v_mul_f32_e32 v2, 0x3fb8aa3b, v0
	v_add_f32_e32 v0, v0, v0
	v_mul_f32_e32 v16, 0x3fb8aa3b, v0
	v_rndne_f32_e32 v16, v16
	v_fmamk_f32 v17, v16, 0xbf317218, v0
	v_fmac_f32_e32 v17, 0x3102e308, v16
	v_fmamk_f32 v18, v17, 0x395133b1, v192
	v_cmp_eq_f32_e32 vcc, s21, v16
	v_cvt_i32_f32_e32 v16, v16
	v_fmaak_f32 v18, v17, v18, 0x3c0887f9
	v_fmaak_f32 v18, v17, v18, 0x3d2aaa81
	v_fmaak_f32 v18, v17, v18, 0x3e2aaaab
	v_fma_f32 v18, v17, v18, 0.5
	v_ldexp_f32 v16, 1.0, v16
	v_mul_f32_e32 v18, v17, v18
	v_cndmask_b32_e32 v16, v16, v202, vcc
	v_fmac_f32_e32 v17, v17, v18
	v_add_f32_e32 v18, -1.0, v16
	v_fmac_f32_e32 v18, v16, v17
	v_add_f32_e32 v16, v18, v18
	v_cndmask_b32_e32 v16, v18, v16, vcc
	v_cmp_nlt_f32_e32 vcc, s22, v0
	v_exp_f32_e32 v2, v2
	s_nop 0
	v_cndmask_b32_e64 v16, v201, -v16, vcc
	v_cmp_gt_f32_e32 vcc, s23, v16
	v_mul_f32_e32 v17, 0x4f800000, v16
	s_nop 0
	v_cndmask_b32_e32 v16, v16, v17, vcc
	v_sqrt_f32_e32 v17, v16
	s_nop 0
	v_add_u32_e32 v18, -1, v17
	v_fma_f32 v40, -v18, v17, v16
	v_cmp_ge_f32_e64 s[0:1], 0, v40
	v_add_u32_e32 v40, 1, v17
	s_nop 0
	v_cndmask_b32_e64 v18, v17, v18, s[0:1]
	v_fma_f32 v17, -v40, v17, v16
	v_cmp_lt_f32_e64 s[0:1], 0, v17
	s_nop 1
	v_cndmask_b32_e64 v17, v18, v40, s[0:1]
	v_mul_f32_e32 v18, 0x37800000, v17
	v_cndmask_b32_e32 v17, v17, v18, vcc
	v_cmp_class_f32_e32 vcc, v16, v193
	s_nop 1
	v_cndmask_b32_e32 v16, v17, v16, vcc
	v_cmp_ngt_f32_e32 vcc, s24, v0
	s_nop 1
	v_cndmask_b32_e32 v0, 1.0, v16, vcc
	v_mul_f32_e32 v0, v1, v0
	v_mul_f32_e32 v0, v137, v0
	ds_write_b32 v144, v2 offset:640
	ds_write_b32 v144, v0 offset:37504
	v_add_f32_e32 v0, v19, v36
	v_mul_f32_e32 v0, 0xbfb8aa3b, v0
	v_exp_f32_e32 v0, v0
	v_add_f32_e32 v1, v3, v38
	v_mul_f32_e32 v1, 0xbfb8aa3b, v1
	v_exp_f32_e32 v1, v1
	v_add_f32_e32 v0, 1.0, v0
	v_rcp_f32_e32 v0, v0
	v_add_f32_e32 v1, 1.0, v1
	v_rcp_f32_e32 v1, v1
	v_mul_f32_e32 v0, v0, v32
	v_mul_f32_e32 v2, 0x3fb8aa3b, v0
	v_add_f32_e32 v0, v0, v0
	v_mul_f32_e32 v3, 0x3fb8aa3b, v0
	v_rndne_f32_e32 v3, v3
	v_fmamk_f32 v16, v3, 0xbf317218, v0
	v_fmac_f32_e32 v16, 0x3102e308, v3
	v_fmamk_f32 v17, v16, 0x395133b1, v192
	v_cmp_eq_f32_e32 vcc, s21, v3
	v_cvt_i32_f32_e32 v3, v3
	v_fmaak_f32 v17, v16, v17, 0x3c0887f9
	v_fmaak_f32 v17, v16, v17, 0x3d2aaa81
	v_fmaak_f32 v17, v16, v17, 0x3e2aaaab
	v_fma_f32 v17, v16, v17, 0.5
	v_ldexp_f32 v3, 1.0, v3
	v_mul_f32_e32 v17, v16, v17
	v_cndmask_b32_e32 v3, v3, v202, vcc
	v_fmac_f32_e32 v16, v16, v17
	v_add_f32_e32 v17, -1.0, v3
	v_fmac_f32_e32 v17, v3, v16
	v_add_f32_e32 v3, v17, v17
	v_cndmask_b32_e32 v3, v17, v3, vcc
	v_cmp_nlt_f32_e32 vcc, s22, v0
	v_exp_f32_e32 v2, v2
	s_nop 0
	v_cndmask_b32_e64 v3, v201, -v3, vcc
	v_cmp_gt_f32_e32 vcc, s23, v3
	v_mul_f32_e32 v16, 0x4f800000, v3
	s_nop 0
	v_cndmask_b32_e32 v3, v3, v16, vcc
	v_sqrt_f32_e32 v16, v3
	s_nop 0
	v_add_u32_e32 v17, -1, v16
	v_fma_f32 v18, -v17, v16, v3
	v_cmp_ge_f32_e64 s[0:1], 0, v18
	v_add_u32_e32 v18, 1, v16
	s_nop 0
	v_cndmask_b32_e64 v17, v16, v17, s[0:1]
	v_fma_f32 v16, -v18, v16, v3
	v_cmp_lt_f32_e64 s[0:1], 0, v16
	s_nop 1
	v_cndmask_b32_e64 v16, v17, v18, s[0:1]
	v_mul_f32_e32 v17, 0x37800000, v16
	v_cndmask_b32_e32 v16, v16, v17, vcc
	v_cmp_class_f32_e32 vcc, v3, v193
	s_nop 1
	v_cndmask_b32_e32 v3, v16, v3, vcc
	v_cmp_ngt_f32_e32 vcc, s24, v0
	s_nop 1
	v_cndmask_b32_e32 v0, 1.0, v3, vcc
	v_mul_f32_e32 v0, v1, v0
	v_mul_f32_e32 v0, v51, v0
	ds_write_b32 v144, v2 offset:896
	ds_write_b32 v144, v0 offset:37760
	v_add_f32_e32 v0, v20, v36
	v_mul_f32_e32 v0, 0xbfb8aa3b, v0
	v_exp_f32_e32 v0, v0
	v_add_f32_e32 v1, v4, v38
	v_mul_f32_e32 v1, 0xbfb8aa3b, v1
	v_exp_f32_e32 v1, v1
	v_add_f32_e32 v0, 1.0, v0
	v_rcp_f32_e32 v0, v0
	v_add_f32_e32 v1, 1.0, v1
	v_rcp_f32_e32 v1, v1
	v_mul_f32_e32 v0, v0, v32
	v_mul_f32_e32 v2, 0x3fb8aa3b, v0
	v_add_f32_e32 v0, v0, v0
	v_mul_f32_e32 v3, 0x3fb8aa3b, v0
	v_rndne_f32_e32 v3, v3
	v_fmamk_f32 v4, v3, 0xbf317218, v0
	v_fmac_f32_e32 v4, 0x3102e308, v3
	v_fmamk_f32 v16, v4, 0x395133b1, v192
	v_cmp_eq_f32_e32 vcc, s21, v3
	v_cvt_i32_f32_e32 v3, v3
	v_fmaak_f32 v16, v4, v16, 0x3c0887f9
	v_fmaak_f32 v16, v4, v16, 0x3d2aaa81
	v_fmaak_f32 v16, v4, v16, 0x3e2aaaab
	v_fma_f32 v16, v4, v16, 0.5
	v_ldexp_f32 v3, 1.0, v3
	v_mul_f32_e32 v16, v4, v16
	v_cndmask_b32_e32 v3, v3, v202, vcc
	v_fmac_f32_e32 v4, v4, v16
	v_add_f32_e32 v16, -1.0, v3
	v_fmac_f32_e32 v16, v3, v4
	v_add_f32_e32 v3, v16, v16
	v_cndmask_b32_e32 v3, v16, v3, vcc
	v_cmp_nlt_f32_e32 vcc, s22, v0
	v_exp_f32_e32 v2, v2
	s_nop 0
	v_cndmask_b32_e64 v3, v201, -v3, vcc
	v_cmp_gt_f32_e32 vcc, s23, v3
	v_mul_f32_e32 v4, 0x4f800000, v3
	s_nop 0
	v_cndmask_b32_e32 v3, v3, v4, vcc
	v_sqrt_f32_e32 v4, v3
	s_nop 0
	v_add_u32_e32 v16, -1, v4
	v_fma_f32 v17, -v16, v4, v3
	v_cmp_ge_f32_e64 s[0:1], 0, v17
	v_add_u32_e32 v17, 1, v4
	s_nop 0
	v_cndmask_b32_e64 v16, v4, v16, s[0:1]
	v_fma_f32 v4, -v17, v4, v3
	v_cmp_lt_f32_e64 s[0:1], 0, v4
	s_nop 1
	v_cndmask_b32_e64 v4, v16, v17, s[0:1]
	v_mul_f32_e32 v16, 0x37800000, v4
	v_cndmask_b32_e32 v4, v4, v16, vcc
	v_cmp_class_f32_e32 vcc, v3, v193
	s_nop 1
	v_cndmask_b32_e32 v3, v4, v3, vcc
	v_cmp_ngt_f32_e32 vcc, s24, v0
	s_nop 1
	v_cndmask_b32_e32 v0, 1.0, v3, vcc
	v_mul_f32_e32 v0, v1, v0
	v_mul_f32_e32 v0, v139, v0
	ds_write_b32 v144, v2 offset:2176
	ds_write_b32 v144, v0 offset:39040
	v_add_f32_e32 v0, v21, v36
	v_mul_f32_e32 v0, 0xbfb8aa3b, v0
	v_exp_f32_e32 v0, v0
	v_add_f32_e32 v1, v5, v38
	v_mul_f32_e32 v1, 0xbfb8aa3b, v1
	v_exp_f32_e32 v1, v1
	v_add_f32_e32 v0, 1.0, v0
	v_rcp_f32_e32 v0, v0
	v_add_f32_e32 v1, 1.0, v1
	v_rcp_f32_e32 v1, v1
	v_mul_f32_e32 v0, v0, v32
	v_mul_f32_e32 v2, 0x3fb8aa3b, v0
	v_add_f32_e32 v0, v0, v0
	v_mul_f32_e32 v3, 0x3fb8aa3b, v0
	v_rndne_f32_e32 v3, v3
	v_fmamk_f32 v4, v3, 0xbf317218, v0
	v_fmac_f32_e32 v4, 0x3102e308, v3
	v_fmamk_f32 v5, v4, 0x395133b1, v192
	v_cmp_eq_f32_e32 vcc, s21, v3
	v_cvt_i32_f32_e32 v3, v3
	v_fmaak_f32 v5, v4, v5, 0x3c0887f9
	v_fmaak_f32 v5, v4, v5, 0x3d2aaa81
	v_fmaak_f32 v5, v4, v5, 0x3e2aaaab
	v_fma_f32 v5, v4, v5, 0.5
	v_ldexp_f32 v3, 1.0, v3
	v_mul_f32_e32 v5, v4, v5
	v_cndmask_b32_e32 v3, v3, v202, vcc
	v_fmac_f32_e32 v4, v4, v5
	v_add_f32_e32 v5, -1.0, v3
	v_fmac_f32_e32 v5, v3, v4
	v_add_f32_e32 v3, v5, v5
	v_cndmask_b32_e32 v3, v5, v3, vcc
	v_cmp_nlt_f32_e32 vcc, s22, v0
	v_exp_f32_e32 v2, v2
	s_nop 0
	v_cndmask_b32_e64 v3, v201, -v3, vcc
	v_cmp_gt_f32_e32 vcc, s23, v3
	v_mul_f32_e32 v4, 0x4f800000, v3
	s_nop 0
	v_cndmask_b32_e32 v3, v3, v4, vcc
	v_sqrt_f32_e32 v4, v3
	s_nop 0
	v_add_u32_e32 v5, -1, v4
	v_fma_f32 v16, -v5, v4, v3
	v_cmp_ge_f32_e64 s[0:1], 0, v16
	v_add_u32_e32 v16, 1, v4
	s_nop 0
	v_cndmask_b32_e64 v5, v4, v5, s[0:1]
	v_fma_f32 v4, -v16, v4, v3
	v_cmp_lt_f32_e64 s[0:1], 0, v4
	s_nop 1
	v_cndmask_b32_e64 v4, v5, v16, s[0:1]
	v_mul_f32_e32 v5, 0x37800000, v4
	v_cndmask_b32_e32 v4, v4, v5, vcc
	v_cmp_class_f32_e32 vcc, v3, v193
	s_nop 1
	v_cndmask_b32_e32 v3, v4, v3, vcc
	v_cmp_ngt_f32_e32 vcc, s24, v0
	s_nop 1
	v_cndmask_b32_e32 v0, 1.0, v3, vcc
	v_mul_f32_e32 v0, v1, v0
	v_mul_f32_e32 v0, v37, v0
	ds_write_b32 v144, v2 offset:2432
	ds_write_b32 v144, v0 offset:39296
	v_add_f32_e32 v0, v22, v36
	v_mul_f32_e32 v0, 0xbfb8aa3b, v0
	v_exp_f32_e32 v0, v0
	v_add_f32_e32 v1, v6, v38
	v_mul_f32_e32 v1, 0xbfb8aa3b, v1
	v_exp_f32_e32 v1, v1
	v_add_f32_e32 v0, 1.0, v0
	v_rcp_f32_e32 v0, v0
	v_add_f32_e32 v1, 1.0, v1
	v_rcp_f32_e32 v1, v1
	v_mul_f32_e32 v0, v0, v32
	v_mul_f32_e32 v2, 0x3fb8aa3b, v0
	v_add_f32_e32 v0, v0, v0
	v_mul_f32_e32 v3, 0x3fb8aa3b, v0
	v_rndne_f32_e32 v3, v3
	v_fmamk_f32 v4, v3, 0xbf317218, v0
	v_fmac_f32_e32 v4, 0x3102e308, v3
	v_fmamk_f32 v5, v4, 0x395133b1, v192
	v_cmp_eq_f32_e32 vcc, s21, v3
	v_cvt_i32_f32_e32 v3, v3
	v_fmaak_f32 v5, v4, v5, 0x3c0887f9
	v_fmaak_f32 v5, v4, v5, 0x3d2aaa81
	v_fmaak_f32 v5, v4, v5, 0x3e2aaaab
	v_fma_f32 v5, v4, v5, 0.5
	v_ldexp_f32 v3, 1.0, v3
	v_mul_f32_e32 v5, v4, v5
	v_cndmask_b32_e32 v3, v3, v202, vcc
	v_fmac_f32_e32 v4, v4, v5
	v_add_f32_e32 v5, -1.0, v3
	v_fmac_f32_e32 v5, v3, v4
	v_add_f32_e32 v3, v5, v5
	v_cndmask_b32_e32 v3, v5, v3, vcc
	v_cmp_nlt_f32_e32 vcc, s22, v0
	v_exp_f32_e32 v2, v2
	s_nop 0
	v_cndmask_b32_e64 v3, v201, -v3, vcc
	v_cmp_gt_f32_e32 vcc, s23, v3
	v_mul_f32_e32 v4, 0x4f800000, v3
	s_nop 0
	v_cndmask_b32_e32 v3, v3, v4, vcc
	v_sqrt_f32_e32 v4, v3
	s_nop 0
	v_add_u32_e32 v5, -1, v4
	v_fma_f32 v6, -v5, v4, v3
	v_cmp_ge_f32_e64 s[0:1], 0, v6
	v_add_u32_e32 v6, 1, v4
	s_nop 0
	v_cndmask_b32_e64 v5, v4, v5, s[0:1]
	v_fma_f32 v4, -v6, v4, v3
	v_cmp_lt_f32_e64 s[0:1], 0, v4
	s_nop 1
	v_cndmask_b32_e64 v4, v5, v6, s[0:1]
	v_mul_f32_e32 v5, 0x37800000, v4
	v_cndmask_b32_e32 v4, v4, v5, vcc
	v_cmp_class_f32_e32 vcc, v3, v193
	s_nop 1
	v_cndmask_b32_e32 v3, v4, v3, vcc
	v_cmp_ngt_f32_e32 vcc, s24, v0
	s_nop 1
	v_cndmask_b32_e32 v0, 1.0, v3, vcc
	v_mul_f32_e32 v0, v1, v0
	v_mul_f32_e32 v0, v53, v0
	ds_write_b32 v144, v2 offset:2688
	ds_write_b32 v144, v0 offset:39552
	v_add_f32_e32 v0, v23, v36
	v_mul_f32_e32 v0, 0xbfb8aa3b, v0
	v_exp_f32_e32 v0, v0
	v_add_f32_e32 v1, v7, v38
	v_mul_f32_e32 v1, 0xbfb8aa3b, v1
	v_exp_f32_e32 v1, v1
	v_add_f32_e32 v0, 1.0, v0
	v_rcp_f32_e32 v0, v0
	v_add_f32_e32 v1, 1.0, v1
	v_rcp_f32_e32 v1, v1
	v_mul_f32_e32 v0, v0, v32
	v_mul_f32_e32 v2, 0x3fb8aa3b, v0
	v_add_f32_e32 v0, v0, v0
	v_mul_f32_e32 v3, 0x3fb8aa3b, v0
	v_rndne_f32_e32 v3, v3
	v_fmamk_f32 v4, v3, 0xbf317218, v0
	v_fmac_f32_e32 v4, 0x3102e308, v3
	v_fmamk_f32 v5, v4, 0x395133b1, v192
	v_cmp_eq_f32_e32 vcc, s21, v3
	v_cvt_i32_f32_e32 v3, v3
	v_fmaak_f32 v5, v4, v5, 0x3c0887f9
	v_fmaak_f32 v5, v4, v5, 0x3d2aaa81
	v_fmaak_f32 v5, v4, v5, 0x3e2aaaab
	v_fma_f32 v5, v4, v5, 0.5
	v_ldexp_f32 v3, 1.0, v3
	v_mul_f32_e32 v5, v4, v5
	v_cndmask_b32_e32 v3, v3, v202, vcc
	v_fmac_f32_e32 v4, v4, v5
	v_add_f32_e32 v5, -1.0, v3
	v_fmac_f32_e32 v5, v3, v4
	v_add_f32_e32 v3, v5, v5
	v_cndmask_b32_e32 v3, v5, v3, vcc
	v_cmp_nlt_f32_e32 vcc, s22, v0
	v_exp_f32_e32 v2, v2
	s_nop 0
	v_cndmask_b32_e64 v3, v201, -v3, vcc
	v_cmp_gt_f32_e32 vcc, s23, v3
	v_mul_f32_e32 v4, 0x4f800000, v3
	s_nop 0
	v_cndmask_b32_e32 v3, v3, v4, vcc
	v_sqrt_f32_e32 v4, v3
	s_nop 0
	v_add_u32_e32 v5, -1, v4
	v_fma_f32 v6, -v5, v4, v3
	v_cmp_ge_f32_e64 s[0:1], 0, v6
	v_add_u32_e32 v6, 1, v4
	s_nop 0
	v_cndmask_b32_e64 v5, v4, v5, s[0:1]
	v_fma_f32 v4, -v6, v4, v3
	v_cmp_lt_f32_e64 s[0:1], 0, v4
	s_nop 1
	v_cndmask_b32_e64 v4, v5, v6, s[0:1]
	v_mul_f32_e32 v5, 0x37800000, v4
	v_cndmask_b32_e32 v4, v4, v5, vcc
	v_cmp_class_f32_e32 vcc, v3, v193
	s_nop 1
	v_cndmask_b32_e32 v3, v4, v3, vcc
	v_cmp_ngt_f32_e32 vcc, s24, v0
	s_nop 1
	v_cndmask_b32_e32 v0, 1.0, v3, vcc
	v_mul_f32_e32 v0, v1, v0
	v_mul_f32_e32 v0, v39, v0
	ds_write_b32 v144, v2 offset:2944
	ds_write_b32 v144, v0 offset:39808
	v_add_f32_e32 v0, v24, v36
	v_mul_f32_e32 v0, 0xbfb8aa3b, v0
	v_exp_f32_e32 v0, v0
	v_add_f32_e32 v1, v8, v38
	v_mul_f32_e32 v1, 0xbfb8aa3b, v1
	v_exp_f32_e32 v1, v1
	v_add_f32_e32 v0, 1.0, v0
	v_rcp_f32_e32 v0, v0
	v_add_f32_e32 v1, 1.0, v1
	v_rcp_f32_e32 v1, v1
	v_mul_f32_e32 v0, v0, v32
	v_mul_f32_e32 v2, 0x3fb8aa3b, v0
	v_add_f32_e32 v0, v0, v0
	v_mul_f32_e32 v3, 0x3fb8aa3b, v0
	v_rndne_f32_e32 v3, v3
	v_fmamk_f32 v4, v3, 0xbf317218, v0
	v_fmac_f32_e32 v4, 0x3102e308, v3
	v_fmamk_f32 v5, v4, 0x395133b1, v192
	v_cmp_eq_f32_e32 vcc, s21, v3
	v_cvt_i32_f32_e32 v3, v3
	v_fmaak_f32 v5, v4, v5, 0x3c0887f9
	v_fmaak_f32 v5, v4, v5, 0x3d2aaa81
	v_fmaak_f32 v5, v4, v5, 0x3e2aaaab
	v_fma_f32 v5, v4, v5, 0.5
	v_ldexp_f32 v3, 1.0, v3
	v_mul_f32_e32 v5, v4, v5
	v_cndmask_b32_e32 v3, v3, v202, vcc
	v_fmac_f32_e32 v4, v4, v5
	v_add_f32_e32 v5, -1.0, v3
	v_fmac_f32_e32 v5, v3, v4
	v_add_f32_e32 v3, v5, v5
	v_cndmask_b32_e32 v3, v5, v3, vcc
	v_cmp_nlt_f32_e32 vcc, s22, v0
	v_exp_f32_e32 v2, v2
	s_nop 0
	v_cndmask_b32_e64 v3, v201, -v3, vcc
	v_cmp_gt_f32_e32 vcc, s23, v3
	v_mul_f32_e32 v4, 0x4f800000, v3
	s_nop 0
	v_cndmask_b32_e32 v3, v3, v4, vcc
	v_sqrt_f32_e32 v4, v3
	s_nop 0
	v_add_u32_e32 v5, -1, v4
	v_fma_f32 v6, -v5, v4, v3
	v_cmp_ge_f32_e64 s[0:1], 0, v6
	v_add_u32_e32 v6, 1, v4
	s_nop 0
	v_cndmask_b32_e64 v5, v4, v5, s[0:1]
	v_fma_f32 v4, -v6, v4, v3
	v_cmp_lt_f32_e64 s[0:1], 0, v4
	s_nop 1
	v_cndmask_b32_e64 v4, v5, v6, s[0:1]
	v_mul_f32_e32 v5, 0x37800000, v4
	v_cndmask_b32_e32 v4, v4, v5, vcc
	v_cmp_class_f32_e32 vcc, v3, v193
	s_nop 1
	v_cndmask_b32_e32 v3, v4, v3, vcc
	v_cmp_ngt_f32_e32 vcc, s24, v0
	s_nop 1
	v_cndmask_b32_e32 v0, 1.0, v3, vcc
	v_mul_f32_e32 v0, v1, v0
	v_mul_f32_e32 v0, v55, v0
	ds_write_b32 v144, v2 offset:4224
	ds_write_b32 v144, v0 offset:41088
	v_add_f32_e32 v0, v25, v36
	v_mul_f32_e32 v0, 0xbfb8aa3b, v0
	v_exp_f32_e32 v0, v0
	v_add_f32_e32 v1, v9, v38
	v_mul_f32_e32 v1, 0xbfb8aa3b, v1
	v_exp_f32_e32 v1, v1
	v_add_f32_e32 v0, 1.0, v0
	v_rcp_f32_e32 v0, v0
	v_add_f32_e32 v1, 1.0, v1
	v_rcp_f32_e32 v1, v1
	v_mul_f32_e32 v0, v0, v32
	v_mul_f32_e32 v2, 0x3fb8aa3b, v0
	v_add_f32_e32 v0, v0, v0
	v_mul_f32_e32 v3, 0x3fb8aa3b, v0
	v_rndne_f32_e32 v3, v3
	v_fmamk_f32 v4, v3, 0xbf317218, v0
	v_fmac_f32_e32 v4, 0x3102e308, v3
	v_fmamk_f32 v5, v4, 0x395133b1, v192
	v_cmp_eq_f32_e32 vcc, s21, v3
	v_cvt_i32_f32_e32 v3, v3
	v_fmaak_f32 v5, v4, v5, 0x3c0887f9
	v_fmaak_f32 v5, v4, v5, 0x3d2aaa81
	v_fmaak_f32 v5, v4, v5, 0x3e2aaaab
	v_fma_f32 v5, v4, v5, 0.5
	v_ldexp_f32 v3, 1.0, v3
	v_mul_f32_e32 v5, v4, v5
	v_cndmask_b32_e32 v3, v3, v202, vcc
	v_fmac_f32_e32 v4, v4, v5
	v_add_f32_e32 v5, -1.0, v3
	v_fmac_f32_e32 v5, v3, v4
	v_add_f32_e32 v3, v5, v5
	v_cndmask_b32_e32 v3, v5, v3, vcc
	v_cmp_nlt_f32_e32 vcc, s22, v0
	v_exp_f32_e32 v2, v2
	s_nop 0
	v_cndmask_b32_e64 v3, v201, -v3, vcc
	v_cmp_gt_f32_e32 vcc, s23, v3
	v_mul_f32_e32 v4, 0x4f800000, v3
	s_nop 0
	v_cndmask_b32_e32 v3, v3, v4, vcc
	v_sqrt_f32_e32 v4, v3
	s_nop 0
	v_add_u32_e32 v5, -1, v4
	v_fma_f32 v6, -v5, v4, v3
	v_cmp_ge_f32_e64 s[0:1], 0, v6
	v_add_u32_e32 v6, 1, v4
	s_nop 0
	v_cndmask_b32_e64 v5, v4, v5, s[0:1]
	v_fma_f32 v4, -v6, v4, v3
	v_cmp_lt_f32_e64 s[0:1], 0, v4
	s_nop 1
	v_cndmask_b32_e64 v4, v5, v6, s[0:1]
	v_mul_f32_e32 v5, 0x37800000, v4
	v_cndmask_b32_e32 v4, v4, v5, vcc
	v_cmp_class_f32_e32 vcc, v3, v193
	s_nop 1
	v_cndmask_b32_e32 v3, v4, v3, vcc
	v_cmp_ngt_f32_e32 vcc, s24, v0
	s_nop 1
	v_cndmask_b32_e32 v0, 1.0, v3, vcc
	v_mul_f32_e32 v0, v1, v0
	v_mul_f32_e32 v0, v41, v0
	ds_write_b32 v144, v2 offset:4480
	ds_write_b32 v144, v0 offset:41344
	v_add_f32_e32 v0, v26, v36
	v_mul_f32_e32 v0, 0xbfb8aa3b, v0
	v_exp_f32_e32 v0, v0
	v_add_f32_e32 v1, v10, v38
	v_mul_f32_e32 v1, 0xbfb8aa3b, v1
	v_exp_f32_e32 v1, v1
	v_add_f32_e32 v0, 1.0, v0
	v_rcp_f32_e32 v0, v0
	v_add_f32_e32 v1, 1.0, v1
	v_rcp_f32_e32 v1, v1
	v_mul_f32_e32 v0, v0, v32
	v_mul_f32_e32 v2, 0x3fb8aa3b, v0
	v_add_f32_e32 v0, v0, v0
	v_mul_f32_e32 v3, 0x3fb8aa3b, v0
	v_rndne_f32_e32 v3, v3
	v_fmamk_f32 v4, v3, 0xbf317218, v0
	v_fmac_f32_e32 v4, 0x3102e308, v3
	v_fmamk_f32 v5, v4, 0x395133b1, v192
	v_cmp_eq_f32_e32 vcc, s21, v3
	v_cvt_i32_f32_e32 v3, v3
	v_fmaak_f32 v5, v4, v5, 0x3c0887f9
	v_fmaak_f32 v5, v4, v5, 0x3d2aaa81
	v_fmaak_f32 v5, v4, v5, 0x3e2aaaab
	v_fma_f32 v5, v4, v5, 0.5
	v_ldexp_f32 v3, 1.0, v3
	v_mul_f32_e32 v5, v4, v5
	v_cndmask_b32_e32 v3, v3, v202, vcc
	v_fmac_f32_e32 v4, v4, v5
	v_add_f32_e32 v5, -1.0, v3
	v_fmac_f32_e32 v5, v3, v4
	v_add_f32_e32 v3, v5, v5
	v_cndmask_b32_e32 v3, v5, v3, vcc
	v_cmp_nlt_f32_e32 vcc, s22, v0
	v_exp_f32_e32 v2, v2
	s_nop 0
	v_cndmask_b32_e64 v3, v201, -v3, vcc
	v_cmp_gt_f32_e32 vcc, s23, v3
	v_mul_f32_e32 v4, 0x4f800000, v3
	s_nop 0
	v_cndmask_b32_e32 v3, v3, v4, vcc
	v_sqrt_f32_e32 v4, v3
	s_nop 0
	v_add_u32_e32 v5, -1, v4
	v_fma_f32 v6, -v5, v4, v3
	v_cmp_ge_f32_e64 s[0:1], 0, v6
	v_add_u32_e32 v6, 1, v4
	s_nop 0
	v_cndmask_b32_e64 v5, v4, v5, s[0:1]
	v_fma_f32 v4, -v6, v4, v3
	v_cmp_lt_f32_e64 s[0:1], 0, v4
	s_nop 1
	v_cndmask_b32_e64 v4, v5, v6, s[0:1]
	v_mul_f32_e32 v5, 0x37800000, v4
	v_cndmask_b32_e32 v4, v4, v5, vcc
	v_cmp_class_f32_e32 vcc, v3, v193
	s_nop 1
	v_cndmask_b32_e32 v3, v4, v3, vcc
	v_cmp_ngt_f32_e32 vcc, s24, v0
	s_nop 1
	v_cndmask_b32_e32 v0, 1.0, v3, vcc
	v_mul_f32_e32 v0, v1, v0
	v_mul_f32_e32 v0, v57, v0
	ds_write_b32 v144, v2 offset:4736
	ds_write_b32 v144, v0 offset:41600
	v_add_f32_e32 v0, v27, v36
	v_mul_f32_e32 v0, 0xbfb8aa3b, v0
	v_exp_f32_e32 v0, v0
	v_add_f32_e32 v1, v11, v38
	v_mul_f32_e32 v1, 0xbfb8aa3b, v1
	v_exp_f32_e32 v1, v1
	v_add_f32_e32 v0, 1.0, v0
	v_rcp_f32_e32 v0, v0
	v_add_f32_e32 v1, 1.0, v1
	v_rcp_f32_e32 v1, v1
	v_mul_f32_e32 v0, v0, v32
	v_mul_f32_e32 v2, 0x3fb8aa3b, v0
	v_add_f32_e32 v0, v0, v0
	v_mul_f32_e32 v3, 0x3fb8aa3b, v0
	v_rndne_f32_e32 v3, v3
	v_fmamk_f32 v4, v3, 0xbf317218, v0
	v_fmac_f32_e32 v4, 0x3102e308, v3
	v_fmamk_f32 v5, v4, 0x395133b1, v192
	v_cmp_eq_f32_e32 vcc, s21, v3
	v_cvt_i32_f32_e32 v3, v3
	v_fmaak_f32 v5, v4, v5, 0x3c0887f9
	v_fmaak_f32 v5, v4, v5, 0x3d2aaa81
	v_fmaak_f32 v5, v4, v5, 0x3e2aaaab
	v_fma_f32 v5, v4, v5, 0.5
	v_ldexp_f32 v3, 1.0, v3
	v_mul_f32_e32 v5, v4, v5
	v_cndmask_b32_e32 v3, v3, v202, vcc
	v_fmac_f32_e32 v4, v4, v5
	v_add_f32_e32 v5, -1.0, v3
	v_fmac_f32_e32 v5, v3, v4
	v_add_f32_e32 v3, v5, v5
	v_cndmask_b32_e32 v3, v5, v3, vcc
	v_cmp_nlt_f32_e32 vcc, s22, v0
	v_exp_f32_e32 v2, v2
	s_nop 0
	v_cndmask_b32_e64 v3, v201, -v3, vcc
	v_cmp_gt_f32_e32 vcc, s23, v3
	v_mul_f32_e32 v4, 0x4f800000, v3
	s_nop 0
	v_cndmask_b32_e32 v3, v3, v4, vcc
	v_sqrt_f32_e32 v4, v3
	s_nop 0
	v_add_u32_e32 v5, -1, v4
	v_fma_f32 v6, -v5, v4, v3
	v_cmp_ge_f32_e64 s[0:1], 0, v6
	v_add_u32_e32 v6, 1, v4
	s_nop 0
	v_cndmask_b32_e64 v5, v4, v5, s[0:1]
	v_fma_f32 v4, -v6, v4, v3
	v_cmp_lt_f32_e64 s[0:1], 0, v4
	s_nop 1
	v_cndmask_b32_e64 v4, v5, v6, s[0:1]
	v_mul_f32_e32 v5, 0x37800000, v4
	v_cndmask_b32_e32 v4, v4, v5, vcc
	v_cmp_class_f32_e32 vcc, v3, v193
	s_nop 1
	v_cndmask_b32_e32 v3, v4, v3, vcc
	v_cmp_ngt_f32_e32 vcc, s24, v0
	s_nop 1
	v_cndmask_b32_e32 v0, 1.0, v3, vcc
	v_mul_f32_e32 v0, v1, v0
	v_mul_f32_e32 v0, v43, v0
	ds_write_b32 v144, v2 offset:4992
	ds_write_b32 v144, v0 offset:41856
	v_add_f32_e32 v0, v28, v36
	v_mul_f32_e32 v0, 0xbfb8aa3b, v0
	v_exp_f32_e32 v0, v0
	v_add_f32_e32 v1, v12, v38
	v_mul_f32_e32 v1, 0xbfb8aa3b, v1
	v_exp_f32_e32 v1, v1
	v_add_f32_e32 v0, 1.0, v0
	v_rcp_f32_e32 v0, v0
	v_add_f32_e32 v1, 1.0, v1
	v_rcp_f32_e32 v1, v1
	v_mul_f32_e32 v0, v0, v32
	v_mul_f32_e32 v2, 0x3fb8aa3b, v0
	v_add_f32_e32 v0, v0, v0
	v_mul_f32_e32 v3, 0x3fb8aa3b, v0
	v_rndne_f32_e32 v3, v3
	v_fmamk_f32 v4, v3, 0xbf317218, v0
	v_fmac_f32_e32 v4, 0x3102e308, v3
	v_fmamk_f32 v5, v4, 0x395133b1, v192
	v_cmp_eq_f32_e32 vcc, s21, v3
	v_cvt_i32_f32_e32 v3, v3
	v_fmaak_f32 v5, v4, v5, 0x3c0887f9
	v_fmaak_f32 v5, v4, v5, 0x3d2aaa81
	v_fmaak_f32 v5, v4, v5, 0x3e2aaaab
	v_fma_f32 v5, v4, v5, 0.5
	v_ldexp_f32 v3, 1.0, v3
	v_mul_f32_e32 v5, v4, v5
	v_cndmask_b32_e32 v3, v3, v202, vcc
	v_fmac_f32_e32 v4, v4, v5
	v_add_f32_e32 v5, -1.0, v3
	v_fmac_f32_e32 v5, v3, v4
	v_add_f32_e32 v3, v5, v5
	v_cndmask_b32_e32 v3, v5, v3, vcc
	v_cmp_nlt_f32_e32 vcc, s22, v0
	v_exp_f32_e32 v2, v2
	s_nop 0
	v_cndmask_b32_e64 v3, v201, -v3, vcc
	v_cmp_gt_f32_e32 vcc, s23, v3
	v_mul_f32_e32 v4, 0x4f800000, v3
	s_nop 0
	v_cndmask_b32_e32 v3, v3, v4, vcc
	v_sqrt_f32_e32 v4, v3
	s_nop 0
	v_add_u32_e32 v5, -1, v4
	v_fma_f32 v6, -v5, v4, v3
	v_cmp_ge_f32_e64 s[0:1], 0, v6
	v_add_u32_e32 v6, 1, v4
	s_nop 0
	v_cndmask_b32_e64 v5, v4, v5, s[0:1]
	v_fma_f32 v4, -v6, v4, v3
	v_cmp_lt_f32_e64 s[0:1], 0, v4
	s_nop 1
	v_cndmask_b32_e64 v4, v5, v6, s[0:1]
	v_mul_f32_e32 v5, 0x37800000, v4
	v_cndmask_b32_e32 v4, v4, v5, vcc
	v_cmp_class_f32_e32 vcc, v3, v193
	s_nop 1
	v_cndmask_b32_e32 v3, v4, v3, vcc
	v_cmp_ngt_f32_e32 vcc, s24, v0
	s_nop 1
	v_cndmask_b32_e32 v0, 1.0, v3, vcc
	v_mul_f32_e32 v0, v1, v0
	v_mul_f32_e32 v0, v59, v0
	ds_write_b32 v144, v2 offset:6272
	ds_write_b32 v144, v0 offset:43136
	v_add_f32_e32 v0, v29, v36
	v_mul_f32_e32 v0, 0xbfb8aa3b, v0
	v_exp_f32_e32 v0, v0
	v_add_f32_e32 v1, v13, v38
	v_mul_f32_e32 v1, 0xbfb8aa3b, v1
	v_exp_f32_e32 v1, v1
	v_add_f32_e32 v0, 1.0, v0
	v_rcp_f32_e32 v0, v0
	v_add_f32_e32 v1, 1.0, v1
	v_rcp_f32_e32 v1, v1
	v_mul_f32_e32 v0, v0, v32
	v_mul_f32_e32 v2, 0x3fb8aa3b, v0
	v_add_f32_e32 v0, v0, v0
	v_mul_f32_e32 v3, 0x3fb8aa3b, v0
	v_rndne_f32_e32 v3, v3
	v_fmamk_f32 v4, v3, 0xbf317218, v0
	v_fmac_f32_e32 v4, 0x3102e308, v3
	v_fmamk_f32 v5, v4, 0x395133b1, v192
	v_cmp_eq_f32_e32 vcc, s21, v3
	v_cvt_i32_f32_e32 v3, v3
	v_fmaak_f32 v5, v4, v5, 0x3c0887f9
	v_fmaak_f32 v5, v4, v5, 0x3d2aaa81
	v_fmaak_f32 v5, v4, v5, 0x3e2aaaab
	v_fma_f32 v5, v4, v5, 0.5
	v_ldexp_f32 v3, 1.0, v3
	v_mul_f32_e32 v5, v4, v5
	v_cndmask_b32_e32 v3, v3, v202, vcc
	v_fmac_f32_e32 v4, v4, v5
	v_add_f32_e32 v5, -1.0, v3
	v_fmac_f32_e32 v5, v3, v4
	v_add_f32_e32 v3, v5, v5
	v_cndmask_b32_e32 v3, v5, v3, vcc
	v_cmp_nlt_f32_e32 vcc, s22, v0
	v_exp_f32_e32 v2, v2
	s_nop 0
	v_cndmask_b32_e64 v3, v201, -v3, vcc
	v_cmp_gt_f32_e32 vcc, s23, v3
	v_mul_f32_e32 v4, 0x4f800000, v3
	s_nop 0
	v_cndmask_b32_e32 v3, v3, v4, vcc
	v_sqrt_f32_e32 v4, v3
	s_nop 0
	v_add_u32_e32 v5, -1, v4
	v_fma_f32 v6, -v5, v4, v3
	v_cmp_ge_f32_e64 s[0:1], 0, v6
	v_add_u32_e32 v6, 1, v4
	s_nop 0
	v_cndmask_b32_e64 v5, v4, v5, s[0:1]
	v_fma_f32 v4, -v6, v4, v3
	v_cmp_lt_f32_e64 s[0:1], 0, v4
	s_nop 1
	v_cndmask_b32_e64 v4, v5, v6, s[0:1]
	v_mul_f32_e32 v5, 0x37800000, v4
	v_cndmask_b32_e32 v4, v4, v5, vcc
	v_cmp_class_f32_e32 vcc, v3, v193
	s_nop 1
	v_cndmask_b32_e32 v3, v4, v3, vcc
	v_cmp_ngt_f32_e32 vcc, s24, v0
	s_nop 1
	v_cndmask_b32_e32 v0, 1.0, v3, vcc
	v_mul_f32_e32 v0, v1, v0
	v_mul_f32_e32 v0, v45, v0
	ds_write_b32 v144, v2 offset:6528
	ds_write_b32 v144, v0 offset:43392
	v_add_f32_e32 v0, v30, v36
	v_mul_f32_e32 v0, 0xbfb8aa3b, v0
	v_exp_f32_e32 v0, v0
	v_add_f32_e32 v1, v14, v38
	v_mul_f32_e32 v1, 0xbfb8aa3b, v1
	v_exp_f32_e32 v1, v1
	v_add_f32_e32 v0, 1.0, v0
	v_rcp_f32_e32 v0, v0
	v_add_f32_e32 v1, 1.0, v1
	v_rcp_f32_e32 v1, v1
	v_mul_f32_e32 v0, v0, v32
	v_mul_f32_e32 v2, 0x3fb8aa3b, v0
	v_add_f32_e32 v0, v0, v0
	v_mul_f32_e32 v3, 0x3fb8aa3b, v0
	v_rndne_f32_e32 v3, v3
	v_fmamk_f32 v4, v3, 0xbf317218, v0
	v_fmac_f32_e32 v4, 0x3102e308, v3
	v_fmamk_f32 v5, v4, 0x395133b1, v192
	v_cmp_eq_f32_e32 vcc, s21, v3
	v_cvt_i32_f32_e32 v3, v3
	v_fmaak_f32 v5, v4, v5, 0x3c0887f9
	v_fmaak_f32 v5, v4, v5, 0x3d2aaa81
	v_fmaak_f32 v5, v4, v5, 0x3e2aaaab
	v_fma_f32 v5, v4, v5, 0.5
	v_ldexp_f32 v3, 1.0, v3
	v_mul_f32_e32 v5, v4, v5
	v_cndmask_b32_e32 v3, v3, v202, vcc
	v_fmac_f32_e32 v4, v4, v5
	v_add_f32_e32 v5, -1.0, v3
	v_fmac_f32_e32 v5, v3, v4
	v_add_f32_e32 v3, v5, v5
	v_cndmask_b32_e32 v3, v5, v3, vcc
	v_cmp_nlt_f32_e32 vcc, s22, v0
	v_exp_f32_e32 v2, v2
	s_nop 0
	v_cndmask_b32_e64 v3, v201, -v3, vcc
	v_cmp_gt_f32_e32 vcc, s23, v3
	v_mul_f32_e32 v4, 0x4f800000, v3
	s_nop 0
	v_cndmask_b32_e32 v3, v3, v4, vcc
	v_sqrt_f32_e32 v4, v3
	s_nop 0
	v_add_u32_e32 v5, -1, v4
	v_fma_f32 v6, -v5, v4, v3
	v_cmp_ge_f32_e64 s[0:1], 0, v6
	v_add_u32_e32 v6, 1, v4
	s_nop 0
	v_cndmask_b32_e64 v5, v4, v5, s[0:1]
	v_fma_f32 v4, -v6, v4, v3
	v_cmp_lt_f32_e64 s[0:1], 0, v4
	s_nop 1
	v_cndmask_b32_e64 v4, v5, v6, s[0:1]
	v_mul_f32_e32 v5, 0x37800000, v4
	v_cndmask_b32_e32 v4, v4, v5, vcc
	v_cmp_class_f32_e32 vcc, v3, v193
	s_nop 1
	v_cndmask_b32_e32 v3, v4, v3, vcc
	v_cmp_ngt_f32_e32 vcc, s24, v0
	s_nop 1
	v_cndmask_b32_e32 v0, 1.0, v3, vcc
	v_mul_f32_e32 v0, v1, v0
	v_mul_f32_e32 v0, v35, v0
	v_add_u32_e32 v1, 0x1800, v144
	ds_write2_b32 v1, v2, v34 offset0:160 offset1:192
	ds_write_b32 v144, v0 offset:43648
	v_add_f32_e32 v0, v31, v36
	v_mul_f32_e32 v0, 0xbfb8aa3b, v0
	v_exp_f32_e32 v0, v0
	v_add_f32_e32 v1, v15, v38
	v_mul_f32_e32 v1, 0xbfb8aa3b, v1
	v_exp_f32_e32 v1, v1
	v_add_f32_e32 v0, 1.0, v0
	v_rcp_f32_e32 v0, v0
	v_add_f32_e32 v1, 1.0, v1
	v_rcp_f32_e32 v1, v1
	v_mul_f32_e32 v0, v0, v32
	v_mul_f32_e32 v2, 0x3fb8aa3b, v0
	v_add_f32_e32 v0, v0, v0
	v_mul_f32_e32 v3, 0x3fb8aa3b, v0
	v_rndne_f32_e32 v3, v3
	v_fmamk_f32 v4, v3, 0xbf317218, v0
	v_fmac_f32_e32 v4, 0x3102e308, v3
	v_fmamk_f32 v5, v4, 0x395133b1, v192
	v_cmp_eq_f32_e32 vcc, s21, v3
	v_cvt_i32_f32_e32 v3, v3
	v_fmaak_f32 v5, v4, v5, 0x3c0887f9
	v_fmaak_f32 v5, v4, v5, 0x3d2aaa81
	v_fmaak_f32 v5, v4, v5, 0x3e2aaaab
	v_fma_f32 v5, v4, v5, 0.5
	v_ldexp_f32 v3, 1.0, v3
	v_mul_f32_e32 v5, v4, v5
	v_cndmask_b32_e32 v3, v3, v202, vcc
	v_fmac_f32_e32 v4, v4, v5
	v_add_f32_e32 v5, -1.0, v3
	v_fmac_f32_e32 v5, v3, v4
	v_add_f32_e32 v3, v5, v5
	v_cndmask_b32_e32 v3, v5, v3, vcc
	v_cmp_nlt_f32_e32 vcc, s22, v0
	v_exp_f32_e32 v2, v2
	s_mov_b32 s21, 0x84000
	v_cndmask_b32_e64 v3, v201, -v3, vcc
	v_cmp_gt_f32_e32 vcc, s23, v3
	v_mul_f32_e32 v4, 0x4f800000, v3
	s_mov_b32 s22, 0x2d000
	v_cndmask_b32_e32 v3, v3, v4, vcc
	v_sqrt_f32_e32 v4, v3
	s_mov_b32 s23, 0x59000
	v_add_u32_e32 v5, -1, v4
	v_fma_f32 v6, -v5, v4, v3
	v_cmp_ge_f32_e64 s[0:1], 0, v6
	v_add_u32_e32 v6, 1, v4
	s_nop 0
	v_cndmask_b32_e64 v5, v4, v5, s[0:1]
	v_fma_f32 v4, -v6, v4, v3
	v_cmp_lt_f32_e64 s[0:1], 0, v4
	s_nop 1
	v_cndmask_b32_e64 v4, v5, v6, s[0:1]
	v_mul_f32_e32 v5, 0x37800000, v4
	v_cndmask_b32_e32 v4, v4, v5, vcc
	v_cmp_class_f32_e32 vcc, v3, v193
	v_mov_b32_e32 v5, 0
	s_nop 0
	v_cndmask_b32_e32 v3, v4, v3, vcc
	v_cmp_ngt_f32_e32 vcc, s24, v0
	v_readlane_b32 s24, v248, 7
	s_nop 0
	v_cndmask_b32_e32 v0, 1.0, v3, vcc
	v_mul_f32_e32 v0, v1, v0
	v_mul_f32_e32 v0, v33, v0
	ds_write_b32 v144, v2 offset:7040
	ds_write_b32 v144, v0 offset:43904
	v_mov_b32_e32 v0, 0
	s_waitcnt lgkmcnt(0)
	s_barrier
	s_cbranch_scc1 .LBB0_915
	v_lshl_add_u64 v[2:3], v[64:65], 0, s[4:5]
	v_add_co_u32_e32 v4, vcc, 0x13000, v2
	s_sub_i32 s0, s2, s12
	s_nop 0
	v_addc_co_u32_e32 v5, vcc, 0, v3, vcc
	global_load_dwordx2 v[4:5], v[4:5], off
	s_cmp_eq_u32 s0, 1
	s_waitcnt vmcnt(0)
	v_fmac_f32_e32 v5, 0, v4
	s_cbranch_scc1 .LBB0_915
	v_add_co_u32_e32 v2, vcc, 0x12000, v2
	s_cmp_eq_u32 s0, 2
	s_nop 0
	v_addc_co_u32_e32 v3, vcc, 0, v3, vcc
	global_load_dwordx2 v[2:3], v[2:3], off
	s_waitcnt vmcnt(0)
	v_fmac_f32_e32 v3, v5, v2
	s_cbranch_scc1 .LBB0_914
	s_mul_i32 s1, s11, 36
	s_add_i32 s2, s1, 36
	s_ashr_i32 s3, s2, 31
	s_lshl_b64 s[2:3], s[2:3], 12
	v_readlane_b32 s1, v249, 47
	s_add_u32 s2, s1, s2
	v_readlane_b32 s1, v249, 48
	v_add_lshl_u32 v96, s13, v141, 3
	s_addc_u32 s3, s1, s3
	v_lshl_add_u64 v[4:5], s[2:3], 0, v[96:97]
	s_add_i32 s0, s0, -2

.LBB0_947:
	s_or_b64 exec, exec, s[0:1]
	v_add_f32_e32 v0, 0, v110
	v_add_f32_e32 v0, v0, v111
	v_add_f32_e32 v0, v0, v109
	v_cvt_pk_bf16_f32 v110, v110, v111
	v_cvt_pk_bf16_f32 v111, v109, v112
	v_xor_b32_e32 v109, 16, v105
	v_cmp_lt_i32_e64 s[0:1], v109, v106
	v_add_f32_e32 v118, v0, v112
	v_lshl_add_u32 v113, v99, 3, 0
	v_cndmask_b32_e64 v109, v105, v109, s[0:1]
	v_lshlrev_b32_e32 v229, 2, v109
	v_mul_lo_u32 v0, v100, s87
	v_mov_b32_e32 v109, v118
	v_mov_b32_e32 v255, v118
	s_nop 1
	v_permlane16_swap_b32_e32 v109, v255
	v_add_u32_e32 v0, v113, v0
	ds_write_b64 v0, v[110:111] offset:34816
	v_xor_b32_e32 v110, 8, v105
	v_cmp_lt_i32_e64 s[0:1], v110, v106
	s_waitcnt lgkmcnt(1)
	v_add_f32_e32 v109, v109, v255
	v_cmp_eq_u32_e32 vcc, 0, v99
	v_cndmask_b32_e64 v110, v105, v110, s[0:1]
	v_lshlrev_b32_e32 v230, 2, v110
	s_waitcnt lgkmcnt(0)
	v_add_f32_dpp v109, v109, v109 row_ror:8 row_mask:0xf bank_mask:0xf
	v_xor_b32_e32 v110, 4, v105
	v_cmp_lt_i32_e64 s[0:1], v110, v106
	s_nop 1
	v_cndmask_b32_e64 v110, v105, v110, s[0:1]
	s_nop 0
	v_mov_b32_dpp v110, v109 row_shl:4 row_mask:0xf bank_mask:0x5
	v_mov_b32_dpp v110, v109 row_shr:4 row_mask:0xf bank_mask:0xa
	v_add_f32_e32 v109, v109, v110
	v_xor_b32_e32 v110, 2, v105
	v_cmp_lt_i32_e64 s[0:1], v110, v106
	s_nop 1
	v_cndmask_b32_e64 v110, v105, v110, s[0:1]
	v_lshlrev_b32_e32 v232, 2, v110
	v_add_f32_dpp v109, v109, v109 quad_perm:[2,3,0,1] row_mask:0xf bank_mask:0xf
	v_xor_b32_e32 v110, 1, v105
	v_cmp_lt_i32_e64 s[0:1], v110, v106
	s_nop 1
	v_cndmask_b32_e64 v105, v105, v110, s[0:1]
	v_lshlrev_b32_e32 v233, 2, v105
	v_mov_b32_dpp v105, v109 quad_perm:[1,0,3,2] row_mask:0xf bank_mask:0xf
	s_and_saveexec_b64 s[0:1], vcc
	s_cbranch_execz .LBB0_949
	s_nop 0
	v_add_f32_e32 v105, v109, v105
	s_waitcnt vmcnt(0)
	v_sub_f32_e32 v106, v96, v108
	v_add_u32_e32 v109, 0x11c00, v107
	v_mul_f32_e32 v106, 0x3fb8aa3b, v106
	ds_read_b32 v109, v109
	v_exp_f32_e32 v106, v106
	s_waitcnt lgkmcnt(0)
	v_fmac_f32_e32 v105, v106, v109
	v_add_u32_e32 v109, 0x11e00, v107
	ds_write_b32 v109, v105
	v_add_u32_e32 v105, 0x12000, v107
	ds_write_b32 v105, v106
	v_add_u32_e32 v105, 0x11800, v107
	ds_read_b32 v105, v105
	v_add_u32_e32 v106, 0x12200, v107
	s_waitcnt lgkmcnt(0)
	v_add_f32_e32 v105, v108, v105
	v_mul_f32_e32 v105, 0xbfb8aa3b, v105
	v_exp_f32_e32 v105, v105
	ds_write_b32 v106, v105

.LBB0_957:
	s_or_b64 exec, exec, s[68:69]
	v_add_f32_e32 v1, 0, v108
	v_add_f32_e32 v1, v1, v107
	v_add_f32_e32 v1, v1, v49
	v_add_f32_e32 v1, v1, v33
	v_mov_b32_e32 v17, v1
	v_mov_b32_e32 v255, v1
	s_nop 1
	v_permlane16_swap_b32_e32 v17, v255
	s_nop 1
	v_mov_b32_dpp v17, v255 quad_perm:[0,1,2,3] row_mask:0x5 bank_mask:0xf
	v_cvt_pk_bf16_f32 v108, v108, v107
	v_cvt_pk_bf16_f32 v109, v49, v33
	ds_write_b64 v0, v[108:109] offset:35088
	s_waitcnt lgkmcnt(1)
	v_add_f32_e32 v1, v1, v17
	s_nop 1
	v_mov_b32_dpp v17, v1 row_ror:8 row_mask:0xf bank_mask:0xf
	s_waitcnt lgkmcnt(0)
	v_add_f32_e32 v1, v1, v17
	s_nop 1
	v_mov_b32_dpp v17, v1 row_shl:4 row_mask:0xf bank_mask:0x5
	v_mov_b32_dpp v17, v1 row_shr:4 row_mask:0xf bank_mask:0xa
	s_nop 0
	v_add_f32_e32 v1, v1, v17
	s_nop 1
	v_mov_b32_dpp v17, v1 quad_perm:[2,3,0,1] row_mask:0xf bank_mask:0xf
	s_nop 0
	v_add_f32_e32 v1, v1, v17
	s_nop 1
	v_mov_b32_dpp v17, v1 quad_perm:[1,0,3,2] row_mask:0xf bank_mask:0xf
	s_and_saveexec_b64 s[0:1], vcc
	s_cbranch_execz .LBB0_959
	s_nop 0
	v_add_f32_e32 v1, v1, v17
	s_waitcnt vmcnt(0)
	v_sub_f32_e32 v17, v96, v106
	v_add_u32_e32 v33, 0x11c00, v105
	v_mul_f32_e32 v17, 0x3fb8aa3b, v17
	ds_read_b32 v33, v33
	v_exp_f32_e32 v17, v17
	s_waitcnt lgkmcnt(0)
	v_fmac_f32_e32 v1, v17, v33
	v_add_u32_e32 v33, 0x11e00, v105
	ds_write_b32 v33, v1
	v_add_u32_e32 v1, 0x12000, v105
	ds_write_b32 v1, v17
	v_add_u32_e32 v1, 0x11800, v105
	ds_read_b32 v1, v1
	v_add_u32_e32 v17, 0x12200, v105
	s_waitcnt lgkmcnt(0)
	v_add_f32_e32 v1, v106, v1
	v_mul_f32_e32 v1, 0xbfb8aa3b, v1
	v_exp_f32_e32 v1, v1
	ds_write_b32 v17, v1

.LBB0_967:
	s_or_b64 exec, exec, s[68:69]
	v_add_f32_e32 v2, 0, v49
	v_add_f32_e32 v2, v2, v33
	v_add_f32_e32 v2, v2, v50
	v_add_f32_e32 v2, v2, v34
	v_mov_b32_e32 v18, v2
	v_mov_b32_e32 v255, v2
	s_nop 1
	v_permlane16_swap_b32_e32 v18, v255
	s_nop 1
	v_mov_b32_dpp v18, v255 quad_perm:[0,1,2,3] row_mask:0x5 bank_mask:0xf
	v_cvt_pk_bf16_f32 v106, v49, v33
	v_cvt_pk_bf16_f32 v107, v50, v34
	ds_write_b64 v0, v[106:107] offset:35360
	s_waitcnt lgkmcnt(1)
	v_add_f32_e32 v2, v2, v18
	s_nop 1
	v_mov_b32_dpp v18, v2 row_ror:8 row_mask:0xf bank_mask:0xf
	s_waitcnt lgkmcnt(0)
	v_add_f32_e32 v2, v2, v18
	s_nop 1
	v_mov_b32_dpp v18, v2 row_shl:4 row_mask:0xf bank_mask:0x5
	v_mov_b32_dpp v18, v2 row_shr:4 row_mask:0xf bank_mask:0xa
	s_nop 0
	v_add_f32_e32 v2, v2, v18
	s_nop 1
	v_mov_b32_dpp v18, v2 quad_perm:[2,3,0,1] row_mask:0xf bank_mask:0xf
	s_nop 0
	v_add_f32_e32 v2, v2, v18
	s_nop 1
	v_mov_b32_dpp v18, v2 quad_perm:[1,0,3,2] row_mask:0xf bank_mask:0xf
	s_and_saveexec_b64 s[0:1], vcc
	s_cbranch_execz .LBB0_969
	s_nop 0
	v_add_f32_e32 v2, v2, v18
	s_waitcnt vmcnt(0)
	v_sub_f32_e32 v18, v96, v17
	v_add_u32_e32 v33, 0x11c00, v1
	v_mul_f32_e32 v18, 0x3fb8aa3b, v18
	ds_read_b32 v33, v33
	v_exp_f32_e32 v18, v18
	s_waitcnt lgkmcnt(0)
	v_fmac_f32_e32 v2, v18, v33
	v_add_u32_e32 v33, 0x11e00, v1
	ds_write_b32 v33, v2
	v_add_u32_e32 v2, 0x12000, v1
	ds_write_b32 v2, v18
	v_add_u32_e32 v2, 0x11800, v1
	ds_read_b32 v2, v2
	v_add_u32_e32 v1, 0x12200, v1
	s_waitcnt lgkmcnt(0)
	v_add_f32_e32 v2, v17, v2
	v_mul_f32_e32 v2, 0xbfb8aa3b, v2
	v_exp_f32_e32 v2, v2
	ds_write_b32 v1, v2

.LBB0_977:
	s_or_b64 exec, exec, s[68:69]
	v_add_f32_e32 v3, 0, v18
	v_add_f32_e32 v3, v3, v17
	v_add_f32_e32 v3, v3, v35
	v_add_f32_e32 v3, v3, v34
	v_cvt_pk_bf16_f32 v18, v18, v17
	v_mov_b32_e32 v17, v3
	v_mov_b32_e32 v255, v3
	s_nop 1
	v_permlane16_swap_b32_e32 v17, v255
	s_nop 1
	v_mov_b32_dpp v17, v255 quad_perm:[0,1,2,3] row_mask:0x5 bank_mask:0xf
	v_cvt_pk_bf16_f32 v19, v35, v34
	ds_write_b64 v0, v[18:19] offset:35632
	s_waitcnt lgkmcnt(1)
	v_add_f32_e32 v3, v3, v17
	s_nop 1
	v_mov_b32_dpp v17, v3 row_ror:8 row_mask:0xf bank_mask:0xf
	s_waitcnt lgkmcnt(0)
	v_add_f32_e32 v3, v3, v17
	s_nop 1
	v_mov_b32_dpp v17, v3 row_shl:4 row_mask:0xf bank_mask:0x5
	v_mov_b32_dpp v17, v3 row_shr:4 row_mask:0xf bank_mask:0xa
	s_nop 0
	v_add_f32_e32 v3, v3, v17
	s_nop 1
	v_mov_b32_dpp v17, v3 quad_perm:[2,3,0,1] row_mask:0xf bank_mask:0xf
	s_nop 0
	v_add_f32_e32 v3, v3, v17
	s_nop 1
	v_mov_b32_dpp v17, v3 quad_perm:[1,0,3,2] row_mask:0xf bank_mask:0xf
	s_and_saveexec_b64 s[0:1], vcc
	s_cbranch_execz .LBB0_979
	s_nop 0
	v_add_f32_e32 v3, v3, v17
	s_waitcnt vmcnt(0)
	v_sub_f32_e32 v17, v96, v2
	v_add_u32_e32 v18, 0x11c00, v1
	v_mul_f32_e32 v17, 0x3fb8aa3b, v17
	ds_read_b32 v18, v18
	v_exp_f32_e32 v17, v17
	s_waitcnt lgkmcnt(0)
	v_fmac_f32_e32 v3, v17, v18
	v_add_u32_e32 v18, 0x11e00, v1
	ds_write_b32 v18, v3
	v_add_u32_e32 v3, 0x12000, v1
	ds_write_b32 v3, v17
	v_add_u32_e32 v3, 0x11800, v1
	ds_read_b32 v3, v3
	v_add_u32_e32 v1, 0x12200, v1
	s_waitcnt lgkmcnt(0)
	v_add_f32_e32 v2, v2, v3
	v_mul_f32_e32 v2, 0xbfb8aa3b, v2
	v_exp_f32_e32 v2, v2
	ds_write_b32 v1, v2

.LBB0_987:
	s_or_b64 exec, exec, s[68:69]
	v_add_f32_e32 v4, 0, v17
	v_add_f32_e32 v4, v4, v3
	v_add_f32_e32 v4, v4, v19
	v_add_f32_e32 v4, v4, v18
	v_cvt_pk_bf16_f32 v34, v17, v3
	v_mov_b32_e32 v3, v4
	v_mov_b32_e32 v255, v4
	s_nop 1
	v_permlane16_swap_b32_e32 v3, v255
	v_cvt_pk_bf16_f32 v35, v19, v18
	ds_write_b64 v0, v[34:35] offset:36992
	s_waitcnt lgkmcnt(1)
	v_add_f32_e32 v3, v3, v255
	s_nop 1
	v_mov_b32_dpp v4, v3 row_ror:8 row_mask:0xf bank_mask:0xf
	s_waitcnt lgkmcnt(0)
	v_add_f32_e32 v3, v3, v4
	s_nop 1
	v_mov_b32_dpp v4, v3 row_shl:4 row_mask:0xf bank_mask:0x5
	v_mov_b32_dpp v4, v3 row_shr:4 row_mask:0xf bank_mask:0xa
	s_nop 0
	v_add_f32_e32 v3, v3, v4
	s_nop 1
	v_mov_b32_dpp v4, v3 quad_perm:[2,3,0,1] row_mask:0xf bank_mask:0xf
	s_nop 0
	v_add_f32_e32 v3, v3, v4
	s_nop 1
	v_mov_b32_dpp v4, v3 quad_perm:[1,0,3,2] row_mask:0xf bank_mask:0xf
	s_and_saveexec_b64 s[0:1], vcc
	s_cbranch_execz .LBB0_989
	v_lshl_add_u32 v2, v2, 2, 0
	s_nop 0
	v_add_f32_e32 v3, v3, v4
	s_waitcnt vmcnt(0)
	v_sub_f32_e32 v4, v96, v1
	v_add_u32_e32 v17, 0x11c00, v2
	v_mul_f32_e32 v4, 0x3fb8aa3b, v4
	ds_read_b32 v17, v17
	v_exp_f32_e32 v4, v4
	s_waitcnt lgkmcnt(0)
	v_fmac_f32_e32 v3, v4, v17
	v_add_u32_e32 v17, 0x11e00, v2
	ds_write_b32 v17, v3
	v_add_u32_e32 v3, 0x12000, v2
	ds_write_b32 v3, v4
	v_add_u32_e32 v3, 0x11800, v2
	ds_read_b32 v3, v3
	v_add_u32_e32 v2, 0x12200, v2
	s_waitcnt lgkmcnt(0)
	v_add_f32_e32 v1, v1, v3
	v_mul_f32_e32 v1, 0xbfb8aa3b, v1
	v_exp_f32_e32 v1, v1
	ds_write_b32 v2, v1

.LBB0_997:
	s_or_b64 exec, exec, s[68:69]
	v_add_f32_e32 v5, 0, v4
	v_add_f32_e32 v5, v5, v3
	v_add_f32_e32 v5, v5, v18
	v_add_f32_e32 v19, v5, v17
	v_cvt_pk_bf16_f32 v4, v4, v3
	v_mov_b32_e32 v3, v19
	v_mov_b32_e32 v255, v19
	s_nop 1
	v_permlane16_swap_b32_e32 v3, v255
	v_cvt_pk_bf16_f32 v5, v18, v17
	ds_write_b64 v0, v[4:5] offset:37264
	s_waitcnt lgkmcnt(1)
	v_add_f32_e32 v3, v3, v255
	s_nop 1
	v_mov_b32_dpp v4, v3 row_ror:8 row_mask:0xf bank_mask:0xf
	s_waitcnt lgkmcnt(0)
	v_add_f32_e32 v3, v3, v4
	s_nop 1
	v_mov_b32_dpp v4, v3 row_shl:4 row_mask:0xf bank_mask:0x5
	v_mov_b32_dpp v4, v3 row_shr:4 row_mask:0xf bank_mask:0xa
	s_nop 0
	v_add_f32_e32 v3, v3, v4
	s_nop 1
	v_mov_b32_dpp v4, v3 quad_perm:[2,3,0,1] row_mask:0xf bank_mask:0xf
	s_nop 0
	v_add_f32_e32 v3, v3, v4
	s_nop 1
	v_mov_b32_dpp v4, v3 quad_perm:[1,0,3,2] row_mask:0xf bank_mask:0xf
	s_and_saveexec_b64 s[0:1], vcc
	s_cbranch_execz .LBB0_999
	v_lshl_add_u32 v2, v2, 2, 0
	s_nop 0
	v_add_f32_e32 v3, v3, v4
	s_waitcnt vmcnt(0)
	v_sub_f32_e32 v4, v96, v1
	v_add_u32_e32 v5, 0x11c00, v2
	v_mul_f32_e32 v4, 0x3fb8aa3b, v4
	ds_read_b32 v5, v5
	v_exp_f32_e32 v4, v4
	s_waitcnt lgkmcnt(0)
	v_fmac_f32_e32 v3, v4, v5
	v_add_u32_e32 v5, 0x11e00, v2
	ds_write_b32 v5, v3
	v_add_u32_e32 v3, 0x12000, v2
	ds_write_b32 v3, v4
	v_add_u32_e32 v3, 0x11800, v2
	ds_read_b32 v3, v3
	v_add_u32_e32 v2, 0x12200, v2
	s_waitcnt lgkmcnt(0)
	v_add_f32_e32 v1, v1, v3
	v_mul_f32_e32 v1, 0xbfb8aa3b, v1
	v_exp_f32_e32 v1, v1
	ds_write_b32 v2, v1

.LBB0_1007:
	s_or_b64 exec, exec, s[68:69]
	v_add_f32_e32 v6, 0, v4
	v_add_f32_e32 v6, v6, v3
	v_add_f32_e32 v6, v6, v17
	v_add_f32_e32 v6, v6, v5
	v_cvt_pk_bf16_f32 v4, v4, v3
	v_mov_b32_e32 v3, v6
	v_mov_b32_e32 v255, v6
	s_nop 1
	v_permlane16_swap_b32_e32 v3, v255
	v_cvt_pk_bf16_f32 v5, v17, v5
	ds_write_b64 v0, v[4:5] offset:37536
	s_waitcnt lgkmcnt(1)
	v_add_f32_e32 v3, v3, v255
	s_nop 1
	v_mov_b32_dpp v4, v3 row_ror:8 row_mask:0xf bank_mask:0xf
	s_waitcnt lgkmcnt(0)
	v_add_f32_e32 v3, v3, v4
	s_nop 1
	v_mov_b32_dpp v4, v3 row_shl:4 row_mask:0xf bank_mask:0x5
	v_mov_b32_dpp v4, v3 row_shr:4 row_mask:0xf bank_mask:0xa
	s_nop 0
	v_add_f32_e32 v3, v3, v4
	s_nop 1
	v_mov_b32_dpp v4, v3 quad_perm:[2,3,0,1] row_mask:0xf bank_mask:0xf
	s_nop 0
	v_add_f32_e32 v3, v3, v4
	s_nop 1
	v_mov_b32_dpp v4, v3 quad_perm:[1,0,3,2] row_mask:0xf bank_mask:0xf
	s_and_saveexec_b64 s[0:1], vcc
	s_cbranch_execz .LBB0_1009
	v_lshl_add_u32 v2, v2, 2, 0
	s_nop 0
	v_add_f32_e32 v3, v3, v4
	s_waitcnt vmcnt(0)
	v_sub_f32_e32 v4, v96, v1
	v_add_u32_e32 v5, 0x11c00, v2
	v_mul_f32_e32 v4, 0x3fb8aa3b, v4
	ds_read_b32 v5, v5
	v_exp_f32_e32 v4, v4
	s_waitcnt lgkmcnt(0)
	v_fmac_f32_e32 v3, v4, v5
	v_add_u32_e32 v5, 0x11e00, v2
	ds_write_b32 v5, v3
	v_add_u32_e32 v3, 0x12000, v2
	ds_write_b32 v3, v4
	v_add_u32_e32 v3, 0x11800, v2
	ds_read_b32 v3, v3
	v_add_u32_e32 v2, 0x12200, v2
	s_waitcnt lgkmcnt(0)
	v_add_f32_e32 v1, v1, v3
	v_mul_f32_e32 v1, 0xbfb8aa3b, v1
	v_exp_f32_e32 v1, v1
	ds_write_b32 v2, v1

.LBB0_1017:
	s_or_b64 exec, exec, s[68:69]
	v_add_f32_e32 v7, 0, v4
	v_add_f32_e32 v7, v7, v3
	v_add_f32_e32 v7, v7, v6
	v_add_f32_e32 v7, v7, v5
	v_cvt_pk_bf16_f32 v4, v4, v3
	v_mov_b32_e32 v3, v7
	v_mov_b32_e32 v255, v7
	s_nop 1
	v_permlane16_swap_b32_e32 v3, v255
	v_cvt_pk_bf16_f32 v5, v6, v5
	ds_write_b64 v0, v[4:5] offset:37808
	s_waitcnt lgkmcnt(1)
	v_add_f32_e32 v3, v3, v255
	s_nop 1
	v_mov_b32_dpp v4, v3 row_ror:8 row_mask:0xf bank_mask:0xf
	s_waitcnt lgkmcnt(0)
	v_add_f32_e32 v3, v3, v4
	s_nop 1
	v_mov_b32_dpp v4, v3 row_shl:4 row_mask:0xf bank_mask:0x5
	v_mov_b32_dpp v4, v3 row_shr:4 row_mask:0xf bank_mask:0xa
	s_nop 0
	v_add_f32_e32 v3, v3, v4
	s_nop 1
	v_mov_b32_dpp v4, v3 quad_perm:[2,3,0,1] row_mask:0xf bank_mask:0xf
	s_nop 0
	v_add_f32_e32 v3, v3, v4
	s_nop 1
	v_mov_b32_dpp v4, v3 quad_perm:[1,0,3,2] row_mask:0xf bank_mask:0xf
	s_and_saveexec_b64 s[0:1], vcc
	s_cbranch_execz .LBB0_1019
	v_lshl_add_u32 v2, v2, 2, 0
	s_nop 0
	v_add_f32_e32 v3, v3, v4
	s_waitcnt vmcnt(0)
	v_sub_f32_e32 v4, v96, v1
	v_add_u32_e32 v5, 0x11c00, v2
	v_mul_f32_e32 v4, 0x3fb8aa3b, v4
	ds_read_b32 v5, v5
	v_exp_f32_e32 v4, v4
	s_waitcnt lgkmcnt(0)
	v_fmac_f32_e32 v3, v4, v5
	v_add_u32_e32 v5, 0x11e00, v2
	ds_write_b32 v5, v3
	v_add_u32_e32 v3, 0x12000, v2
	ds_write_b32 v3, v4
	v_add_u32_e32 v3, 0x11800, v2
	ds_read_b32 v3, v3
	v_add_u32_e32 v2, 0x12200, v2
	s_waitcnt lgkmcnt(0)
	v_add_f32_e32 v1, v1, v3
	v_mul_f32_e32 v1, 0xbfb8aa3b, v1
	v_exp_f32_e32 v1, v1
	ds_write_b32 v2, v1

.LBB0_1027:
	s_or_b64 exec, exec, s[68:69]
	v_add_f32_e32 v7, 0, v4
	v_add_f32_e32 v7, v7, v3
	v_add_f32_e32 v7, v7, v6
	v_add_f32_e32 v7, v7, v5
	v_cvt_pk_bf16_f32 v4, v4, v3
	v_mov_b32_e32 v3, v7
	v_mov_b32_e32 v255, v7
	s_nop 1
	v_permlane16_swap_b32_e32 v3, v255
	v_cvt_pk_bf16_f32 v5, v6, v5
	ds_write_b64 v0, v[4:5] offset:39168
	s_waitcnt lgkmcnt(1)
	v_add_f32_e32 v3, v3, v255
	s_nop 1
	v_mov_b32_dpp v4, v3 row_ror:8 row_mask:0xf bank_mask:0xf
	s_waitcnt lgkmcnt(0)
	v_add_f32_e32 v3, v3, v4
	s_nop 1
	v_mov_b32_dpp v4, v3 row_shl:4 row_mask:0xf bank_mask:0x5
	v_mov_b32_dpp v4, v3 row_shr:4 row_mask:0xf bank_mask:0xa
	s_nop 0
	v_add_f32_e32 v3, v3, v4
	s_nop 1
	v_mov_b32_dpp v4, v3 quad_perm:[2,3,0,1] row_mask:0xf bank_mask:0xf
	s_nop 0
	v_add_f32_e32 v3, v3, v4
	s_nop 1
	v_mov_b32_dpp v4, v3 quad_perm:[1,0,3,2] row_mask:0xf bank_mask:0xf
	s_and_saveexec_b64 s[0:1], vcc
	s_cbranch_execz .LBB0_1029
	v_lshl_add_u32 v2, v2, 2, 0
	s_nop 0
	v_add_f32_e32 v3, v3, v4
	s_waitcnt vmcnt(0)
	v_sub_f32_e32 v4, v96, v1
	v_add_u32_e32 v5, 0x11c00, v2
	v_mul_f32_e32 v4, 0x3fb8aa3b, v4
	ds_read_b32 v5, v5
	v_exp_f32_e32 v4, v4
	s_waitcnt lgkmcnt(0)
	v_fmac_f32_e32 v3, v4, v5
	v_add_u32_e32 v5, 0x11e00, v2
	ds_write_b32 v5, v3
	v_add_u32_e32 v3, 0x12000, v2
	ds_write_b32 v3, v4
	v_add_u32_e32 v3, 0x11800, v2
	ds_read_b32 v3, v3
	v_add_u32_e32 v2, 0x12200, v2
	s_waitcnt lgkmcnt(0)
	v_add_f32_e32 v1, v1, v3
	v_mul_f32_e32 v1, 0xbfb8aa3b, v1
	v_exp_f32_e32 v1, v1
	ds_write_b32 v2, v1

.LBB0_1037:
	s_or_b64 exec, exec, s[68:69]
	v_add_f32_e32 v7, 0, v4
	v_add_f32_e32 v7, v7, v3
	v_add_f32_e32 v7, v7, v6
	v_add_f32_e32 v7, v7, v5
	v_cvt_pk_bf16_f32 v4, v4, v3
	v_mov_b32_e32 v3, v7
	v_mov_b32_e32 v255, v7
	s_nop 1
	v_permlane16_swap_b32_e32 v3, v255
	v_cvt_pk_bf16_f32 v5, v6, v5
	ds_write_b64 v0, v[4:5] offset:39440
	s_waitcnt lgkmcnt(1)
	v_add_f32_e32 v3, v3, v255
	s_nop 1
	v_mov_b32_dpp v4, v3 row_ror:8 row_mask:0xf bank_mask:0xf
	s_waitcnt lgkmcnt(0)
	v_add_f32_e32 v3, v3, v4
	s_nop 1
	v_mov_b32_dpp v4, v3 row_shl:4 row_mask:0xf bank_mask:0x5
	v_mov_b32_dpp v4, v3 row_shr:4 row_mask:0xf bank_mask:0xa
	s_nop 0
	v_add_f32_e32 v3, v3, v4
	s_nop 1
	v_mov_b32_dpp v4, v3 quad_perm:[2,3,0,1] row_mask:0xf bank_mask:0xf
	s_nop 0
	v_add_f32_e32 v3, v3, v4
	s_nop 1
	v_mov_b32_dpp v4, v3 quad_perm:[1,0,3,2] row_mask:0xf bank_mask:0xf
	s_and_saveexec_b64 s[0:1], vcc
	s_cbranch_execz .LBB0_1039
	v_lshl_add_u32 v2, v2, 2, 0
	s_nop 0
	v_add_f32_e32 v3, v3, v4
	s_waitcnt vmcnt(0)
	v_sub_f32_e32 v4, v96, v1
	v_add_u32_e32 v5, 0x11c00, v2
	v_mul_f32_e32 v4, 0x3fb8aa3b, v4
	ds_read_b32 v5, v5
	v_exp_f32_e32 v4, v4
	s_waitcnt lgkmcnt(0)
	v_fmac_f32_e32 v3, v4, v5
	v_add_u32_e32 v5, 0x11e00, v2
	ds_write_b32 v5, v3
	v_add_u32_e32 v3, 0x12000, v2
	ds_write_b32 v3, v4
	v_add_u32_e32 v3, 0x11800, v2
	ds_read_b32 v3, v3
	v_add_u32_e32 v2, 0x12200, v2
	s_waitcnt lgkmcnt(0)
	v_add_f32_e32 v1, v1, v3
	v_mul_f32_e32 v1, 0xbfb8aa3b, v1
	v_exp_f32_e32 v1, v1
	ds_write_b32 v2, v1

.LBB0_1047:
	s_or_b64 exec, exec, s[68:69]
	v_add_f32_e32 v7, 0, v4
	v_add_f32_e32 v7, v7, v3
	v_add_f32_e32 v7, v7, v6
	v_add_f32_e32 v7, v7, v5
	v_cvt_pk_bf16_f32 v4, v4, v3
	v_mov_b32_e32 v3, v7
	v_mov_b32_e32 v255, v7
	s_nop 1
	v_permlane16_swap_b32_e32 v3, v255
	v_cvt_pk_bf16_f32 v5, v6, v5
	ds_write_b64 v0, v[4:5] offset:39712
	s_waitcnt lgkmcnt(1)
	v_add_f32_e32 v3, v3, v255
	s_nop 1
	v_mov_b32_dpp v4, v3 row_ror:8 row_mask:0xf bank_mask:0xf
	s_waitcnt lgkmcnt(0)
	v_add_f32_e32 v3, v3, v4
	s_nop 1
	v_mov_b32_dpp v4, v3 row_shl:4 row_mask:0xf bank_mask:0x5
	v_mov_b32_dpp v4, v3 row_shr:4 row_mask:0xf bank_mask:0xa
	s_nop 0
	v_add_f32_e32 v3, v3, v4
	s_nop 1
	v_mov_b32_dpp v4, v3 quad_perm:[2,3,0,1] row_mask:0xf bank_mask:0xf
	s_nop 0
	v_add_f32_e32 v3, v3, v4
	s_nop 1
	v_mov_b32_dpp v4, v3 quad_perm:[1,0,3,2] row_mask:0xf bank_mask:0xf
	s_and_saveexec_b64 s[0:1], vcc
	s_cbranch_execz .LBB0_1049
	v_lshl_add_u32 v2, v2, 2, 0
	s_nop 0
	v_add_f32_e32 v3, v3, v4
	s_waitcnt vmcnt(0)
	v_sub_f32_e32 v4, v96, v1
	v_add_u32_e32 v5, 0x11c00, v2
	v_mul_f32_e32 v4, 0x3fb8aa3b, v4
	ds_read_b32 v5, v5
	v_exp_f32_e32 v4, v4
	s_waitcnt lgkmcnt(0)
	v_fmac_f32_e32 v3, v4, v5
	v_add_u32_e32 v5, 0x11e00, v2
	ds_write_b32 v5, v3
	v_add_u32_e32 v3, 0x12000, v2
	ds_write_b32 v3, v4
	v_add_u32_e32 v3, 0x11800, v2
	ds_read_b32 v3, v3
	v_add_u32_e32 v2, 0x12200, v2
	s_waitcnt lgkmcnt(0)
	v_add_f32_e32 v1, v1, v3
	v_mul_f32_e32 v1, 0xbfb8aa3b, v1
	v_exp_f32_e32 v1, v1
	ds_write_b32 v2, v1

.LBB0_1057:
	s_or_b64 exec, exec, s[68:69]
	v_add_f32_e32 v7, 0, v4
	v_add_f32_e32 v7, v7, v3
	v_add_f32_e32 v7, v7, v6
	v_add_f32_e32 v7, v7, v5
	v_cvt_pk_bf16_f32 v4, v4, v3
	v_mov_b32_e32 v3, v7
	v_mov_b32_e32 v255, v7
	s_nop 1
	v_permlane16_swap_b32_e32 v3, v255
	v_cvt_pk_bf16_f32 v5, v6, v5
	ds_write_b64 v0, v[4:5] offset:39984
	s_waitcnt lgkmcnt(1)
	v_add_f32_e32 v3, v3, v255
	s_nop 1
	v_mov_b32_dpp v4, v3 row_ror:8 row_mask:0xf bank_mask:0xf
	s_waitcnt lgkmcnt(0)
	v_add_f32_e32 v3, v3, v4
	s_nop 1
	v_mov_b32_dpp v4, v3 row_shl:4 row_mask:0xf bank_mask:0x5
	v_mov_b32_dpp v4, v3 row_shr:4 row_mask:0xf bank_mask:0xa
	s_nop 0
	v_add_f32_e32 v3, v3, v4
	s_nop 1
	v_mov_b32_dpp v4, v3 quad_perm:[2,3,0,1] row_mask:0xf bank_mask:0xf
	s_nop 0
	v_add_f32_e32 v3, v3, v4
	s_nop 1
	v_mov_b32_dpp v4, v3 quad_perm:[1,0,3,2] row_mask:0xf bank_mask:0xf
	s_and_saveexec_b64 s[0:1], vcc
	s_cbranch_execz .LBB0_1059
	v_lshl_add_u32 v2, v2, 2, 0
	s_nop 0
	v_add_f32_e32 v3, v3, v4
	s_waitcnt vmcnt(0)
	v_sub_f32_e32 v4, v96, v1
	v_add_u32_e32 v5, 0x11c00, v2
	v_mul_f32_e32 v4, 0x3fb8aa3b, v4
	ds_read_b32 v5, v5
	v_exp_f32_e32 v4, v4
	s_waitcnt lgkmcnt(0)
	v_fmac_f32_e32 v3, v4, v5
	v_add_u32_e32 v5, 0x11e00, v2
	ds_write_b32 v5, v3
	v_add_u32_e32 v3, 0x12000, v2
	ds_write_b32 v3, v4
	v_add_u32_e32 v3, 0x11800, v2
	ds_read_b32 v3, v3
	v_add_u32_e32 v2, 0x12200, v2
	s_waitcnt lgkmcnt(0)
	v_add_f32_e32 v1, v1, v3
	v_mul_f32_e32 v1, 0xbfb8aa3b, v1
	v_exp_f32_e32 v1, v1
	ds_write_b32 v2, v1

.LBB0_1067:
	s_or_b64 exec, exec, s[68:69]
	v_add_f32_e32 v7, 0, v4
	v_add_f32_e32 v7, v7, v3
	v_add_f32_e32 v7, v7, v6
	v_add_f32_e32 v7, v7, v5
	v_cvt_pk_bf16_f32 v4, v4, v3
	v_mov_b32_e32 v3, v7
	v_mov_b32_e32 v255, v7
	s_nop 1
	v_permlane16_swap_b32_e32 v3, v255
	v_cvt_pk_bf16_f32 v5, v6, v5
	ds_write_b64 v0, v[4:5] offset:41344
	s_waitcnt lgkmcnt(1)
	v_add_f32_e32 v3, v3, v255
	s_nop 1
	v_mov_b32_dpp v4, v3 row_ror:8 row_mask:0xf bank_mask:0xf
	s_waitcnt lgkmcnt(0)
	v_add_f32_e32 v3, v3, v4
	s_nop 1
	v_mov_b32_dpp v4, v3 row_shl:4 row_mask:0xf bank_mask:0x5
	v_mov_b32_dpp v4, v3 row_shr:4 row_mask:0xf bank_mask:0xa
	s_nop 0
	v_add_f32_e32 v3, v3, v4
	s_nop 1
	v_mov_b32_dpp v4, v3 quad_perm:[2,3,0,1] row_mask:0xf bank_mask:0xf
	s_nop 0
	v_add_f32_e32 v3, v3, v4
	s_nop 1
	v_mov_b32_dpp v4, v3 quad_perm:[1,0,3,2] row_mask:0xf bank_mask:0xf
	s_and_saveexec_b64 s[0:1], vcc
	s_cbranch_execz .LBB0_1069
	v_lshl_add_u32 v2, v2, 2, 0
	s_nop 0
	v_add_f32_e32 v3, v3, v4
	s_waitcnt vmcnt(0)
	v_sub_f32_e32 v4, v96, v1
	v_add_u32_e32 v5, 0x11c00, v2
	v_mul_f32_e32 v4, 0x3fb8aa3b, v4
	ds_read_b32 v5, v5
	v_exp_f32_e32 v4, v4
	s_waitcnt lgkmcnt(0)
	v_fmac_f32_e32 v3, v4, v5
	v_add_u32_e32 v5, 0x11e00, v2
	ds_write_b32 v5, v3
	v_add_u32_e32 v3, 0x12000, v2
	ds_write_b32 v3, v4
	v_add_u32_e32 v3, 0x11800, v2
	ds_read_b32 v3, v3
	v_add_u32_e32 v2, 0x12200, v2
	s_waitcnt lgkmcnt(0)
	v_add_f32_e32 v1, v1, v3
	v_mul_f32_e32 v1, 0xbfb8aa3b, v1
	v_exp_f32_e32 v1, v1
	ds_write_b32 v2, v1

.LBB0_1077:
	s_or_b64 exec, exec, s[68:69]
	v_add_f32_e32 v7, 0, v4
	v_add_f32_e32 v7, v7, v3
	v_add_f32_e32 v7, v7, v6
	v_add_f32_e32 v7, v7, v5
	v_cvt_pk_bf16_f32 v4, v4, v3
	v_mov_b32_e32 v3, v7
	v_mov_b32_e32 v255, v7
	s_nop 1
	v_permlane16_swap_b32_e32 v3, v255
	v_cvt_pk_bf16_f32 v5, v6, v5
	ds_write_b64 v0, v[4:5] offset:41616
	s_waitcnt lgkmcnt(1)
	v_add_f32_e32 v3, v3, v255
	s_nop 1
	v_mov_b32_dpp v4, v3 row_ror:8 row_mask:0xf bank_mask:0xf
	s_waitcnt lgkmcnt(0)
	v_add_f32_e32 v3, v3, v4
	s_nop 1
	v_mov_b32_dpp v4, v3 row_shl:4 row_mask:0xf bank_mask:0x5
	v_mov_b32_dpp v4, v3 row_shr:4 row_mask:0xf bank_mask:0xa
	s_nop 0
	v_add_f32_e32 v3, v3, v4
	s_nop 1
	v_mov_b32_dpp v4, v3 quad_perm:[2,3,0,1] row_mask:0xf bank_mask:0xf
	s_nop 0
	v_add_f32_e32 v3, v3, v4
	s_nop 1
	v_mov_b32_dpp v4, v3 quad_perm:[1,0,3,2] row_mask:0xf bank_mask:0xf
	s_and_saveexec_b64 s[0:1], vcc
	s_cbranch_execz .LBB0_1079
	v_lshl_add_u32 v2, v2, 2, 0
	s_nop 0
	v_add_f32_e32 v3, v3, v4
	s_waitcnt vmcnt(0)
	v_sub_f32_e32 v4, v96, v1
	v_add_u32_e32 v5, 0x11c00, v2
	v_mul_f32_e32 v4, 0x3fb8aa3b, v4
	ds_read_b32 v5, v5
	v_exp_f32_e32 v4, v4
	s_waitcnt lgkmcnt(0)
	v_fmac_f32_e32 v3, v4, v5
	v_add_u32_e32 v5, 0x11e00, v2
	ds_write_b32 v5, v3
	v_add_u32_e32 v3, 0x12000, v2
	ds_write_b32 v3, v4
	v_add_u32_e32 v3, 0x11800, v2
	ds_read_b32 v3, v3
	v_add_u32_e32 v2, 0x12200, v2
	s_waitcnt lgkmcnt(0)
	v_add_f32_e32 v1, v1, v3
	v_mul_f32_e32 v1, 0xbfb8aa3b, v1
	v_exp_f32_e32 v1, v1
	ds_write_b32 v2, v1

.LBB0_1087:
	s_or_b64 exec, exec, s[68:69]
	v_add_f32_e32 v7, 0, v4
	v_add_f32_e32 v7, v7, v3
	v_add_f32_e32 v7, v7, v6
	v_add_f32_e32 v7, v7, v5
	v_cvt_pk_bf16_f32 v4, v4, v3
	v_mov_b32_e32 v3, v7
	v_mov_b32_e32 v255, v7
	s_nop 1
	v_permlane16_swap_b32_e32 v3, v255
	v_cvt_pk_bf16_f32 v5, v6, v5
	ds_write_b64 v0, v[4:5] offset:41888
	s_waitcnt lgkmcnt(1)
	v_add_f32_e32 v3, v3, v255
	s_nop 1
	v_mov_b32_dpp v4, v3 row_ror:8 row_mask:0xf bank_mask:0xf
	s_waitcnt lgkmcnt(0)
	v_add_f32_e32 v3, v3, v4
	s_nop 1
	v_mov_b32_dpp v4, v3 row_shl:4 row_mask:0xf bank_mask:0x5
	v_mov_b32_dpp v4, v3 row_shr:4 row_mask:0xf bank_mask:0xa
	s_nop 0
	v_add_f32_e32 v3, v3, v4
	s_nop 1
	v_mov_b32_dpp v4, v3 quad_perm:[2,3,0,1] row_mask:0xf bank_mask:0xf
	s_nop 0
	v_add_f32_e32 v3, v3, v4
	s_nop 1
	v_mov_b32_dpp v4, v3 quad_perm:[1,0,3,2] row_mask:0xf bank_mask:0xf
	s_and_saveexec_b64 s[0:1], vcc
	s_cbranch_execz .LBB0_1089
	v_lshl_add_u32 v2, v2, 2, 0
	s_nop 0
	v_add_f32_e32 v3, v3, v4
	s_waitcnt vmcnt(0)
	v_sub_f32_e32 v4, v96, v1
	v_add_u32_e32 v5, 0x11c00, v2
	v_mul_f32_e32 v4, 0x3fb8aa3b, v4
	ds_read_b32 v5, v5
	v_exp_f32_e32 v4, v4
	s_waitcnt lgkmcnt(0)
	v_fmac_f32_e32 v3, v4, v5
	v_add_u32_e32 v5, 0x11e00, v2
	ds_write_b32 v5, v3
	v_add_u32_e32 v3, 0x12000, v2
	ds_write_b32 v3, v4
	v_add_u32_e32 v3, 0x11800, v2
	ds_read_b32 v3, v3
	v_add_u32_e32 v2, 0x12200, v2
	s_waitcnt lgkmcnt(0)
	v_add_f32_e32 v1, v1, v3
	v_mul_f32_e32 v1, 0xbfb8aa3b, v1
	v_exp_f32_e32 v1, v1
	ds_write_b32 v2, v1

.LBB0_1097:
	s_or_b64 exec, exec, s[6:7]
	v_add_f32_e32 v7, 0, v4
	v_add_f32_e32 v7, v7, v3
	v_add_f32_e32 v7, v7, v6
	v_add_f32_e32 v7, v7, v5
	v_cvt_pk_bf16_f32 v4, v4, v3
	v_cvt_pk_bf16_f32 v5, v6, v5
	ds_write_b64 v0, v[4:5] offset:42160
	v_mov_b32_e32 v0, v7
	v_mov_b32_e32 v255, v7
	s_nop 1
	v_permlane16_swap_b32_e32 v0, v255
	s_waitcnt lgkmcnt(0)
	v_add_f32_e32 v0, v0, v255
	s_nop 1
	v_mov_b32_dpp v3, v0 row_ror:8 row_mask:0xf bank_mask:0xf
	s_nop 0
	v_add_f32_e32 v0, v0, v3
	s_nop 1
	v_mov_b32_dpp v3, v0 row_shl:4 row_mask:0xf bank_mask:0x5
	v_mov_b32_dpp v3, v0 row_shr:4 row_mask:0xf bank_mask:0xa
	s_nop 0
	v_add_f32_e32 v0, v0, v3
	s_nop 1
	v_mov_b32_dpp v3, v0 quad_perm:[2,3,0,1] row_mask:0xf bank_mask:0xf
	s_nop 0
	v_add_f32_e32 v0, v0, v3
	s_nop 1
	v_mov_b32_dpp v3, v0 quad_perm:[1,0,3,2] row_mask:0xf bank_mask:0xf
	s_and_saveexec_b64 s[0:1], vcc
	s_cbranch_execz .LBB0_1099
	v_lshl_add_u32 v2, v2, 2, 0
	s_nop 0
	v_add_f32_e32 v0, v0, v3
	s_waitcnt vmcnt(0)
	v_sub_f32_e32 v3, v96, v1
	v_add_u32_e32 v4, 0x11c00, v2
	v_mul_f32_e32 v3, 0x3fb8aa3b, v3
	ds_read_b32 v4, v4
	v_exp_f32_e32 v3, v3
	s_waitcnt lgkmcnt(0)
	v_fmac_f32_e32 v0, v3, v4
	v_add_u32_e32 v4, 0x11e00, v2
	ds_write_b32 v4, v0
	v_add_u32_e32 v0, 0x12000, v2
	ds_write_b32 v0, v3
	v_add_u32_e32 v0, 0x11800, v2
	ds_read_b32 v0, v0
	s_waitcnt lgkmcnt(0)
	v_add_f32_e32 v0, v1, v0
	v_mul_f32_e32 v0, 0xbfb8aa3b, v0
	v_exp_f32_e32 v0, v0
	v_add_u32_e32 v1, 0x12200, v2
	ds_write_b32 v1, v0

.LBB0_1101:
	s_waitcnt lgkmcnt(0)
	v_ashrrev_i32_e32 v3, 31, v0
	v_lshrrev_b32_e32 v3, 28, v3
	v_add_u32_e32 v3, v0, v3
	v_ashrrev_i32_e32 v4, 4, v3
	v_ashrrev_i32_e32 v5, 31, v4
	v_lshlrev_b32_e32 v6, 7, v4
	v_lshlrev_b64 v[4:5], 8, v[4:5]
	v_sub_u32_e32 v6, v2, v6
	v_lshl_add_u64 v[4:5], s[6:7], 0, v[4:5]
	v_ashrrev_i32_e32 v7, 31, v6
	v_lshl_add_u64 v[4:5], v[6:7], 1, v[4:5]
	global_load_dwordx4 v[16:19], v[4:5], off
	v_add_u32_e32 v8, 0x100, v0
	v_cmp_lt_i32_e32 vcc, s77, v0
	v_and_b32_e32 v3, -16, v3
	s_or_b64 s[12:13], vcc, s[12:13]
	v_mov_b32_e32 v0, v8
	v_add_u32_e32 v3, v1, v3
	v_add_u32_e32 v1, 0x1000, v1
	v_add_u32_e32 v2, 0x800, v2
	v_mov_b32_e32 v44, v3
	v_ashrrev_i32_e32 v3, 31, v0
	v_lshrrev_b32_e32 v3, 28, v3
	v_add_u32_e32 v3, v0, v3
	v_ashrrev_i32_e32 v4, 4, v3
	v_ashrrev_i32_e32 v5, 31, v4
	v_lshlrev_b32_e32 v6, 7, v4
	v_lshlrev_b64 v[4:5], 8, v[4:5]
	v_sub_u32_e32 v6, v2, v6
	v_lshl_add_u64 v[4:5], s[6:7], 0, v[4:5]
	v_ashrrev_i32_e32 v7, 31, v6
	v_lshl_add_u64 v[4:5], v[6:7], 1, v[4:5]
	global_load_dwordx4 v[20:23], v[4:5], off
	v_add_u32_e32 v8, 0x100, v0
	v_cmp_lt_i32_e32 vcc, s77, v0
	v_and_b32_e32 v3, -16, v3
	s_or_b64 s[12:13], vcc, s[12:13]
	v_mov_b32_e32 v0, v8
	v_add_u32_e32 v3, v1, v3
	v_add_u32_e32 v1, 0x1000, v1
	v_add_u32_e32 v2, 0x800, v2
	v_mov_b32_e32 v45, v3
	v_ashrrev_i32_e32 v3, 31, v0
	v_lshrrev_b32_e32 v3, 28, v3
	v_add_u32_e32 v3, v0, v3
	v_ashrrev_i32_e32 v4, 4, v3
	v_ashrrev_i32_e32 v5, 31, v4
	v_lshlrev_b32_e32 v6, 7, v4
	v_lshlrev_b64 v[4:5], 8, v[4:5]
	v_sub_u32_e32 v6, v2, v6
	v_lshl_add_u64 v[4:5], s[6:7], 0, v[4:5]
	v_ashrrev_i32_e32 v7, 31, v6
	v_lshl_add_u64 v[4:5], v[6:7], 1, v[4:5]
	global_load_dwordx4 v[24:27], v[4:5], off
	v_add_u32_e32 v8, 0x100, v0
	v_cmp_lt_i32_e32 vcc, s77, v0
	v_and_b32_e32 v3, -16, v3
	s_or_b64 s[12:13], vcc, s[12:13]
	v_mov_b32_e32 v0, v8
	v_add_u32_e32 v3, v1, v3
	v_add_u32_e32 v1, 0x1000, v1
	v_add_u32_e32 v2, 0x800, v2
	v_mov_b32_e32 v46, v3
	v_ashrrev_i32_e32 v3, 31, v0
	v_lshrrev_b32_e32 v3, 28, v3
	v_add_u32_e32 v3, v0, v3
	v_ashrrev_i32_e32 v4, 4, v3
	v_ashrrev_i32_e32 v5, 31, v4
	v_lshlrev_b32_e32 v6, 7, v4
	v_lshlrev_b64 v[4:5], 8, v[4:5]
	v_sub_u32_e32 v6, v2, v6
	v_lshl_add_u64 v[4:5], s[6:7], 0, v[4:5]
	v_ashrrev_i32_e32 v7, 31, v6
	v_lshl_add_u64 v[4:5], v[6:7], 1, v[4:5]
	global_load_dwordx4 v[28:31], v[4:5], off
	v_add_u32_e32 v8, 0x100, v0
	v_cmp_lt_i32_e32 vcc, s77, v0
	v_and_b32_e32 v3, -16, v3
	s_or_b64 s[12:13], vcc, s[12:13]
	v_mov_b32_e32 v0, v8
	v_add_u32_e32 v3, v1, v3
	v_add_u32_e32 v1, 0x1000, v1
	v_add_u32_e32 v2, 0x800, v2
	v_mov_b32_e32 v47, v3
	v_ashrrev_i32_e32 v3, 31, v0
	v_lshrrev_b32_e32 v3, 28, v3
	v_add_u32_e32 v3, v0, v3
	v_ashrrev_i32_e32 v4, 4, v3
	v_ashrrev_i32_e32 v5, 31, v4
	v_lshlrev_b32_e32 v6, 7, v4
	v_lshlrev_b64 v[4:5], 8, v[4:5]
	v_sub_u32_e32 v6, v2, v6
	v_lshl_add_u64 v[4:5], s[6:7], 0, v[4:5]
	v_ashrrev_i32_e32 v7, 31, v6
	v_lshl_add_u64 v[4:5], v[6:7], 1, v[4:5]
	global_load_dwordx4 v[32:35], v[4:5], off
	v_add_u32_e32 v8, 0x100, v0
	v_cmp_lt_i32_e32 vcc, s77, v0
	v_and_b32_e32 v3, -16, v3
	s_or_b64 s[12:13], vcc, s[12:13]
	v_mov_b32_e32 v0, v8
	v_add_u32_e32 v3, v1, v3
	v_add_u32_e32 v1, 0x1000, v1
	v_add_u32_e32 v2, 0x800, v2
	v_mov_b32_e32 v48, v3
	v_ashrrev_i32_e32 v3, 31, v0
	v_lshrrev_b32_e32 v3, 28, v3
	v_add_u32_e32 v3, v0, v3
	v_ashrrev_i32_e32 v4, 4, v3
	v_ashrrev_i32_e32 v5, 31, v4
	v_lshlrev_b32_e32 v6, 7, v4
	v_lshlrev_b64 v[4:5], 8, v[4:5]
	v_sub_u32_e32 v6, v2, v6
	v_lshl_add_u64 v[4:5], s[6:7], 0, v[4:5]
	v_ashrrev_i32_e32 v7, 31, v6
	v_lshl_add_u64 v[4:5], v[6:7], 1, v[4:5]
	global_load_dwordx4 v[36:39], v[4:5], off
	v_add_u32_e32 v8, 0x100, v0
	v_cmp_lt_i32_e32 vcc, s77, v0
	v_and_b32_e32 v3, -16, v3
	s_or_b64 s[12:13], vcc, s[12:13]
	v_mov_b32_e32 v0, v8
	v_add_u32_e32 v3, v1, v3
	v_add_u32_e32 v1, 0x1000, v1
	v_add_u32_e32 v2, 0x800, v2
	v_mov_b32_e32 v49, v3
	v_ashrrev_i32_e32 v3, 31, v0
	v_lshrrev_b32_e32 v3, 28, v3
	v_add_u32_e32 v3, v0, v3
	v_ashrrev_i32_e32 v4, 4, v3
	v_ashrrev_i32_e32 v5, 31, v4
	v_lshlrev_b32_e32 v6, 7, v4
	v_lshlrev_b64 v[4:5], 8, v[4:5]
	v_sub_u32_e32 v6, v2, v6
	v_lshl_add_u64 v[4:5], s[6:7], 0, v[4:5]
	v_ashrrev_i32_e32 v7, 31, v6
	v_lshl_add_u64 v[4:5], v[6:7], 1, v[4:5]
	global_load_dwordx4 v[40:43], v[4:5], off
	v_add_u32_e32 v8, 0x100, v0
	v_cmp_lt_i32_e32 vcc, s77, v0
	v_and_b32_e32 v3, -16, v3
	s_or_b64 s[12:13], vcc, s[12:13]
	v_mov_b32_e32 v0, v8
	v_add_u32_e32 v3, v1, v3
	v_add_u32_e32 v1, 0x1000, v1
	v_add_u32_e32 v2, 0x800, v2
	v_mov_b32_e32 v50, v3
	v_ashrrev_i32_e32 v3, 31, v0
	v_lshrrev_b32_e32 v3, 28, v3
	v_add_u32_e32 v3, v0, v3
	v_ashrrev_i32_e32 v4, 4, v3
	v_ashrrev_i32_e32 v5, 31, v4
	v_lshlrev_b32_e32 v6, 7, v4
	v_lshlrev_b64 v[4:5], 8, v[4:5]
	v_sub_u32_e32 v6, v2, v6
	v_lshl_add_u64 v[4:5], s[6:7], 0, v[4:5]
	v_ashrrev_i32_e32 v7, 31, v6
	v_lshl_add_u64 v[4:5], v[6:7], 1, v[4:5]
	global_load_dwordx4 v[4:7], v[4:5], off
	v_cmp_lt_i32_e32 vcc, s77, v0
	v_and_b32_e32 v3, -16, v3
	s_or_b64 s[12:13], vcc, s[12:13]
	v_add_u32_e32 v3, v1, v3
	s_waitcnt vmcnt(7)
	ds_write_b128 v44, v[16:19]
	s_waitcnt vmcnt(6)
	ds_write_b128 v45, v[20:23]
	s_waitcnt vmcnt(5)
	ds_write_b128 v46, v[24:27]
	s_waitcnt vmcnt(4)
	ds_write_b128 v47, v[28:31]
	s_waitcnt vmcnt(3)
	ds_write_b128 v48, v[32:35]
	s_waitcnt vmcnt(2)
	ds_write_b128 v49, v[36:39]
	s_waitcnt vmcnt(1)
	ds_write_b128 v50, v[40:43]
	s_waitcnt vmcnt(0)
	ds_write_b128 v3, v[4:7]
	s_or_b64 exec, exec, s[12:13]

.LBB0_1353:
	v_readlane_b32 s42, v248, 8
	v_readlane_b32 s43, v248, 9
	s_add_u32 s7, s42, s40
	s_addc_u32 s13, s43, s41
	s_and_b64 s[40:41], s[44:45], exec
	s_cselect_b32 s40, s7, 0
	v_readlane_b32 s7, v249, 33
	s_cselect_b32 s41, s13, 0
	s_add_u32 s7, s7, s46
	v_readlane_b32 s8, v249, 34
	s_addc_u32 s13, s8, s47
	s_and_b64 s[46:47], s[44:45], exec
	s_cselect_b32 s47, s13, 0
	s_cselect_b32 s46, s7, 0
	v_lshl_add_u64 v[4:5], s[40:41], 0, v[0:1]
	v_lshl_add_u64 v[0:1], s[46:47], 0, v[0:1]
	v_lshl_add_u64 v[146:147], v[0:1], 0, v[96:97]
	v_lshrrev_b32_e32 v0, 1, v2
	v_and_b32_e32 v1, 31, v2
	v_and_or_b32 v1, v0, s81, v1
	v_lshrrev_b32_e32 v0, 2, v2
	v_and_b32_e32 v0, 8, v0
	v_lshl_add_u64 v[148:149], v[4:5], 0, v[96:97]
	v_mad_u64_u32 v[4:5], s[40:41], v1, s84, v[0:1]
	v_and_b32_e32 v1, 0x5f, v2
	v_mad_u32_u24 v0, v1, s84, v0
	v_lshl_add_u32 v176, v4, 1, 0
	v_lshl_add_u32 v96, v0, 1, 0
	v_add_u32_e32 v177, 0xd800, v175
	s_setprio 1
	ds_read_b128 v[212:215], v96 offset:36864
	ds_read_b128 v[216:219], v176
	ds_read_b128 v[220:223], v176 offset:4608
	ds_read_b128 v[224:227], v96 offset:36896
	ds_read_b128 v[228:231], v176 offset:32
	ds_read_b128 v[244:247], v176 offset:4640
	ds_read_b128 v[252:255], v96 offset:41472
	s_waitcnt lgkmcnt(5)
	v_mfma_f32_32x32x16_bf16 v[32:47], v[212:215], v[216:219], 0
	s_waitcnt lgkmcnt(4)
	v_mfma_f32_32x32x16_bf16 v[0:15], v[212:215], v[220:223], 0
	ds_read_b128 v[212:215], v96 offset:41504
	s_waitcnt lgkmcnt(3)
	v_mfma_f32_32x32x16_bf16 v[32:47], v[224:227], v[228:231], v[32:47]
	s_waitcnt lgkmcnt(2)
	v_mfma_f32_32x32x16_bf16 v[0:15], v[224:227], v[244:247], v[0:15]
	ds_read_b128 v[224:227], v96 offset:36928
	s_waitcnt lgkmcnt(2)
	v_mfma_f32_32x32x16_bf16 v[48:63], v[252:255], v[216:219], 0
	ds_read_b128 v[216:219], v176 offset:64
	v_mfma_f32_32x32x16_bf16 v[16:31], v[252:255], v[220:223], 0
	ds_read_b128 v[252:255], v176 offset:4672
	ds_read_b128 v[220:223], v96 offset:41536
	s_waitcnt lgkmcnt(4)
	v_mfma_f32_32x32x16_bf16 v[48:63], v[212:215], v[228:231], v[48:63]
	ds_read_b128 v[228:231], v96 offset:36960
	v_mfma_f32_32x32x16_bf16 v[16:31], v[212:215], v[244:247], v[16:31]
	ds_read_b128 v[212:215], v176 offset:96
	ds_read_b128 v[244:247], v176 offset:4704
	s_waitcnt lgkmcnt(5)
	v_mfma_f32_32x32x16_bf16 v[32:47], v[224:227], v[216:219], v[32:47]
	v_add_co_u32_e32 v154, vcc, s9, v152
	s_waitcnt vmcnt(11)
	ds_write_b128 v175, v[100:103] offset:18432
	s_waitcnt vmcnt(10)
	ds_write_b128 v175, v[104:107] offset:23040
	s_waitcnt lgkmcnt(6)
	v_mfma_f32_32x32x16_bf16 v[0:15], v[224:227], v[252:255], v[0:15]
	ds_read_b128 v[224:227], v96 offset:41568
	s_waitcnt vmcnt(9)
	ds_write_b128 v175, v[108:111] offset:27648
	s_waitcnt vmcnt(8)
	ds_write_b128 v175, v[112:115] offset:32256
	s_waitcnt vmcnt(7)
	s_waitcnt lgkmcnt(8)
	v_mfma_f32_32x32x16_bf16 v[48:63], v[220:223], v[216:219], v[48:63]
	ds_write_b128 v175, v[116:119] offset:55296
	s_waitcnt vmcnt(6)
	ds_write_b128 v175, v[124:127] offset:59904
	s_waitcnt vmcnt(5)
	ds_write_b128 v175, v[120:123] offset:64512
	v_mfma_f32_32x32x16_bf16 v[16:31], v[220:223], v[252:255], v[16:31]
	s_waitcnt vmcnt(4)
	ds_write_b128 v177, v[128:131] offset:13824
	v_addc_co_u32_e32 v155, vcc, 0, v153, vcc
	v_add_co_u32_e32 v156, vcc, s16, v152
	s_waitcnt lgkmcnt(10)
	v_mfma_f32_32x32x16_bf16 v[32:47], v[228:231], v[212:215], v[32:47]
	global_load_dwordx4 v[98:101], v[152:153], off offset:384
	global_load_dwordx4 v[102:105], v[154:155], off offset:384
	v_addc_co_u32_e32 v157, vcc, 0, v153, vcc
	v_add_co_u32_e32 v158, vcc, s17, v152
	global_load_dwordx4 v[106:109], v[156:157], off offset:384
	s_waitcnt lgkmcnt(9)
	v_mfma_f32_32x32x16_bf16 v[0:15], v[228:231], v[244:247], v[0:15]
	s_nop 0
	v_addc_co_u32_e32 v159, vcc, 0, v153, vcc
	v_add_co_u32_e32 v160, vcc, s9, v150
	global_load_dwordx4 v[110:113], v[158:159], off offset:384
	global_load_dwordx4 v[114:117], v[150:151], off offset:384
	s_waitcnt lgkmcnt(6)
	v_mfma_f32_32x32x16_bf16 v[48:63], v[224:227], v[212:215], v[48:63]
	v_addc_co_u32_e32 v161, vcc, 0, v151, vcc
	v_add_co_u32_e32 v170, vcc, s16, v150
	global_load_dwordx4 v[118:121], v[160:161], off offset:384
	s_nop 0
	v_addc_co_u32_e32 v171, vcc, 0, v151, vcc
	v_mfma_f32_32x32x16_bf16 v[16:31], v[224:227], v[244:247], v[16:31]
	v_add_co_u32_e32 v172, vcc, s17, v150
	global_load_dwordx4 v[122:125], v[170:171], off offset:384
	s_nop 0
	v_addc_co_u32_e32 v173, vcc, 0, v151, vcc
	global_load_dwordx4 v[130:133], v[172:173], off offset:384
	s_setprio 0
	s_waitcnt lgkmcnt(0)
	s_barrier
	s_setprio 1
	ds_read_b128 v[212:215], v96 offset:55296
	ds_read_b128 v[216:219], v176 offset:18432
	ds_read_b128 v[220:223], v176 offset:23040
	ds_read_b128 v[224:227], v96 offset:59904
	ds_read_b128 v[228:231], v96 offset:55328
	ds_read_b128 v[244:247], v176 offset:18464
	ds_read_b128 v[252:255], v176 offset:23072
	s_waitcnt lgkmcnt(5)
	v_mfma_f32_32x32x16_bf16 v[32:47], v[212:215], v[216:219], v[32:47]
	s_waitcnt lgkmcnt(4)
	v_mfma_f32_32x32x16_bf16 v[0:15], v[212:215], v[220:223], v[0:15]
	ds_read_b128 v[212:215], v96 offset:59936
	s_waitcnt lgkmcnt(4)
	v_mfma_f32_32x32x16_bf16 v[48:63], v[224:227], v[216:219], v[48:63]
	ds_read_b128 v[216:219], v96 offset:55360
	v_mfma_f32_32x32x16_bf16 v[16:31], v[224:227], v[220:223], v[16:31]
	ds_read_b128 v[224:227], v176 offset:18496
	ds_read_b128 v[220:223], v176 offset:23104
	s_waitcnt lgkmcnt(5)
	v_mfma_f32_32x32x16_bf16 v[32:47], v[228:231], v[244:247], v[32:47]
	s_waitcnt lgkmcnt(4)
	v_mfma_f32_32x32x16_bf16 v[0:15], v[228:231], v[252:255], v[0:15]
	ds_read_b128 v[228:231], v96 offset:59968
	s_waitcnt lgkmcnt(4)
	v_mfma_f32_32x32x16_bf16 v[48:63], v[212:215], v[244:247], v[48:63]
	ds_read_b128 v[244:247], v96 offset:55392
	v_mfma_f32_32x32x16_bf16 v[16:31], v[212:215], v[252:255], v[16:31]
	ds_read_b128 v[212:215], v176 offset:18528
	ds_read_b128 v[252:255], v176 offset:23136
	s_waitcnt lgkmcnt(5)
	v_mfma_f32_32x32x16_bf16 v[32:47], v[216:219], v[224:227], v[32:47]
	s_nop 0
	ds_write_b128 v175, v[64:67]
	global_load_dwordx4 v[64:67], v[152:153], off offset:512
	s_waitcnt lgkmcnt(5)
	v_mfma_f32_32x32x16_bf16 v[0:15], v[216:219], v[220:223], v[0:15]
	ds_read_b128 v[216:219], v96 offset:60000
	s_nop 0
	ds_write_b128 v175, v[68:71] offset:4608
	s_nop 0
	ds_write_b128 v175, v[72:75] offset:9216
	s_waitcnt lgkmcnt(7)
	v_mfma_f32_32x32x16_bf16 v[48:63], v[228:231], v[224:227], v[48:63]
	global_load_dwordx4 v[72:75], v[154:155], off offset:512
	s_nop 0
	ds_write_b128 v175, v[76:79] offset:13824
	v_mfma_f32_32x32x16_bf16 v[16:31], v[228:231], v[220:223], v[16:31]
	global_load_dwordx4 v[76:79], v[156:157], off offset:512
	s_waitcnt vmcnt(14)
	ds_write_b128 v175, v[80:83] offset:36864
	s_waitcnt lgkmcnt(7)
	v_mfma_f32_32x32x16_bf16 v[32:47], v[244:247], v[212:215], v[32:47]
	global_load_dwordx4 v[80:83], v[158:159], off offset:512
	global_load_dwordx4 v[126:129], v[150:151], off offset:512
	s_waitcnt lgkmcnt(6)
	v_mfma_f32_32x32x16_bf16 v[0:15], v[244:247], v[252:255], v[0:15]
	s_waitcnt vmcnt(15)
	ds_write_b128 v175, v[84:87] offset:41472
	global_load_dwordx4 v[134:137], v[160:161], off offset:512
	s_waitcnt lgkmcnt(5)
	v_mfma_f32_32x32x16_bf16 v[48:63], v[216:219], v[212:215], v[48:63]
	s_waitcnt vmcnt(15)
	ds_write_b128 v175, v[88:91] offset:46080
	global_load_dwordx4 v[138:141], v[170:171], off offset:512
	v_mfma_f32_32x32x16_bf16 v[16:31], v[216:219], v[252:255], v[16:31]
	s_waitcnt vmcnt(15)
	ds_write_b128 v175, v[92:95] offset:50688
	global_load_dwordx4 v[142:145], v[172:173], off offset:512
	s_setprio 0
	s_waitcnt lgkmcnt(0)
	s_barrier
	s_setprio 1
	ds_read_b128 v[212:215], v96 offset:36864
	ds_read_b128 v[216:219], v176
	ds_read_b128 v[220:223], v176 offset:4608
	ds_read_b128 v[224:227], v96 offset:41472
	ds_read_b128 v[228:231], v96 offset:36896
	ds_read_b128 v[244:247], v176 offset:32
	ds_read_b128 v[252:255], v176 offset:4640
	s_waitcnt lgkmcnt(5)
	v_mfma_f32_32x32x16_bf16 v[32:47], v[212:215], v[216:219], v[32:47]
	s_waitcnt lgkmcnt(4)
	v_mfma_f32_32x32x16_bf16 v[0:15], v[212:215], v[220:223], v[0:15]
	ds_read_b128 v[212:215], v96 offset:41504
	s_waitcnt lgkmcnt(4)
	v_mfma_f32_32x32x16_bf16 v[48:63], v[224:227], v[216:219], v[48:63]
	ds_read_b128 v[216:219], v96 offset:36928
	v_mfma_f32_32x32x16_bf16 v[16:31], v[224:227], v[220:223], v[16:31]
	ds_read_b128 v[224:227], v176 offset:64
	ds_read_b128 v[220:223], v176 offset:4672
	s_waitcnt lgkmcnt(5)
	v_mfma_f32_32x32x16_bf16 v[32:47], v[228:231], v[244:247], v[32:47]
	s_waitcnt lgkmcnt(4)
	v_mfma_f32_32x32x16_bf16 v[0:15], v[228:231], v[252:255], v[0:15]
	ds_read_b128 v[228:231], v96 offset:41536
	s_waitcnt lgkmcnt(4)
	v_mfma_f32_32x32x16_bf16 v[48:63], v[212:215], v[244:247], v[48:63]
	ds_read_b128 v[244:247], v96 offset:36960
	v_mfma_f32_32x32x16_bf16 v[16:31], v[212:215], v[252:255], v[16:31]
	ds_read_b128 v[212:215], v176 offset:96
	ds_read_b128 v[252:255], v176 offset:4704
	s_waitcnt lgkmcnt(5)
	v_mfma_f32_32x32x16_bf16 v[32:47], v[216:219], v[224:227], v[32:47]
	s_waitcnt vmcnt(15)
	ds_write_b128 v175, v[98:101] offset:18432
	global_load_dwordx4 v[68:71], v[152:153], off offset:640
	s_waitcnt lgkmcnt(5)
	v_mfma_f32_32x32x16_bf16 v[0:15], v[216:219], v[220:223], v[0:15]
	ds_read_b128 v[216:219], v96 offset:41568
	s_waitcnt vmcnt(15)
	ds_write_b128 v175, v[102:105] offset:23040
	global_load_dwordx4 v[84:87], v[154:155], off offset:640
	s_waitcnt lgkmcnt(6)
	v_mfma_f32_32x32x16_bf16 v[48:63], v[228:231], v[224:227], v[48:63]
	s_waitcnt vmcnt(15)
	ds_write_b128 v175, v[106:109] offset:27648
	global_load_dwordx4 v[88:91], v[156:157], off offset:640
	v_mfma_f32_32x32x16_bf16 v[16:31], v[228:231], v[220:223], v[16:31]
	s_waitcnt vmcnt(15)
	ds_write_b128 v175, v[110:113] offset:32256
	global_load_dwordx4 v[92:95], v[158:159], off offset:640
	s_waitcnt lgkmcnt(6)
	v_mfma_f32_32x32x16_bf16 v[32:47], v[244:247], v[212:215], v[32:47]
	s_waitcnt vmcnt(15)
	ds_write_b128 v175, v[114:117] offset:55296
	global_load_dwordx4 v[98:101], v[150:151], off offset:640
	s_waitcnt lgkmcnt(6)
	v_mfma_f32_32x32x16_bf16 v[0:15], v[244:247], v[252:255], v[0:15]
	s_waitcnt vmcnt(15)
	ds_write_b128 v175, v[118:121] offset:59904
	global_load_dwordx4 v[106:109], v[160:161], off offset:640
	s_waitcnt lgkmcnt(5)
	v_mfma_f32_32x32x16_bf16 v[48:63], v[216:219], v[212:215], v[48:63]
	s_waitcnt vmcnt(15)
	ds_write_b128 v175, v[122:125] offset:64512
	global_load_dwordx4 v[110:113], v[170:171], off offset:640
	v_mfma_f32_32x32x16_bf16 v[16:31], v[216:219], v[252:255], v[16:31]
	s_waitcnt vmcnt(15)
	ds_write_b128 v177, v[130:133] offset:13824
	global_load_dwordx4 v[114:117], v[172:173], off offset:640
	s_setprio 0
	s_waitcnt lgkmcnt(0)
	s_barrier
	s_setprio 1
	ds_read_b128 v[212:215], v96 offset:55296
	ds_read_b128 v[216:219], v176 offset:18432
	ds_read_b128 v[220:223], v176 offset:23040
	ds_read_b128 v[224:227], v96 offset:59904
	ds_read_b128 v[228:231], v96 offset:55328
	ds_read_b128 v[244:247], v176 offset:18464
	ds_read_b128 v[252:255], v176 offset:23072
	s_waitcnt lgkmcnt(5)
	v_mfma_f32_32x32x16_bf16 v[32:47], v[212:215], v[216:219], v[32:47]
	s_waitcnt lgkmcnt(4)
	v_mfma_f32_32x32x16_bf16 v[0:15], v[212:215], v[220:223], v[0:15]
	ds_read_b128 v[212:215], v96 offset:59936
	s_waitcnt lgkmcnt(4)
	v_mfma_f32_32x32x16_bf16 v[48:63], v[224:227], v[216:219], v[48:63]
	ds_read_b128 v[216:219], v96 offset:55360
	v_mfma_f32_32x32x16_bf16 v[16:31], v[224:227], v[220:223], v[16:31]
	ds_read_b128 v[224:227], v176 offset:18496
	ds_read_b128 v[220:223], v176 offset:23104
	s_waitcnt lgkmcnt(5)
	v_mfma_f32_32x32x16_bf16 v[32:47], v[228:231], v[244:247], v[32:47]
	s_waitcnt lgkmcnt(4)
	v_mfma_f32_32x32x16_bf16 v[0:15], v[228:231], v[252:255], v[0:15]
	ds_read_b128 v[228:231], v96 offset:59968
	s_waitcnt lgkmcnt(4)
	v_mfma_f32_32x32x16_bf16 v[48:63], v[212:215], v[244:247], v[48:63]
	ds_read_b128 v[244:247], v96 offset:55392
	v_mfma_f32_32x32x16_bf16 v[16:31], v[212:215], v[252:255], v[16:31]
	ds_read_b128 v[212:215], v176 offset:18528
	ds_read_b128 v[252:255], v176 offset:23136
	s_waitcnt lgkmcnt(5)
	v_mfma_f32_32x32x16_bf16 v[32:47], v[216:219], v[224:227], v[32:47]
	s_waitcnt vmcnt(15)
	ds_write_b128 v175, v[64:67]
	global_load_dwordx4 v[64:67], v[152:153], off offset:768
	s_waitcnt lgkmcnt(5)
	v_mfma_f32_32x32x16_bf16 v[0:15], v[216:219], v[220:223], v[0:15]
	ds_read_b128 v[216:219], v96 offset:60000
	s_waitcnt vmcnt(15)
	ds_write_b128 v175, v[72:75] offset:4608
	global_load_dwordx4 v[72:75], v[154:155], off offset:768
	s_waitcnt lgkmcnt(6)
	v_mfma_f32_32x32x16_bf16 v[48:63], v[228:231], v[224:227], v[48:63]
	s_waitcnt vmcnt(15)
	ds_write_b128 v175, v[76:79] offset:9216
	global_load_dwordx4 v[76:79], v[156:157], off offset:768
	v_mfma_f32_32x32x16_bf16 v[16:31], v[228:231], v[220:223], v[16:31]
	s_waitcnt vmcnt(15)
	ds_write_b128 v175, v[80:83] offset:13824
	global_load_dwordx4 v[80:83], v[158:159], off offset:768
	s_waitcnt lgkmcnt(6)
	v_mfma_f32_32x32x16_bf16 v[32:47], v[244:247], v[212:215], v[32:47]
	s_waitcnt vmcnt(15)
	ds_write_b128 v175, v[126:129] offset:36864
	global_load_dwordx4 v[102:105], v[150:151], off offset:768
	s_waitcnt lgkmcnt(6)
	v_mfma_f32_32x32x16_bf16 v[0:15], v[244:247], v[252:255], v[0:15]
	s_waitcnt vmcnt(15)
	ds_write_b128 v175, v[134:137] offset:41472
	global_load_dwordx4 v[118:121], v[160:161], off offset:768
	s_waitcnt lgkmcnt(5)
	v_mfma_f32_32x32x16_bf16 v[48:63], v[216:219], v[212:215], v[48:63]
	s_waitcnt vmcnt(15)
	ds_write_b128 v175, v[138:141] offset:46080
	global_load_dwordx4 v[122:125], v[170:171], off offset:768
	v_mfma_f32_32x32x16_bf16 v[16:31], v[216:219], v[252:255], v[16:31]
	s_waitcnt vmcnt(15)
	ds_write_b128 v175, v[142:145] offset:50688
	global_load_dwordx4 v[126:129], v[172:173], off offset:768
	s_setprio 0
	s_waitcnt lgkmcnt(0)
	s_barrier
	s_setprio 1
	ds_read_b128 v[212:215], v96 offset:36864
	ds_read_b128 v[216:219], v176
	ds_read_b128 v[220:223], v176 offset:4608
	ds_read_b128 v[224:227], v96 offset:41472
	ds_read_b128 v[228:231], v96 offset:36896
	ds_read_b128 v[244:247], v176 offset:32
	ds_read_b128 v[252:255], v176 offset:4640
	s_waitcnt lgkmcnt(5)
	v_mfma_f32_32x32x16_bf16 v[32:47], v[212:215], v[216:219], v[32:47]
	s_waitcnt lgkmcnt(4)
	v_mfma_f32_32x32x16_bf16 v[0:15], v[212:215], v[220:223], v[0:15]
	ds_read_b128 v[212:215], v96 offset:41504
	s_waitcnt lgkmcnt(4)
	v_mfma_f32_32x32x16_bf16 v[48:63], v[224:227], v[216:219], v[48:63]
	ds_read_b128 v[216:219], v96 offset:36928
	v_mfma_f32_32x32x16_bf16 v[16:31], v[224:227], v[220:223], v[16:31]
	ds_read_b128 v[224:227], v176 offset:64
	ds_read_b128 v[220:223], v176 offset:4672
	s_waitcnt lgkmcnt(5)
	v_mfma_f32_32x32x16_bf16 v[32:47], v[228:231], v[244:247], v[32:47]
	s_waitcnt lgkmcnt(4)
	v_mfma_f32_32x32x16_bf16 v[0:15], v[228:231], v[252:255], v[0:15]
	ds_read_b128 v[228:231], v96 offset:41536
	s_waitcnt lgkmcnt(4)
	v_mfma_f32_32x32x16_bf16 v[48:63], v[212:215], v[244:247], v[48:63]
	ds_read_b128 v[244:247], v96 offset:36960
	v_mfma_f32_32x32x16_bf16 v[16:31], v[212:215], v[252:255], v[16:31]
	ds_read_b128 v[212:215], v176 offset:96
	ds_read_b128 v[252:255], v176 offset:4704
	s_waitcnt lgkmcnt(5)
	v_mfma_f32_32x32x16_bf16 v[32:47], v[216:219], v[224:227], v[32:47]
	s_waitcnt vmcnt(15)
	ds_write_b128 v175, v[68:71] offset:18432
	global_load_dwordx4 v[68:71], v[152:153], off offset:896
	s_waitcnt lgkmcnt(5)
	v_mfma_f32_32x32x16_bf16 v[0:15], v[216:219], v[220:223], v[0:15]
	ds_read_b128 v[216:219], v96 offset:41568
	s_waitcnt vmcnt(15)
	ds_write_b128 v175, v[84:87] offset:23040
	global_load_dwordx4 v[84:87], v[154:155], off offset:896
	s_waitcnt lgkmcnt(6)
	v_mfma_f32_32x32x16_bf16 v[48:63], v[228:231], v[224:227], v[48:63]
	s_waitcnt vmcnt(15)
	ds_write_b128 v175, v[88:91] offset:27648
	global_load_dwordx4 v[88:91], v[156:157], off offset:896
	v_mfma_f32_32x32x16_bf16 v[16:31], v[228:231], v[220:223], v[16:31]
	s_waitcnt vmcnt(15)
	ds_write_b128 v175, v[92:95] offset:32256
	global_load_dwordx4 v[92:95], v[158:159], off offset:896
	s_waitcnt lgkmcnt(6)
	v_mfma_f32_32x32x16_bf16 v[32:47], v[244:247], v[212:215], v[32:47]
	s_waitcnt vmcnt(15)
	ds_write_b128 v175, v[98:101] offset:55296
	global_load_dwordx4 v[98:101], v[150:151], off offset:896
	s_waitcnt lgkmcnt(6)
	v_mfma_f32_32x32x16_bf16 v[0:15], v[244:247], v[252:255], v[0:15]
	s_waitcnt vmcnt(15)
	ds_write_b128 v175, v[106:109] offset:59904
	global_load_dwordx4 v[106:109], v[160:161], off offset:896
	s_waitcnt lgkmcnt(5)
	v_mfma_f32_32x32x16_bf16 v[48:63], v[216:219], v[212:215], v[48:63]
	s_waitcnt vmcnt(15)
	ds_write_b128 v175, v[110:113] offset:64512
	global_load_dwordx4 v[110:113], v[170:171], off offset:896
	v_mfma_f32_32x32x16_bf16 v[16:31], v[216:219], v[252:255], v[16:31]
	s_waitcnt vmcnt(15)
	ds_write_b128 v177, v[114:117] offset:13824
	global_load_dwordx4 v[114:117], v[172:173], off offset:896
	s_setprio 0
	s_waitcnt lgkmcnt(0)
	s_barrier
	s_setprio 1
	ds_read_b128 v[212:215], v96 offset:55296
	ds_read_b128 v[216:219], v176 offset:18432
	ds_read_b128 v[220:223], v176 offset:23040
	ds_read_b128 v[224:227], v96 offset:59904
	ds_read_b128 v[228:231], v96 offset:55328
	ds_read_b128 v[244:247], v176 offset:18464
	ds_read_b128 v[252:255], v176 offset:23072
	s_waitcnt lgkmcnt(5)
	v_mfma_f32_32x32x16_bf16 v[32:47], v[212:215], v[216:219], v[32:47]
	s_waitcnt lgkmcnt(4)
	v_mfma_f32_32x32x16_bf16 v[0:15], v[212:215], v[220:223], v[0:15]
	ds_read_b128 v[212:215], v96 offset:59936
	s_waitcnt lgkmcnt(4)
	v_mfma_f32_32x32x16_bf16 v[48:63], v[224:227], v[216:219], v[48:63]
	ds_read_b128 v[216:219], v96 offset:55360
	v_mfma_f32_32x32x16_bf16 v[16:31], v[224:227], v[220:223], v[16:31]
	ds_read_b128 v[224:227], v176 offset:18496
	ds_read_b128 v[220:223], v176 offset:23104
	s_waitcnt lgkmcnt(5)
	v_mfma_f32_32x32x16_bf16 v[32:47], v[228:231], v[244:247], v[32:47]
	s_waitcnt lgkmcnt(4)
	v_mfma_f32_32x32x16_bf16 v[0:15], v[228:231], v[252:255], v[0:15]
	ds_read_b128 v[228:231], v96 offset:59968
	s_waitcnt lgkmcnt(4)
	v_mfma_f32_32x32x16_bf16 v[48:63], v[212:215], v[244:247], v[48:63]
	ds_read_b128 v[244:247], v96 offset:55392
	v_mfma_f32_32x32x16_bf16 v[16:31], v[212:215], v[252:255], v[16:31]
	ds_read_b128 v[212:215], v176 offset:18528
	ds_read_b128 v[252:255], v176 offset:23136
	s_waitcnt lgkmcnt(5)
	v_mfma_f32_32x32x16_bf16 v[32:47], v[216:219], v[224:227], v[32:47]
	s_waitcnt vmcnt(15)
	ds_write_b128 v175, v[64:67]
	global_load_dwordx4 v[64:67], v[152:153], off offset:1024
	s_waitcnt lgkmcnt(5)
	v_mfma_f32_32x32x16_bf16 v[0:15], v[216:219], v[220:223], v[0:15]
	ds_read_b128 v[216:219], v96 offset:60000
	s_waitcnt vmcnt(15)
	ds_write_b128 v175, v[72:75] offset:4608
	global_load_dwordx4 v[72:75], v[154:155], off offset:1024
	s_waitcnt lgkmcnt(6)
	v_mfma_f32_32x32x16_bf16 v[48:63], v[228:231], v[224:227], v[48:63]
	s_waitcnt vmcnt(15)
	ds_write_b128 v175, v[76:79] offset:9216
	global_load_dwordx4 v[76:79], v[156:157], off offset:1024
	v_mfma_f32_32x32x16_bf16 v[16:31], v[228:231], v[220:223], v[16:31]
	s_waitcnt vmcnt(15)
	ds_write_b128 v175, v[80:83] offset:13824
	global_load_dwordx4 v[80:83], v[158:159], off offset:1024
	s_waitcnt lgkmcnt(6)
	v_mfma_f32_32x32x16_bf16 v[32:47], v[244:247], v[212:215], v[32:47]
	s_waitcnt vmcnt(15)
	ds_write_b128 v175, v[102:105] offset:36864
	global_load_dwordx4 v[102:105], v[150:151], off offset:1024
	s_waitcnt lgkmcnt(6)
	v_mfma_f32_32x32x16_bf16 v[0:15], v[244:247], v[252:255], v[0:15]
	s_waitcnt vmcnt(15)
	ds_write_b128 v175, v[118:121] offset:41472
	global_load_dwordx4 v[118:121], v[160:161], off offset:1024
	s_waitcnt lgkmcnt(5)
	v_mfma_f32_32x32x16_bf16 v[48:63], v[216:219], v[212:215], v[48:63]
	s_waitcnt vmcnt(15)
	ds_write_b128 v175, v[122:125] offset:46080
	global_load_dwordx4 v[122:125], v[170:171], off offset:1024
	v_mfma_f32_32x32x16_bf16 v[16:31], v[216:219], v[252:255], v[16:31]
	s_waitcnt vmcnt(15)
	ds_write_b128 v175, v[126:129] offset:50688
	global_load_dwordx4 v[126:129], v[172:173], off offset:1024
	s_setprio 0
	s_waitcnt lgkmcnt(0)
	s_barrier
	s_setprio 1
	ds_read_b128 v[212:215], v96 offset:36864
	ds_read_b128 v[216:219], v176
	ds_read_b128 v[220:223], v176 offset:4608
	ds_read_b128 v[224:227], v96 offset:41472
	ds_read_b128 v[228:231], v96 offset:36896
	ds_read_b128 v[244:247], v176 offset:32
	ds_read_b128 v[252:255], v176 offset:4640
	s_waitcnt lgkmcnt(5)
	v_mfma_f32_32x32x16_bf16 v[32:47], v[212:215], v[216:219], v[32:47]
	s_waitcnt lgkmcnt(4)
	v_mfma_f32_32x32x16_bf16 v[0:15], v[212:215], v[220:223], v[0:15]
	ds_read_b128 v[212:215], v96 offset:41504
	s_waitcnt lgkmcnt(4)
	v_mfma_f32_32x32x16_bf16 v[48:63], v[224:227], v[216:219], v[48:63]
	ds_read_b128 v[216:219], v96 offset:36928
	v_mfma_f32_32x32x16_bf16 v[16:31], v[224:227], v[220:223], v[16:31]
	ds_read_b128 v[224:227], v176 offset:64
	ds_read_b128 v[220:223], v176 offset:4672
	s_waitcnt lgkmcnt(5)
	v_mfma_f32_32x32x16_bf16 v[32:47], v[228:231], v[244:247], v[32:47]
	s_waitcnt lgkmcnt(4)
	v_mfma_f32_32x32x16_bf16 v[0:15], v[228:231], v[252:255], v[0:15]
	ds_read_b128 v[228:231], v96 offset:41536
	s_waitcnt lgkmcnt(4)
	v_mfma_f32_32x32x16_bf16 v[48:63], v[212:215], v[244:247], v[48:63]
	ds_read_b128 v[244:247], v96 offset:36960
	v_mfma_f32_32x32x16_bf16 v[16:31], v[212:215], v[252:255], v[16:31]
	ds_read_b128 v[212:215], v176 offset:96
	ds_read_b128 v[252:255], v176 offset:4704
	s_waitcnt lgkmcnt(5)
	v_mfma_f32_32x32x16_bf16 v[32:47], v[216:219], v[224:227], v[32:47]
	s_waitcnt vmcnt(15)
	ds_write_b128 v175, v[68:71] offset:18432
	global_load_dwordx4 v[68:71], v[152:153], off offset:1152
	s_waitcnt lgkmcnt(5)
	v_mfma_f32_32x32x16_bf16 v[0:15], v[216:219], v[220:223], v[0:15]
	ds_read_b128 v[216:219], v96 offset:41568
	s_waitcnt vmcnt(15)
	ds_write_b128 v175, v[84:87] offset:23040
	global_load_dwordx4 v[84:87], v[154:155], off offset:1152
	s_waitcnt lgkmcnt(6)
	v_mfma_f32_32x32x16_bf16 v[48:63], v[228:231], v[224:227], v[48:63]
	s_waitcnt vmcnt(15)
	ds_write_b128 v175, v[88:91] offset:27648
	global_load_dwordx4 v[88:91], v[156:157], off offset:1152
	v_mfma_f32_32x32x16_bf16 v[16:31], v[228:231], v[220:223], v[16:31]
	s_waitcnt vmcnt(15)
	ds_write_b128 v175, v[92:95] offset:32256
	global_load_dwordx4 v[92:95], v[158:159], off offset:1152
	s_waitcnt lgkmcnt(6)
	v_mfma_f32_32x32x16_bf16 v[32:47], v[244:247], v[212:215], v[32:47]
	s_waitcnt vmcnt(15)
	ds_write_b128 v175, v[98:101] offset:55296
	global_load_dwordx4 v[98:101], v[150:151], off offset:1152
	s_waitcnt lgkmcnt(6)
	v_mfma_f32_32x32x16_bf16 v[0:15], v[244:247], v[252:255], v[0:15]
	s_waitcnt vmcnt(15)
	ds_write_b128 v175, v[106:109] offset:59904
	global_load_dwordx4 v[106:109], v[160:161], off offset:1152
	s_waitcnt lgkmcnt(5)
	v_mfma_f32_32x32x16_bf16 v[48:63], v[216:219], v[212:215], v[48:63]
	s_waitcnt vmcnt(15)
	ds_write_b128 v175, v[110:113] offset:64512
	global_load_dwordx4 v[110:113], v[170:171], off offset:1152
	v_mfma_f32_32x32x16_bf16 v[16:31], v[216:219], v[252:255], v[16:31]
	s_waitcnt vmcnt(15)
	ds_write_b128 v177, v[114:117] offset:13824
	global_load_dwordx4 v[114:117], v[172:173], off offset:1152
	s_setprio 0
	s_waitcnt lgkmcnt(0)
	s_barrier
	s_setprio 1
	ds_read_b128 v[212:215], v96 offset:55296
	ds_read_b128 v[216:219], v176 offset:18432
	ds_read_b128 v[220:223], v176 offset:23040
	ds_read_b128 v[224:227], v96 offset:59904
	ds_read_b128 v[228:231], v96 offset:55328
	ds_read_b128 v[244:247], v176 offset:18464
	ds_read_b128 v[252:255], v176 offset:23072
	s_waitcnt lgkmcnt(5)
	v_mfma_f32_32x32x16_bf16 v[32:47], v[212:215], v[216:219], v[32:47]
	s_waitcnt lgkmcnt(4)
	v_mfma_f32_32x32x16_bf16 v[0:15], v[212:215], v[220:223], v[0:15]
	ds_read_b128 v[212:215], v96 offset:59936
	s_waitcnt lgkmcnt(4)
	v_mfma_f32_32x32x16_bf16 v[48:63], v[224:227], v[216:219], v[48:63]
	ds_read_b128 v[216:219], v96 offset:55360
	v_mfma_f32_32x32x16_bf16 v[16:31], v[224:227], v[220:223], v[16:31]
	ds_read_b128 v[224:227], v176 offset:18496
	ds_read_b128 v[220:223], v176 offset:23104
	s_waitcnt lgkmcnt(5)
	v_mfma_f32_32x32x16_bf16 v[32:47], v[228:231], v[244:247], v[32:47]
	s_waitcnt lgkmcnt(4)
	v_mfma_f32_32x32x16_bf16 v[0:15], v[228:231], v[252:255], v[0:15]
	ds_read_b128 v[228:231], v96 offset:59968
	s_waitcnt lgkmcnt(4)
	v_mfma_f32_32x32x16_bf16 v[48:63], v[212:215], v[244:247], v[48:63]
	ds_read_b128 v[244:247], v96 offset:55392
	v_mfma_f32_32x32x16_bf16 v[16:31], v[212:215], v[252:255], v[16:31]
	ds_read_b128 v[212:215], v176 offset:18528
	ds_read_b128 v[252:255], v176 offset:23136
	s_waitcnt lgkmcnt(5)
	v_mfma_f32_32x32x16_bf16 v[32:47], v[216:219], v[224:227], v[32:47]
	s_waitcnt vmcnt(15)
	ds_write_b128 v175, v[64:67]
	global_load_dwordx4 v[64:67], v[152:153], off offset:1280
	s_waitcnt lgkmcnt(5)
	v_mfma_f32_32x32x16_bf16 v[0:15], v[216:219], v[220:223], v[0:15]
	ds_read_b128 v[216:219], v96 offset:60000
	s_waitcnt vmcnt(15)
	ds_write_b128 v175, v[72:75] offset:4608
	global_load_dwordx4 v[72:75], v[154:155], off offset:1280
	s_waitcnt lgkmcnt(6)
	v_mfma_f32_32x32x16_bf16 v[48:63], v[228:231], v[224:227], v[48:63]
	s_waitcnt vmcnt(15)
	ds_write_b128 v175, v[76:79] offset:9216
	global_load_dwordx4 v[76:79], v[156:157], off offset:1280
	v_mfma_f32_32x32x16_bf16 v[16:31], v[228:231], v[220:223], v[16:31]
	s_waitcnt vmcnt(15)
	ds_write_b128 v175, v[80:83] offset:13824
	global_load_dwordx4 v[80:83], v[158:159], off offset:1280
	s_waitcnt lgkmcnt(6)
	v_mfma_f32_32x32x16_bf16 v[32:47], v[244:247], v[212:215], v[32:47]
	s_waitcnt vmcnt(15)
	ds_write_b128 v175, v[102:105] offset:36864
	global_load_dwordx4 v[102:105], v[150:151], off offset:1280
	s_waitcnt lgkmcnt(6)
	v_mfma_f32_32x32x16_bf16 v[0:15], v[244:247], v[252:255], v[0:15]
	s_waitcnt vmcnt(15)
	ds_write_b128 v175, v[118:121] offset:41472
	global_load_dwordx4 v[118:121], v[160:161], off offset:1280
	s_waitcnt lgkmcnt(5)
	v_mfma_f32_32x32x16_bf16 v[48:63], v[216:219], v[212:215], v[48:63]
	s_waitcnt vmcnt(15)
	ds_write_b128 v175, v[122:125] offset:46080
	global_load_dwordx4 v[122:125], v[170:171], off offset:1280
	v_mfma_f32_32x32x16_bf16 v[16:31], v[216:219], v[252:255], v[16:31]
	s_waitcnt vmcnt(15)
	ds_write_b128 v175, v[126:129] offset:50688
	global_load_dwordx4 v[126:129], v[172:173], off offset:1280
	s_setprio 0
	s_waitcnt lgkmcnt(0)
	s_barrier
	s_setprio 1
	ds_read_b128 v[212:215], v96 offset:36864
	ds_read_b128 v[216:219], v176
	ds_read_b128 v[220:223], v176 offset:4608
	ds_read_b128 v[224:227], v96 offset:41472
	ds_read_b128 v[228:231], v96 offset:36896
	ds_read_b128 v[244:247], v176 offset:32
	ds_read_b128 v[252:255], v176 offset:4640
	s_waitcnt lgkmcnt(5)
	v_mfma_f32_32x32x16_bf16 v[32:47], v[212:215], v[216:219], v[32:47]
	s_waitcnt lgkmcnt(4)
	v_mfma_f32_32x32x16_bf16 v[0:15], v[212:215], v[220:223], v[0:15]
	ds_read_b128 v[212:215], v96 offset:41504
	s_waitcnt lgkmcnt(4)
	v_mfma_f32_32x32x16_bf16 v[48:63], v[224:227], v[216:219], v[48:63]
	ds_read_b128 v[216:219], v96 offset:36928
	v_mfma_f32_32x32x16_bf16 v[16:31], v[224:227], v[220:223], v[16:31]
	ds_read_b128 v[224:227], v176 offset:64
	ds_read_b128 v[220:223], v176 offset:4672
	s_waitcnt lgkmcnt(5)
	v_mfma_f32_32x32x16_bf16 v[32:47], v[228:231], v[244:247], v[32:47]
	s_waitcnt lgkmcnt(4)
	v_mfma_f32_32x32x16_bf16 v[0:15], v[228:231], v[252:255], v[0:15]
	ds_read_b128 v[228:231], v96 offset:41536
	s_waitcnt lgkmcnt(4)
	v_mfma_f32_32x32x16_bf16 v[48:63], v[212:215], v[244:247], v[48:63]
	ds_read_b128 v[244:247], v96 offset:36960
	v_mfma_f32_32x32x16_bf16 v[16:31], v[212:215], v[252:255], v[16:31]
	ds_read_b128 v[212:215], v176 offset:96
	ds_read_b128 v[252:255], v176 offset:4704
	s_waitcnt lgkmcnt(5)
	v_mfma_f32_32x32x16_bf16 v[32:47], v[216:219], v[224:227], v[32:47]
	s_waitcnt vmcnt(15)
	ds_write_b128 v175, v[68:71] offset:18432
	global_load_dwordx4 v[68:71], v[152:153], off offset:1408
	s_waitcnt lgkmcnt(5)
	v_mfma_f32_32x32x16_bf16 v[0:15], v[216:219], v[220:223], v[0:15]
	ds_read_b128 v[216:219], v96 offset:41568
	s_waitcnt vmcnt(15)
	ds_write_b128 v175, v[84:87] offset:23040
	global_load_dwordx4 v[84:87], v[154:155], off offset:1408
	s_waitcnt lgkmcnt(6)
	v_mfma_f32_32x32x16_bf16 v[48:63], v[228:231], v[224:227], v[48:63]
	s_waitcnt vmcnt(15)
	ds_write_b128 v175, v[88:91] offset:27648
	global_load_dwordx4 v[88:91], v[156:157], off offset:1408
	v_mfma_f32_32x32x16_bf16 v[16:31], v[228:231], v[220:223], v[16:31]
	s_waitcnt vmcnt(15)
	ds_write_b128 v175, v[92:95] offset:32256
	global_load_dwordx4 v[92:95], v[158:159], off offset:1408
	s_waitcnt lgkmcnt(6)
	v_mfma_f32_32x32x16_bf16 v[32:47], v[244:247], v[212:215], v[32:47]
	s_waitcnt vmcnt(15)
	ds_write_b128 v175, v[98:101] offset:55296
	global_load_dwordx4 v[98:101], v[150:151], off offset:1408
	s_waitcnt lgkmcnt(6)
	v_mfma_f32_32x32x16_bf16 v[0:15], v[244:247], v[252:255], v[0:15]
	s_waitcnt vmcnt(15)
	ds_write_b128 v175, v[106:109] offset:59904
	global_load_dwordx4 v[106:109], v[160:161], off offset:1408
	s_waitcnt lgkmcnt(5)
	v_mfma_f32_32x32x16_bf16 v[48:63], v[216:219], v[212:215], v[48:63]
	s_waitcnt vmcnt(15)
	ds_write_b128 v175, v[110:113] offset:64512
	global_load_dwordx4 v[110:113], v[170:171], off offset:1408
	v_mfma_f32_32x32x16_bf16 v[16:31], v[216:219], v[252:255], v[16:31]
	s_waitcnt vmcnt(15)
	ds_write_b128 v177, v[114:117] offset:13824
	global_load_dwordx4 v[130:133], v[172:173], off offset:1408
	s_setprio 0
	s_waitcnt lgkmcnt(0)
	s_barrier
	s_setprio 1
	ds_read_b128 v[212:215], v96 offset:55296
	ds_read_b128 v[216:219], v176 offset:18432
	ds_read_b128 v[220:223], v176 offset:23040
	ds_read_b128 v[224:227], v96 offset:59904
	ds_read_b128 v[228:231], v96 offset:55328
	ds_read_b128 v[244:247], v176 offset:18464
	ds_read_b128 v[252:255], v176 offset:23072
	s_waitcnt lgkmcnt(5)
	v_mfma_f32_32x32x16_bf16 v[32:47], v[212:215], v[216:219], v[32:47]
	s_waitcnt lgkmcnt(4)
	v_mfma_f32_32x32x16_bf16 v[0:15], v[212:215], v[220:223], v[0:15]
	ds_read_b128 v[212:215], v96 offset:59936
	s_waitcnt lgkmcnt(4)
	v_mfma_f32_32x32x16_bf16 v[48:63], v[224:227], v[216:219], v[48:63]
	ds_read_b128 v[216:219], v96 offset:55360
	v_mfma_f32_32x32x16_bf16 v[16:31], v[224:227], v[220:223], v[16:31]
	ds_read_b128 v[224:227], v176 offset:18496
	ds_read_b128 v[220:223], v176 offset:23104
	s_waitcnt lgkmcnt(5)
	v_mfma_f32_32x32x16_bf16 v[32:47], v[228:231], v[244:247], v[32:47]
	s_waitcnt lgkmcnt(4)
	v_mfma_f32_32x32x16_bf16 v[0:15], v[228:231], v[252:255], v[0:15]
	ds_read_b128 v[228:231], v96 offset:59968
	s_waitcnt lgkmcnt(4)
	v_mfma_f32_32x32x16_bf16 v[48:63], v[212:215], v[244:247], v[48:63]
	ds_read_b128 v[244:247], v96 offset:55392
	v_mfma_f32_32x32x16_bf16 v[16:31], v[212:215], v[252:255], v[16:31]
	ds_read_b128 v[212:215], v176 offset:18528
	ds_read_b128 v[252:255], v176 offset:23136
	s_waitcnt lgkmcnt(5)
	v_mfma_f32_32x32x16_bf16 v[32:47], v[216:219], v[224:227], v[32:47]
	s_waitcnt vmcnt(15)
	ds_write_b128 v175, v[64:67]
	global_load_dwordx4 v[64:67], v[152:153], off offset:1536
	s_waitcnt lgkmcnt(5)
	v_mfma_f32_32x32x16_bf16 v[0:15], v[216:219], v[220:223], v[0:15]
	ds_read_b128 v[216:219], v96 offset:60000
	s_waitcnt vmcnt(15)
	ds_write_b128 v175, v[72:75] offset:4608
	global_load_dwordx4 v[72:75], v[154:155], off offset:1536
	s_waitcnt lgkmcnt(6)
	v_mfma_f32_32x32x16_bf16 v[48:63], v[228:231], v[224:227], v[48:63]
	s_waitcnt vmcnt(15)
	ds_write_b128 v175, v[76:79] offset:9216
	global_load_dwordx4 v[76:79], v[156:157], off offset:1536
	v_mfma_f32_32x32x16_bf16 v[16:31], v[228:231], v[220:223], v[16:31]
	s_waitcnt vmcnt(15)
	ds_write_b128 v175, v[80:83] offset:13824
	global_load_dwordx4 v[80:83], v[158:159], off offset:1536
	s_waitcnt lgkmcnt(6)
	v_mfma_f32_32x32x16_bf16 v[32:47], v[244:247], v[212:215], v[32:47]
	s_waitcnt vmcnt(15)
	ds_write_b128 v175, v[102:105] offset:36864
	global_load_dwordx4 v[114:117], v[150:151], off offset:1536
	s_waitcnt lgkmcnt(6)
	v_mfma_f32_32x32x16_bf16 v[0:15], v[244:247], v[252:255], v[0:15]
	s_waitcnt vmcnt(15)
	ds_write_b128 v175, v[118:121] offset:41472
	s_waitcnt vmcnt(14)
	ds_write_b128 v175, v[122:125] offset:46080
	s_waitcnt lgkmcnt(6)
	v_mfma_f32_32x32x16_bf16 v[48:63], v[216:219], v[212:215], v[48:63]
	global_load_dwordx4 v[122:125], v[160:161], off offset:1536
	s_waitcnt vmcnt(14)
	ds_write_b128 v175, v[126:129] offset:50688
	v_mfma_f32_32x32x16_bf16 v[16:31], v[216:219], v[252:255], v[16:31]
	global_load_dwordx4 v[126:129], v[170:171], off offset:1536
	global_load_dwordx4 v[134:137], v[172:173], off offset:1536
	s_setprio 0
	s_waitcnt lgkmcnt(0)
	s_barrier
	s_setprio 1
	ds_read_b128 v[212:215], v96 offset:36864
	ds_read_b128 v[216:219], v176
	ds_read_b128 v[220:223], v176 offset:4608
	ds_read_b128 v[224:227], v96 offset:41472
	ds_read_b128 v[228:231], v96 offset:36896
	ds_read_b128 v[244:247], v176 offset:32
	ds_read_b128 v[252:255], v176 offset:4640
	s_waitcnt lgkmcnt(5)
	v_mfma_f32_32x32x16_bf16 v[32:47], v[212:215], v[216:219], v[32:47]
	s_waitcnt lgkmcnt(4)
	v_mfma_f32_32x32x16_bf16 v[0:15], v[212:215], v[220:223], v[0:15]
	ds_read_b128 v[212:215], v96 offset:41504
	s_waitcnt lgkmcnt(4)
	v_mfma_f32_32x32x16_bf16 v[48:63], v[224:227], v[216:219], v[48:63]
	ds_read_b128 v[216:219], v96 offset:36928
	v_mfma_f32_32x32x16_bf16 v[16:31], v[224:227], v[220:223], v[16:31]
	ds_read_b128 v[224:227], v176 offset:64
	ds_read_b128 v[220:223], v176 offset:4672
	s_waitcnt lgkmcnt(5)
	v_mfma_f32_32x32x16_bf16 v[32:47], v[228:231], v[244:247], v[32:47]
	s_waitcnt lgkmcnt(4)
	v_mfma_f32_32x32x16_bf16 v[0:15], v[228:231], v[252:255], v[0:15]
	ds_read_b128 v[228:231], v96 offset:41536
	s_waitcnt lgkmcnt(4)
	v_mfma_f32_32x32x16_bf16 v[48:63], v[212:215], v[244:247], v[48:63]
	ds_read_b128 v[244:247], v96 offset:36960
	v_mfma_f32_32x32x16_bf16 v[16:31], v[212:215], v[252:255], v[16:31]
	ds_read_b128 v[212:215], v176 offset:96
	ds_read_b128 v[252:255], v176 offset:4704
	s_waitcnt lgkmcnt(5)
	v_mfma_f32_32x32x16_bf16 v[32:47], v[216:219], v[224:227], v[32:47]
	s_waitcnt vmcnt(15)
	ds_write_b128 v175, v[68:71] offset:18432
	s_waitcnt vmcnt(14)
	ds_write_b128 v175, v[84:87] offset:23040
	s_waitcnt lgkmcnt(6)
	v_mfma_f32_32x32x16_bf16 v[0:15], v[216:219], v[220:223], v[0:15]
	ds_read_b128 v[216:219], v96 offset:41568
	s_waitcnt vmcnt(13)
	ds_write_b128 v175, v[88:91] offset:27648
	s_waitcnt vmcnt(12)
	ds_write_b128 v175, v[92:95] offset:32256
	s_waitcnt lgkmcnt(8)
	v_mfma_f32_32x32x16_bf16 v[48:63], v[228:231], v[224:227], v[48:63]
	s_waitcnt vmcnt(11)
	ds_write_b128 v175, v[98:101] offset:55296
	v_mfma_f32_32x32x16_bf16 v[16:31], v[228:231], v[220:223], v[16:31]
	global_load_dwordx4 v[98:101], v[152:153], off offset:1664
	global_load_dwordx4 v[102:105], v[154:155], off offset:1664
	s_waitcnt vmcnt(12)
	ds_write_b128 v175, v[106:109] offset:59904
	s_waitcnt lgkmcnt(8)
	v_mfma_f32_32x32x16_bf16 v[32:47], v[244:247], v[212:215], v[32:47]
	global_load_dwordx4 v[106:109], v[156:157], off offset:1664
	s_waitcnt vmcnt(12)
	ds_write_b128 v175, v[110:113] offset:64512
	s_waitcnt lgkmcnt(8)
	v_mfma_f32_32x32x16_bf16 v[0:15], v[244:247], v[252:255], v[0:15]
	global_load_dwordx4 v[110:113], v[158:159], off offset:1664
	global_load_dwordx4 v[118:121], v[150:151], off offset:1664
	s_waitcnt lgkmcnt(5)
	v_mfma_f32_32x32x16_bf16 v[48:63], v[216:219], v[212:215], v[48:63]
	s_waitcnt vmcnt(13)
	ds_write_b128 v177, v[130:133] offset:13824
	global_load_dwordx4 v[130:133], v[160:161], off offset:1664
	v_mfma_f32_32x32x16_bf16 v[16:31], v[216:219], v[252:255], v[16:31]
	global_load_dwordx4 v[138:141], v[170:171], off offset:1664
	global_load_dwordx4 v[142:145], v[172:173], off offset:1664
	s_setprio 0
	s_waitcnt lgkmcnt(0)
	s_barrier
	s_setprio 1
	ds_read_b128 v[212:215], v96 offset:55296
	ds_read_b128 v[216:219], v176 offset:18432
	ds_read_b128 v[220:223], v176 offset:23040
	ds_read_b128 v[224:227], v96 offset:59904
	ds_read_b128 v[228:231], v96 offset:55328
	ds_read_b128 v[244:247], v176 offset:18464
	ds_read_b128 v[252:255], v176 offset:23072
	s_waitcnt lgkmcnt(5)
	v_mfma_f32_32x32x16_bf16 v[32:47], v[212:215], v[216:219], v[32:47]
	s_waitcnt lgkmcnt(4)
	v_mfma_f32_32x32x16_bf16 v[0:15], v[212:215], v[220:223], v[0:15]
	ds_read_b128 v[212:215], v96 offset:59936
	s_waitcnt lgkmcnt(4)
	v_mfma_f32_32x32x16_bf16 v[48:63], v[224:227], v[216:219], v[48:63]
	ds_read_b128 v[216:219], v96 offset:55360
	v_mfma_f32_32x32x16_bf16 v[16:31], v[224:227], v[220:223], v[16:31]
	ds_read_b128 v[224:227], v176 offset:18496
	ds_read_b128 v[220:223], v176 offset:23104
	s_waitcnt lgkmcnt(5)
	v_mfma_f32_32x32x16_bf16 v[32:47], v[228:231], v[244:247], v[32:47]
	s_waitcnt lgkmcnt(4)
	v_mfma_f32_32x32x16_bf16 v[0:15], v[228:231], v[252:255], v[0:15]
	ds_read_b128 v[228:231], v96 offset:59968
	s_waitcnt lgkmcnt(4)
	v_mfma_f32_32x32x16_bf16 v[48:63], v[212:215], v[244:247], v[48:63]
	ds_read_b128 v[244:247], v96 offset:55392
	v_mfma_f32_32x32x16_bf16 v[16:31], v[212:215], v[252:255], v[16:31]
	ds_read_b128 v[212:215], v176 offset:18528
	ds_read_b128 v[252:255], v176 offset:23136
	s_waitcnt lgkmcnt(5)
	v_mfma_f32_32x32x16_bf16 v[32:47], v[216:219], v[224:227], v[32:47]
	s_waitcnt vmcnt(15)
	ds_write_b128 v175, v[64:67]
	global_load_dwordx4 v[64:67], v[152:153], off offset:1792
	s_waitcnt lgkmcnt(5)
	v_mfma_f32_32x32x16_bf16 v[0:15], v[216:219], v[220:223], v[0:15]
	ds_read_b128 v[216:219], v96 offset:60000
	s_waitcnt vmcnt(15)
	ds_write_b128 v175, v[72:75] offset:4608
	global_load_dwordx4 v[68:71], v[154:155], off offset:1792
	s_waitcnt lgkmcnt(6)
	v_mfma_f32_32x32x16_bf16 v[48:63], v[228:231], v[224:227], v[48:63]
	s_waitcnt vmcnt(15)
	ds_write_b128 v175, v[76:79] offset:9216
	global_load_dwordx4 v[72:75], v[156:157], off offset:1792
	v_mfma_f32_32x32x16_bf16 v[16:31], v[228:231], v[220:223], v[16:31]
	s_waitcnt vmcnt(15)
	ds_write_b128 v175, v[80:83] offset:13824
	global_load_dwordx4 v[76:79], v[158:159], off offset:1792
	s_waitcnt lgkmcnt(6)
	v_mfma_f32_32x32x16_bf16 v[32:47], v[244:247], v[212:215], v[32:47]
	s_waitcnt vmcnt(15)
	ds_write_b128 v175, v[114:117] offset:36864
	global_load_dwordx4 v[80:83], v[150:151], off offset:1792
	s_waitcnt lgkmcnt(6)
	v_mfma_f32_32x32x16_bf16 v[0:15], v[244:247], v[252:255], v[0:15]
	s_waitcnt vmcnt(15)
	ds_write_b128 v175, v[122:125] offset:41472
	global_load_dwordx4 v[84:87], v[160:161], off offset:1792
	s_waitcnt lgkmcnt(5)
	v_mfma_f32_32x32x16_bf16 v[48:63], v[216:219], v[212:215], v[48:63]
	s_waitcnt vmcnt(15)
	ds_write_b128 v175, v[126:129] offset:46080
	global_load_dwordx4 v[88:91], v[170:171], off offset:1792
	v_mfma_f32_32x32x16_bf16 v[16:31], v[216:219], v[252:255], v[16:31]
	s_waitcnt vmcnt(15)
	ds_write_b128 v175, v[134:137] offset:50688
	global_load_dwordx4 v[92:95], v[172:173], off offset:1792
	s_setprio 0
	s_waitcnt lgkmcnt(0)
	s_barrier
	s_setprio 1
	ds_read_b128 v[212:215], v96 offset:36864
	ds_read_b128 v[216:219], v176
	ds_read_b128 v[220:223], v176 offset:4608
	ds_read_b128 v[224:227], v96 offset:41472
	ds_read_b128 v[228:231], v96 offset:36896
	ds_read_b128 v[244:247], v176 offset:32
	ds_read_b128 v[252:255], v176 offset:4640
	s_waitcnt lgkmcnt(5)
	v_mfma_f32_32x32x16_bf16 v[32:47], v[212:215], v[216:219], v[32:47]
	s_waitcnt lgkmcnt(4)
	v_mfma_f32_32x32x16_bf16 v[0:15], v[212:215], v[220:223], v[0:15]
	ds_read_b128 v[212:215], v96 offset:41504
	s_waitcnt lgkmcnt(4)
	v_mfma_f32_32x32x16_bf16 v[48:63], v[224:227], v[216:219], v[48:63]
	ds_read_b128 v[216:219], v96 offset:36928
	v_mfma_f32_32x32x16_bf16 v[16:31], v[224:227], v[220:223], v[16:31]
	ds_read_b128 v[224:227], v176 offset:64
	ds_read_b128 v[220:223], v176 offset:4672
	s_waitcnt lgkmcnt(5)
	v_mfma_f32_32x32x16_bf16 v[32:47], v[228:231], v[244:247], v[32:47]
	s_waitcnt lgkmcnt(4)
	v_mfma_f32_32x32x16_bf16 v[0:15], v[228:231], v[252:255], v[0:15]
	ds_read_b128 v[228:231], v96 offset:41536
	s_waitcnt lgkmcnt(4)
	v_mfma_f32_32x32x16_bf16 v[48:63], v[212:215], v[244:247], v[48:63]
	ds_read_b128 v[244:247], v96 offset:36960
	v_mfma_f32_32x32x16_bf16 v[16:31], v[212:215], v[252:255], v[16:31]
	ds_read_b128 v[212:215], v176 offset:96
	ds_read_b128 v[252:255], v176 offset:4704
	s_waitcnt lgkmcnt(5)
	v_mfma_f32_32x32x16_bf16 v[32:47], v[216:219], v[224:227], v[32:47]
	s_waitcnt vmcnt(15)
	ds_write_b128 v175, v[98:101] offset:18432
	s_waitcnt vmcnt(14)
	ds_write_b128 v175, v[102:105] offset:23040
	s_waitcnt lgkmcnt(6)
	v_mfma_f32_32x32x16_bf16 v[0:15], v[216:219], v[220:223], v[0:15]
	ds_read_b128 v[216:219], v96 offset:41568
	global_load_dwordx4 v[100:103], v[152:153], off offset:1920
	s_waitcnt vmcnt(14)
	ds_write_b128 v175, v[106:109] offset:27648
	s_waitcnt lgkmcnt(7)
	v_mfma_f32_32x32x16_bf16 v[48:63], v[228:231], v[224:227], v[48:63]
	global_load_dwordx4 v[104:107], v[154:155], off offset:1920
	s_waitcnt vmcnt(14)
	ds_write_b128 v175, v[110:113] offset:32256
	v_mfma_f32_32x32x16_bf16 v[16:31], v[228:231], v[220:223], v[16:31]
	global_load_dwordx4 v[108:111], v[156:157], off offset:1920
	global_load_dwordx4 v[112:115], v[158:159], off offset:1920
	s_waitcnt lgkmcnt(6)
	v_mfma_f32_32x32x16_bf16 v[32:47], v[244:247], v[212:215], v[32:47]
	s_waitcnt vmcnt(15)
	ds_write_b128 v175, v[118:121] offset:55296
	global_load_dwordx4 v[116:119], v[150:151], off offset:1920
	s_waitcnt lgkmcnt(6)
	v_mfma_f32_32x32x16_bf16 v[0:15], v[244:247], v[252:255], v[0:15]
	s_waitcnt vmcnt(15)
	ds_write_b128 v175, v[130:133] offset:59904
	global_load_dwordx4 v[124:127], v[160:161], off offset:1920
	s_waitcnt lgkmcnt(4)
	v_mfma_f32_32x32x16_bf16 v[48:63], v[216:219], v[212:215], v[48:63]
	s_waitcnt vmcnt(15)
	ds_write_b128 v175, v[138:141] offset:64512
	global_load_dwordx4 v[120:123], v[170:171], off offset:1920
	v_mfma_f32_32x32x16_bf16 v[16:31], v[216:219], v[252:255], v[16:31]
	s_waitcnt vmcnt(15)
	ds_write_b128 v177, v[142:145] offset:13824
	global_load_dwordx4 v[128:131], v[172:173], off offset:1920
	s_setprio 0
	s_waitcnt lgkmcnt(0)
	s_barrier
	s_setprio 1
	ds_read_b128 v[212:215], v96 offset:55296
	ds_read_b128 v[216:219], v176 offset:18432
	ds_read_b128 v[220:223], v176 offset:23040
	ds_read_b128 v[224:227], v96 offset:59904
	ds_read_b128 v[228:231], v96 offset:55328
	ds_read_b128 v[244:247], v176 offset:18464
	ds_read_b128 v[252:255], v176 offset:23072
	s_waitcnt lgkmcnt(5)
	v_mfma_f32_32x32x16_bf16 v[32:47], v[212:215], v[216:219], v[32:47]
	s_waitcnt lgkmcnt(4)
	v_mfma_f32_32x32x16_bf16 v[0:15], v[212:215], v[220:223], v[0:15]
	ds_read_b128 v[212:215], v96 offset:59936
	s_waitcnt lgkmcnt(4)
	v_mfma_f32_32x32x16_bf16 v[48:63], v[224:227], v[216:219], v[48:63]
	ds_read_b128 v[216:219], v96 offset:55360
	v_mfma_f32_32x32x16_bf16 v[16:31], v[224:227], v[220:223], v[16:31]
	ds_read_b128 v[224:227], v176 offset:18496
	ds_read_b128 v[220:223], v176 offset:23104
	s_waitcnt lgkmcnt(5)
	v_mfma_f32_32x32x16_bf16 v[32:47], v[228:231], v[244:247], v[32:47]
	s_waitcnt lgkmcnt(4)
	v_mfma_f32_32x32x16_bf16 v[0:15], v[228:231], v[252:255], v[0:15]
	ds_read_b128 v[228:231], v96 offset:59968
	s_waitcnt lgkmcnt(4)
	v_mfma_f32_32x32x16_bf16 v[48:63], v[212:215], v[244:247], v[48:63]
	ds_read_b128 v[244:247], v96 offset:55392
	v_mfma_f32_32x32x16_bf16 v[16:31], v[212:215], v[252:255], v[16:31]
	ds_read_b128 v[212:215], v176 offset:18528
	ds_read_b128 v[252:255], v176 offset:23136
	s_waitcnt lgkmcnt(5)
	v_mfma_f32_32x32x16_bf16 v[32:47], v[216:219], v[224:227], v[32:47]
	s_waitcnt lgkmcnt(4)
	v_mfma_f32_32x32x16_bf16 v[0:15], v[216:219], v[220:223], v[0:15]
	ds_read_b128 v[216:219], v96 offset:60000
	s_waitcnt lgkmcnt(4)
	v_mfma_f32_32x32x16_bf16 v[48:63], v[228:231], v[224:227], v[48:63]
	v_mfma_f32_32x32x16_bf16 v[16:31], v[228:231], v[220:223], v[16:31]
	s_waitcnt lgkmcnt(2)
	v_mfma_f32_32x32x16_bf16 v[32:47], v[244:247], v[212:215], v[32:47]
	s_waitcnt lgkmcnt(1)
	v_mfma_f32_32x32x16_bf16 v[0:15], v[244:247], v[252:255], v[0:15]
	s_waitcnt lgkmcnt(0)
	v_mfma_f32_32x32x16_bf16 v[48:63], v[216:219], v[212:215], v[48:63]
	v_mfma_f32_32x32x16_bf16 v[16:31], v[216:219], v[252:255], v[16:31]
	s_setprio 0
	v_cndmask_b32_e64 v98, 0, 1, s[44:45]
	v_cmp_ne_u32_e64 s[40:41], 1, v98
	s_andn2_b64 vcc, exec, s[44:45]
	s_waitcnt vmcnt(15)
	ds_write_b128 v175, v[64:67]
	s_waitcnt vmcnt(14)
	ds_write_b128 v175, v[68:71] offset:4608
	s_waitcnt vmcnt(13)
	ds_write_b128 v175, v[72:75] offset:9216
	s_waitcnt vmcnt(12)
	ds_write_b128 v175, v[76:79] offset:13824
	s_waitcnt vmcnt(11)
	ds_write_b128 v175, v[80:83] offset:36864
	s_waitcnt vmcnt(10)
	ds_write_b128 v175, v[84:87] offset:41472
	s_waitcnt vmcnt(9)
	ds_write_b128 v175, v[88:91] offset:46080
	s_waitcnt vmcnt(8)
	ds_write_b128 v175, v[92:95] offset:50688
	s_cbranch_vccnz .LBB0_1355
	v_add_co_u32_e32 v68, vcc, 0x10000, v148
	global_load_dwordx4 v[64:67], v[148:149], off
	s_nop 0
	v_addc_co_u32_e32 v69, vcc, 0, v149, vcc
	v_add_co_u32_e32 v72, vcc, 0x20000, v148
	s_nop 1
	v_addc_co_u32_e32 v73, vcc, 0, v149, vcc
	v_add_co_u32_e32 v76, vcc, 0x30000, v148
	global_load_dwordx4 v[68:71], v[68:69], off
	global_load_dwordx4 v[72:75], v[72:73], off
	v_addc_co_u32_e32 v77, vcc, 0, v149, vcc
	v_add_co_u32_e32 v84, vcc, 0x10000, v146
	global_load_dwordx4 v[76:79], v[76:77], off
	s_nop 0
	global_load_dwordx4 v[80:83], v[146:147], off
	v_addc_co_u32_e32 v85, vcc, 0, v147, vcc
	v_add_co_u32_e32 v88, vcc, 0x20000, v146
	s_nop 1
	v_addc_co_u32_e32 v89, vcc, 0, v147, vcc
	v_add_co_u32_e32 v92, vcc, 0x30000, v146
	global_load_dwordx4 v[84:87], v[84:85], off
	s_nop 0
	global_load_dwordx4 v[88:91], v[88:89], off
	v_addc_co_u32_e32 v93, vcc, 0, v147, vcc
	global_load_dwordx4 v[92:95], v[92:93], off
